# UV sweep with one 8-byte-entry list per wave for the whole sweep (no per-chunk rebuilds), grouped U tail, coefficient stored in the list entry
# speedup vs baseline: 1.0623x; 1.0029x over previous
; __device__ __forceinline__ unsigned f2key(float f) { const unsigned u = __float_as_uint(f); return (u & 0x80000000u) ? ~u : (u | 0x80000000u); }
; __device__ __forceinline__ void peer_tile(const Args& A, LAS unsigned char* lds, int tile) {
;     ...
;                 const int hp = 2 * h + p;
;                 unsigned k0[16], k1[16];
;                 { const bf16_t* sp = QRY + m * 2048 + hp * 128 + 32 * g;
;                   const u32x4 s0 = *(const u32x4*)sp, s1 = *(const u32x4*)(sp + 8), s2 = *(const u32x4*)(sp + 16), s3 = *(const u32x4*)(sp + 24);
;                   const unsigned sw[16] = {s0.x, s0.y, s0.z, s0.w, s1.x, s1.y, s1.z, s1.w, s2.x, s2.y, s2.z, s2.w, s3.x, s3.y, s3.z, s3.w};
; #pragma unroll
;                   for (int i = 0; i < 16; ++i) {
;                       const float lo = (float)__builtin_bit_cast(_Float16, (unsigned short)(sw[i] & 0xffffu)), hi = (float)__builtin_bit_cast(_Float16, (unsigned short)(sw[i] >> 16));
;                       const unsigned klo = (f2key(lo) & ~127u) | (unsigned)(127 - (32 * g + 2 * i)), khi = (f2key(hi) & ~127u) | (unsigned)(127 - (32 * g + 2 * i + 1));
;                       if (i < 8) { k0[2 * i] = klo; k0[2 * i + 1] = khi; } else { k1[2 * (i - 8)] = klo; k1[2 * (i - 8) + 1] = khi; } } }
.LBB0_699:
	v_mov_b32_e32 v19, v214
	s_ashr_i32 s3, s2, 31
	v_ashrrev_i32_e32 v7, 6, v19
	v_and_b32_e32 v0, 15, v19
	v_lshlrev_b32_e32 v1, 4, v7
	v_and_or_b32 v13, v1, 48, v0
	s_lshl_b64 s[28:29], s[2:3], 6
	v_or_b32_e32 v0, s28, v13
	v_mov_b32_e32 v1, s29
	v_bfe_u32 v221, v19, 4, 2
	v_ashrrev_i32_e32 v11, 8, v19
	v_lshlrev_b64 v[0:1], 12, v[0:1]
	v_lshlrev_b32_e32 v2, 10, v11
	v_lshl_add_u64 v[0:1], s[54:55], 0, v[0:1]
	v_lshlrev_b32_e32 v112, 6, v221
	v_lshl_add_u64 v[0:1], v[0:1], 0, v[112:113]
	v_ashrrev_i32_e32 v3, 31, v2
	v_lshl_add_u64 v[4:5], v[2:3], 1, v[0:1]
	global_load_dwordx4 v[20:23], v[4:5], off
	global_load_dwordx4 v[24:27], v[4:5], off offset:16
	global_load_dwordx4 v[0:3], v[4:5], off offset:48
	global_load_dwordx4 v[28:31], v[4:5], off offset:32
	v_lshlrev_b32_e32 v15, 5, v221
	v_or_b32_e32 v8, 8, v15
	v_or_b32_e32 v14, 2, v15
	v_or_b32_e32 v12, 4, v15
	v_or_b32_e32 v10, 6, v15
	v_and_b32_e32 v9, 63, v19
	v_cmp_gt_u32_e64 s[0:1], 16, v9
	v_cmp_gt_u32_e64 s[4:5], 32, v9
	v_mul_lo_u32 v6, v19, s17
	s_mov_b32 s3, 8
	s_waitcnt vmcnt(3)
	v_cvt_f32_f16_sdwa v17, v20 dst_sel:DWORD dst_unused:UNUSED_PAD src0_sel:WORD_1
	v_cvt_f32_f16_e32 v16, v20
	v_cvt_f32_f16_sdwa v20, v21 dst_sel:DWORD dst_unused:UNUSED_PAD src0_sel:WORD_1
	v_cvt_f32_f16_e32 v18, v21
	v_cvt_f32_f16_e32 v21, v22
	v_cvt_f32_f16_sdwa v22, v22 dst_sel:DWORD dst_unused:UNUSED_PAD src0_sel:WORD_1
	v_not_b32_e32 v34, v17
	v_or_b32_e32 v35, 0x80000000, v17
	v_cmp_gt_i32_e32 vcc, 0, v17
	v_not_b32_e32 v36, v16
	v_or_b32_e32 v37, 0x80000000, v16
	v_cndmask_b32_e32 v17, v35, v34, vcc
	v_cmp_gt_i32_e32 vcc, 0, v16
	v_cvt_f32_f16_e32 v32, v23
	v_cvt_f32_f16_sdwa v23, v23 dst_sel:DWORD dst_unused:UNUSED_PAD src0_sel:WORD_1
	v_not_b32_e32 v38, v20
	v_or_b32_e32 v39, 0x80000000, v20
	v_cndmask_b32_e32 v16, v37, v36, vcc
	v_cmp_gt_i32_e32 vcc, 0, v20
	v_not_b32_e32 v40, v18
	v_or_b32_e32 v41, 0x80000000, v18
	v_cndmask_b32_e32 v20, v39, v38, vcc
	v_cmp_gt_i32_e32 vcc, 0, v18
	s_waitcnt vmcnt(2)
	v_cvt_f32_f16_e32 v33, v24
	v_cvt_f32_f16_sdwa v24, v24 dst_sel:DWORD dst_unused:UNUSED_PAD src0_sel:WORD_1
	v_not_b32_e32 v42, v22
	v_or_b32_e32 v43, 0x80000000, v22
	v_cndmask_b32_e32 v18, v41, v40, vcc
	v_cmp_gt_i32_e32 vcc, 0, v22
	v_not_b32_e32 v44, v21
	v_or_b32_e32 v45, 0x80000000, v21
	v_cndmask_b32_e32 v22, v43, v42, vcc
	v_cmp_gt_i32_e32 vcc, 0, v21
	v_not_b32_e32 v46, v23
	v_or_b32_e32 v47, 0x80000000, v23
	v_cndmask_b32_e32 v21, v45, v44, vcc
	v_cmp_gt_i32_e32 vcc, 0, v23
	v_not_b32_e32 v48, v32
	v_or_b32_e32 v49, 0x80000000, v32
	v_cndmask_b32_e32 v23, v47, v46, vcc
	v_cmp_gt_i32_e32 vcc, 0, v32
	v_and_b32_e32 v16, 0xffffff80, v16
	v_not_b32_e32 v50, v24
	v_or_b32_e32 v51, 0x80000000, v24
	v_cndmask_b32_e32 v32, v49, v48, vcc
	v_sub_u32_e32 v16, v16, v15
	v_cmp_gt_i32_e32 vcc, 0, v24
	v_add_u32_e32 v35, 0x7f, v16
	v_and_b32_e32 v17, 0xffffff80, v17
	v_cndmask_b32_e32 v16, v51, v50, vcc
	v_and_b32_e32 v16, 0xffffff80, v16
	v_sub_u32_e32 v17, v17, v15
	v_sub_u32_e32 v16, v16, v8
	v_add_u32_e32 v34, 0x7e, v17
	v_add_u32_e32 v41, 0x7e, v16
	v_not_b32_e32 v16, v33
	v_or_b32_e32 v17, 0x80000000, v33
	v_cmp_gt_i32_e32 vcc, 0, v33
	v_and_b32_e32 v20, 0xffffff80, v20
	v_and_b32_e32 v18, 0xffffff80, v18
	v_cndmask_b32_e32 v16, v17, v16, vcc
	v_cvt_f32_f16_sdwa v17, v25 dst_sel:DWORD dst_unused:UNUSED_PAD src0_sel:WORD_1
	v_and_b32_e32 v21, 0xffffff80, v21
	v_sub_u32_e32 v20, v20, v14
	v_sub_u32_e32 v18, v18, v14
	v_sub_u32_e32 v21, v21, v12
	v_add_u32_e32 v36, 0x7e, v20
	v_add_u32_e32 v37, 0x7f, v18
	v_add_u32_e32 v39, 0x7f, v21
	v_and_b32_e32 v16, 0xffffff80, v16
	v_cvt_f32_f16_e32 v18, v25
	v_not_b32_e32 v20, v17
	v_or_b32_e32 v21, 0x80000000, v17
	v_cmp_gt_i32_e32 vcc, 0, v17
	v_sub_u32_e32 v16, v16, v8
	v_add_u32_e32 v33, 0x7f, v16
	v_cndmask_b32_e32 v17, v21, v20, vcc
	v_or_b32_e32 v16, 10, v15
	v_and_b32_e32 v17, 0xffffff80, v17
	v_sub_u32_e32 v17, v17, v16
	v_add_u32_e32 v42, 0x7e, v17
	v_not_b32_e32 v17, v18
	v_or_b32_e32 v20, 0x80000000, v18
	v_cmp_gt_i32_e32 vcc, 0, v18
	v_cvt_f32_f16_sdwa v18, v26 dst_sel:DWORD dst_unused:UNUSED_PAD src0_sel:WORD_1
	v_and_b32_e32 v22, 0xffffff80, v22
	v_sub_u32_e32 v22, v22, v12
	v_cndmask_b32_e32 v17, v20, v17, vcc
	v_add_u32_e32 v38, 0x7e, v22
	v_and_b32_e32 v17, 0xffffff80, v17
	v_cvt_f32_f16_e32 v20, v26
	v_not_b32_e32 v21, v18
	v_or_b32_e32 v22, 0x80000000, v18
	v_cmp_gt_i32_e32 vcc, 0, v18
	v_sub_u32_e32 v17, v17, v16
	v_add_u32_e32 v43, 0x7f, v17
	v_cndmask_b32_e32 v18, v22, v21, vcc
	v_or_b32_e32 v17, 12, v15
	v_and_b32_e32 v18, 0xffffff80, v18
	v_sub_u32_e32 v18, v18, v17
	v_add_u32_e32 v44, 0x7e, v18
	v_not_b32_e32 v18, v20
	v_or_b32_e32 v21, 0x80000000, v20
	v_cmp_gt_i32_e32 vcc, 0, v20
	v_cvt_f32_f16_sdwa v20, v27 dst_sel:DWORD dst_unused:UNUSED_PAD src0_sel:WORD_1
	v_and_b32_e32 v23, 0xffffff80, v23
	v_sub_u32_e32 v23, v23, v10
	v_cndmask_b32_e32 v18, v21, v18, vcc
	v_add_u32_e32 v40, 0x7e, v23
	v_and_b32_e32 v18, 0xffffff80, v18
	v_cvt_f32_f16_e32 v21, v27
	v_not_b32_e32 v22, v20
	v_or_b32_e32 v23, 0x80000000, v20
	v_cmp_gt_i32_e32 vcc, 0, v20
	v_sub_u32_e32 v18, v18, v17
	v_add_u32_e32 v45, 0x7f, v18
	v_cndmask_b32_e32 v20, v23, v22, vcc
	v_or_b32_e32 v18, 14, v15
	v_and_b32_e32 v20, 0xffffff80, v20
	v_sub_u32_e32 v20, v20, v18
	v_add_u32_e32 v27, 0x7e, v20
	v_not_b32_e32 v20, v21
	v_or_b32_e32 v22, 0x80000000, v21
	v_cmp_gt_i32_e32 vcc, 0, v21
	s_waitcnt vmcnt(0)
; __device__ __forceinline__ unsigned f2key(float f) { const unsigned u = __float_as_uint(f); return (u & 0x80000000u) ? ~u : (u | 0x80000000u); }
; __device__ __forceinline__ void peer_tile(const Args& A, LAS unsigned char* lds, int tile) {
;     ...
;                   for (int i = 0; i < 16; ++i) {
;                       const float lo = (float)__builtin_bit_cast(_Float16, (unsigned short)(sw[i] & 0xffffu)), hi = (float)__builtin_bit_cast(_Float16, (unsigned short)(sw[i] >> 16));
;                       const unsigned klo = (f2key(lo) & ~127u) | (unsigned)(127 - (32 * g + 2 * i)), khi = (f2key(hi) & ~127u) | (unsigned)(127 - (32 * g + 2 * i + 1));
;                       if (i < 8) { k0[2 * i] = klo; k0[2 * i + 1] = khi; } else { k1[2 * (i - 8)] = klo; k1[2 * (i - 8) + 1] = khi; } } }
;                 sort16_desc(k0); sort16_desc(k1); merge16(k0, k1);
	v_cvt_f32_f16_sdwa v21, v28 dst_sel:DWORD dst_unused:UNUSED_PAD src0_sel:WORD_1
	v_and_b32_e32 v32, 0xffffff80, v32
	v_cndmask_b32_e32 v20, v22, v20, vcc
	v_and_b32_e32 v20, 0xffffff80, v20
	v_cvt_f32_f16_e32 v22, v28
	v_not_b32_e32 v23, v21
	v_or_b32_e32 v24, 0x80000000, v21
	v_cmp_gt_i32_e32 vcc, 0, v21
	v_sub_u32_e32 v20, v20, v18
	v_add_u32_e32 v46, 0x7f, v20
	v_cndmask_b32_e32 v21, v24, v23, vcc
	v_or_b32_e32 v20, 16, v15
	v_and_b32_e32 v21, 0xffffff80, v21
	v_sub_u32_e32 v21, v21, v20
	v_add_u32_e32 v47, 0x7e, v21
	v_not_b32_e32 v21, v22
	v_or_b32_e32 v23, 0x80000000, v22
	v_cmp_gt_i32_e32 vcc, 0, v22
	v_cvt_f32_f16_sdwa v22, v29 dst_sel:DWORD dst_unused:UNUSED_PAD src0_sel:WORD_1
	v_sub_u32_e32 v32, v32, v10
	v_cndmask_b32_e32 v21, v23, v21, vcc
	v_and_b32_e32 v21, 0xffffff80, v21
	v_cvt_f32_f16_e32 v23, v29
	v_not_b32_e32 v24, v22
	v_or_b32_e32 v25, 0x80000000, v22
	v_cmp_gt_i32_e32 vcc, 0, v22
	v_sub_u32_e32 v21, v21, v20
	v_add_u32_e32 v48, 0x7f, v21
	v_cndmask_b32_e32 v22, v25, v24, vcc
	v_or_b32_e32 v21, 18, v15
	v_and_b32_e32 v22, 0xffffff80, v22
	v_sub_u32_e32 v22, v22, v21
	v_add_u32_e32 v29, 0x7e, v22
	v_not_b32_e32 v22, v23
	v_or_b32_e32 v24, 0x80000000, v23
	v_cmp_gt_i32_e32 vcc, 0, v23
	v_cvt_f32_f16_sdwa v23, v30 dst_sel:DWORD dst_unused:UNUSED_PAD src0_sel:WORD_1
	v_add_u32_e32 v32, 0x7f, v32
	v_cndmask_b32_e32 v22, v24, v22, vcc
	v_and_b32_e32 v22, 0xffffff80, v22
	v_cvt_f32_f16_e32 v24, v30
	v_not_b32_e32 v25, v23
	v_or_b32_e32 v26, 0x80000000, v23
	v_cmp_gt_i32_e32 vcc, 0, v23
	v_sub_u32_e32 v22, v22, v21
	v_add_u32_e32 v49, 0x7f, v22
	v_cndmask_b32_e32 v23, v26, v25, vcc
	v_or_b32_e32 v22, 20, v15
	v_and_b32_e32 v23, 0xffffff80, v23
	v_sub_u32_e32 v23, v23, v22
	v_add_u32_e32 v30, 0x7e, v23
	v_not_b32_e32 v23, v24
	v_or_b32_e32 v25, 0x80000000, v24
	v_cmp_gt_i32_e32 vcc, 0, v24
	v_cvt_f32_f16_sdwa v24, v31 dst_sel:DWORD dst_unused:UNUSED_PAD src0_sel:WORD_1
	v_max_u32_e32 v64, v48, v47
	v_cndmask_b32_e32 v23, v25, v23, vcc
	v_and_b32_e32 v23, 0xffffff80, v23
	v_cvt_f32_f16_e32 v25, v31
	v_not_b32_e32 v26, v24
	v_or_b32_e32 v28, 0x80000000, v24
	v_cmp_gt_i32_e32 vcc, 0, v24
	v_sub_u32_e32 v23, v23, v22
	v_add_u32_e32 v50, 0x7f, v23
	v_cndmask_b32_e32 v24, v28, v26, vcc
	v_or_b32_e32 v23, 22, v15
	v_and_b32_e32 v24, 0xffffff80, v24
	v_sub_u32_e32 v24, v24, v23
	v_add_u32_e32 v31, 0x7e, v24
	v_not_b32_e32 v24, v25
	v_or_b32_e32 v26, 0x80000000, v25
	v_cmp_gt_i32_e32 vcc, 0, v25
	v_cvt_f32_f16_sdwa v25, v0 dst_sel:DWORD dst_unused:UNUSED_PAD src0_sel:WORD_1
	v_cvt_f32_f16_e32 v0, v0
	v_cndmask_b32_e32 v24, v26, v24, vcc
	v_and_b32_e32 v24, 0xffffff80, v24
	v_not_b32_e32 v26, v25
	v_or_b32_e32 v28, 0x80000000, v25
	v_cmp_gt_i32_e32 vcc, 0, v25
	v_sub_u32_e32 v24, v24, v23
	v_add_u32_e32 v51, 0x7f, v24
	v_cndmask_b32_e32 v25, v28, v26, vcc
	v_or_b32_e32 v24, 24, v15
	v_and_b32_e32 v25, 0xffffff80, v25
	v_sub_u32_e32 v25, v25, v24
	v_add_u32_e32 v52, 0x7e, v25
	v_not_b32_e32 v25, v0
	v_or_b32_e32 v26, 0x80000000, v0
	v_cmp_gt_i32_e32 vcc, 0, v0
	v_min_u32_e32 v47, v48, v47
	v_max_u32_e32 v48, v29, v49
	v_cndmask_b32_e32 v0, v26, v25, vcc
	v_cvt_f32_f16_sdwa v26, v1 dst_sel:DWORD dst_unused:UNUSED_PAD src0_sel:WORD_1
	v_cvt_f32_f16_e32 v1, v1
	v_or_b32_e32 v25, 26, v15
	v_and_b32_e32 v0, 0xffffff80, v0
	v_not_b32_e32 v28, v26
	v_or_b32_e32 v53, 0x80000000, v26
	v_cmp_gt_i32_e32 vcc, 0, v26
	v_sub_u32_e32 v0, v0, v24
	v_add_u32_e32 v0, 0x7f, v0
	v_cndmask_b32_e32 v26, v53, v28, vcc
	v_and_b32_e32 v26, 0xffffff80, v26
	v_sub_u32_e32 v26, v26, v25
	v_add_u32_e32 v53, 0x7e, v26
	v_not_b32_e32 v26, v1
	v_or_b32_e32 v28, 0x80000000, v1
	v_cmp_gt_i32_e32 vcc, 0, v1
	v_min_u32_e32 v29, v29, v49
	v_max_u32_e32 v49, v50, v30
	v_cndmask_b32_e32 v1, v28, v26, vcc
	v_cvt_f32_f16_sdwa v28, v2 dst_sel:DWORD dst_unused:UNUSED_PAD src0_sel:WORD_1
	v_cvt_f32_f16_e32 v2, v2
	v_or_b32_e32 v26, 28, v15
	v_and_b32_e32 v1, 0xffffff80, v1
	v_not_b32_e32 v54, v28
	v_or_b32_e32 v55, 0x80000000, v28
	v_cmp_gt_i32_e32 vcc, 0, v28
	v_sub_u32_e32 v1, v1, v25
	v_add_u32_e32 v1, 0x7f, v1
	v_cndmask_b32_e32 v28, v55, v54, vcc
	v_and_b32_e32 v28, 0xffffff80, v28
	v_sub_u32_e32 v28, v28, v26
	v_add_u32_e32 v54, 0x7e, v28
	v_not_b32_e32 v28, v2
	v_or_b32_e32 v55, 0x80000000, v2
	v_cmp_gt_i32_e32 vcc, 0, v2
	v_min_u32_e32 v30, v50, v30
	v_max_u32_e32 v50, v31, v51
	v_cndmask_b32_e32 v2, v55, v28, vcc
	v_cvt_f32_f16_e32 v55, v3
	v_cvt_f32_f16_sdwa v3, v3 dst_sel:DWORD dst_unused:UNUSED_PAD src0_sel:WORD_1
	v_and_b32_e32 v2, 0xffffff80, v2
	v_or_b32_e32 v28, 30, v15
	v_not_b32_e32 v56, v55
	v_or_b32_e32 v57, 0x80000000, v55
	v_cmp_gt_i32_e32 vcc, 0, v55
	v_sub_u32_e32 v2, v2, v26
	v_add_u32_e32 v2, 0x7f, v2
	v_cndmask_b32_e32 v55, v57, v56, vcc
	v_not_b32_e32 v56, v3
	v_or_b32_e32 v57, 0x80000000, v3
	v_cmp_gt_i32_e32 vcc, 0, v3
	v_and_b32_e32 v55, 0xffffff80, v55
	v_sub_u32_e32 v55, v55, v28
	v_cndmask_b32_e32 v3, v57, v56, vcc
	v_and_b32_e32 v3, 0xffffff80, v3
	v_sub_u32_e32 v3, v3, v28
	v_add_u32_e32 v55, 0x7f, v55
	v_add_u32_e32 v3, 0x7e, v3
	v_max_u32_e32 v56, v35, v34
	v_min_u32_e32 v34, v35, v34
	v_max_u32_e32 v35, v36, v37
	v_min_u32_e32 v36, v36, v37
	v_max_u32_e32 v37, v39, v38
	v_min_u32_e32 v38, v39, v38
	v_max_u32_e32 v39, v40, v32
	v_min_u32_e32 v32, v40, v32
	v_max_u32_e32 v40, v33, v41
	v_min_u32_e32 v33, v33, v41
	v_max_u32_e32 v41, v42, v43
	v_min_u32_e32 v42, v42, v43
	v_max_u32_e32 v43, v45, v44
	v_min_u32_e32 v44, v45, v44
	v_max_u32_e32 v45, v27, v46
	v_min_u32_e32 v27, v27, v46
	v_min_u32_e32 v31, v31, v51
	v_max_u32_e32 v51, v0, v52
	v_min_u32_e32 v0, v0, v52
	v_max_u32_e32 v52, v53, v1
	v_min_u32_e32 v1, v53, v1
	v_max_u32_e32 v53, v2, v54
; #define CE_DESC(a, b) do { const unsigned _mx = (a) > (b) ? (a) : (b), _mn = (a) > (b) ? (b) : (a); (a) = _mx; (b) = _mn; } while (0)
; __device__ __forceinline__ void sort16_desc(unsigned (&k)[16]) {
; #pragma unroll
;     for (int size = 2; size <= 16; size <<= 1)
; #pragma unroll
;         for (int stride = size >> 1; stride > 0; stride >>= 1)
; #pragma unroll
;             for (int i = 0; i < 16; ++i) { const int j = i ^ stride;
;                 if (j > i) { if ((i & size) == 0) CE_DESC(k[i], k[j]); else CE_DESC(k[j], k[i]); } }
; }
	v_min_u32_e32 v2, v2, v54
	v_max_u32_e32 v54, v3, v55
	v_min_u32_e32 v3, v3, v55
	v_max_u32_e32 v46, v56, v36
	v_min_u32_e32 v36, v56, v36
	v_max_u32_e32 v56, v34, v35
	v_min_u32_e32 v34, v34, v35
	v_max_u32_e32 v35, v32, v37
	v_min_u32_e32 v32, v32, v37
	v_max_u32_e32 v37, v39, v38
	v_min_u32_e32 v38, v39, v38
	v_max_u32_e32 v39, v40, v42
	v_min_u32_e32 v40, v40, v42
	v_max_u32_e32 v42, v33, v41
	v_min_u32_e32 v33, v33, v41
	v_max_u32_e32 v41, v27, v43
	v_min_u32_e32 v27, v27, v43
	v_max_u32_e32 v43, v45, v44
	v_min_u32_e32 v44, v45, v44
	v_max_u32_e32 v55, v64, v29
	v_min_u32_e32 v29, v64, v29
	v_max_u32_e32 v64, v47, v48
	v_min_u32_e32 v47, v47, v48
	v_max_u32_e32 v48, v31, v49
	v_min_u32_e32 v31, v31, v49
	v_max_u32_e32 v49, v50, v30
	v_min_u32_e32 v30, v50, v30
	v_max_u32_e32 v50, v51, v1
	v_min_u32_e32 v1, v51, v1
	v_max_u32_e32 v51, v0, v52
	v_min_u32_e32 v0, v0, v52
	v_max_u32_e32 v52, v3, v53
	v_min_u32_e32 v3, v3, v53
	v_max_u32_e32 v53, v54, v2
	v_min_u32_e32 v2, v54, v2
	v_max_u32_e32 v45, v46, v56
	v_min_u32_e32 v46, v46, v56
	v_max_u32_e32 v56, v36, v34
	v_min_u32_e32 v34, v36, v34
	v_max_u32_e32 v36, v38, v32
	v_min_u32_e32 v32, v38, v32
	v_max_u32_e32 v38, v37, v35
	v_min_u32_e32 v35, v37, v35
	v_max_u32_e32 v37, v39, v42
	v_min_u32_e32 v39, v39, v42
	v_max_u32_e32 v42, v40, v33
	v_min_u32_e32 v33, v40, v33
	v_max_u32_e32 v40, v44, v27
	v_min_u32_e32 v27, v44, v27
	v_max_u32_e32 v44, v43, v41
	v_min_u32_e32 v41, v43, v41
	v_max_u32_e32 v54, v55, v64
	v_min_u32_e32 v55, v55, v64
	v_max_u32_e32 v64, v29, v47
	v_min_u32_e32 v29, v29, v47
	v_max_u32_e32 v47, v30, v31
	v_min_u32_e32 v30, v30, v31
	v_max_u32_e32 v31, v49, v48
	v_min_u32_e32 v48, v49, v48
	v_max_u32_e32 v49, v50, v51
	v_min_u32_e32 v50, v50, v51
	v_max_u32_e32 v51, v1, v0
	v_min_u32_e32 v0, v1, v0
	v_max_u32_e32 v1, v2, v3
	v_min_u32_e32 v2, v2, v3
	v_max_u32_e32 v3, v53, v52
	v_min_u32_e32 v52, v53, v52
	v_max_u32_e32 v43, v45, v32
	v_min_u32_e32 v32, v45, v32
	v_max_u32_e32 v45, v46, v36
	v_min_u32_e32 v36, v46, v36
	v_max_u32_e32 v46, v56, v35
	v_min_u32_e32 v35, v56, v35
	v_max_u32_e32 v56, v34, v38
	v_min_u32_e32 v34, v34, v38
	v_max_u32_e32 v38, v27, v37
	v_min_u32_e32 v27, v27, v37
	v_max_u32_e32 v37, v40, v39
	v_min_u32_e32 v39, v40, v39
	v_max_u32_e32 v40, v41, v42
	v_min_u32_e32 v41, v41, v42
	v_max_u32_e32 v42, v44, v33
	v_min_u32_e32 v33, v44, v33
	v_max_u32_e32 v53, v54, v30
	v_min_u32_e32 v30, v54, v30
	v_max_u32_e32 v54, v55, v47
	v_min_u32_e32 v47, v55, v47
	v_max_u32_e32 v55, v64, v48
	v_min_u32_e32 v48, v64, v48
	v_max_u32_e32 v64, v29, v31
	v_min_u32_e32 v29, v29, v31
	v_max_u32_e32 v31, v2, v49
	v_min_u32_e32 v2, v2, v49
	v_max_u32_e32 v49, v1, v50
	v_min_u32_e32 v1, v1, v50
	v_max_u32_e32 v50, v52, v51
	v_min_u32_e32 v51, v52, v51
	v_max_u32_e32 v52, v3, v0
	v_min_u32_e32 v0, v3, v0
	v_max_u32_e32 v44, v43, v46
	v_min_u32_e32 v43, v43, v46
	v_max_u32_e32 v46, v45, v56
	v_min_u32_e32 v45, v45, v56
	v_max_u32_e32 v56, v32, v35
	v_min_u32_e32 v32, v32, v35
	v_max_u32_e32 v35, v36, v34
	v_min_u32_e32 v34, v36, v34
	v_max_u32_e32 v36, v41, v27
	v_min_u32_e32 v27, v41, v27
	v_max_u32_e32 v41, v33, v39
	v_min_u32_e32 v33, v33, v39
	v_max_u32_e32 v39, v40, v38
	v_min_u32_e32 v38, v40, v38
	v_max_u32_e32 v40, v42, v37
	v_min_u32_e32 v37, v42, v37
	v_max_u32_e32 v3, v53, v55
	v_min_u32_e32 v53, v53, v55
	v_max_u32_e32 v55, v54, v64
	v_min_u32_e32 v54, v54, v64
	v_max_u32_e32 v64, v30, v48
	v_min_u32_e32 v30, v30, v48
	v_max_u32_e32 v48, v47, v29
	v_min_u32_e32 v29, v47, v29
	v_max_u32_e32 v47, v51, v2
	v_min_u32_e32 v2, v51, v2
	v_max_u32_e32 v51, v0, v1
	v_min_u32_e32 v0, v0, v1
	v_max_u32_e32 v1, v50, v31
	v_min_u32_e32 v31, v50, v31
	v_max_u32_e32 v50, v52, v49
	v_min_u32_e32 v49, v52, v49
	v_max_u32_e32 v42, v44, v46
	v_min_u32_e32 v44, v44, v46
	v_max_u32_e32 v46, v43, v45
	v_min_u32_e32 v43, v43, v45
	v_max_u32_e32 v45, v56, v35
	v_min_u32_e32 v35, v56, v35
	v_max_u32_e32 v56, v32, v34
	v_min_u32_e32 v32, v32, v34
	v_max_u32_e32 v34, v33, v27
	v_min_u32_e32 v27, v33, v27
	v_max_u32_e32 v33, v41, v36
	v_min_u32_e32 v36, v41, v36
	v_max_u32_e32 v41, v37, v38
	v_min_u32_e32 v37, v37, v38
	v_max_u32_e32 v38, v40, v39
	v_min_u32_e32 v39, v40, v39
	v_max_u32_e32 v52, v3, v55
	v_min_u32_e32 v3, v3, v55
	v_max_u32_e32 v55, v53, v54
	v_min_u32_e32 v53, v53, v54
	v_max_u32_e32 v54, v64, v48
	v_min_u32_e32 v48, v64, v48
	v_max_u32_e32 v64, v30, v29
	v_min_u32_e32 v29, v30, v29
	v_max_u32_e32 v30, v0, v2
	v_min_u32_e32 v0, v0, v2
	v_max_u32_e32 v2, v51, v47
	v_min_u32_e32 v47, v51, v47
	v_max_u32_e32 v51, v49, v31
	v_min_u32_e32 v31, v49, v31
	v_max_u32_e32 v49, v50, v1
	v_min_u32_e32 v1, v50, v1
	v_max_u32_e32 v40, v42, v27
	v_min_u32_e32 v27, v42, v27
	v_max_u32_e32 v42, v44, v34
	v_min_u32_e32 v34, v44, v34
	v_max_u32_e32 v44, v46, v36
	v_min_u32_e32 v36, v46, v36
	v_max_u32_e32 v46, v43, v33
	v_min_u32_e32 v33, v43, v33
	v_max_u32_e32 v43, v45, v37
	v_min_u32_e32 v37, v45, v37
	v_max_u32_e32 v45, v35, v41
	v_min_u32_e32 v35, v35, v41
	v_max_u32_e32 v41, v56, v39
	v_min_u32_e32 v39, v56, v39
	v_max_u32_e32 v56, v32, v38
	v_min_u32_e32 v32, v32, v38
	v_max_u32_e32 v50, v52, v0
	v_min_u32_e32 v0, v52, v0
	v_max_u32_e32 v52, v3, v30
	v_min_u32_e32 v3, v3, v30
	v_max_u32_e32 v30, v55, v47
	v_min_u32_e32 v47, v55, v47
	v_max_u32_e32 v55, v53, v2
	v_min_u32_e32 v2, v53, v2
	v_max_u32_e32 v53, v54, v31
	v_min_u32_e32 v31, v54, v31
	v_max_u32_e32 v54, v48, v51
	v_min_u32_e32 v48, v48, v51
	v_max_u32_e32 v51, v64, v1
	v_min_u32_e32 v1, v64, v1
	v_max_u32_e32 v64, v29, v49
	v_min_u32_e32 v29, v29, v49
	v_max_u32_e32 v38, v40, v43
	v_min_u32_e32 v40, v40, v43
; #define CE_DESC(a, b) do { const unsigned _mx = (a) > (b) ? (a) : (b), _mn = (a) > (b) ? (b) : (a); (a) = _mx; (b) = _mn; } while (0)
; __device__ __forceinline__ void merge16(unsigned (&a)[16], const unsigned (&b)[16]) {
; #pragma unroll
;     for (int i = 0; i < 16; ++i) a[i] = a[i] > b[15 - i] ? a[i] : b[15 - i];
; #pragma unroll
;     for (int stride = 8; stride > 0; stride >>= 1)
; #pragma unroll
;         for (int i = 0; i < 16; ++i) { const int j = i ^ stride; if (j > i) CE_DESC(a[i], a[j]); }
; }
; __device__ __forceinline__ void peer_tile(const Args& A, LAS unsigned char* lds, int tile) {
;     ...
;                 for (int msk = 16; msk <= 32; msk <<= 1) {
; #pragma unroll
;                     for (int i = 0; i < 16; ++i) k1[i] = (unsigned)__shfl_xor((int)k0[i], msk);
;                     merge16(k0, k1); }
	v_max_u32_e32 v43, v42, v45
	v_min_u32_e32 v42, v42, v45
	v_max_u32_e32 v45, v44, v41
	v_min_u32_e32 v41, v44, v41
	v_max_u32_e32 v44, v46, v56
	v_min_u32_e32 v46, v46, v56
	v_max_u32_e32 v56, v27, v37
	v_min_u32_e32 v27, v27, v37
	v_max_u32_e32 v37, v34, v35
	v_min_u32_e32 v34, v34, v35
	v_max_u32_e32 v35, v36, v39
	v_min_u32_e32 v36, v36, v39
	v_max_u32_e32 v39, v33, v32
	v_min_u32_e32 v32, v33, v32
	v_max_u32_e32 v49, v50, v53
	v_min_u32_e32 v50, v50, v53
	v_max_u32_e32 v53, v52, v54
	v_min_u32_e32 v52, v52, v54
	v_max_u32_e32 v54, v30, v51
	v_min_u32_e32 v30, v30, v51
	v_max_u32_e32 v51, v55, v64
	v_min_u32_e32 v55, v55, v64
	v_max_u32_e32 v64, v0, v31
	v_min_u32_e32 v0, v0, v31
	v_max_u32_e32 v31, v3, v48
	v_min_u32_e32 v3, v3, v48
	v_max_u32_e32 v48, v47, v1
	v_min_u32_e32 v1, v47, v1
	v_max_u32_e32 v47, v2, v29
	v_min_u32_e32 v2, v2, v29
	v_max_u32_e32 v33, v38, v45
	v_min_u32_e32 v38, v38, v45
	v_max_u32_e32 v45, v43, v44
	v_min_u32_e32 v43, v43, v44
	v_max_u32_e32 v44, v40, v41
	v_min_u32_e32 v40, v40, v41
	v_max_u32_e32 v41, v42, v46
	v_min_u32_e32 v42, v42, v46
	v_max_u32_e32 v46, v56, v35
	v_min_u32_e32 v35, v56, v35
	v_max_u32_e32 v56, v37, v39
	v_min_u32_e32 v37, v37, v39
	v_max_u32_e32 v39, v27, v36
	v_min_u32_e32 v27, v27, v36
	v_max_u32_e32 v36, v34, v32
	v_min_u32_e32 v32, v34, v32
	v_max_u32_e32 v29, v49, v54
	v_min_u32_e32 v49, v49, v54
	v_max_u32_e32 v54, v53, v51
	v_min_u32_e32 v51, v53, v51
	v_max_u32_e32 v53, v50, v30
	v_min_u32_e32 v30, v50, v30
	v_max_u32_e32 v50, v52, v55
	v_min_u32_e32 v52, v52, v55
	v_max_u32_e32 v55, v64, v48
	v_min_u32_e32 v48, v64, v48
	v_max_u32_e32 v64, v31, v47
	v_min_u32_e32 v31, v31, v47
	v_max_u32_e32 v47, v0, v1
	v_min_u32_e32 v0, v0, v1
	v_max_u32_e32 v1, v3, v2
	v_min_u32_e32 v2, v3, v2
	v_min_u32_e32 v34, v33, v45
	v_min_u32_e32 v57, v38, v43
	v_min_u32_e32 v58, v44, v41
	v_min_u32_e32 v59, v40, v42
	v_min_u32_e32 v60, v46, v56
	v_min_u32_e32 v61, v35, v37
	v_min_u32_e32 v62, v39, v36
	v_min_u32_e32 v63, v27, v32
	v_min_u32_e32 v3, v29, v54
	v_min_u32_e32 v65, v49, v51
	v_min_u32_e32 v66, v53, v50
	v_min_u32_e32 v67, v30, v52
	v_min_u32_e32 v68, v55, v64
	v_min_u32_e32 v69, v48, v31
	v_min_u32_e32 v70, v47, v1
	v_min_u32_e32 v71, v0, v2
	v_max3_u32 v33, v33, v45, v71
	v_max3_u32 v0, v34, v0, v2
	v_max3_u32 v2, v38, v43, v70
	v_max3_u32 v1, v57, v47, v1
	v_max3_u32 v34, v44, v41, v69
	v_max3_u32 v31, v58, v48, v31
	v_max3_u32 v38, v40, v42, v68
	v_max3_u32 v40, v59, v55, v64
	v_max3_u32 v41, v46, v56, v67
	v_max3_u32 v30, v60, v30, v52
	v_max3_u32 v35, v35, v37, v66
	v_max3_u32 v37, v61, v53, v50
	v_max3_u32 v36, v39, v36, v65
	v_max3_u32 v39, v62, v49, v51
	v_max3_u32 v3, v27, v32, v3
	v_max3_u32 v27, v63, v29, v54
	v_max_u32_e32 v29, v33, v41
	v_min_u32_e32 v32, v33, v41
	v_max_u32_e32 v33, v0, v30
	v_min_u32_e32 v0, v0, v30
	v_max_u32_e32 v30, v2, v35
	v_min_u32_e32 v2, v2, v35
	v_max_u32_e32 v35, v1, v37
	v_min_u32_e32 v1, v1, v37
	v_max_u32_e32 v37, v34, v36
	v_min_u32_e32 v34, v34, v36
	v_max_u32_e32 v36, v31, v39
	v_min_u32_e32 v31, v31, v39
	v_max_u32_e32 v39, v38, v3
	v_min_u32_e32 v3, v38, v3
	v_max_u32_e32 v38, v40, v27
	v_min_u32_e32 v27, v40, v27
	v_max_u32_e32 v40, v29, v37
	v_min_u32_e32 v29, v29, v37
	v_max_u32_e32 v37, v33, v36
	v_min_u32_e32 v33, v33, v36
	v_max_u32_e32 v36, v30, v39
	v_min_u32_e32 v30, v30, v39
	v_max_u32_e32 v39, v35, v38
	v_min_u32_e32 v35, v35, v38
	v_max_u32_e32 v38, v32, v34
	v_min_u32_e32 v32, v32, v34
	v_max_u32_e32 v34, v0, v31
	v_min_u32_e32 v0, v0, v31
	v_max_u32_e32 v31, v2, v3
	v_min_u32_e32 v2, v2, v3
	v_max_u32_e32 v3, v1, v27
	v_min_u32_e32 v1, v1, v27
	v_max_u32_e32 v27, v40, v36
	v_min_u32_e32 v36, v40, v36
	v_max_u32_e32 v40, v37, v39
	v_min_u32_e32 v37, v37, v39
	v_max_u32_e32 v39, v29, v30
	v_min_u32_e32 v29, v29, v30
	v_max_u32_e32 v30, v33, v35
	v_min_u32_e32 v33, v33, v35
	v_max_u32_e32 v35, v38, v31
	v_min_u32_e32 v31, v38, v31
	v_max_u32_e32 v38, v34, v3
	v_min_u32_e32 v3, v34, v3
	v_max_u32_e32 v34, v32, v2
	v_min_u32_e32 v2, v32, v2
	v_max_u32_e32 v32, v0, v1
	v_min_u32_e32 v0, v0, v1
	v_cmp_lt_i32_e32 vcc, v217, v216
	v_max_u32_e32 v41, v36, v37
	v_min_u32_e32 v36, v36, v37
	v_max_u32_e32 v37, v39, v30
	v_min_u32_e32 v30, v39, v30
	v_max_u32_e32 v39, v29, v33
	v_min_u32_e32 v29, v29, v33
	v_max_u32_e32 v33, v35, v38
	v_min_u32_e32 v35, v35, v38
	v_max_u32_e32 v38, v31, v3
	v_min_u32_e32 v3, v31, v3
	v_max_u32_e32 v31, v34, v32
	v_min_u32_e32 v32, v34, v32
	v_max_u32_e32 v34, v2, v0
	v_min_u32_e32 v0, v2, v0
	v_cndmask_b32_e32 v2, v215, v217, vcc
	v_max_u32_e32 v1, v27, v40
	v_min_u32_e32 v40, v27, v40
	v_lshlrev_b32_e32 v27, 2, v2
	ds_bpermute_b32 v2, v27, v1
	ds_bpermute_b32 v42, v27, v40
	ds_bpermute_b32 v43, v27, v41
	ds_bpermute_b32 v44, v27, v36
	ds_bpermute_b32 v45, v27, v37
	ds_bpermute_b32 v46, v27, v30
	ds_bpermute_b32 v47, v27, v39
	ds_bpermute_b32 v48, v27, v29
	ds_bpermute_b32 v49, v27, v33
	ds_bpermute_b32 v50, v27, v35
	ds_bpermute_b32 v51, v27, v38
	ds_bpermute_b32 v52, v27, v0
	ds_bpermute_b32 v53, v27, v34
	ds_bpermute_b32 v54, v27, v32
	ds_bpermute_b32 v55, v27, v31
	ds_bpermute_b32 v56, v27, v3
	s_waitcnt lgkmcnt(4)
	v_max_u32_e32 v1, v1, v52
	s_waitcnt lgkmcnt(3)
	v_max_u32_e32 v40, v40, v53
	s_waitcnt lgkmcnt(2)
	v_max_u32_e32 v41, v41, v54
	s_waitcnt lgkmcnt(1)
	v_max_u32_e32 v36, v36, v55
	s_waitcnt lgkmcnt(0)
; __device__ __forceinline__ void peer_tile(const Args& A, LAS unsigned char* lds, int tile) {
;     ...
;                 { const bf16_t* sp = QRY + m * 2048 + hp * 128 + 32 * g;
;                   const u32x4 s0 = *(const u32x4*)sp, s1 = *(const u32x4*)(sp + 8), s2 = *(const u32x4*)(sp + 16), s3 = *(const u32x4*)(sp + 24);
;     ...
;                 for (int msk = 16; msk <= 32; msk <<= 1) {
; #pragma unroll
;                     for (int i = 0; i < 16; ++i) k1[i] = (unsigned)__shfl_xor((int)k0[i], msk);
;                     merge16(k0, k1); }
	v_max_u32_e32 v37, v37, v56
	v_max_u32_e32 v30, v30, v51
	v_max_u32_e32 v39, v39, v50
	v_max_u32_e32 v29, v29, v49
	v_max_u32_e32 v33, v33, v48
	v_max_u32_e32 v35, v35, v47
	v_max_u32_e32 v38, v38, v46
	v_max_u32_e32 v3, v3, v45
	v_max_u32_e32 v31, v31, v44
	v_max_u32_e32 v32, v32, v43
	v_max_u32_e32 v34, v34, v42
	v_max_u32_e32 v0, v0, v2
	v_max_u32_e32 v2, v1, v33
	v_min_u32_e32 v1, v1, v33
	v_max_u32_e32 v33, v40, v35
	v_min_u32_e32 v35, v40, v35
	v_max_u32_e32 v40, v41, v38
	v_min_u32_e32 v38, v41, v38
	v_max_u32_e32 v41, v36, v3
	v_min_u32_e32 v3, v36, v3
	v_max_u32_e32 v36, v37, v31
	v_min_u32_e32 v31, v37, v31
	v_max_u32_e32 v37, v30, v32
	v_min_u32_e32 v30, v30, v32
	v_max_u32_e32 v32, v39, v34
	v_min_u32_e32 v34, v39, v34
	v_max_u32_e32 v39, v29, v0
	v_min_u32_e32 v0, v29, v0
	v_max_u32_e32 v29, v2, v36
	v_min_u32_e32 v2, v2, v36
	v_max_u32_e32 v36, v33, v37
	v_min_u32_e32 v33, v33, v37
	v_max_u32_e32 v37, v40, v32
	v_min_u32_e32 v32, v40, v32
	v_max_u32_e32 v40, v41, v39
	v_min_u32_e32 v39, v41, v39
	v_max_u32_e32 v41, v1, v31
	v_min_u32_e32 v1, v1, v31
	v_max_u32_e32 v31, v35, v30
	v_min_u32_e32 v30, v35, v30
	v_max_u32_e32 v35, v38, v34
	v_min_u32_e32 v34, v38, v34
	v_max_u32_e32 v38, v3, v0
	v_min_u32_e32 v0, v3, v0
	v_max_u32_e32 v3, v29, v37
	v_min_u32_e32 v29, v29, v37
	v_max_u32_e32 v37, v36, v40
	v_min_u32_e32 v36, v36, v40
	v_max_u32_e32 v40, v2, v32
	v_min_u32_e32 v2, v2, v32
	v_max_u32_e32 v32, v33, v39
	v_min_u32_e32 v33, v33, v39
	v_max_u32_e32 v39, v41, v35
	v_min_u32_e32 v35, v41, v35
	v_max_u32_e32 v41, v31, v38
	v_min_u32_e32 v31, v31, v38
	v_max_u32_e32 v38, v1, v34
	v_min_u32_e32 v1, v1, v34
	v_max_u32_e32 v34, v30, v0
	v_min_u32_e32 v0, v30, v0
	v_cmp_lt_i32_e32 vcc, v218, v216
	v_max_u32_e32 v42, v40, v32
	v_min_u32_e32 v32, v40, v32
	v_max_u32_e32 v40, v2, v33
	v_min_u32_e32 v2, v2, v33
	v_max_u32_e32 v33, v39, v41
	v_min_u32_e32 v39, v39, v41
	v_max_u32_e32 v41, v35, v31
	v_min_u32_e32 v31, v35, v31
	v_max_u32_e32 v35, v38, v34
	v_min_u32_e32 v34, v38, v34
	v_max_u32_e32 v38, v1, v0
	v_min_u32_e32 v0, v1, v0
	v_cndmask_b32_e32 v1, v215, v218, vcc
	v_max_u32_e32 v30, v3, v37
	v_min_u32_e32 v3, v3, v37
	v_max_u32_e32 v37, v29, v36
	v_min_u32_e32 v36, v29, v36
	v_lshlrev_b32_e32 v29, 2, v1
	ds_bpermute_b32 v46, v29, v0
	ds_bpermute_b32 v1, v29, v30
	ds_bpermute_b32 v43, v29, v3
	ds_bpermute_b32 v44, v29, v37
	ds_bpermute_b32 v45, v29, v36
	s_waitcnt lgkmcnt(4)
	v_max_u32_e32 v30, v30, v46
	global_load_dwordx4 v[46:49], v[4:5], off offset:272
	global_load_dwordx4 v[50:53], v[4:5], off offset:256
	ds_bpermute_b32 v54, v29, v42
	ds_bpermute_b32 v55, v29, v32
	ds_bpermute_b32 v56, v29, v40
	ds_bpermute_b32 v57, v29, v2
	ds_bpermute_b32 v58, v29, v33
	ds_bpermute_b32 v59, v29, v39
	ds_bpermute_b32 v60, v29, v41
	ds_bpermute_b32 v61, v29, v31
	ds_bpermute_b32 v62, v29, v35
	ds_bpermute_b32 v63, v29, v38
	ds_bpermute_b32 v64, v29, v34
	s_waitcnt lgkmcnt(4)
	v_max_u32_e32 v32, v32, v60
	s_waitcnt lgkmcnt(3)
	v_max_u32_e32 v42, v42, v61
	s_waitcnt lgkmcnt(2)
	v_max_u32_e32 v36, v36, v62
	s_waitcnt lgkmcnt(1)
	v_max_u32_e32 v3, v3, v63
	s_waitcnt lgkmcnt(0)
	v_max_u32_e32 v37, v37, v64
	v_max_u32_e32 v40, v40, v59
	v_max_u32_e32 v2, v2, v58
	v_max_u32_e32 v33, v33, v57
	v_max_u32_e32 v39, v39, v56
	v_max_u32_e32 v41, v41, v55
	v_max_u32_e32 v31, v31, v54
	v_max_u32_e32 v35, v35, v45
	v_max_u32_e32 v34, v34, v44
	v_max_u32_e32 v38, v38, v43
	v_max_u32_e32 v0, v0, v1
	v_max_u32_e32 v1, v30, v33
	v_min_u32_e32 v30, v30, v33
	v_max_u32_e32 v33, v3, v39
	v_min_u32_e32 v3, v3, v39
	v_max_u32_e32 v39, v37, v41
	v_min_u32_e32 v37, v37, v41
	v_max_u32_e32 v41, v36, v31
	v_min_u32_e32 v31, v36, v31
	v_max_u32_e32 v36, v42, v35
	v_min_u32_e32 v35, v42, v35
	v_max_u32_e32 v42, v32, v34
	v_min_u32_e32 v32, v32, v34
	v_max_u32_e32 v34, v40, v38
	v_min_u32_e32 v38, v40, v38
	v_max_u32_e32 v40, v2, v0
	v_min_u32_e32 v0, v2, v0
	v_max_u32_e32 v2, v1, v36
	v_min_u32_e32 v1, v1, v36
	v_max_u32_e32 v36, v33, v42
	v_min_u32_e32 v33, v33, v42
	v_max_u32_e32 v42, v39, v34
	v_min_u32_e32 v34, v39, v34
	v_max_u32_e32 v39, v41, v40
	v_min_u32_e32 v40, v41, v40
	v_max_u32_e32 v41, v30, v35
	v_min_u32_e32 v30, v30, v35
	v_max_u32_e32 v35, v3, v32
	v_min_u32_e32 v3, v3, v32
	v_max_u32_e32 v32, v37, v38
	v_min_u32_e32 v37, v37, v38
	v_max_u32_e32 v38, v31, v0
	v_min_u32_e32 v0, v31, v0
	v_max_u32_e32 v31, v2, v42
	v_min_u32_e32 v2, v2, v42
	v_max_u32_e32 v42, v36, v39
	v_min_u32_e32 v36, v36, v39
	v_max_u32_e32 v39, v1, v34
	v_min_u32_e32 v1, v1, v34
	v_max_u32_e32 v34, v33, v40
	v_min_u32_e32 v33, v33, v40
	v_max_u32_e32 v54, v41, v32
	v_min_u32_e32 v32, v41, v32
	v_max_u32_e32 v55, v35, v38
	v_min_u32_e32 v56, v35, v38
	v_max_u32_e32 v57, v30, v37
	v_min_u32_e32 v30, v30, v37
	v_max_u32_e32 v58, v3, v0
	v_min_u32_e32 v0, v3, v0
	v_max_u32_e32 v45, v31, v42
	v_min_u32_e32 v44, v31, v42
	v_max_u32_e32 v43, v2, v36
	v_min_u32_e32 v42, v2, v36
	v_max_u32_e32 v41, v39, v34
	v_min_u32_e32 v40, v39, v34
	v_max_u32_e32 v39, v1, v33
	v_min_u32_e32 v38, v1, v33
	v_max_u32_e32 v37, v54, v55
	v_min_u32_e32 v36, v54, v55
	v_max_u32_e32 v35, v32, v56
	v_min_u32_e32 v34, v32, v56
	v_max_u32_e32 v33, v57, v58
	v_min_u32_e32 v32, v57, v58
	v_max_u32_e32 v31, v30, v0
	v_min_u32_e32 v30, v30, v0
	global_load_dwordx4 v[0:3], v[4:5], off offset:304
	global_load_dwordx4 v[54:57], v[4:5], off offset:288
	s_waitcnt vmcnt(2)
; __device__ __forceinline__ unsigned f2key(float f) { const unsigned u = __float_as_uint(f); return (u & 0x80000000u) ? ~u : (u | 0x80000000u); }
; __device__ __forceinline__ void peer_tile(const Args& A, LAS unsigned char* lds, int tile) {
;     ...
;                   for (int i = 0; i < 16; ++i) {
;                       const float lo = (float)__builtin_bit_cast(_Float16, (unsigned short)(sw[i] & 0xffffu)), hi = (float)__builtin_bit_cast(_Float16, (unsigned short)(sw[i] >> 16));
;                       const unsigned klo = (f2key(lo) & ~127u) | (unsigned)(127 - (32 * g + 2 * i)), khi = (f2key(hi) & ~127u) | (unsigned)(127 - (32 * g + 2 * i + 1));
;                       if (i < 8) { k0[2 * i] = klo; k0[2 * i + 1] = khi; } else { k1[2 * (i - 8)] = klo; k1[2 * (i - 8) + 1] = khi; } } }
	v_cvt_f32_f16_sdwa v58, v50 dst_sel:DWORD dst_unused:UNUSED_PAD src0_sel:WORD_1
	v_cvt_f32_f16_e32 v50, v50
	v_not_b32_e32 v59, v58
	v_or_b32_e32 v60, 0x80000000, v58
	v_cmp_gt_i32_e32 vcc, 0, v58
	s_nop 1
	v_cndmask_b32_e32 v58, v60, v59, vcc
	v_not_b32_e32 v59, v50
	v_or_b32_e32 v60, 0x80000000, v50
	v_cmp_gt_i32_e32 vcc, 0, v50
	v_and_b32_e32 v58, 0xffffff80, v58
	v_sub_u32_e32 v58, v58, v15
	v_cndmask_b32_e32 v50, v60, v59, vcc
	v_cvt_f32_f16_sdwa v59, v51 dst_sel:DWORD dst_unused:UNUSED_PAD src0_sel:WORD_1
	v_cvt_f32_f16_e32 v51, v51
	v_and_b32_e32 v50, 0xffffff80, v50
	v_sub_u32_e32 v50, v50, v15
	v_not_b32_e32 v60, v59
	v_or_b32_e32 v61, 0x80000000, v59
	v_cmp_gt_i32_e32 vcc, 0, v59
	v_add_u32_e32 v58, 0x7e, v58
	v_add_u32_e32 v50, 0x7f, v50
	v_cndmask_b32_e32 v59, v61, v60, vcc
	v_not_b32_e32 v60, v51
	v_or_b32_e32 v61, 0x80000000, v51
	v_cmp_gt_i32_e32 vcc, 0, v51
	v_and_b32_e32 v59, 0xffffff80, v59
	v_sub_u32_e32 v59, v59, v14
	v_cndmask_b32_e32 v51, v61, v60, vcc
	v_cvt_f32_f16_sdwa v60, v52 dst_sel:DWORD dst_unused:UNUSED_PAD src0_sel:WORD_1
	v_cvt_f32_f16_e32 v52, v52
	v_and_b32_e32 v51, 0xffffff80, v51
	v_sub_u32_e32 v51, v51, v14
	v_not_b32_e32 v61, v60
	v_or_b32_e32 v62, 0x80000000, v60
	v_cmp_gt_i32_e32 vcc, 0, v60
	v_add_u32_e32 v59, 0x7e, v59
	v_add_u32_e32 v51, 0x7f, v51
	v_cndmask_b32_e32 v60, v62, v61, vcc
	v_not_b32_e32 v61, v52
	v_or_b32_e32 v62, 0x80000000, v52
	v_cmp_gt_i32_e32 vcc, 0, v52
	v_and_b32_e32 v60, 0xffffff80, v60
	v_sub_u32_e32 v60, v60, v12
	v_cndmask_b32_e32 v52, v62, v61, vcc
	v_cvt_f32_f16_sdwa v61, v53 dst_sel:DWORD dst_unused:UNUSED_PAD src0_sel:WORD_1
	v_cvt_f32_f16_e32 v53, v53
	v_and_b32_e32 v52, 0xffffff80, v52
	v_sub_u32_e32 v52, v52, v12
	v_not_b32_e32 v62, v61
	v_or_b32_e32 v63, 0x80000000, v61
	v_cmp_gt_i32_e32 vcc, 0, v61
	v_add_u32_e32 v60, 0x7e, v60
	v_add_u32_e32 v52, 0x7f, v52
	v_cndmask_b32_e32 v61, v63, v62, vcc
	v_not_b32_e32 v62, v53
	v_or_b32_e32 v63, 0x80000000, v53
	v_cmp_gt_i32_e32 vcc, 0, v53
	v_and_b32_e32 v61, 0xffffff80, v61
	v_sub_u32_e32 v61, v61, v10
	v_cndmask_b32_e32 v53, v63, v62, vcc
	v_cvt_f32_f16_sdwa v62, v46 dst_sel:DWORD dst_unused:UNUSED_PAD src0_sel:WORD_1
	v_cvt_f32_f16_e32 v46, v46
	v_and_b32_e32 v53, 0xffffff80, v53
	v_sub_u32_e32 v53, v53, v10
	v_not_b32_e32 v63, v62
	v_or_b32_e32 v64, 0x80000000, v62
	v_cmp_gt_i32_e32 vcc, 0, v62
	v_add_u32_e32 v61, 0x7e, v61
	v_add_u32_e32 v53, 0x7f, v53
	v_cndmask_b32_e32 v62, v64, v63, vcc
	v_not_b32_e32 v63, v46
	v_or_b32_e32 v64, 0x80000000, v46
	v_cmp_gt_i32_e32 vcc, 0, v46
	v_and_b32_e32 v62, 0xffffff80, v62
	v_sub_u32_e32 v62, v62, v8
	v_cndmask_b32_e32 v46, v64, v63, vcc
	v_cvt_f32_f16_sdwa v63, v47 dst_sel:DWORD dst_unused:UNUSED_PAD src0_sel:WORD_1
	v_cvt_f32_f16_e32 v47, v47
	v_and_b32_e32 v46, 0xffffff80, v46
	v_sub_u32_e32 v46, v46, v8
	v_not_b32_e32 v64, v63
	v_or_b32_e32 v65, 0x80000000, v63
	v_cmp_gt_i32_e32 vcc, 0, v63
	v_add_u32_e32 v62, 0x7e, v62
	v_add_u32_e32 v46, 0x7f, v46
	v_cndmask_b32_e32 v63, v65, v64, vcc
	v_not_b32_e32 v64, v47
	v_or_b32_e32 v65, 0x80000000, v47
	v_cmp_gt_i32_e32 vcc, 0, v47
	v_and_b32_e32 v63, 0xffffff80, v63
	v_sub_u32_e32 v63, v63, v16
	v_cndmask_b32_e32 v47, v65, v64, vcc
	v_cvt_f32_f16_sdwa v64, v48 dst_sel:DWORD dst_unused:UNUSED_PAD src0_sel:WORD_1
	v_cvt_f32_f16_e32 v48, v48
	v_and_b32_e32 v47, 0xffffff80, v47
	v_sub_u32_e32 v47, v47, v16
	v_not_b32_e32 v65, v64
	v_or_b32_e32 v66, 0x80000000, v64
	v_cmp_gt_i32_e32 vcc, 0, v64
	v_add_u32_e32 v63, 0x7e, v63
	v_add_u32_e32 v47, 0x7f, v47
	v_cndmask_b32_e32 v64, v66, v65, vcc
	v_not_b32_e32 v65, v48
	v_or_b32_e32 v66, 0x80000000, v48
	v_cmp_gt_i32_e32 vcc, 0, v48
	v_and_b32_e32 v64, 0xffffff80, v64
	v_sub_u32_e32 v64, v64, v17
	v_cndmask_b32_e32 v48, v66, v65, vcc
	v_cvt_f32_f16_sdwa v65, v49 dst_sel:DWORD dst_unused:UNUSED_PAD src0_sel:WORD_1
	v_cvt_f32_f16_e32 v49, v49
	v_and_b32_e32 v48, 0xffffff80, v48
	v_sub_u32_e32 v48, v48, v17
	v_not_b32_e32 v66, v65
	v_or_b32_e32 v67, 0x80000000, v65
	v_cmp_gt_i32_e32 vcc, 0, v65
	v_add_u32_e32 v64, 0x7e, v64
	v_add_u32_e32 v48, 0x7f, v48
	v_cndmask_b32_e32 v65, v67, v66, vcc
	v_not_b32_e32 v66, v49
	v_or_b32_e32 v67, 0x80000000, v49
	v_cmp_gt_i32_e32 vcc, 0, v49
	v_and_b32_e32 v65, 0xffffff80, v65
	v_sub_u32_e32 v65, v65, v18
	v_cndmask_b32_e32 v49, v67, v66, vcc
	s_waitcnt vmcnt(0)
; __device__ __forceinline__ unsigned f2key(float f) { const unsigned u = __float_as_uint(f); return (u & 0x80000000u) ? ~u : (u | 0x80000000u); }
; #define CE_DESC(a, b) do { const unsigned _mx = (a) > (b) ? (a) : (b), _mn = (a) > (b) ? (b) : (a); (a) = _mx; (b) = _mn; } while (0)
; __device__ __forceinline__ void sort16_desc(unsigned (&k)[16]) {
; #pragma unroll
;     for (int size = 2; size <= 16; size <<= 1)
; #pragma unroll
;         for (int stride = size >> 1; stride > 0; stride >>= 1)
; #pragma unroll
;             for (int i = 0; i < 16; ++i) { const int j = i ^ stride;
;                 if (j > i) { if ((i & size) == 0) CE_DESC(k[i], k[j]); else CE_DESC(k[j], k[i]); } }
; }
; __device__ __forceinline__ void peer_tile(const Args& A, LAS unsigned char* lds, int tile) {
;     ...
;                   for (int i = 0; i < 16; ++i) {
;                       const float lo = (float)__builtin_bit_cast(_Float16, (unsigned short)(sw[i] & 0xffffu)), hi = (float)__builtin_bit_cast(_Float16, (unsigned short)(sw[i] >> 16));
;                       const unsigned klo = (f2key(lo) & ~127u) | (unsigned)(127 - (32 * g + 2 * i)), khi = (f2key(hi) & ~127u) | (unsigned)(127 - (32 * g + 2 * i + 1));
;                       if (i < 8) { k0[2 * i] = klo; k0[2 * i + 1] = khi; } else { k1[2 * (i - 8)] = klo; k1[2 * (i - 8) + 1] = khi; } } }
;                 sort16_desc(k0); sort16_desc(k1); merge16(k0, k1);
	v_cvt_f32_f16_sdwa v66, v54 dst_sel:DWORD dst_unused:UNUSED_PAD src0_sel:WORD_1
	v_cvt_f32_f16_e32 v54, v54
	v_and_b32_e32 v49, 0xffffff80, v49
	v_sub_u32_e32 v49, v49, v18
	v_not_b32_e32 v67, v66
	v_or_b32_e32 v68, 0x80000000, v66
	v_cmp_gt_i32_e32 vcc, 0, v66
	v_add_u32_e32 v65, 0x7e, v65
	v_add_u32_e32 v49, 0x7f, v49
	v_cndmask_b32_e32 v66, v68, v67, vcc
	v_not_b32_e32 v67, v54
	v_or_b32_e32 v68, 0x80000000, v54
	v_cmp_gt_i32_e32 vcc, 0, v54
	v_and_b32_e32 v66, 0xffffff80, v66
	v_sub_u32_e32 v66, v66, v20
	v_cndmask_b32_e32 v54, v68, v67, vcc
	v_cvt_f32_f16_sdwa v67, v55 dst_sel:DWORD dst_unused:UNUSED_PAD src0_sel:WORD_1
	v_cvt_f32_f16_e32 v55, v55
	v_and_b32_e32 v54, 0xffffff80, v54
	v_sub_u32_e32 v54, v54, v20
	v_not_b32_e32 v68, v67
	v_or_b32_e32 v69, 0x80000000, v67
	v_cmp_gt_i32_e32 vcc, 0, v67
	v_add_u32_e32 v66, 0x7e, v66
	v_add_u32_e32 v54, 0x7f, v54
	v_cndmask_b32_e32 v67, v69, v68, vcc
	v_not_b32_e32 v68, v55
	v_or_b32_e32 v69, 0x80000000, v55
	v_cmp_gt_i32_e32 vcc, 0, v55
	v_and_b32_e32 v67, 0xffffff80, v67
	v_sub_u32_e32 v67, v67, v21
	v_cndmask_b32_e32 v55, v69, v68, vcc
	v_cvt_f32_f16_sdwa v68, v56 dst_sel:DWORD dst_unused:UNUSED_PAD src0_sel:WORD_1
	v_cvt_f32_f16_e32 v56, v56
	v_and_b32_e32 v55, 0xffffff80, v55
	v_sub_u32_e32 v55, v55, v21
	v_not_b32_e32 v69, v68
	v_or_b32_e32 v70, 0x80000000, v68
	v_cmp_gt_i32_e32 vcc, 0, v68
	v_add_u32_e32 v67, 0x7e, v67
	v_add_u32_e32 v55, 0x7f, v55
	v_cndmask_b32_e32 v68, v70, v69, vcc
	v_not_b32_e32 v69, v56
	v_or_b32_e32 v70, 0x80000000, v56
	v_cmp_gt_i32_e32 vcc, 0, v56
	v_and_b32_e32 v68, 0xffffff80, v68
	v_sub_u32_e32 v68, v68, v22
	v_cndmask_b32_e32 v56, v70, v69, vcc
	v_cvt_f32_f16_sdwa v69, v57 dst_sel:DWORD dst_unused:UNUSED_PAD src0_sel:WORD_1
	v_cvt_f32_f16_e32 v57, v57
	v_and_b32_e32 v56, 0xffffff80, v56
	v_sub_u32_e32 v56, v56, v22
	v_not_b32_e32 v70, v69
	v_or_b32_e32 v71, 0x80000000, v69
	v_cmp_gt_i32_e32 vcc, 0, v69
	v_add_u32_e32 v68, 0x7e, v68
	v_add_u32_e32 v56, 0x7f, v56
	v_cndmask_b32_e32 v69, v71, v70, vcc
	v_not_b32_e32 v70, v57
	v_or_b32_e32 v71, 0x80000000, v57
	v_cmp_gt_i32_e32 vcc, 0, v57
	v_and_b32_e32 v69, 0xffffff80, v69
	v_sub_u32_e32 v69, v69, v23
	v_cndmask_b32_e32 v57, v71, v70, vcc
	v_cvt_f32_f16_sdwa v70, v0 dst_sel:DWORD dst_unused:UNUSED_PAD src0_sel:WORD_1
	v_cvt_f32_f16_e32 v0, v0
	v_and_b32_e32 v57, 0xffffff80, v57
	v_sub_u32_e32 v57, v57, v23
	v_not_b32_e32 v71, v70
	v_or_b32_e32 v72, 0x80000000, v70
	v_cmp_gt_i32_e32 vcc, 0, v70
	v_add_u32_e32 v69, 0x7e, v69
	v_add_u32_e32 v57, 0x7f, v57
	v_cndmask_b32_e32 v70, v72, v71, vcc
	v_not_b32_e32 v71, v0
	v_or_b32_e32 v72, 0x80000000, v0
	v_cmp_gt_i32_e32 vcc, 0, v0
	v_and_b32_e32 v70, 0xffffff80, v70
	v_sub_u32_e32 v70, v70, v24
	v_cndmask_b32_e32 v0, v72, v71, vcc
	v_cvt_f32_f16_sdwa v71, v1 dst_sel:DWORD dst_unused:UNUSED_PAD src0_sel:WORD_1
	v_cvt_f32_f16_e32 v1, v1
	v_and_b32_e32 v0, 0xffffff80, v0
	v_sub_u32_e32 v0, v0, v24
	v_not_b32_e32 v72, v71
	v_or_b32_e32 v73, 0x80000000, v71
	v_cmp_gt_i32_e32 vcc, 0, v71
	v_add_u32_e32 v70, 0x7e, v70
	v_add_u32_e32 v0, 0x7f, v0
	v_cndmask_b32_e32 v71, v73, v72, vcc
	v_not_b32_e32 v72, v1
	v_or_b32_e32 v73, 0x80000000, v1
	v_cmp_gt_i32_e32 vcc, 0, v1
	v_and_b32_e32 v71, 0xffffff80, v71
	v_sub_u32_e32 v71, v71, v25
	v_cndmask_b32_e32 v1, v73, v72, vcc
	v_cvt_f32_f16_sdwa v72, v2 dst_sel:DWORD dst_unused:UNUSED_PAD src0_sel:WORD_1
	v_cvt_f32_f16_e32 v2, v2
	v_and_b32_e32 v1, 0xffffff80, v1
	v_sub_u32_e32 v1, v1, v25
	v_not_b32_e32 v73, v72
	v_or_b32_e32 v74, 0x80000000, v72
	v_cmp_gt_i32_e32 vcc, 0, v72
	v_add_u32_e32 v71, 0x7e, v71
	v_add_u32_e32 v1, 0x7f, v1
	v_cndmask_b32_e32 v72, v74, v73, vcc
	v_not_b32_e32 v73, v2
	v_or_b32_e32 v74, 0x80000000, v2
	v_cmp_gt_i32_e32 vcc, 0, v2
	v_and_b32_e32 v72, 0xffffff80, v72
	v_sub_u32_e32 v72, v72, v26
	v_cndmask_b32_e32 v2, v74, v73, vcc
	v_cvt_f32_f16_sdwa v73, v3 dst_sel:DWORD dst_unused:UNUSED_PAD src0_sel:WORD_1
	v_cvt_f32_f16_e32 v3, v3
	v_and_b32_e32 v2, 0xffffff80, v2
	v_sub_u32_e32 v2, v2, v26
	v_not_b32_e32 v74, v73
	v_or_b32_e32 v75, 0x80000000, v73
	v_cmp_gt_i32_e32 vcc, 0, v73
	v_add_u32_e32 v72, 0x7e, v72
	v_add_u32_e32 v2, 0x7f, v2
	v_cndmask_b32_e32 v73, v75, v74, vcc
	v_not_b32_e32 v74, v3
	v_or_b32_e32 v75, 0x80000000, v3
	v_cmp_gt_i32_e32 vcc, 0, v3
	v_and_b32_e32 v73, 0xffffff80, v73
	v_sub_u32_e32 v73, v73, v28
	v_cndmask_b32_e32 v3, v75, v74, vcc
	v_and_b32_e32 v3, 0xffffff80, v3
	v_sub_u32_e32 v3, v3, v28
	v_add_u32_e32 v73, 0x7e, v73
	v_add_u32_e32 v3, 0x7f, v3
	v_max_u32_e32 v74, v50, v58
	v_min_u32_e32 v50, v50, v58
	v_max_u32_e32 v58, v59, v51
	v_min_u32_e32 v51, v59, v51
	v_max_u32_e32 v59, v52, v60
	v_min_u32_e32 v52, v52, v60
	v_max_u32_e32 v60, v61, v53
	v_min_u32_e32 v53, v61, v53
	v_max_u32_e32 v61, v46, v62
	v_min_u32_e32 v46, v46, v62
	v_max_u32_e32 v62, v63, v47
	v_min_u32_e32 v47, v63, v47
	v_max_u32_e32 v63, v48, v64
	v_min_u32_e32 v48, v48, v64
	v_max_u32_e32 v64, v65, v49
	v_min_u32_e32 v49, v65, v49
	v_max_u32_e32 v82, v54, v66
	v_min_u32_e32 v54, v54, v66
	v_max_u32_e32 v66, v67, v55
	v_min_u32_e32 v55, v67, v55
	v_max_u32_e32 v67, v56, v68
	v_min_u32_e32 v56, v56, v68
	v_max_u32_e32 v68, v69, v57
	v_min_u32_e32 v57, v69, v57
	v_max_u32_e32 v69, v0, v70
	v_min_u32_e32 v0, v0, v70
	v_max_u32_e32 v70, v71, v1
	v_min_u32_e32 v1, v71, v1
	v_max_u32_e32 v71, v2, v72
	v_min_u32_e32 v2, v2, v72
	v_max_u32_e32 v72, v73, v3
	v_min_u32_e32 v3, v73, v3
	v_max_u32_e32 v65, v74, v51
	v_min_u32_e32 v51, v74, v51
	v_max_u32_e32 v74, v50, v58
	v_min_u32_e32 v50, v50, v58
	v_max_u32_e32 v58, v53, v59
	v_min_u32_e32 v53, v53, v59
	v_max_u32_e32 v59, v60, v52
	v_min_u32_e32 v52, v60, v52
; #define CE_DESC(a, b) do { const unsigned _mx = (a) > (b) ? (a) : (b), _mn = (a) > (b) ? (b) : (a); (a) = _mx; (b) = _mn; } while (0)
; __device__ __forceinline__ void sort16_desc(unsigned (&k)[16]) {
; #pragma unroll
;     for (int size = 2; size <= 16; size <<= 1)
; #pragma unroll
;         for (int stride = size >> 1; stride > 0; stride >>= 1)
; #pragma unroll
;             for (int i = 0; i < 16; ++i) { const int j = i ^ stride;
;                 if (j > i) { if ((i & size) == 0) CE_DESC(k[i], k[j]); else CE_DESC(k[j], k[i]); } }
; }
	v_max_u32_e32 v60, v61, v47
	v_min_u32_e32 v47, v61, v47
	v_max_u32_e32 v61, v46, v62
	v_min_u32_e32 v46, v46, v62
	v_max_u32_e32 v62, v49, v63
	v_min_u32_e32 v49, v49, v63
	v_max_u32_e32 v63, v64, v48
	v_min_u32_e32 v48, v64, v48
	v_max_u32_e32 v73, v82, v55
	v_min_u32_e32 v55, v82, v55
	v_max_u32_e32 v82, v54, v66
	v_min_u32_e32 v54, v54, v66
	v_max_u32_e32 v66, v57, v67
	v_min_u32_e32 v57, v57, v67
	v_max_u32_e32 v67, v68, v56
	v_min_u32_e32 v56, v68, v56
	v_max_u32_e32 v68, v69, v1
	v_min_u32_e32 v1, v69, v1
	v_max_u32_e32 v69, v0, v70
	v_min_u32_e32 v0, v0, v70
	v_max_u32_e32 v70, v3, v71
	v_min_u32_e32 v3, v3, v71
	v_max_u32_e32 v71, v72, v2
	v_min_u32_e32 v2, v72, v2
	v_max_u32_e32 v64, v65, v74
	v_min_u32_e32 v65, v65, v74
	v_max_u32_e32 v74, v51, v50
	v_min_u32_e32 v50, v51, v50
	v_max_u32_e32 v51, v52, v53
	v_min_u32_e32 v52, v52, v53
	v_max_u32_e32 v53, v59, v58
	v_min_u32_e32 v58, v59, v58
	v_max_u32_e32 v59, v60, v61
	v_min_u32_e32 v60, v60, v61
	v_max_u32_e32 v61, v47, v46
	v_min_u32_e32 v46, v47, v46
	v_max_u32_e32 v47, v48, v49
	v_min_u32_e32 v48, v48, v49
	v_max_u32_e32 v49, v63, v62
	v_min_u32_e32 v62, v63, v62
	v_max_u32_e32 v72, v73, v82
	v_min_u32_e32 v73, v73, v82
	v_max_u32_e32 v82, v55, v54
	v_min_u32_e32 v54, v55, v54
	v_max_u32_e32 v55, v56, v57
	v_min_u32_e32 v56, v56, v57
	v_max_u32_e32 v57, v67, v66
	v_min_u32_e32 v66, v67, v66
	v_max_u32_e32 v67, v68, v69
	v_min_u32_e32 v68, v68, v69
	v_max_u32_e32 v69, v1, v0
	v_min_u32_e32 v0, v1, v0
	v_max_u32_e32 v1, v2, v3
	v_min_u32_e32 v2, v2, v3
	v_max_u32_e32 v3, v71, v70
	v_min_u32_e32 v70, v71, v70
	v_max_u32_e32 v63, v64, v52
	v_min_u32_e32 v52, v64, v52
	v_max_u32_e32 v64, v65, v51
	v_min_u32_e32 v51, v65, v51
	v_max_u32_e32 v65, v74, v58
	v_min_u32_e32 v58, v74, v58
	v_max_u32_e32 v74, v50, v53
	v_min_u32_e32 v50, v50, v53
	v_max_u32_e32 v53, v48, v59
	v_min_u32_e32 v48, v48, v59
	v_max_u32_e32 v59, v47, v60
	v_min_u32_e32 v47, v47, v60
	v_max_u32_e32 v60, v62, v61
	v_min_u32_e32 v61, v62, v61
	v_max_u32_e32 v62, v49, v46
	v_min_u32_e32 v46, v49, v46
	v_max_u32_e32 v71, v72, v56
	v_min_u32_e32 v56, v72, v56
	v_max_u32_e32 v72, v73, v55
	v_min_u32_e32 v55, v73, v55
	v_max_u32_e32 v73, v82, v66
	v_min_u32_e32 v66, v82, v66
	v_max_u32_e32 v82, v54, v57
	v_min_u32_e32 v54, v54, v57
	v_max_u32_e32 v57, v2, v67
	v_min_u32_e32 v2, v2, v67
	v_max_u32_e32 v67, v1, v68
	v_min_u32_e32 v1, v1, v68
	v_max_u32_e32 v68, v70, v69
	v_min_u32_e32 v69, v70, v69
	v_max_u32_e32 v70, v3, v0
	v_min_u32_e32 v0, v3, v0
	v_max_u32_e32 v49, v63, v65
	v_min_u32_e32 v63, v63, v65
	v_max_u32_e32 v65, v64, v74
	v_min_u32_e32 v64, v64, v74
	v_max_u32_e32 v74, v52, v58
	v_min_u32_e32 v52, v52, v58
	v_max_u32_e32 v58, v51, v50
	v_min_u32_e32 v50, v51, v50
	v_max_u32_e32 v51, v61, v48
	v_min_u32_e32 v48, v61, v48
	v_max_u32_e32 v61, v46, v47
	v_min_u32_e32 v46, v46, v47
	v_max_u32_e32 v47, v60, v53
	v_min_u32_e32 v53, v60, v53
	v_max_u32_e32 v60, v62, v59
	v_min_u32_e32 v59, v62, v59
	v_max_u32_e32 v3, v71, v73
	v_min_u32_e32 v71, v71, v73
	v_max_u32_e32 v73, v72, v82
	v_min_u32_e32 v72, v72, v82
	v_max_u32_e32 v82, v56, v66
	v_min_u32_e32 v56, v56, v66
	v_max_u32_e32 v66, v55, v54
	v_min_u32_e32 v54, v55, v54
	v_max_u32_e32 v55, v69, v2
	v_min_u32_e32 v2, v69, v2
	v_max_u32_e32 v69, v0, v1
	v_min_u32_e32 v0, v0, v1
	v_max_u32_e32 v1, v68, v57
	v_min_u32_e32 v57, v68, v57
	v_max_u32_e32 v68, v70, v67
	v_min_u32_e32 v67, v70, v67
	v_max_u32_e32 v62, v49, v65
	v_min_u32_e32 v49, v49, v65
	v_max_u32_e32 v65, v63, v64
	v_min_u32_e32 v63, v63, v64
	v_max_u32_e32 v64, v74, v58
	v_min_u32_e32 v58, v74, v58
	v_max_u32_e32 v74, v52, v50
	v_min_u32_e32 v50, v52, v50
	v_max_u32_e32 v52, v46, v48
	v_min_u32_e32 v46, v46, v48
	v_max_u32_e32 v48, v61, v51
	v_min_u32_e32 v51, v61, v51
	v_max_u32_e32 v61, v59, v53
	v_min_u32_e32 v53, v59, v53
	v_max_u32_e32 v59, v60, v47
	v_min_u32_e32 v47, v60, v47
	v_max_u32_e32 v70, v3, v73
	v_min_u32_e32 v3, v3, v73
	v_max_u32_e32 v73, v71, v72
	v_min_u32_e32 v71, v71, v72
	v_max_u32_e32 v72, v82, v66
	v_min_u32_e32 v66, v82, v66
	v_max_u32_e32 v82, v56, v54
	v_min_u32_e32 v54, v56, v54
	v_max_u32_e32 v56, v0, v2
	v_min_u32_e32 v0, v0, v2
	v_max_u32_e32 v2, v69, v55
	v_min_u32_e32 v55, v69, v55
	v_max_u32_e32 v69, v67, v57
	v_min_u32_e32 v57, v67, v57
	v_max_u32_e32 v67, v68, v1
	v_min_u32_e32 v1, v68, v1
	v_max_u32_e32 v60, v62, v46
	v_min_u32_e32 v46, v62, v46
	v_max_u32_e32 v62, v49, v52
	v_min_u32_e32 v49, v49, v52
	v_max_u32_e32 v52, v65, v51
	v_min_u32_e32 v51, v65, v51
	v_max_u32_e32 v65, v63, v48
	v_min_u32_e32 v48, v63, v48
	v_max_u32_e32 v63, v64, v53
	v_min_u32_e32 v53, v64, v53
	v_max_u32_e32 v64, v58, v61
	v_min_u32_e32 v58, v58, v61
	v_max_u32_e32 v61, v74, v47
	v_min_u32_e32 v47, v74, v47
	v_max_u32_e32 v74, v50, v59
	v_min_u32_e32 v50, v50, v59
	v_max_u32_e32 v68, v70, v0
	v_min_u32_e32 v0, v70, v0
	v_max_u32_e32 v70, v3, v56
	v_min_u32_e32 v3, v3, v56
	v_max_u32_e32 v56, v73, v55
	v_min_u32_e32 v55, v73, v55
	v_max_u32_e32 v73, v71, v2
	v_min_u32_e32 v2, v71, v2
	v_max_u32_e32 v71, v72, v57
	v_min_u32_e32 v57, v72, v57
	v_max_u32_e32 v72, v66, v69
	v_min_u32_e32 v66, v66, v69
	v_max_u32_e32 v69, v82, v1
	v_min_u32_e32 v1, v82, v1
	v_max_u32_e32 v82, v54, v67
	v_min_u32_e32 v54, v54, v67
	v_max_u32_e32 v59, v60, v63
	v_min_u32_e32 v60, v60, v63
	v_max_u32_e32 v63, v62, v64
	v_min_u32_e32 v62, v62, v64
	v_max_u32_e32 v64, v52, v61
	v_min_u32_e32 v52, v52, v61
	v_max_u32_e32 v61, v65, v74
	v_min_u32_e32 v65, v65, v74
	v_max_u32_e32 v74, v46, v53
	v_min_u32_e32 v46, v46, v53
	v_max_u32_e32 v53, v49, v58
	v_min_u32_e32 v49, v49, v58
	v_max_u32_e32 v58, v51, v47
; #define CE_DESC(a, b) do { const unsigned _mx = (a) > (b) ? (a) : (b), _mn = (a) > (b) ? (b) : (a); (a) = _mx; (b) = _mn; } while (0)
; __device__ __forceinline__ void sort16_desc(unsigned (&k)[16]) {
; #pragma unroll
;     for (int size = 2; size <= 16; size <<= 1)
; #pragma unroll
;         for (int stride = size >> 1; stride > 0; stride >>= 1)
; #pragma unroll
;             for (int i = 0; i < 16; ++i) { const int j = i ^ stride;
;                 if (j > i) { if ((i & size) == 0) CE_DESC(k[i], k[j]); else CE_DESC(k[j], k[i]); } }
; }
; __device__ __forceinline__ void merge16(unsigned (&a)[16], const unsigned (&b)[16]) {
; #pragma unroll
;     for (int i = 0; i < 16; ++i) a[i] = a[i] > b[15 - i] ? a[i] : b[15 - i];
; #pragma unroll
;     for (int stride = 8; stride > 0; stride >>= 1)
; #pragma unroll
;         for (int i = 0; i < 16; ++i) { const int j = i ^ stride; if (j > i) CE_DESC(a[i], a[j]); }
; }
; __device__ __forceinline__ void peer_tile(const Args& A, LAS unsigned char* lds, int tile) {
;     ...
;                 sort16_desc(k0); sort16_desc(k1); merge16(k0, k1);
; #pragma unroll
;                 for (int msk = 16; msk <= 32; msk <<= 1) {
; #pragma unroll
;                     for (int i = 0; i < 16; ++i) k1[i] = (unsigned)__shfl_xor((int)k0[i], msk);
;                     merge16(k0, k1); }
	v_min_u32_e32 v47, v51, v47
	v_max_u32_e32 v51, v48, v50
	v_min_u32_e32 v48, v48, v50
	v_max_u32_e32 v67, v68, v71
	v_min_u32_e32 v68, v68, v71
	v_max_u32_e32 v71, v70, v72
	v_min_u32_e32 v70, v70, v72
	v_max_u32_e32 v72, v56, v69
	v_min_u32_e32 v56, v56, v69
	v_max_u32_e32 v69, v73, v82
	v_min_u32_e32 v73, v73, v82
	v_max_u32_e32 v82, v0, v57
	v_min_u32_e32 v0, v0, v57
	v_max_u32_e32 v57, v3, v66
	v_min_u32_e32 v3, v3, v66
	v_max_u32_e32 v66, v55, v1
	v_min_u32_e32 v1, v55, v1
	v_max_u32_e32 v55, v2, v54
	v_min_u32_e32 v2, v2, v54
	v_max_u32_e32 v50, v59, v64
	v_min_u32_e32 v59, v59, v64
	v_max_u32_e32 v64, v63, v61
	v_min_u32_e32 v61, v63, v61
	v_max_u32_e32 v63, v60, v52
	v_min_u32_e32 v52, v60, v52
	v_max_u32_e32 v60, v62, v65
	v_min_u32_e32 v62, v62, v65
	v_max_u32_e32 v65, v74, v58
	v_min_u32_e32 v58, v74, v58
	v_max_u32_e32 v74, v53, v51
	v_min_u32_e32 v51, v53, v51
	v_max_u32_e32 v53, v46, v47
	v_min_u32_e32 v46, v46, v47
	v_max_u32_e32 v47, v49, v48
	v_min_u32_e32 v48, v49, v48
	v_max_u32_e32 v54, v67, v72
	v_min_u32_e32 v67, v67, v72
	v_max_u32_e32 v72, v71, v69
	v_min_u32_e32 v69, v71, v69
	v_max_u32_e32 v71, v68, v56
	v_min_u32_e32 v56, v68, v56
	v_max_u32_e32 v68, v70, v73
	v_min_u32_e32 v70, v70, v73
	v_max_u32_e32 v73, v82, v66
	v_min_u32_e32 v66, v82, v66
	v_max_u32_e32 v82, v57, v55
	v_min_u32_e32 v55, v57, v55
	v_max_u32_e32 v57, v0, v1
	v_min_u32_e32 v0, v0, v1
	v_max_u32_e32 v1, v3, v2
	v_min_u32_e32 v2, v3, v2
	v_min_u32_e32 v49, v50, v64
	v_min_u32_e32 v75, v59, v61
	v_min_u32_e32 v76, v63, v60
	v_min_u32_e32 v77, v52, v62
	v_min_u32_e32 v78, v65, v74
	v_min_u32_e32 v79, v58, v51
	v_min_u32_e32 v80, v53, v47
	v_min_u32_e32 v81, v46, v48
	v_min_u32_e32 v3, v54, v72
	v_min_u32_e32 v83, v67, v69
	v_min_u32_e32 v84, v71, v68
	v_min_u32_e32 v85, v56, v70
	v_min_u32_e32 v86, v73, v82
	v_min_u32_e32 v87, v66, v55
	v_min_u32_e32 v88, v57, v1
	v_min_u32_e32 v89, v0, v2
	v_max3_u32 v50, v50, v64, v89
	v_max3_u32 v0, v49, v0, v2
	v_max3_u32 v2, v59, v61, v88
	v_max3_u32 v1, v75, v57, v1
	v_max3_u32 v49, v63, v60, v87
	v_max3_u32 v55, v76, v66, v55
	v_max3_u32 v52, v52, v62, v86
	v_max3_u32 v57, v77, v73, v82
	v_max3_u32 v59, v65, v74, v85
	v_max3_u32 v56, v78, v56, v70
	v_max3_u32 v51, v58, v51, v84
	v_max3_u32 v58, v79, v71, v68
	v_max3_u32 v47, v53, v47, v83
	v_max3_u32 v53, v80, v67, v69
	v_max3_u32 v3, v46, v48, v3
	v_max3_u32 v46, v81, v54, v72
	v_max_u32_e32 v48, v50, v59
	v_min_u32_e32 v50, v50, v59
	v_max_u32_e32 v54, v0, v56
	v_min_u32_e32 v0, v0, v56
	v_max_u32_e32 v56, v2, v51
	v_min_u32_e32 v2, v2, v51
	v_max_u32_e32 v51, v1, v58
	v_min_u32_e32 v1, v1, v58
	v_max_u32_e32 v58, v49, v47
	v_min_u32_e32 v47, v49, v47
	v_max_u32_e32 v49, v55, v53
	v_min_u32_e32 v53, v55, v53
	v_max_u32_e32 v55, v52, v3
	v_min_u32_e32 v3, v52, v3
	v_max_u32_e32 v52, v57, v46
	v_min_u32_e32 v46, v57, v46
	v_max_u32_e32 v57, v48, v58
	v_min_u32_e32 v48, v48, v58
	v_max_u32_e32 v58, v54, v49
	v_min_u32_e32 v49, v54, v49
	v_max_u32_e32 v54, v56, v55
	v_min_u32_e32 v55, v56, v55
	v_max_u32_e32 v56, v51, v52
	v_min_u32_e32 v51, v51, v52
	v_max_u32_e32 v52, v50, v47
	v_min_u32_e32 v47, v50, v47
	v_max_u32_e32 v50, v0, v53
	v_min_u32_e32 v0, v0, v53
	v_max_u32_e32 v53, v2, v3
	v_min_u32_e32 v2, v2, v3
	v_max_u32_e32 v3, v1, v46
	v_min_u32_e32 v1, v1, v46
	v_max_u32_e32 v46, v57, v54
	v_min_u32_e32 v54, v57, v54
	v_max_u32_e32 v57, v58, v56
	v_min_u32_e32 v56, v58, v56
	v_max_u32_e32 v58, v48, v55
	v_min_u32_e32 v48, v48, v55
	v_max_u32_e32 v55, v49, v51
	v_min_u32_e32 v49, v49, v51
	v_max_u32_e32 v51, v52, v53
	v_min_u32_e32 v52, v52, v53
	v_max_u32_e32 v53, v50, v3
	v_min_u32_e32 v3, v50, v3
	v_max_u32_e32 v50, v47, v2
	v_min_u32_e32 v2, v47, v2
	v_max_u32_e32 v47, v0, v1
	v_min_u32_e32 v0, v0, v1
	v_max_u32_e32 v1, v46, v57
	v_min_u32_e32 v46, v46, v57
	v_max_u32_e32 v57, v54, v56
	v_min_u32_e32 v54, v54, v56
	v_max_u32_e32 v56, v58, v55
	v_min_u32_e32 v55, v58, v55
	v_max_u32_e32 v58, v48, v49
	v_min_u32_e32 v48, v48, v49
	v_max_u32_e32 v49, v51, v53
	v_min_u32_e32 v51, v51, v53
	v_max_u32_e32 v53, v52, v3
	v_min_u32_e32 v3, v52, v3
	v_max_u32_e32 v52, v50, v47
	v_min_u32_e32 v47, v50, v47
	v_max_u32_e32 v50, v2, v0
	v_min_u32_e32 v0, v2, v0
	ds_bpermute_b32 v2, v27, v1
	ds_bpermute_b32 v59, v27, v46
	ds_bpermute_b32 v60, v27, v57
	ds_bpermute_b32 v61, v27, v54
	ds_bpermute_b32 v62, v27, v56
	ds_bpermute_b32 v63, v27, v55
	ds_bpermute_b32 v64, v27, v58
	ds_bpermute_b32 v65, v27, v48
	ds_bpermute_b32 v66, v27, v49
	ds_bpermute_b32 v67, v27, v51
	ds_bpermute_b32 v68, v27, v53
	ds_bpermute_b32 v69, v27, v0
	ds_bpermute_b32 v70, v27, v50
	ds_bpermute_b32 v71, v27, v47
	ds_bpermute_b32 v72, v27, v52
	ds_bpermute_b32 v73, v27, v3
	s_waitcnt lgkmcnt(4)
	v_max_u32_e32 v1, v1, v69
	s_waitcnt lgkmcnt(3)
	v_max_u32_e32 v46, v46, v70
	s_waitcnt lgkmcnt(2)
	v_max_u32_e32 v57, v57, v71
	s_waitcnt lgkmcnt(1)
	v_max_u32_e32 v54, v54, v72
	s_waitcnt lgkmcnt(0)
; #define CE_DESC(a, b) do { const unsigned _mx = (a) > (b) ? (a) : (b), _mn = (a) > (b) ? (b) : (a); (a) = _mx; (b) = _mn; } while (0)
; __device__ __forceinline__ void sort16_desc(unsigned (&k)[16]) {
; #pragma unroll
;     for (int size = 2; size <= 16; size <<= 1)
; #pragma unroll
;         for (int stride = size >> 1; stride > 0; stride >>= 1)
; #pragma unroll
;             for (int i = 0; i < 16; ++i) { const int j = i ^ stride;
;                 if (j > i) { if ((i & size) == 0) CE_DESC(k[i], k[j]); else CE_DESC(k[j], k[i]); } }
; }
; __device__ __forceinline__ void merge16(unsigned (&a)[16], const unsigned (&b)[16]) {
; #pragma unroll
;     for (int i = 0; i < 16; ++i) a[i] = a[i] > b[15 - i] ? a[i] : b[15 - i];
; #pragma unroll
;     for (int stride = 8; stride > 0; stride >>= 1)
; #pragma unroll
;         for (int i = 0; i < 16; ++i) { const int j = i ^ stride; if (j > i) CE_DESC(a[i], a[j]); }
; }
; __device__ __forceinline__ void peer_tile(const Args& A, LAS unsigned char* lds, int tile) {
;     ...
;                 { const bf16_t* sp = QRY + m * 2048 + hp * 128 + 32 * g;
;                   const u32x4 s0 = *(const u32x4*)sp, s1 = *(const u32x4*)(sp + 8), s2 = *(const u32x4*)(sp + 16), s3 = *(const u32x4*)(sp + 24);
;     ...
;                 sort16_desc(k0); sort16_desc(k1); merge16(k0, k1);
; #pragma unroll
;                 for (int msk = 16; msk <= 32; msk <<= 1) {
; #pragma unroll
;                     for (int i = 0; i < 16; ++i) k1[i] = (unsigned)__shfl_xor((int)k0[i], msk);
;                     merge16(k0, k1); }
	v_max_u32_e32 v56, v56, v73
	v_max_u32_e32 v55, v55, v68
	v_max_u32_e32 v58, v58, v67
	v_max_u32_e32 v48, v48, v66
	v_max_u32_e32 v49, v49, v65
	v_max_u32_e32 v51, v51, v64
	v_max_u32_e32 v53, v53, v63
	v_max_u32_e32 v3, v3, v62
	v_max_u32_e32 v52, v52, v61
	v_max_u32_e32 v47, v47, v60
	v_max_u32_e32 v50, v50, v59
	v_max_u32_e32 v0, v0, v2
	v_max_u32_e32 v2, v1, v49
	v_min_u32_e32 v1, v1, v49
	v_max_u32_e32 v49, v46, v51
	v_min_u32_e32 v46, v46, v51
	v_max_u32_e32 v51, v57, v53
	v_min_u32_e32 v53, v57, v53
	v_max_u32_e32 v57, v54, v3
	v_min_u32_e32 v3, v54, v3
	v_max_u32_e32 v54, v56, v52
	v_min_u32_e32 v52, v56, v52
	v_max_u32_e32 v56, v55, v47
	v_min_u32_e32 v47, v55, v47
	v_max_u32_e32 v55, v58, v50
	v_min_u32_e32 v50, v58, v50
	v_max_u32_e32 v58, v48, v0
	v_min_u32_e32 v0, v48, v0
	v_max_u32_e32 v48, v2, v54
	v_min_u32_e32 v2, v2, v54
	v_max_u32_e32 v54, v49, v56
	v_min_u32_e32 v49, v49, v56
	v_max_u32_e32 v56, v51, v55
	v_min_u32_e32 v51, v51, v55
	v_max_u32_e32 v55, v57, v58
	v_min_u32_e32 v57, v57, v58
	v_max_u32_e32 v58, v1, v52
	v_min_u32_e32 v1, v1, v52
	v_max_u32_e32 v52, v46, v47
	v_min_u32_e32 v46, v46, v47
	v_max_u32_e32 v47, v53, v50
	v_min_u32_e32 v50, v53, v50
	v_max_u32_e32 v53, v3, v0
	v_min_u32_e32 v0, v3, v0
	v_max_u32_e32 v3, v48, v56
	v_min_u32_e32 v48, v48, v56
	v_max_u32_e32 v56, v54, v55
	v_min_u32_e32 v54, v54, v55
	v_max_u32_e32 v55, v2, v51
	v_min_u32_e32 v2, v2, v51
	v_max_u32_e32 v51, v49, v57
	v_min_u32_e32 v49, v49, v57
	v_max_u32_e32 v57, v58, v47
	v_min_u32_e32 v47, v58, v47
	v_max_u32_e32 v58, v52, v53
	v_min_u32_e32 v52, v52, v53
	v_max_u32_e32 v53, v1, v50
	v_min_u32_e32 v1, v1, v50
	v_max_u32_e32 v50, v46, v0
	v_min_u32_e32 v0, v46, v0
	v_max_u32_e32 v46, v3, v56
	v_min_u32_e32 v3, v3, v56
	v_max_u32_e32 v56, v48, v54
	v_min_u32_e32 v48, v48, v54
	v_max_u32_e32 v54, v55, v51
	v_min_u32_e32 v51, v55, v51
	v_max_u32_e32 v55, v2, v49
	v_min_u32_e32 v2, v2, v49
	v_max_u32_e32 v49, v57, v58
	v_min_u32_e32 v57, v57, v58
	v_max_u32_e32 v58, v47, v52
	v_min_u32_e32 v47, v47, v52
	v_max_u32_e32 v52, v53, v50
	v_min_u32_e32 v50, v53, v50
	v_max_u32_e32 v53, v1, v0
	v_min_u32_e32 v0, v1, v0
	ds_bpermute_b32 v62, v29, v0
	ds_bpermute_b32 v1, v29, v46
	ds_bpermute_b32 v59, v29, v3
	ds_bpermute_b32 v60, v29, v56
	ds_bpermute_b32 v61, v29, v48
	s_waitcnt lgkmcnt(4)
	v_max_u32_e32 v46, v46, v62
	global_load_dwordx4 v[62:65], v[4:5], off offset:528
	global_load_dwordx4 v[66:69], v[4:5], off offset:512
	ds_bpermute_b32 v70, v29, v54
	ds_bpermute_b32 v71, v29, v51
	ds_bpermute_b32 v72, v29, v55
	ds_bpermute_b32 v73, v29, v2
	ds_bpermute_b32 v74, v29, v49
	ds_bpermute_b32 v75, v29, v57
	ds_bpermute_b32 v76, v29, v58
	ds_bpermute_b32 v77, v29, v47
	ds_bpermute_b32 v78, v29, v52
	ds_bpermute_b32 v79, v29, v53
	ds_bpermute_b32 v80, v29, v50
	s_waitcnt lgkmcnt(4)
	v_max_u32_e32 v51, v51, v76
	s_waitcnt lgkmcnt(3)
	v_max_u32_e32 v54, v54, v77
	s_waitcnt lgkmcnt(2)
	v_max_u32_e32 v48, v48, v78
	s_waitcnt lgkmcnt(1)
	v_max_u32_e32 v3, v3, v79
	s_waitcnt lgkmcnt(0)
	v_max_u32_e32 v56, v56, v80
	v_max_u32_e32 v55, v55, v75
	v_max_u32_e32 v2, v2, v74
	v_max_u32_e32 v49, v49, v73
	v_max_u32_e32 v57, v57, v72
	v_max_u32_e32 v58, v58, v71
	v_max_u32_e32 v47, v47, v70
	v_max_u32_e32 v52, v52, v61
	v_max_u32_e32 v50, v50, v60
	v_max_u32_e32 v53, v53, v59
	v_max_u32_e32 v0, v0, v1
	v_max_u32_e32 v1, v46, v49
	v_min_u32_e32 v46, v46, v49
	v_max_u32_e32 v49, v3, v57
	v_min_u32_e32 v3, v3, v57
	v_max_u32_e32 v57, v56, v58
	v_min_u32_e32 v56, v56, v58
	v_max_u32_e32 v58, v48, v47
	v_min_u32_e32 v47, v48, v47
	v_max_u32_e32 v48, v54, v52
	v_min_u32_e32 v52, v54, v52
	v_max_u32_e32 v54, v51, v50
	v_min_u32_e32 v50, v51, v50
	v_max_u32_e32 v51, v55, v53
	v_min_u32_e32 v53, v55, v53
	v_max_u32_e32 v55, v2, v0
	v_min_u32_e32 v0, v2, v0
	v_max_u32_e32 v2, v1, v48
	v_min_u32_e32 v1, v1, v48
	v_max_u32_e32 v48, v49, v54
	v_min_u32_e32 v49, v49, v54
	v_max_u32_e32 v54, v57, v51
	v_min_u32_e32 v51, v57, v51
	v_max_u32_e32 v57, v58, v55
	v_min_u32_e32 v55, v58, v55
	v_max_u32_e32 v58, v46, v52
	v_min_u32_e32 v46, v46, v52
	v_max_u32_e32 v52, v3, v50
	v_min_u32_e32 v3, v3, v50
	v_max_u32_e32 v50, v56, v53
	v_min_u32_e32 v53, v56, v53
	v_max_u32_e32 v56, v47, v0
	v_min_u32_e32 v0, v47, v0
	v_max_u32_e32 v47, v2, v54
	v_min_u32_e32 v2, v2, v54
	v_max_u32_e32 v54, v48, v57
	v_min_u32_e32 v48, v48, v57
	v_max_u32_e32 v70, v1, v51
	v_min_u32_e32 v1, v1, v51
	v_max_u32_e32 v51, v49, v55
	v_min_u32_e32 v49, v49, v55
	v_max_u32_e32 v71, v58, v50
	v_min_u32_e32 v50, v58, v50
	v_max_u32_e32 v72, v52, v56
	v_min_u32_e32 v73, v52, v56
	v_max_u32_e32 v74, v46, v53
	v_min_u32_e32 v46, v46, v53
	v_max_u32_e32 v75, v3, v0
	v_min_u32_e32 v0, v3, v0
	v_max_u32_e32 v61, v47, v54
	v_min_u32_e32 v60, v47, v54
	v_max_u32_e32 v59, v2, v48
	v_min_u32_e32 v58, v2, v48
	v_max_u32_e32 v57, v70, v51
	v_min_u32_e32 v56, v70, v51
	v_max_u32_e32 v55, v1, v49
	v_min_u32_e32 v54, v1, v49
	v_max_u32_e32 v53, v71, v72
	v_min_u32_e32 v52, v71, v72
	v_max_u32_e32 v51, v50, v73
	v_min_u32_e32 v50, v50, v73
	v_max_u32_e32 v47, v46, v0
	v_min_u32_e32 v46, v46, v0
	global_load_dwordx4 v[0:3], v[4:5], off offset:560
	global_load_dwordx4 v[70:73], v[4:5], off offset:544
	v_max_u32_e32 v49, v74, v75
	v_min_u32_e32 v48, v74, v75
	s_waitcnt vmcnt(2)
; __device__ __forceinline__ unsigned f2key(float f) { const unsigned u = __float_as_uint(f); return (u & 0x80000000u) ? ~u : (u | 0x80000000u); }
; __device__ __forceinline__ void peer_tile(const Args& A, LAS unsigned char* lds, int tile) {
;     ...
;                 { const bf16_t* sp = QRY + m * 2048 + hp * 128 + 32 * g;
;                   const u32x4 s0 = *(const u32x4*)sp, s1 = *(const u32x4*)(sp + 8), s2 = *(const u32x4*)(sp + 16), s3 = *(const u32x4*)(sp + 24);
;                   const unsigned sw[16] = {s0.x, s0.y, s0.z, s0.w, s1.x, s1.y, s1.z, s1.w, s2.x, s2.y, s2.z, s2.w, s3.x, s3.y, s3.z, s3.w};
; #pragma unroll
;                   for (int i = 0; i < 16; ++i) {
;                       const float lo = (float)__builtin_bit_cast(_Float16, (unsigned short)(sw[i] & 0xffffu)), hi = (float)__builtin_bit_cast(_Float16, (unsigned short)(sw[i] >> 16));
;                       const unsigned klo = (f2key(lo) & ~127u) | (unsigned)(127 - (32 * g + 2 * i)), khi = (f2key(hi) & ~127u) | (unsigned)(127 - (32 * g + 2 * i + 1));
;                       if (i < 8) { k0[2 * i] = klo; k0[2 * i + 1] = khi; } else { k1[2 * (i - 8)] = klo; k1[2 * (i - 8) + 1] = khi; } } }
	v_cvt_f32_f16_sdwa v74, v66 dst_sel:DWORD dst_unused:UNUSED_PAD src0_sel:WORD_1
	v_cvt_f32_f16_e32 v66, v66
	v_not_b32_e32 v75, v74
	v_or_b32_e32 v76, 0x80000000, v74
	v_cmp_gt_i32_e32 vcc, 0, v74
	s_nop 1
	v_cndmask_b32_e32 v74, v76, v75, vcc
	v_not_b32_e32 v75, v66
	v_or_b32_e32 v76, 0x80000000, v66
	v_cmp_gt_i32_e32 vcc, 0, v66
	v_and_b32_e32 v74, 0xffffff80, v74
	v_sub_u32_e32 v74, v74, v15
	v_cndmask_b32_e32 v66, v76, v75, vcc
	v_cvt_f32_f16_sdwa v75, v67 dst_sel:DWORD dst_unused:UNUSED_PAD src0_sel:WORD_1
	v_cvt_f32_f16_e32 v67, v67
	v_and_b32_e32 v66, 0xffffff80, v66
	v_sub_u32_e32 v66, v66, v15
	v_not_b32_e32 v76, v75
	v_or_b32_e32 v77, 0x80000000, v75
	v_cmp_gt_i32_e32 vcc, 0, v75
	v_add_u32_e32 v74, 0x7e, v74
	v_add_u32_e32 v66, 0x7f, v66
	v_cndmask_b32_e32 v75, v77, v76, vcc
	v_not_b32_e32 v76, v67
	v_or_b32_e32 v77, 0x80000000, v67
	v_cmp_gt_i32_e32 vcc, 0, v67
	v_and_b32_e32 v75, 0xffffff80, v75
	v_sub_u32_e32 v75, v75, v14
	v_cndmask_b32_e32 v67, v77, v76, vcc
	v_cvt_f32_f16_sdwa v76, v68 dst_sel:DWORD dst_unused:UNUSED_PAD src0_sel:WORD_1
	v_cvt_f32_f16_e32 v68, v68
	v_and_b32_e32 v67, 0xffffff80, v67
	v_sub_u32_e32 v67, v67, v14
	v_not_b32_e32 v77, v76
	v_or_b32_e32 v78, 0x80000000, v76
	v_cmp_gt_i32_e32 vcc, 0, v76
	v_add_u32_e32 v75, 0x7e, v75
	v_add_u32_e32 v67, 0x7f, v67
	v_cndmask_b32_e32 v76, v78, v77, vcc
	v_not_b32_e32 v77, v68
	v_or_b32_e32 v78, 0x80000000, v68
	v_cmp_gt_i32_e32 vcc, 0, v68
	v_and_b32_e32 v76, 0xffffff80, v76
	v_sub_u32_e32 v76, v76, v12
	v_cndmask_b32_e32 v68, v78, v77, vcc
	v_cvt_f32_f16_sdwa v77, v69 dst_sel:DWORD dst_unused:UNUSED_PAD src0_sel:WORD_1
	v_cvt_f32_f16_e32 v69, v69
	v_and_b32_e32 v68, 0xffffff80, v68
	v_sub_u32_e32 v68, v68, v12
	v_not_b32_e32 v78, v77
	v_or_b32_e32 v79, 0x80000000, v77
	v_cmp_gt_i32_e32 vcc, 0, v77
	v_add_u32_e32 v76, 0x7e, v76
	v_add_u32_e32 v68, 0x7f, v68
	v_cndmask_b32_e32 v77, v79, v78, vcc
	v_not_b32_e32 v78, v69
	v_or_b32_e32 v79, 0x80000000, v69
	v_cmp_gt_i32_e32 vcc, 0, v69
	v_and_b32_e32 v77, 0xffffff80, v77
	v_sub_u32_e32 v77, v77, v10
	v_cndmask_b32_e32 v69, v79, v78, vcc
	v_cvt_f32_f16_sdwa v78, v62 dst_sel:DWORD dst_unused:UNUSED_PAD src0_sel:WORD_1
	v_cvt_f32_f16_e32 v62, v62
	v_and_b32_e32 v69, 0xffffff80, v69
	v_sub_u32_e32 v69, v69, v10
	v_not_b32_e32 v79, v78
	v_or_b32_e32 v80, 0x80000000, v78
	v_cmp_gt_i32_e32 vcc, 0, v78
	v_add_u32_e32 v77, 0x7e, v77
	v_add_u32_e32 v69, 0x7f, v69
	v_cndmask_b32_e32 v78, v80, v79, vcc
	v_not_b32_e32 v79, v62
	v_or_b32_e32 v80, 0x80000000, v62
	v_cmp_gt_i32_e32 vcc, 0, v62
	v_and_b32_e32 v78, 0xffffff80, v78
	v_sub_u32_e32 v78, v78, v8
	v_cndmask_b32_e32 v62, v80, v79, vcc
	v_cvt_f32_f16_sdwa v79, v63 dst_sel:DWORD dst_unused:UNUSED_PAD src0_sel:WORD_1
	v_cvt_f32_f16_e32 v63, v63
	v_and_b32_e32 v62, 0xffffff80, v62
	v_sub_u32_e32 v62, v62, v8
	v_not_b32_e32 v80, v79
	v_or_b32_e32 v81, 0x80000000, v79
	v_cmp_gt_i32_e32 vcc, 0, v79
	v_add_u32_e32 v78, 0x7e, v78
	v_add_u32_e32 v62, 0x7f, v62
	v_cndmask_b32_e32 v79, v81, v80, vcc
	v_not_b32_e32 v80, v63
	v_or_b32_e32 v81, 0x80000000, v63
	v_cmp_gt_i32_e32 vcc, 0, v63
	v_and_b32_e32 v79, 0xffffff80, v79
	v_sub_u32_e32 v79, v79, v16
	v_cndmask_b32_e32 v63, v81, v80, vcc
	v_cvt_f32_f16_sdwa v80, v64 dst_sel:DWORD dst_unused:UNUSED_PAD src0_sel:WORD_1
	v_cvt_f32_f16_e32 v64, v64
	v_and_b32_e32 v63, 0xffffff80, v63
	v_sub_u32_e32 v63, v63, v16
	v_not_b32_e32 v81, v80
	v_or_b32_e32 v82, 0x80000000, v80
	v_cmp_gt_i32_e32 vcc, 0, v80
	v_add_u32_e32 v79, 0x7e, v79
	v_add_u32_e32 v63, 0x7f, v63
	v_cndmask_b32_e32 v80, v82, v81, vcc
	v_not_b32_e32 v81, v64
	v_or_b32_e32 v82, 0x80000000, v64
	v_cmp_gt_i32_e32 vcc, 0, v64
	v_and_b32_e32 v80, 0xffffff80, v80
	v_sub_u32_e32 v80, v80, v17
	v_cndmask_b32_e32 v64, v82, v81, vcc
	v_cvt_f32_f16_sdwa v81, v65 dst_sel:DWORD dst_unused:UNUSED_PAD src0_sel:WORD_1
	v_cvt_f32_f16_e32 v65, v65
	v_and_b32_e32 v64, 0xffffff80, v64
	v_sub_u32_e32 v64, v64, v17
	v_not_b32_e32 v82, v81
	v_or_b32_e32 v83, 0x80000000, v81
	v_cmp_gt_i32_e32 vcc, 0, v81
	v_add_u32_e32 v80, 0x7e, v80
	v_add_u32_e32 v64, 0x7f, v64
	v_cndmask_b32_e32 v81, v83, v82, vcc
	v_not_b32_e32 v82, v65
	v_or_b32_e32 v83, 0x80000000, v65
	v_cmp_gt_i32_e32 vcc, 0, v65
	v_and_b32_e32 v81, 0xffffff80, v81
	v_sub_u32_e32 v81, v81, v18
	v_cndmask_b32_e32 v65, v83, v82, vcc
	s_waitcnt vmcnt(0)
; __device__ __forceinline__ unsigned f2key(float f) { const unsigned u = __float_as_uint(f); return (u & 0x80000000u) ? ~u : (u | 0x80000000u); }
; #define CE_DESC(a, b) do { const unsigned _mx = (a) > (b) ? (a) : (b), _mn = (a) > (b) ? (b) : (a); (a) = _mx; (b) = _mn; } while (0)
; __device__ __forceinline__ void sort16_desc(unsigned (&k)[16]) {
; #pragma unroll
;     for (int size = 2; size <= 16; size <<= 1)
; #pragma unroll
;         for (int stride = size >> 1; stride > 0; stride >>= 1)
; #pragma unroll
;             for (int i = 0; i < 16; ++i) { const int j = i ^ stride;
;                 if (j > i) { if ((i & size) == 0) CE_DESC(k[i], k[j]); else CE_DESC(k[j], k[i]); } }
; }
; __device__ __forceinline__ void peer_tile(const Args& A, LAS unsigned char* lds, int tile) {
;     ...
;                 { const bf16_t* sp = QRY + m * 2048 + hp * 128 + 32 * g;
;                   const u32x4 s0 = *(const u32x4*)sp, s1 = *(const u32x4*)(sp + 8), s2 = *(const u32x4*)(sp + 16), s3 = *(const u32x4*)(sp + 24);
;                   const unsigned sw[16] = {s0.x, s0.y, s0.z, s0.w, s1.x, s1.y, s1.z, s1.w, s2.x, s2.y, s2.z, s2.w, s3.x, s3.y, s3.z, s3.w};
; #pragma unroll
;                   for (int i = 0; i < 16; ++i) {
;                       const float lo = (float)__builtin_bit_cast(_Float16, (unsigned short)(sw[i] & 0xffffu)), hi = (float)__builtin_bit_cast(_Float16, (unsigned short)(sw[i] >> 16));
;                       const unsigned klo = (f2key(lo) & ~127u) | (unsigned)(127 - (32 * g + 2 * i)), khi = (f2key(hi) & ~127u) | (unsigned)(127 - (32 * g + 2 * i + 1));
;                       if (i < 8) { k0[2 * i] = klo; k0[2 * i + 1] = khi; } else { k1[2 * (i - 8)] = klo; k1[2 * (i - 8) + 1] = khi; } } }
	v_cvt_f32_f16_sdwa v82, v70 dst_sel:DWORD dst_unused:UNUSED_PAD src0_sel:WORD_1
	v_cvt_f32_f16_e32 v70, v70
	v_and_b32_e32 v65, 0xffffff80, v65
	v_sub_u32_e32 v65, v65, v18
	v_not_b32_e32 v83, v82
	v_or_b32_e32 v84, 0x80000000, v82
	v_cmp_gt_i32_e32 vcc, 0, v82
	v_add_u32_e32 v81, 0x7e, v81
	v_add_u32_e32 v65, 0x7f, v65
	v_cndmask_b32_e32 v82, v84, v83, vcc
	v_not_b32_e32 v83, v70
	v_or_b32_e32 v84, 0x80000000, v70
	v_cmp_gt_i32_e32 vcc, 0, v70
	v_and_b32_e32 v82, 0xffffff80, v82
	v_sub_u32_e32 v82, v82, v20
	v_cndmask_b32_e32 v70, v84, v83, vcc
	v_cvt_f32_f16_sdwa v83, v71 dst_sel:DWORD dst_unused:UNUSED_PAD src0_sel:WORD_1
	v_cvt_f32_f16_e32 v71, v71
	v_and_b32_e32 v70, 0xffffff80, v70
	v_sub_u32_e32 v70, v70, v20
	v_not_b32_e32 v84, v83
	v_or_b32_e32 v85, 0x80000000, v83
	v_cmp_gt_i32_e32 vcc, 0, v83
	v_add_u32_e32 v82, 0x7e, v82
	v_add_u32_e32 v70, 0x7f, v70
	v_cndmask_b32_e32 v83, v85, v84, vcc
	v_not_b32_e32 v84, v71
	v_or_b32_e32 v85, 0x80000000, v71
	v_cmp_gt_i32_e32 vcc, 0, v71
	v_and_b32_e32 v83, 0xffffff80, v83
	v_sub_u32_e32 v83, v83, v21
	v_cndmask_b32_e32 v71, v85, v84, vcc
	v_cvt_f32_f16_sdwa v84, v72 dst_sel:DWORD dst_unused:UNUSED_PAD src0_sel:WORD_1
	v_cvt_f32_f16_e32 v72, v72
	v_and_b32_e32 v71, 0xffffff80, v71
	v_sub_u32_e32 v71, v71, v21
	v_not_b32_e32 v85, v84
	v_or_b32_e32 v86, 0x80000000, v84
	v_cmp_gt_i32_e32 vcc, 0, v84
	v_add_u32_e32 v83, 0x7e, v83
	v_add_u32_e32 v71, 0x7f, v71
	v_cndmask_b32_e32 v84, v86, v85, vcc
	v_not_b32_e32 v85, v72
	v_or_b32_e32 v86, 0x80000000, v72
	v_cmp_gt_i32_e32 vcc, 0, v72
	v_and_b32_e32 v84, 0xffffff80, v84
	v_sub_u32_e32 v84, v84, v22
	v_cndmask_b32_e32 v72, v86, v85, vcc
	v_cvt_f32_f16_sdwa v85, v73 dst_sel:DWORD dst_unused:UNUSED_PAD src0_sel:WORD_1
	v_cvt_f32_f16_e32 v73, v73
	v_and_b32_e32 v72, 0xffffff80, v72
	v_sub_u32_e32 v72, v72, v22
	v_not_b32_e32 v86, v85
	v_or_b32_e32 v87, 0x80000000, v85
	v_cmp_gt_i32_e32 vcc, 0, v85
	v_add_u32_e32 v84, 0x7e, v84
	v_add_u32_e32 v72, 0x7f, v72
	v_cndmask_b32_e32 v85, v87, v86, vcc
	v_not_b32_e32 v86, v73
	v_or_b32_e32 v87, 0x80000000, v73
	v_cmp_gt_i32_e32 vcc, 0, v73
	v_and_b32_e32 v85, 0xffffff80, v85
	v_sub_u32_e32 v85, v85, v23
	v_cndmask_b32_e32 v73, v87, v86, vcc
	v_cvt_f32_f16_sdwa v86, v0 dst_sel:DWORD dst_unused:UNUSED_PAD src0_sel:WORD_1
	v_cvt_f32_f16_e32 v0, v0
	v_and_b32_e32 v73, 0xffffff80, v73
	v_sub_u32_e32 v73, v73, v23
	v_not_b32_e32 v87, v86
	v_or_b32_e32 v88, 0x80000000, v86
	v_cmp_gt_i32_e32 vcc, 0, v86
	v_add_u32_e32 v85, 0x7e, v85
	v_add_u32_e32 v73, 0x7f, v73
	v_cndmask_b32_e32 v86, v88, v87, vcc
	v_not_b32_e32 v87, v0
	v_or_b32_e32 v88, 0x80000000, v0
	v_cmp_gt_i32_e32 vcc, 0, v0
	v_and_b32_e32 v86, 0xffffff80, v86
	v_sub_u32_e32 v86, v86, v24
	v_cndmask_b32_e32 v0, v88, v87, vcc
	v_cvt_f32_f16_sdwa v87, v1 dst_sel:DWORD dst_unused:UNUSED_PAD src0_sel:WORD_1
	v_cvt_f32_f16_e32 v1, v1
	v_and_b32_e32 v0, 0xffffff80, v0
	v_sub_u32_e32 v0, v0, v24
	v_not_b32_e32 v88, v87
	v_or_b32_e32 v89, 0x80000000, v87
	v_cmp_gt_i32_e32 vcc, 0, v87
	v_add_u32_e32 v86, 0x7e, v86
	v_add_u32_e32 v0, 0x7f, v0
	v_cndmask_b32_e32 v87, v89, v88, vcc
	v_not_b32_e32 v88, v1
	v_or_b32_e32 v89, 0x80000000, v1
	v_cmp_gt_i32_e32 vcc, 0, v1
	v_and_b32_e32 v87, 0xffffff80, v87
	v_sub_u32_e32 v87, v87, v25
	v_cndmask_b32_e32 v1, v89, v88, vcc
	v_cvt_f32_f16_sdwa v88, v2 dst_sel:DWORD dst_unused:UNUSED_PAD src0_sel:WORD_1
	v_cvt_f32_f16_e32 v2, v2
	v_and_b32_e32 v1, 0xffffff80, v1
	v_sub_u32_e32 v1, v1, v25
	v_not_b32_e32 v89, v88
	v_or_b32_e32 v90, 0x80000000, v88
	v_cmp_gt_i32_e32 vcc, 0, v88
	v_add_u32_e32 v87, 0x7e, v87
	v_add_u32_e32 v1, 0x7f, v1
	v_cndmask_b32_e32 v88, v90, v89, vcc
	v_not_b32_e32 v89, v2
	v_or_b32_e32 v90, 0x80000000, v2
	v_cmp_gt_i32_e32 vcc, 0, v2
	v_and_b32_e32 v88, 0xffffff80, v88
	v_sub_u32_e32 v88, v88, v26
	v_cndmask_b32_e32 v2, v90, v89, vcc
	v_cvt_f32_f16_sdwa v89, v3 dst_sel:DWORD dst_unused:UNUSED_PAD src0_sel:WORD_1
	v_cvt_f32_f16_e32 v3, v3
	v_and_b32_e32 v2, 0xffffff80, v2
	v_sub_u32_e32 v2, v2, v26
	v_not_b32_e32 v90, v89
	v_or_b32_e32 v91, 0x80000000, v89
	v_cmp_gt_i32_e32 vcc, 0, v89
	v_add_u32_e32 v88, 0x7e, v88
	v_add_u32_e32 v2, 0x7f, v2
	v_cndmask_b32_e32 v89, v91, v90, vcc
	v_not_b32_e32 v90, v3
	v_or_b32_e32 v91, 0x80000000, v3
	v_cmp_gt_i32_e32 vcc, 0, v3
	v_and_b32_e32 v89, 0xffffff80, v89
	v_sub_u32_e32 v89, v89, v28
	v_cndmask_b32_e32 v3, v91, v90, vcc
	v_and_b32_e32 v3, 0xffffff80, v3
	v_sub_u32_e32 v3, v3, v28
	v_add_u32_e32 v89, 0x7e, v89
	v_add_u32_e32 v3, 0x7f, v3
	v_max_u32_e32 v90, v66, v74
	v_min_u32_e32 v66, v66, v74
	v_max_u32_e32 v74, v75, v67
	v_min_u32_e32 v67, v75, v67
	v_max_u32_e32 v75, v68, v76
	v_min_u32_e32 v68, v68, v76
	v_max_u32_e32 v76, v77, v69
	v_min_u32_e32 v69, v77, v69
	v_max_u32_e32 v77, v62, v78
	v_min_u32_e32 v62, v62, v78
	v_max_u32_e32 v78, v79, v63
	v_min_u32_e32 v63, v79, v63
	v_max_u32_e32 v79, v64, v80
	v_min_u32_e32 v64, v64, v80
	v_max_u32_e32 v80, v81, v65
	v_min_u32_e32 v65, v81, v65
	v_max_u32_e32 v98, v70, v82
	v_min_u32_e32 v70, v70, v82
	v_max_u32_e32 v82, v83, v71
	v_min_u32_e32 v71, v83, v71
	v_max_u32_e32 v83, v72, v84
	v_min_u32_e32 v72, v72, v84
	v_max_u32_e32 v84, v85, v73
	v_min_u32_e32 v73, v85, v73
	v_max_u32_e32 v85, v0, v86
	v_min_u32_e32 v0, v0, v86
	v_max_u32_e32 v86, v87, v1
	v_min_u32_e32 v1, v87, v1
	v_max_u32_e32 v87, v2, v88
	v_min_u32_e32 v2, v2, v88
	v_max_u32_e32 v88, v89, v3
	v_min_u32_e32 v3, v89, v3
	v_max_u32_e32 v81, v90, v67
	v_min_u32_e32 v67, v90, v67
	v_max_u32_e32 v90, v66, v74
	v_min_u32_e32 v66, v66, v74
	v_max_u32_e32 v74, v69, v75
	v_min_u32_e32 v69, v69, v75
	v_max_u32_e32 v75, v76, v68
	v_min_u32_e32 v68, v76, v68
; #define CE_DESC(a, b) do { const unsigned _mx = (a) > (b) ? (a) : (b), _mn = (a) > (b) ? (b) : (a); (a) = _mx; (b) = _mn; } while (0)
; __device__ __forceinline__ void sort16_desc(unsigned (&k)[16]) {
; #pragma unroll
;     for (int size = 2; size <= 16; size <<= 1)
; #pragma unroll
;         for (int stride = size >> 1; stride > 0; stride >>= 1)
; #pragma unroll
;             for (int i = 0; i < 16; ++i) { const int j = i ^ stride;
;                 if (j > i) { if ((i & size) == 0) CE_DESC(k[i], k[j]); else CE_DESC(k[j], k[i]); } }
; }
	v_max_u32_e32 v76, v77, v63
	v_min_u32_e32 v63, v77, v63
	v_max_u32_e32 v77, v62, v78
	v_min_u32_e32 v62, v62, v78
	v_max_u32_e32 v78, v65, v79
	v_min_u32_e32 v65, v65, v79
	v_max_u32_e32 v79, v80, v64
	v_min_u32_e32 v64, v80, v64
	v_max_u32_e32 v89, v98, v71
	v_min_u32_e32 v71, v98, v71
	v_max_u32_e32 v98, v70, v82
	v_min_u32_e32 v70, v70, v82
	v_max_u32_e32 v82, v73, v83
	v_min_u32_e32 v73, v73, v83
	v_max_u32_e32 v83, v84, v72
	v_min_u32_e32 v72, v84, v72
	v_max_u32_e32 v84, v85, v1
	v_min_u32_e32 v1, v85, v1
	v_max_u32_e32 v85, v0, v86
	v_min_u32_e32 v0, v0, v86
	v_max_u32_e32 v86, v3, v87
	v_min_u32_e32 v3, v3, v87
	v_max_u32_e32 v87, v88, v2
	v_min_u32_e32 v2, v88, v2
	v_max_u32_e32 v80, v81, v90
	v_min_u32_e32 v81, v81, v90
	v_max_u32_e32 v90, v67, v66
	v_min_u32_e32 v66, v67, v66
	v_max_u32_e32 v67, v68, v69
	v_min_u32_e32 v68, v68, v69
	v_max_u32_e32 v69, v75, v74
	v_min_u32_e32 v74, v75, v74
	v_max_u32_e32 v75, v76, v77
	v_min_u32_e32 v76, v76, v77
	v_max_u32_e32 v77, v63, v62
	v_min_u32_e32 v62, v63, v62
	v_max_u32_e32 v63, v64, v65
	v_min_u32_e32 v64, v64, v65
	v_max_u32_e32 v65, v79, v78
	v_min_u32_e32 v78, v79, v78
	v_max_u32_e32 v88, v89, v98
	v_min_u32_e32 v89, v89, v98
	v_max_u32_e32 v98, v71, v70
	v_min_u32_e32 v70, v71, v70
	v_max_u32_e32 v71, v72, v73
	v_min_u32_e32 v72, v72, v73
	v_max_u32_e32 v73, v83, v82
	v_min_u32_e32 v82, v83, v82
	v_max_u32_e32 v83, v84, v85
	v_min_u32_e32 v84, v84, v85
	v_max_u32_e32 v85, v1, v0
	v_min_u32_e32 v0, v1, v0
	v_max_u32_e32 v1, v2, v3
	v_min_u32_e32 v2, v2, v3
	v_max_u32_e32 v3, v87, v86
	v_min_u32_e32 v86, v87, v86
	v_max_u32_e32 v79, v80, v68
	v_min_u32_e32 v68, v80, v68
	v_max_u32_e32 v80, v81, v67
	v_min_u32_e32 v67, v81, v67
	v_max_u32_e32 v81, v90, v74
	v_min_u32_e32 v74, v90, v74
	v_max_u32_e32 v90, v66, v69
	v_min_u32_e32 v66, v66, v69
	v_max_u32_e32 v69, v64, v75
	v_min_u32_e32 v64, v64, v75
	v_max_u32_e32 v75, v63, v76
	v_min_u32_e32 v63, v63, v76
	v_max_u32_e32 v76, v78, v77
	v_min_u32_e32 v77, v78, v77
	v_max_u32_e32 v78, v65, v62
	v_min_u32_e32 v62, v65, v62
	v_max_u32_e32 v87, v88, v72
	v_min_u32_e32 v72, v88, v72
	v_max_u32_e32 v88, v89, v71
	v_min_u32_e32 v71, v89, v71
	v_max_u32_e32 v89, v98, v82
	v_min_u32_e32 v82, v98, v82
	v_max_u32_e32 v98, v70, v73
	v_min_u32_e32 v70, v70, v73
	v_max_u32_e32 v73, v2, v83
	v_min_u32_e32 v2, v2, v83
	v_max_u32_e32 v83, v1, v84
	v_min_u32_e32 v1, v1, v84
	v_max_u32_e32 v84, v86, v85
	v_min_u32_e32 v85, v86, v85
	v_max_u32_e32 v86, v3, v0
	v_min_u32_e32 v0, v3, v0
	v_max_u32_e32 v65, v79, v81
	v_min_u32_e32 v79, v79, v81
	v_max_u32_e32 v81, v80, v90
	v_min_u32_e32 v80, v80, v90
	v_max_u32_e32 v90, v68, v74
	v_min_u32_e32 v68, v68, v74
	v_max_u32_e32 v74, v67, v66
	v_min_u32_e32 v66, v67, v66
	v_max_u32_e32 v67, v77, v64
	v_min_u32_e32 v64, v77, v64
	v_max_u32_e32 v77, v62, v63
	v_min_u32_e32 v62, v62, v63
	v_max_u32_e32 v63, v76, v69
	v_min_u32_e32 v69, v76, v69
	v_max_u32_e32 v76, v78, v75
	v_min_u32_e32 v75, v78, v75
	v_max_u32_e32 v3, v87, v89
	v_min_u32_e32 v87, v87, v89
	v_max_u32_e32 v89, v88, v98
	v_min_u32_e32 v88, v88, v98
	v_max_u32_e32 v98, v72, v82
	v_min_u32_e32 v72, v72, v82
	v_max_u32_e32 v82, v71, v70
	v_min_u32_e32 v70, v71, v70
	v_max_u32_e32 v71, v85, v2
	v_min_u32_e32 v2, v85, v2
	v_max_u32_e32 v85, v0, v1
	v_min_u32_e32 v0, v0, v1
	v_max_u32_e32 v1, v84, v73
	v_min_u32_e32 v73, v84, v73
	v_max_u32_e32 v84, v86, v83
	v_min_u32_e32 v83, v86, v83
	v_max_u32_e32 v78, v65, v81
	v_min_u32_e32 v65, v65, v81
	v_max_u32_e32 v81, v79, v80
	v_min_u32_e32 v79, v79, v80
	v_max_u32_e32 v80, v90, v74
	v_min_u32_e32 v74, v90, v74
	v_max_u32_e32 v90, v68, v66
	v_min_u32_e32 v66, v68, v66
	v_max_u32_e32 v68, v62, v64
	v_min_u32_e32 v62, v62, v64
	v_max_u32_e32 v64, v77, v67
	v_min_u32_e32 v67, v77, v67
	v_max_u32_e32 v77, v75, v69
	v_min_u32_e32 v69, v75, v69
	v_max_u32_e32 v75, v76, v63
	v_min_u32_e32 v63, v76, v63
	v_max_u32_e32 v86, v3, v89
	v_min_u32_e32 v3, v3, v89
	v_max_u32_e32 v89, v87, v88
	v_min_u32_e32 v87, v87, v88
	v_max_u32_e32 v88, v98, v82
	v_min_u32_e32 v82, v98, v82
	v_max_u32_e32 v98, v72, v70
	v_min_u32_e32 v70, v72, v70
	v_max_u32_e32 v72, v0, v2
	v_min_u32_e32 v0, v0, v2
	v_max_u32_e32 v2, v85, v71
	v_min_u32_e32 v71, v85, v71
	v_max_u32_e32 v85, v83, v73
	v_min_u32_e32 v73, v83, v73
	v_max_u32_e32 v83, v84, v1
	v_min_u32_e32 v1, v84, v1
	v_max_u32_e32 v76, v78, v62
	v_min_u32_e32 v62, v78, v62
	v_max_u32_e32 v78, v65, v68
	v_min_u32_e32 v65, v65, v68
	v_max_u32_e32 v68, v81, v67
	v_min_u32_e32 v67, v81, v67
	v_max_u32_e32 v81, v79, v64
	v_min_u32_e32 v64, v79, v64
	v_max_u32_e32 v79, v80, v69
	v_min_u32_e32 v69, v80, v69
	v_max_u32_e32 v80, v74, v77
	v_min_u32_e32 v74, v74, v77
	v_max_u32_e32 v77, v90, v63
	v_min_u32_e32 v63, v90, v63
	v_max_u32_e32 v90, v66, v75
	v_min_u32_e32 v66, v66, v75
	v_max_u32_e32 v84, v86, v0
	v_min_u32_e32 v0, v86, v0
	v_max_u32_e32 v86, v3, v72
	v_min_u32_e32 v3, v3, v72
	v_max_u32_e32 v72, v89, v71
	v_min_u32_e32 v71, v89, v71
	v_max_u32_e32 v89, v87, v2
	v_min_u32_e32 v2, v87, v2
	v_max_u32_e32 v87, v88, v73
	v_min_u32_e32 v73, v88, v73
	v_max_u32_e32 v88, v82, v85
	v_min_u32_e32 v82, v82, v85
	v_max_u32_e32 v85, v98, v1
	v_min_u32_e32 v1, v98, v1
	v_max_u32_e32 v98, v70, v83
	v_min_u32_e32 v70, v70, v83
	v_max_u32_e32 v75, v76, v79
	v_min_u32_e32 v76, v76, v79
	v_max_u32_e32 v79, v78, v80
	v_min_u32_e32 v78, v78, v80
	v_max_u32_e32 v80, v68, v77
	v_min_u32_e32 v68, v68, v77
	v_max_u32_e32 v77, v81, v90
	v_min_u32_e32 v81, v81, v90
	v_max_u32_e32 v90, v62, v69
	v_min_u32_e32 v62, v62, v69
	v_max_u32_e32 v69, v65, v74
	v_min_u32_e32 v65, v65, v74
	v_max_u32_e32 v74, v67, v63
; #define CE_DESC(a, b) do { const unsigned _mx = (a) > (b) ? (a) : (b), _mn = (a) > (b) ? (b) : (a); (a) = _mx; (b) = _mn; } while (0)
; __device__ __forceinline__ void sort16_desc(unsigned (&k)[16]) {
; #pragma unroll
;     for (int size = 2; size <= 16; size <<= 1)
; #pragma unroll
;         for (int stride = size >> 1; stride > 0; stride >>= 1)
; #pragma unroll
;             for (int i = 0; i < 16; ++i) { const int j = i ^ stride;
;                 if (j > i) { if ((i & size) == 0) CE_DESC(k[i], k[j]); else CE_DESC(k[j], k[i]); } }
; }
; __device__ __forceinline__ void merge16(unsigned (&a)[16], const unsigned (&b)[16]) {
; #pragma unroll
;     for (int i = 0; i < 16; ++i) a[i] = a[i] > b[15 - i] ? a[i] : b[15 - i];
; #pragma unroll
;     for (int stride = 8; stride > 0; stride >>= 1)
; #pragma unroll
;         for (int i = 0; i < 16; ++i) { const int j = i ^ stride; if (j > i) CE_DESC(a[i], a[j]); }
; }
; __device__ __forceinline__ void peer_tile(const Args& A, LAS unsigned char* lds, int tile) {
;     ...
;                 sort16_desc(k0); sort16_desc(k1); merge16(k0, k1);
; #pragma unroll
;                 for (int msk = 16; msk <= 32; msk <<= 1) {
; #pragma unroll
;                     for (int i = 0; i < 16; ++i) k1[i] = (unsigned)__shfl_xor((int)k0[i], msk);
;                     merge16(k0, k1); }
	v_min_u32_e32 v63, v67, v63
	v_max_u32_e32 v67, v64, v66
	v_min_u32_e32 v64, v64, v66
	v_max_u32_e32 v83, v84, v87
	v_min_u32_e32 v84, v84, v87
	v_max_u32_e32 v87, v86, v88
	v_min_u32_e32 v86, v86, v88
	v_max_u32_e32 v88, v72, v85
	v_min_u32_e32 v72, v72, v85
	v_max_u32_e32 v85, v89, v98
	v_min_u32_e32 v89, v89, v98
	v_max_u32_e32 v98, v0, v73
	v_min_u32_e32 v0, v0, v73
	v_max_u32_e32 v73, v3, v82
	v_min_u32_e32 v3, v3, v82
	v_max_u32_e32 v82, v71, v1
	v_min_u32_e32 v1, v71, v1
	v_max_u32_e32 v71, v2, v70
	v_min_u32_e32 v2, v2, v70
	v_max_u32_e32 v66, v75, v80
	v_min_u32_e32 v75, v75, v80
	v_max_u32_e32 v80, v79, v77
	v_min_u32_e32 v77, v79, v77
	v_max_u32_e32 v79, v76, v68
	v_min_u32_e32 v68, v76, v68
	v_max_u32_e32 v76, v78, v81
	v_min_u32_e32 v78, v78, v81
	v_max_u32_e32 v81, v90, v74
	v_min_u32_e32 v74, v90, v74
	v_max_u32_e32 v90, v69, v67
	v_min_u32_e32 v67, v69, v67
	v_max_u32_e32 v69, v62, v63
	v_min_u32_e32 v62, v62, v63
	v_max_u32_e32 v63, v65, v64
	v_min_u32_e32 v64, v65, v64
	v_max_u32_e32 v70, v83, v88
	v_min_u32_e32 v83, v83, v88
	v_max_u32_e32 v88, v87, v85
	v_min_u32_e32 v85, v87, v85
	v_max_u32_e32 v87, v84, v72
	v_min_u32_e32 v72, v84, v72
	v_max_u32_e32 v84, v86, v89
	v_min_u32_e32 v86, v86, v89
	v_max_u32_e32 v89, v98, v82
	v_min_u32_e32 v82, v98, v82
	v_max_u32_e32 v98, v73, v71
	v_min_u32_e32 v71, v73, v71
	v_max_u32_e32 v73, v0, v1
	v_min_u32_e32 v0, v0, v1
	v_max_u32_e32 v1, v3, v2
	v_min_u32_e32 v2, v3, v2
	v_min_u32_e32 v65, v66, v80
	v_min_u32_e32 v91, v75, v77
	v_min_u32_e32 v92, v79, v76
	v_min_u32_e32 v93, v68, v78
	v_min_u32_e32 v94, v81, v90
	v_min_u32_e32 v95, v74, v67
	v_min_u32_e32 v96, v69, v63
	v_min_u32_e32 v97, v62, v64
	v_min_u32_e32 v3, v70, v88
	v_min_u32_e32 v99, v83, v85
	v_min_u32_e32 v100, v87, v84
	v_min_u32_e32 v101, v72, v86
	v_min_u32_e32 v102, v89, v98
	v_min_u32_e32 v103, v82, v71
	v_min_u32_e32 v104, v73, v1
	v_min_u32_e32 v105, v0, v2
	v_max3_u32 v66, v66, v80, v105
	v_max3_u32 v0, v65, v0, v2
	v_max3_u32 v2, v75, v77, v104
	v_max3_u32 v1, v91, v73, v1
	v_max3_u32 v65, v79, v76, v103
	v_max3_u32 v71, v92, v82, v71
	v_max3_u32 v68, v68, v78, v102
	v_max3_u32 v73, v93, v89, v98
	v_max3_u32 v75, v81, v90, v101
	v_max3_u32 v72, v94, v72, v86
	v_max3_u32 v67, v74, v67, v100
	v_max3_u32 v74, v95, v87, v84
	v_max3_u32 v63, v69, v63, v99
	v_max3_u32 v69, v96, v83, v85
	v_max3_u32 v3, v62, v64, v3
	v_max3_u32 v62, v97, v70, v88
	v_max_u32_e32 v64, v66, v75
	v_min_u32_e32 v66, v66, v75
	v_max_u32_e32 v70, v0, v72
	v_min_u32_e32 v0, v0, v72
	v_max_u32_e32 v72, v2, v67
	v_min_u32_e32 v2, v2, v67
	v_max_u32_e32 v67, v1, v74
	v_min_u32_e32 v1, v1, v74
	v_max_u32_e32 v74, v65, v63
	v_min_u32_e32 v63, v65, v63
	v_max_u32_e32 v65, v71, v69
	v_min_u32_e32 v69, v71, v69
	v_max_u32_e32 v71, v68, v3
	v_min_u32_e32 v3, v68, v3
	v_max_u32_e32 v68, v73, v62
	v_min_u32_e32 v62, v73, v62
	v_max_u32_e32 v73, v64, v74
	v_min_u32_e32 v64, v64, v74
	v_max_u32_e32 v74, v70, v65
	v_min_u32_e32 v65, v70, v65
	v_max_u32_e32 v70, v72, v71
	v_min_u32_e32 v71, v72, v71
	v_max_u32_e32 v72, v67, v68
	v_min_u32_e32 v67, v67, v68
	v_max_u32_e32 v68, v66, v63
	v_min_u32_e32 v63, v66, v63
	v_max_u32_e32 v66, v0, v69
	v_min_u32_e32 v0, v0, v69
	v_max_u32_e32 v69, v2, v3
	v_min_u32_e32 v2, v2, v3
	v_max_u32_e32 v3, v1, v62
	v_min_u32_e32 v1, v1, v62
	v_max_u32_e32 v62, v73, v70
	v_min_u32_e32 v70, v73, v70
	v_max_u32_e32 v73, v74, v72
	v_min_u32_e32 v72, v74, v72
	v_max_u32_e32 v74, v64, v71
	v_min_u32_e32 v64, v64, v71
	v_max_u32_e32 v71, v65, v67
	v_min_u32_e32 v65, v65, v67
	v_max_u32_e32 v67, v68, v69
	v_min_u32_e32 v68, v68, v69
	v_max_u32_e32 v69, v66, v3
	v_min_u32_e32 v3, v66, v3
	v_max_u32_e32 v66, v63, v2
	v_min_u32_e32 v2, v63, v2
	v_max_u32_e32 v63, v0, v1
	v_min_u32_e32 v0, v0, v1
	v_max_u32_e32 v1, v62, v73
	v_min_u32_e32 v62, v62, v73
	v_max_u32_e32 v73, v70, v72
	v_min_u32_e32 v70, v70, v72
	v_max_u32_e32 v72, v74, v71
	v_min_u32_e32 v71, v74, v71
	v_max_u32_e32 v74, v64, v65
	v_min_u32_e32 v64, v64, v65
	v_max_u32_e32 v65, v67, v69
	v_min_u32_e32 v67, v67, v69
	v_max_u32_e32 v69, v68, v3
	v_min_u32_e32 v3, v68, v3
	v_max_u32_e32 v68, v66, v63
	v_min_u32_e32 v63, v66, v63
	v_max_u32_e32 v66, v2, v0
	v_min_u32_e32 v0, v2, v0
	ds_bpermute_b32 v2, v27, v1
	ds_bpermute_b32 v75, v27, v62
	ds_bpermute_b32 v76, v27, v73
	ds_bpermute_b32 v77, v27, v70
	ds_bpermute_b32 v78, v27, v72
	ds_bpermute_b32 v79, v27, v71
	ds_bpermute_b32 v80, v27, v74
	ds_bpermute_b32 v81, v27, v64
	ds_bpermute_b32 v82, v27, v65
	ds_bpermute_b32 v83, v27, v67
	ds_bpermute_b32 v84, v27, v69
	ds_bpermute_b32 v85, v27, v0
	ds_bpermute_b32 v86, v27, v66
	ds_bpermute_b32 v87, v27, v63
	ds_bpermute_b32 v88, v27, v68
	ds_bpermute_b32 v89, v27, v3
	s_waitcnt lgkmcnt(4)
	v_max_u32_e32 v1, v1, v85
	s_waitcnt lgkmcnt(3)
	v_max_u32_e32 v62, v62, v86
	s_waitcnt lgkmcnt(2)
	v_max_u32_e32 v73, v73, v87
	s_waitcnt lgkmcnt(1)
	v_max_u32_e32 v70, v70, v88
	s_waitcnt lgkmcnt(0)
; #define CE_DESC(a, b) do { const unsigned _mx = (a) > (b) ? (a) : (b), _mn = (a) > (b) ? (b) : (a); (a) = _mx; (b) = _mn; } while (0)
; __device__ __forceinline__ void sort16_desc(unsigned (&k)[16]) {
; #pragma unroll
;     for (int size = 2; size <= 16; size <<= 1)
; #pragma unroll
;         for (int stride = size >> 1; stride > 0; stride >>= 1)
; #pragma unroll
;             for (int i = 0; i < 16; ++i) { const int j = i ^ stride;
;                 if (j > i) { if ((i & size) == 0) CE_DESC(k[i], k[j]); else CE_DESC(k[j], k[i]); } }
; }
; __device__ __forceinline__ void merge16(unsigned (&a)[16], const unsigned (&b)[16]) {
; #pragma unroll
;     for (int i = 0; i < 16; ++i) a[i] = a[i] > b[15 - i] ? a[i] : b[15 - i];
; #pragma unroll
;     for (int stride = 8; stride > 0; stride >>= 1)
; #pragma unroll
;         for (int i = 0; i < 16; ++i) { const int j = i ^ stride; if (j > i) CE_DESC(a[i], a[j]); }
; }
; __device__ __forceinline__ void peer_tile(const Args& A, LAS unsigned char* lds, int tile) {
;     ...
;                 { const bf16_t* sp = QRY + m * 2048 + hp * 128 + 32 * g;
;                   const u32x4 s0 = *(const u32x4*)sp, s1 = *(const u32x4*)(sp + 8), s2 = *(const u32x4*)(sp + 16), s3 = *(const u32x4*)(sp + 24);
;     ...
;                 sort16_desc(k0); sort16_desc(k1); merge16(k0, k1);
; #pragma unroll
;                 for (int msk = 16; msk <= 32; msk <<= 1) {
; #pragma unroll
;                     for (int i = 0; i < 16; ++i) k1[i] = (unsigned)__shfl_xor((int)k0[i], msk);
;                     merge16(k0, k1); }
	v_max_u32_e32 v72, v72, v89
	v_max_u32_e32 v71, v71, v84
	v_max_u32_e32 v74, v74, v83
	v_max_u32_e32 v64, v64, v82
	v_max_u32_e32 v65, v65, v81
	v_max_u32_e32 v67, v67, v80
	v_max_u32_e32 v69, v69, v79
	v_max_u32_e32 v3, v3, v78
	v_max_u32_e32 v68, v68, v77
	v_max_u32_e32 v63, v63, v76
	v_max_u32_e32 v66, v66, v75
	v_max_u32_e32 v0, v0, v2
	v_max_u32_e32 v2, v1, v65
	v_min_u32_e32 v1, v1, v65
	v_max_u32_e32 v65, v62, v67
	v_min_u32_e32 v62, v62, v67
	v_max_u32_e32 v67, v73, v69
	v_min_u32_e32 v69, v73, v69
	v_max_u32_e32 v73, v70, v3
	v_min_u32_e32 v3, v70, v3
	v_max_u32_e32 v70, v72, v68
	v_min_u32_e32 v68, v72, v68
	v_max_u32_e32 v72, v71, v63
	v_min_u32_e32 v63, v71, v63
	v_max_u32_e32 v71, v74, v66
	v_min_u32_e32 v66, v74, v66
	v_max_u32_e32 v74, v64, v0
	v_min_u32_e32 v0, v64, v0
	v_max_u32_e32 v64, v2, v70
	v_min_u32_e32 v2, v2, v70
	v_max_u32_e32 v70, v65, v72
	v_min_u32_e32 v65, v65, v72
	v_max_u32_e32 v72, v67, v71
	v_min_u32_e32 v67, v67, v71
	v_max_u32_e32 v71, v73, v74
	v_min_u32_e32 v73, v73, v74
	v_max_u32_e32 v74, v1, v68
	v_min_u32_e32 v1, v1, v68
	v_max_u32_e32 v68, v62, v63
	v_min_u32_e32 v62, v62, v63
	v_max_u32_e32 v63, v69, v66
	v_min_u32_e32 v66, v69, v66
	v_max_u32_e32 v69, v3, v0
	v_min_u32_e32 v0, v3, v0
	v_max_u32_e32 v3, v64, v72
	v_min_u32_e32 v64, v64, v72
	v_max_u32_e32 v72, v70, v71
	v_min_u32_e32 v70, v70, v71
	v_max_u32_e32 v71, v2, v67
	v_min_u32_e32 v2, v2, v67
	v_max_u32_e32 v67, v65, v73
	v_min_u32_e32 v65, v65, v73
	v_max_u32_e32 v73, v74, v63
	v_min_u32_e32 v63, v74, v63
	v_max_u32_e32 v74, v68, v69
	v_min_u32_e32 v68, v68, v69
	v_max_u32_e32 v69, v1, v66
	v_min_u32_e32 v1, v1, v66
	v_max_u32_e32 v66, v62, v0
	v_min_u32_e32 v0, v62, v0
	v_max_u32_e32 v62, v3, v72
	v_min_u32_e32 v3, v3, v72
	v_max_u32_e32 v72, v64, v70
	v_min_u32_e32 v64, v64, v70
	v_max_u32_e32 v70, v71, v67
	v_min_u32_e32 v67, v71, v67
	v_max_u32_e32 v71, v2, v65
	v_min_u32_e32 v2, v2, v65
	v_max_u32_e32 v65, v73, v74
	v_min_u32_e32 v73, v73, v74
	v_max_u32_e32 v74, v63, v68
	v_min_u32_e32 v63, v63, v68
	v_max_u32_e32 v68, v69, v66
	v_min_u32_e32 v66, v69, v66
	v_max_u32_e32 v69, v1, v0
	v_min_u32_e32 v0, v1, v0
	ds_bpermute_b32 v78, v29, v0
	ds_bpermute_b32 v1, v29, v62
	ds_bpermute_b32 v75, v29, v3
	ds_bpermute_b32 v76, v29, v72
	ds_bpermute_b32 v77, v29, v64
	s_waitcnt lgkmcnt(4)
	v_max_u32_e32 v62, v62, v78
	global_load_dwordx4 v[78:81], v[4:5], off offset:784
	global_load_dwordx4 v[82:85], v[4:5], off offset:768
	ds_bpermute_b32 v86, v29, v70
	ds_bpermute_b32 v87, v29, v67
	ds_bpermute_b32 v88, v29, v71
	ds_bpermute_b32 v89, v29, v2
	ds_bpermute_b32 v90, v29, v65
	ds_bpermute_b32 v91, v29, v73
	ds_bpermute_b32 v92, v29, v74
	ds_bpermute_b32 v93, v29, v63
	ds_bpermute_b32 v94, v29, v68
	ds_bpermute_b32 v95, v29, v69
	ds_bpermute_b32 v96, v29, v66
	s_waitcnt lgkmcnt(4)
	v_max_u32_e32 v67, v67, v92
	s_waitcnt lgkmcnt(3)
	v_max_u32_e32 v70, v70, v93
	s_waitcnt lgkmcnt(2)
	v_max_u32_e32 v64, v64, v94
	s_waitcnt lgkmcnt(1)
	v_max_u32_e32 v3, v3, v95
	s_waitcnt lgkmcnt(0)
	v_max_u32_e32 v72, v72, v96
	v_max_u32_e32 v71, v71, v91
	v_max_u32_e32 v2, v2, v90
	v_max_u32_e32 v65, v65, v89
	v_max_u32_e32 v73, v73, v88
	v_max_u32_e32 v74, v74, v87
	v_max_u32_e32 v63, v63, v86
	v_max_u32_e32 v68, v68, v77
	v_max_u32_e32 v66, v66, v76
	v_max_u32_e32 v69, v69, v75
	v_max_u32_e32 v0, v0, v1
	v_max_u32_e32 v1, v62, v65
	v_min_u32_e32 v62, v62, v65
	v_max_u32_e32 v65, v3, v73
	v_min_u32_e32 v3, v3, v73
	v_max_u32_e32 v73, v72, v74
	v_min_u32_e32 v72, v72, v74
	v_max_u32_e32 v74, v64, v63
	v_min_u32_e32 v63, v64, v63
	v_max_u32_e32 v64, v70, v68
	v_min_u32_e32 v68, v70, v68
	v_max_u32_e32 v70, v67, v66
	v_min_u32_e32 v66, v67, v66
	v_max_u32_e32 v67, v71, v69
	v_min_u32_e32 v69, v71, v69
	v_max_u32_e32 v71, v2, v0
	v_min_u32_e32 v0, v2, v0
	v_max_u32_e32 v2, v1, v64
	v_min_u32_e32 v1, v1, v64
	v_max_u32_e32 v64, v65, v70
	v_min_u32_e32 v65, v65, v70
	v_max_u32_e32 v70, v73, v67
	v_min_u32_e32 v67, v73, v67
	v_max_u32_e32 v73, v74, v71
	v_min_u32_e32 v71, v74, v71
	v_max_u32_e32 v74, v62, v68
	v_min_u32_e32 v62, v62, v68
	v_max_u32_e32 v68, v3, v66
	v_min_u32_e32 v3, v3, v66
	v_max_u32_e32 v66, v72, v69
	v_min_u32_e32 v69, v72, v69
	v_max_u32_e32 v72, v63, v0
	v_min_u32_e32 v0, v63, v0
	v_max_u32_e32 v63, v2, v70
	v_min_u32_e32 v2, v2, v70
	v_max_u32_e32 v70, v64, v73
	v_min_u32_e32 v64, v64, v73
	v_max_u32_e32 v86, v1, v67
	v_min_u32_e32 v1, v1, v67
	v_max_u32_e32 v67, v65, v71
	v_min_u32_e32 v65, v65, v71
	v_max_u32_e32 v87, v74, v66
	v_min_u32_e32 v66, v74, v66
	v_max_u32_e32 v88, v68, v72
	v_min_u32_e32 v89, v68, v72
	v_max_u32_e32 v90, v62, v69
	v_min_u32_e32 v62, v62, v69
	v_max_u32_e32 v91, v3, v0
	v_min_u32_e32 v0, v3, v0
	v_max_u32_e32 v77, v63, v70
	v_min_u32_e32 v76, v63, v70
	v_max_u32_e32 v75, v2, v64
	v_min_u32_e32 v74, v2, v64
	v_max_u32_e32 v73, v86, v67
	v_min_u32_e32 v72, v86, v67
	v_max_u32_e32 v71, v1, v65
	v_min_u32_e32 v70, v1, v65
	v_max_u32_e32 v69, v87, v88
	v_min_u32_e32 v68, v87, v88
	v_max_u32_e32 v67, v66, v89
	v_min_u32_e32 v66, v66, v89
	v_max_u32_e32 v63, v62, v0
	v_min_u32_e32 v62, v62, v0
	global_load_dwordx4 v[0:3], v[4:5], off offset:816
	global_load_dwordx4 v[86:89], v[4:5], off offset:800
	v_max_u32_e32 v65, v90, v91
	v_min_u32_e32 v64, v90, v91
	s_waitcnt vmcnt(2)
; __device__ __forceinline__ unsigned f2key(float f) { const unsigned u = __float_as_uint(f); return (u & 0x80000000u) ? ~u : (u | 0x80000000u); }
; __device__ __forceinline__ void peer_tile(const Args& A, LAS unsigned char* lds, int tile) {
;     ...
;                 { const bf16_t* sp = QRY + m * 2048 + hp * 128 + 32 * g;
;                   const u32x4 s0 = *(const u32x4*)sp, s1 = *(const u32x4*)(sp + 8), s2 = *(const u32x4*)(sp + 16), s3 = *(const u32x4*)(sp + 24);
;                   const unsigned sw[16] = {s0.x, s0.y, s0.z, s0.w, s1.x, s1.y, s1.z, s1.w, s2.x, s2.y, s2.z, s2.w, s3.x, s3.y, s3.z, s3.w};
; #pragma unroll
;                   for (int i = 0; i < 16; ++i) {
;                       const float lo = (float)__builtin_bit_cast(_Float16, (unsigned short)(sw[i] & 0xffffu)), hi = (float)__builtin_bit_cast(_Float16, (unsigned short)(sw[i] >> 16));
;                       const unsigned klo = (f2key(lo) & ~127u) | (unsigned)(127 - (32 * g + 2 * i)), khi = (f2key(hi) & ~127u) | (unsigned)(127 - (32 * g + 2 * i + 1));
;                       if (i < 8) { k0[2 * i] = klo; k0[2 * i + 1] = khi; } else { k1[2 * (i - 8)] = klo; k1[2 * (i - 8) + 1] = khi; } } }
;     ...
;                 for (int i = 0; i < 16; ++i) L2[p][i] = (g & 2) ? ((g & 1) ? LA[3][p][i] : LA[2][p][i]) : ((g & 1) ? LA[1][p][i] : LA[0][p][i]);
	v_cvt_f32_f16_sdwa v90, v82 dst_sel:DWORD dst_unused:UNUSED_PAD src0_sel:WORD_1
	v_cvt_f32_f16_e32 v82, v82
	v_cndmask_b32_e64 v38, v70, v38, s[0:1]
	v_cndmask_b32_e64 v37, v69, v37, s[0:1]
	v_not_b32_e32 v91, v90
	v_or_b32_e32 v92, 0x80000000, v90
	v_cmp_gt_i32_e32 vcc, 0, v90
	v_cndmask_b32_e64 v36, v68, v36, s[0:1]
	v_cndmask_b32_e64 v35, v67, v35, s[0:1]
	v_cndmask_b32_e32 v90, v92, v91, vcc
	v_not_b32_e32 v91, v82
	v_or_b32_e32 v92, 0x80000000, v82
	v_cmp_gt_i32_e32 vcc, 0, v82
	v_and_b32_e32 v90, 0xffffff80, v90
	v_sub_u32_e32 v90, v90, v15
	v_cndmask_b32_e32 v82, v92, v91, vcc
	v_cvt_f32_f16_sdwa v91, v83 dst_sel:DWORD dst_unused:UNUSED_PAD src0_sel:WORD_1
	v_cvt_f32_f16_e32 v83, v83
	v_and_b32_e32 v82, 0xffffff80, v82
	v_sub_u32_e32 v82, v82, v15
	v_not_b32_e32 v92, v91
	v_or_b32_e32 v93, 0x80000000, v91
	v_cmp_gt_i32_e32 vcc, 0, v91
	v_add_u32_e32 v90, 0x7e, v90
	v_add_u32_e32 v82, 0x7f, v82
	v_cndmask_b32_e32 v91, v93, v92, vcc
	v_not_b32_e32 v92, v83
	v_or_b32_e32 v93, 0x80000000, v83
	v_cmp_gt_i32_e32 vcc, 0, v83
	v_and_b32_e32 v91, 0xffffff80, v91
	v_sub_u32_e32 v91, v91, v14
	v_cndmask_b32_e32 v83, v93, v92, vcc
	v_cvt_f32_f16_sdwa v92, v84 dst_sel:DWORD dst_unused:UNUSED_PAD src0_sel:WORD_1
	v_cvt_f32_f16_e32 v84, v84
	v_and_b32_e32 v83, 0xffffff80, v83
	v_sub_u32_e32 v83, v83, v14
	v_not_b32_e32 v93, v92
	v_or_b32_e32 v94, 0x80000000, v92
	v_cmp_gt_i32_e32 vcc, 0, v92
	v_add_u32_e32 v91, 0x7e, v91
	v_add_u32_e32 v83, 0x7f, v83
	v_cndmask_b32_e32 v92, v94, v93, vcc
	v_not_b32_e32 v93, v84
	v_or_b32_e32 v94, 0x80000000, v84
	v_cmp_gt_i32_e32 vcc, 0, v84
	v_and_b32_e32 v92, 0xffffff80, v92
	v_sub_u32_e32 v92, v92, v12
	v_cndmask_b32_e32 v84, v94, v93, vcc
	v_cvt_f32_f16_sdwa v93, v85 dst_sel:DWORD dst_unused:UNUSED_PAD src0_sel:WORD_1
	v_cvt_f32_f16_e32 v85, v85
	v_and_b32_e32 v84, 0xffffff80, v84
	v_sub_u32_e32 v84, v84, v12
	v_not_b32_e32 v94, v93
	v_or_b32_e32 v95, 0x80000000, v93
	v_cmp_gt_i32_e32 vcc, 0, v93
	v_add_u32_e32 v92, 0x7e, v92
	v_add_u32_e32 v84, 0x7f, v84
	v_cndmask_b32_e32 v93, v95, v94, vcc
	v_not_b32_e32 v94, v85
	v_or_b32_e32 v95, 0x80000000, v85
	v_cmp_gt_i32_e32 vcc, 0, v85
	v_and_b32_e32 v93, 0xffffff80, v93
	v_sub_u32_e32 v93, v93, v10
	v_cndmask_b32_e32 v85, v95, v94, vcc
	v_cvt_f32_f16_sdwa v94, v78 dst_sel:DWORD dst_unused:UNUSED_PAD src0_sel:WORD_1
	v_cvt_f32_f16_e32 v78, v78
	v_and_b32_e32 v85, 0xffffff80, v85
	v_sub_u32_e32 v85, v85, v10
	v_not_b32_e32 v95, v94
	v_or_b32_e32 v96, 0x80000000, v94
	v_cmp_gt_i32_e32 vcc, 0, v94
	v_add_u32_e32 v93, 0x7e, v93
	v_add_u32_e32 v85, 0x7f, v85
	v_cndmask_b32_e32 v94, v96, v95, vcc
	v_not_b32_e32 v95, v78
	v_or_b32_e32 v96, 0x80000000, v78
	v_cmp_gt_i32_e32 vcc, 0, v78
	v_and_b32_e32 v94, 0xffffff80, v94
	v_sub_u32_e32 v94, v94, v8
	v_cndmask_b32_e32 v78, v96, v95, vcc
	v_cvt_f32_f16_sdwa v95, v79 dst_sel:DWORD dst_unused:UNUSED_PAD src0_sel:WORD_1
	v_cvt_f32_f16_e32 v79, v79
	v_and_b32_e32 v78, 0xffffff80, v78
	v_sub_u32_e32 v78, v78, v8
	v_not_b32_e32 v96, v95
	v_or_b32_e32 v97, 0x80000000, v95
	v_cmp_gt_i32_e32 vcc, 0, v95
	v_add_u32_e32 v94, 0x7e, v94
	v_add_u32_e32 v78, 0x7f, v78
	v_cndmask_b32_e32 v95, v97, v96, vcc
	v_not_b32_e32 v96, v79
	v_or_b32_e32 v97, 0x80000000, v79
	v_cmp_gt_i32_e32 vcc, 0, v79
	v_and_b32_e32 v95, 0xffffff80, v95
	v_sub_u32_e32 v95, v95, v16
	v_cndmask_b32_e32 v79, v97, v96, vcc
	v_cvt_f32_f16_sdwa v96, v80 dst_sel:DWORD dst_unused:UNUSED_PAD src0_sel:WORD_1
	v_cvt_f32_f16_e32 v80, v80
	v_and_b32_e32 v79, 0xffffff80, v79
	v_sub_u32_e32 v79, v79, v16
	v_not_b32_e32 v97, v96
	v_or_b32_e32 v98, 0x80000000, v96
	v_cmp_gt_i32_e32 vcc, 0, v96
	v_add_u32_e32 v95, 0x7e, v95
	v_add_u32_e32 v79, 0x7f, v79
	v_cndmask_b32_e32 v96, v98, v97, vcc
	v_not_b32_e32 v97, v80
	v_or_b32_e32 v98, 0x80000000, v80
	v_cmp_gt_i32_e32 vcc, 0, v80
	v_and_b32_e32 v96, 0xffffff80, v96
	v_sub_u32_e32 v96, v96, v17
	v_cndmask_b32_e32 v80, v98, v97, vcc
	v_cvt_f32_f16_sdwa v97, v81 dst_sel:DWORD dst_unused:UNUSED_PAD src0_sel:WORD_1
	v_cvt_f32_f16_e32 v81, v81
	v_and_b32_e32 v80, 0xffffff80, v80
	v_sub_u32_e32 v80, v80, v17
	v_not_b32_e32 v98, v97
	v_or_b32_e32 v99, 0x80000000, v97
	v_cmp_gt_i32_e32 vcc, 0, v97
	v_add_u32_e32 v96, 0x7e, v96
	v_add_u32_e32 v80, 0x7f, v80
	v_cndmask_b32_e32 v97, v99, v98, vcc
	v_not_b32_e32 v98, v81
	v_or_b32_e32 v99, 0x80000000, v81
	v_cmp_gt_i32_e32 vcc, 0, v81
	v_and_b32_e32 v97, 0xffffff80, v97
	v_sub_u32_e32 v97, v97, v18
	v_cndmask_b32_e32 v81, v99, v98, vcc
	s_waitcnt vmcnt(0)
; __device__ __forceinline__ unsigned f2key(float f) { const unsigned u = __float_as_uint(f); return (u & 0x80000000u) ? ~u : (u | 0x80000000u); }
; #define CE_DESC(a, b) do { const unsigned _mx = (a) > (b) ? (a) : (b), _mn = (a) > (b) ? (b) : (a); (a) = _mx; (b) = _mn; } while (0)
; __device__ __forceinline__ void sort16_desc(unsigned (&k)[16]) {
; #pragma unroll
;     for (int size = 2; size <= 16; size <<= 1)
; #pragma unroll
;         for (int stride = size >> 1; stride > 0; stride >>= 1)
; #pragma unroll
;             for (int i = 0; i < 16; ++i) { const int j = i ^ stride;
;                 if (j > i) { if ((i & size) == 0) CE_DESC(k[i], k[j]); else CE_DESC(k[j], k[i]); } }
; }
; __device__ __forceinline__ void peer_tile(const Args& A, LAS unsigned char* lds, int tile) {
;     ...
;                 { const bf16_t* sp = QRY + m * 2048 + hp * 128 + 32 * g;
;                   const u32x4 s0 = *(const u32x4*)sp, s1 = *(const u32x4*)(sp + 8), s2 = *(const u32x4*)(sp + 16), s3 = *(const u32x4*)(sp + 24);
;                   const unsigned sw[16] = {s0.x, s0.y, s0.z, s0.w, s1.x, s1.y, s1.z, s1.w, s2.x, s2.y, s2.z, s2.w, s3.x, s3.y, s3.z, s3.w};
; #pragma unroll
;                   for (int i = 0; i < 16; ++i) {
;                       const float lo = (float)__builtin_bit_cast(_Float16, (unsigned short)(sw[i] & 0xffffu)), hi = (float)__builtin_bit_cast(_Float16, (unsigned short)(sw[i] >> 16));
;                       const unsigned klo = (f2key(lo) & ~127u) | (unsigned)(127 - (32 * g + 2 * i)), khi = (f2key(hi) & ~127u) | (unsigned)(127 - (32 * g + 2 * i + 1));
;                       if (i < 8) { k0[2 * i] = klo; k0[2 * i + 1] = khi; } else { k1[2 * (i - 8)] = klo; k1[2 * (i - 8) + 1] = khi; } } }
	v_cvt_f32_f16_sdwa v98, v86 dst_sel:DWORD dst_unused:UNUSED_PAD src0_sel:WORD_1
	v_cvt_f32_f16_e32 v86, v86
	v_and_b32_e32 v81, 0xffffff80, v81
	v_sub_u32_e32 v81, v81, v18
	v_not_b32_e32 v99, v98
	v_or_b32_e32 v100, 0x80000000, v98
	v_cmp_gt_i32_e32 vcc, 0, v98
	v_add_u32_e32 v97, 0x7e, v97
	v_add_u32_e32 v81, 0x7f, v81
	v_cndmask_b32_e32 v98, v100, v99, vcc
	v_not_b32_e32 v99, v86
	v_or_b32_e32 v100, 0x80000000, v86
	v_cmp_gt_i32_e32 vcc, 0, v86
	v_and_b32_e32 v98, 0xffffff80, v98
	v_sub_u32_e32 v98, v98, v20
	v_cndmask_b32_e32 v86, v100, v99, vcc
	v_cvt_f32_f16_sdwa v99, v87 dst_sel:DWORD dst_unused:UNUSED_PAD src0_sel:WORD_1
	v_cvt_f32_f16_e32 v87, v87
	v_and_b32_e32 v86, 0xffffff80, v86
	v_sub_u32_e32 v86, v86, v20
	v_not_b32_e32 v100, v99
	v_or_b32_e32 v101, 0x80000000, v99
	v_cmp_gt_i32_e32 vcc, 0, v99
	v_add_u32_e32 v98, 0x7e, v98
	v_add_u32_e32 v86, 0x7f, v86
	v_cndmask_b32_e32 v99, v101, v100, vcc
	v_not_b32_e32 v100, v87
	v_or_b32_e32 v101, 0x80000000, v87
	v_cmp_gt_i32_e32 vcc, 0, v87
	v_and_b32_e32 v99, 0xffffff80, v99
	v_sub_u32_e32 v99, v99, v21
	v_cndmask_b32_e32 v87, v101, v100, vcc
	v_cvt_f32_f16_sdwa v100, v88 dst_sel:DWORD dst_unused:UNUSED_PAD src0_sel:WORD_1
	v_cvt_f32_f16_e32 v88, v88
	v_and_b32_e32 v87, 0xffffff80, v87
	v_sub_u32_e32 v87, v87, v21
	v_not_b32_e32 v101, v100
	v_or_b32_e32 v102, 0x80000000, v100
	v_cmp_gt_i32_e32 vcc, 0, v100
	v_add_u32_e32 v99, 0x7e, v99
	v_add_u32_e32 v87, 0x7f, v87
	v_cndmask_b32_e32 v100, v102, v101, vcc
	v_not_b32_e32 v101, v88
	v_or_b32_e32 v102, 0x80000000, v88
	v_cmp_gt_i32_e32 vcc, 0, v88
	v_and_b32_e32 v100, 0xffffff80, v100
	v_sub_u32_e32 v100, v100, v22
	v_cndmask_b32_e32 v88, v102, v101, vcc
	v_cvt_f32_f16_sdwa v101, v89 dst_sel:DWORD dst_unused:UNUSED_PAD src0_sel:WORD_1
	v_cvt_f32_f16_e32 v89, v89
	v_and_b32_e32 v88, 0xffffff80, v88
	v_sub_u32_e32 v88, v88, v22
	v_not_b32_e32 v102, v101
	v_or_b32_e32 v103, 0x80000000, v101
	v_cmp_gt_i32_e32 vcc, 0, v101
	v_add_u32_e32 v100, 0x7e, v100
	v_add_u32_e32 v88, 0x7f, v88
	v_cndmask_b32_e32 v101, v103, v102, vcc
	v_not_b32_e32 v102, v89
	v_or_b32_e32 v103, 0x80000000, v89
	v_cmp_gt_i32_e32 vcc, 0, v89
	v_and_b32_e32 v101, 0xffffff80, v101
	v_sub_u32_e32 v101, v101, v23
	v_cndmask_b32_e32 v89, v103, v102, vcc
	v_cvt_f32_f16_sdwa v102, v0 dst_sel:DWORD dst_unused:UNUSED_PAD src0_sel:WORD_1
	v_cvt_f32_f16_e32 v0, v0
	v_and_b32_e32 v89, 0xffffff80, v89
	v_sub_u32_e32 v89, v89, v23
	v_not_b32_e32 v103, v102
	v_or_b32_e32 v104, 0x80000000, v102
	v_cmp_gt_i32_e32 vcc, 0, v102
	v_add_u32_e32 v101, 0x7e, v101
	v_add_u32_e32 v89, 0x7f, v89
	v_cndmask_b32_e32 v102, v104, v103, vcc
	v_not_b32_e32 v103, v0
	v_or_b32_e32 v104, 0x80000000, v0
	v_cmp_gt_i32_e32 vcc, 0, v0
	v_and_b32_e32 v102, 0xffffff80, v102
	v_sub_u32_e32 v102, v102, v24
	v_cndmask_b32_e32 v0, v104, v103, vcc
	v_cvt_f32_f16_sdwa v103, v1 dst_sel:DWORD dst_unused:UNUSED_PAD src0_sel:WORD_1
	v_cvt_f32_f16_e32 v1, v1
	v_and_b32_e32 v0, 0xffffff80, v0
	v_sub_u32_e32 v0, v0, v24
	v_not_b32_e32 v104, v103
	v_or_b32_e32 v105, 0x80000000, v103
	v_cmp_gt_i32_e32 vcc, 0, v103
	v_add_u32_e32 v102, 0x7e, v102
	v_add_u32_e32 v0, 0x7f, v0
	v_cndmask_b32_e32 v103, v105, v104, vcc
	v_not_b32_e32 v104, v1
	v_or_b32_e32 v105, 0x80000000, v1
	v_cmp_gt_i32_e32 vcc, 0, v1
	v_and_b32_e32 v103, 0xffffff80, v103
	v_sub_u32_e32 v103, v103, v25
	v_cndmask_b32_e32 v1, v105, v104, vcc
	v_cvt_f32_f16_sdwa v104, v2 dst_sel:DWORD dst_unused:UNUSED_PAD src0_sel:WORD_1
	v_cvt_f32_f16_e32 v2, v2
	v_and_b32_e32 v1, 0xffffff80, v1
	v_sub_u32_e32 v1, v1, v25
	v_not_b32_e32 v105, v104
	v_or_b32_e32 v106, 0x80000000, v104
	v_cmp_gt_i32_e32 vcc, 0, v104
	v_add_u32_e32 v103, 0x7e, v103
	v_add_u32_e32 v1, 0x7f, v1
	v_cndmask_b32_e32 v104, v106, v105, vcc
	v_not_b32_e32 v105, v2
	v_or_b32_e32 v106, 0x80000000, v2
	v_cmp_gt_i32_e32 vcc, 0, v2
	v_and_b32_e32 v104, 0xffffff80, v104
	v_sub_u32_e32 v104, v104, v26
	v_cndmask_b32_e32 v2, v106, v105, vcc
	v_cvt_f32_f16_sdwa v105, v3 dst_sel:DWORD dst_unused:UNUSED_PAD src0_sel:WORD_1
	v_cvt_f32_f16_e32 v3, v3
	v_and_b32_e32 v2, 0xffffff80, v2
	v_sub_u32_e32 v2, v2, v26
	v_not_b32_e32 v106, v105
	v_or_b32_e32 v107, 0x80000000, v105
	v_cmp_gt_i32_e32 vcc, 0, v105
	v_add_u32_e32 v104, 0x7e, v104
	v_add_u32_e32 v2, 0x7f, v2
	v_cndmask_b32_e32 v105, v107, v106, vcc
	v_not_b32_e32 v106, v3
	v_or_b32_e32 v107, 0x80000000, v3
	v_cmp_gt_i32_e32 vcc, 0, v3
	v_and_b32_e32 v105, 0xffffff80, v105
	v_sub_u32_e32 v105, v105, v28
	v_cndmask_b32_e32 v3, v107, v106, vcc
	v_and_b32_e32 v3, 0xffffff80, v3
	v_sub_u32_e32 v3, v3, v28
	v_add_u32_e32 v105, 0x7e, v105
	v_add_u32_e32 v3, 0x7f, v3
	v_max_u32_e32 v106, v82, v90
	v_min_u32_e32 v82, v82, v90
	v_max_u32_e32 v90, v91, v83
	v_min_u32_e32 v83, v91, v83
	v_max_u32_e32 v91, v84, v92
	v_min_u32_e32 v84, v84, v92
	v_max_u32_e32 v92, v93, v85
	v_min_u32_e32 v85, v93, v85
	v_max_u32_e32 v93, v78, v94
	v_min_u32_e32 v78, v78, v94
	v_max_u32_e32 v94, v95, v79
	v_min_u32_e32 v79, v95, v79
	v_max_u32_e32 v95, v80, v96
	v_min_u32_e32 v80, v80, v96
	v_max_u32_e32 v96, v97, v81
	v_min_u32_e32 v81, v97, v81
	v_max_u32_e32 v115, v86, v98
	v_min_u32_e32 v86, v86, v98
	v_max_u32_e32 v98, v99, v87
	v_min_u32_e32 v87, v99, v87
	v_max_u32_e32 v99, v88, v100
	v_min_u32_e32 v88, v88, v100
	v_max_u32_e32 v100, v101, v89
	v_min_u32_e32 v89, v101, v89
	v_max_u32_e32 v101, v0, v102
	v_min_u32_e32 v0, v0, v102
	v_max_u32_e32 v102, v103, v1
	v_min_u32_e32 v1, v103, v1
	v_max_u32_e32 v103, v2, v104
	v_min_u32_e32 v2, v2, v104
	v_max_u32_e32 v104, v105, v3
	v_min_u32_e32 v3, v105, v3
	v_max_u32_e32 v97, v106, v83
	v_min_u32_e32 v83, v106, v83
	v_max_u32_e32 v106, v82, v90
; #define CE_DESC(a, b) do { const unsigned _mx = (a) > (b) ? (a) : (b), _mn = (a) > (b) ? (b) : (a); (a) = _mx; (b) = _mn; } while (0)
; __device__ __forceinline__ void sort16_desc(unsigned (&k)[16]) {
; #pragma unroll
;     for (int size = 2; size <= 16; size <<= 1)
; #pragma unroll
;         for (int stride = size >> 1; stride > 0; stride >>= 1)
; #pragma unroll
;             for (int i = 0; i < 16; ++i) { const int j = i ^ stride;
;                 if (j > i) { if ((i & size) == 0) CE_DESC(k[i], k[j]); else CE_DESC(k[j], k[i]); } }
; }
	v_min_u32_e32 v82, v82, v90
	v_max_u32_e32 v90, v85, v91
	v_min_u32_e32 v85, v85, v91
	v_max_u32_e32 v91, v92, v84
	v_min_u32_e32 v84, v92, v84
	v_max_u32_e32 v92, v93, v79
	v_min_u32_e32 v79, v93, v79
	v_max_u32_e32 v93, v78, v94
	v_min_u32_e32 v78, v78, v94
	v_max_u32_e32 v94, v81, v95
	v_min_u32_e32 v81, v81, v95
	v_max_u32_e32 v95, v96, v80
	v_min_u32_e32 v80, v96, v80
	v_max_u32_e32 v105, v115, v87
	v_min_u32_e32 v87, v115, v87
	v_max_u32_e32 v115, v86, v98
	v_min_u32_e32 v86, v86, v98
	v_max_u32_e32 v98, v89, v99
	v_min_u32_e32 v89, v89, v99
	v_max_u32_e32 v99, v100, v88
	v_min_u32_e32 v88, v100, v88
	v_max_u32_e32 v100, v101, v1
	v_min_u32_e32 v1, v101, v1
	v_max_u32_e32 v101, v0, v102
	v_min_u32_e32 v0, v0, v102
	v_max_u32_e32 v102, v3, v103
	v_min_u32_e32 v3, v3, v103
	v_max_u32_e32 v103, v104, v2
	v_min_u32_e32 v2, v104, v2
	v_max_u32_e32 v96, v97, v106
	v_min_u32_e32 v97, v97, v106
	v_max_u32_e32 v106, v83, v82
	v_min_u32_e32 v82, v83, v82
	v_max_u32_e32 v83, v84, v85
	v_min_u32_e32 v84, v84, v85
	v_max_u32_e32 v85, v91, v90
	v_min_u32_e32 v90, v91, v90
	v_max_u32_e32 v91, v92, v93
	v_min_u32_e32 v92, v92, v93
	v_max_u32_e32 v93, v79, v78
	v_min_u32_e32 v78, v79, v78
	v_max_u32_e32 v79, v80, v81
	v_min_u32_e32 v80, v80, v81
	v_max_u32_e32 v81, v95, v94
	v_min_u32_e32 v94, v95, v94
	v_max_u32_e32 v104, v105, v115
	v_min_u32_e32 v105, v105, v115
	v_max_u32_e32 v115, v87, v86
	v_min_u32_e32 v86, v87, v86
	v_max_u32_e32 v87, v88, v89
	v_min_u32_e32 v88, v88, v89
	v_max_u32_e32 v89, v99, v98
	v_min_u32_e32 v98, v99, v98
	v_max_u32_e32 v99, v100, v101
	v_min_u32_e32 v100, v100, v101
	v_max_u32_e32 v101, v1, v0
	v_min_u32_e32 v0, v1, v0
	v_max_u32_e32 v1, v2, v3
	v_min_u32_e32 v2, v2, v3
	v_max_u32_e32 v3, v103, v102
	v_min_u32_e32 v102, v103, v102
	v_max_u32_e32 v95, v96, v84
	v_min_u32_e32 v84, v96, v84
	v_max_u32_e32 v96, v97, v83
	v_min_u32_e32 v83, v97, v83
	v_max_u32_e32 v97, v106, v90
	v_min_u32_e32 v90, v106, v90
	v_max_u32_e32 v106, v82, v85
	v_min_u32_e32 v82, v82, v85
	v_max_u32_e32 v85, v80, v91
	v_min_u32_e32 v80, v80, v91
	v_max_u32_e32 v91, v79, v92
	v_min_u32_e32 v79, v79, v92
	v_max_u32_e32 v92, v94, v93
	v_min_u32_e32 v93, v94, v93
	v_max_u32_e32 v94, v81, v78
	v_min_u32_e32 v78, v81, v78
	v_max_u32_e32 v103, v104, v88
	v_min_u32_e32 v88, v104, v88
	v_max_u32_e32 v104, v105, v87
	v_min_u32_e32 v87, v105, v87
	v_max_u32_e32 v105, v115, v98
	v_min_u32_e32 v98, v115, v98
	v_max_u32_e32 v115, v86, v89
	v_min_u32_e32 v86, v86, v89
	v_max_u32_e32 v89, v2, v99
	v_min_u32_e32 v2, v2, v99
	v_max_u32_e32 v99, v1, v100
	v_min_u32_e32 v1, v1, v100
	v_max_u32_e32 v100, v102, v101
	v_min_u32_e32 v101, v102, v101
	v_max_u32_e32 v102, v3, v0
	v_min_u32_e32 v0, v3, v0
	v_max_u32_e32 v81, v95, v97
	v_min_u32_e32 v95, v95, v97
	v_max_u32_e32 v97, v96, v106
	v_min_u32_e32 v96, v96, v106
	v_max_u32_e32 v106, v84, v90
	v_min_u32_e32 v84, v84, v90
	v_max_u32_e32 v90, v83, v82
	v_min_u32_e32 v82, v83, v82
	v_max_u32_e32 v83, v93, v80
	v_min_u32_e32 v80, v93, v80
	v_max_u32_e32 v93, v78, v79
	v_min_u32_e32 v78, v78, v79
	v_max_u32_e32 v79, v92, v85
	v_min_u32_e32 v85, v92, v85
	v_max_u32_e32 v92, v94, v91
	v_min_u32_e32 v91, v94, v91
	v_max_u32_e32 v3, v103, v105
	v_min_u32_e32 v103, v103, v105
	v_max_u32_e32 v105, v104, v115
	v_min_u32_e32 v104, v104, v115
	v_max_u32_e32 v115, v88, v98
	v_min_u32_e32 v88, v88, v98
	v_max_u32_e32 v98, v87, v86
	v_min_u32_e32 v86, v87, v86
	v_max_u32_e32 v87, v101, v2
	v_min_u32_e32 v2, v101, v2
	v_max_u32_e32 v101, v0, v1
	v_min_u32_e32 v0, v0, v1
	v_max_u32_e32 v1, v100, v89
	v_min_u32_e32 v89, v100, v89
	v_max_u32_e32 v100, v102, v99
	v_min_u32_e32 v99, v102, v99
	v_max_u32_e32 v94, v81, v97
	v_min_u32_e32 v81, v81, v97
	v_max_u32_e32 v97, v95, v96
	v_min_u32_e32 v95, v95, v96
	v_max_u32_e32 v96, v106, v90
	v_min_u32_e32 v90, v106, v90
	v_max_u32_e32 v106, v84, v82
	v_min_u32_e32 v82, v84, v82
	v_max_u32_e32 v84, v78, v80
	v_min_u32_e32 v78, v78, v80
	v_max_u32_e32 v80, v93, v83
	v_min_u32_e32 v83, v93, v83
	v_max_u32_e32 v93, v91, v85
	v_min_u32_e32 v85, v91, v85
	v_max_u32_e32 v91, v92, v79
	v_min_u32_e32 v79, v92, v79
	v_max_u32_e32 v102, v3, v105
	v_min_u32_e32 v3, v3, v105
	v_max_u32_e32 v105, v103, v104
	v_min_u32_e32 v103, v103, v104
	v_max_u32_e32 v104, v115, v98
	v_min_u32_e32 v98, v115, v98
	v_max_u32_e32 v115, v88, v86
	v_min_u32_e32 v86, v88, v86
	v_max_u32_e32 v88, v0, v2
	v_min_u32_e32 v0, v0, v2
	v_max_u32_e32 v2, v101, v87
	v_min_u32_e32 v87, v101, v87
	v_max_u32_e32 v101, v99, v89
	v_min_u32_e32 v89, v99, v89
	v_max_u32_e32 v99, v100, v1
	v_min_u32_e32 v1, v100, v1
	v_max_u32_e32 v92, v94, v78
	v_min_u32_e32 v78, v94, v78
	v_max_u32_e32 v94, v81, v84
	v_min_u32_e32 v81, v81, v84
	v_max_u32_e32 v84, v97, v83
	v_min_u32_e32 v83, v97, v83
	v_max_u32_e32 v97, v95, v80
	v_min_u32_e32 v80, v95, v80
	v_max_u32_e32 v95, v96, v85
	v_min_u32_e32 v85, v96, v85
	v_max_u32_e32 v96, v90, v93
	v_min_u32_e32 v90, v90, v93
	v_max_u32_e32 v93, v106, v79
	v_min_u32_e32 v79, v106, v79
	v_max_u32_e32 v106, v82, v91
	v_min_u32_e32 v82, v82, v91
	v_max_u32_e32 v100, v102, v0
	v_min_u32_e32 v0, v102, v0
	v_max_u32_e32 v102, v3, v88
	v_min_u32_e32 v3, v3, v88
	v_max_u32_e32 v88, v105, v87
	v_min_u32_e32 v87, v105, v87
	v_max_u32_e32 v105, v103, v2
	v_min_u32_e32 v2, v103, v2
	v_max_u32_e32 v103, v104, v89
	v_min_u32_e32 v89, v104, v89
	v_max_u32_e32 v104, v98, v101
	v_min_u32_e32 v98, v98, v101
	v_max_u32_e32 v101, v115, v1
	v_min_u32_e32 v1, v115, v1
	v_max_u32_e32 v115, v86, v99
	v_min_u32_e32 v86, v86, v99
	v_max_u32_e32 v91, v92, v95
	v_min_u32_e32 v92, v92, v95
	v_max_u32_e32 v95, v94, v96
; #define CE_DESC(a, b) do { const unsigned _mx = (a) > (b) ? (a) : (b), _mn = (a) > (b) ? (b) : (a); (a) = _mx; (b) = _mn; } while (0)
; __device__ __forceinline__ void sort16_desc(unsigned (&k)[16]) {
; #pragma unroll
;     for (int size = 2; size <= 16; size <<= 1)
; #pragma unroll
;         for (int stride = size >> 1; stride > 0; stride >>= 1)
; #pragma unroll
;             for (int i = 0; i < 16; ++i) { const int j = i ^ stride;
;                 if (j > i) { if ((i & size) == 0) CE_DESC(k[i], k[j]); else CE_DESC(k[j], k[i]); } }
; }
; __device__ __forceinline__ void merge16(unsigned (&a)[16], const unsigned (&b)[16]) {
; #pragma unroll
;     for (int i = 0; i < 16; ++i) a[i] = a[i] > b[15 - i] ? a[i] : b[15 - i];
; #pragma unroll
;     for (int stride = 8; stride > 0; stride >>= 1)
; #pragma unroll
;         for (int i = 0; i < 16; ++i) { const int j = i ^ stride; if (j > i) CE_DESC(a[i], a[j]); }
; }
; __device__ __forceinline__ void peer_tile(const Args& A, LAS unsigned char* lds, int tile) {
;     ...
;                 sort16_desc(k0); sort16_desc(k1); merge16(k0, k1);
; #pragma unroll
;                 for (int msk = 16; msk <= 32; msk <<= 1) {
; #pragma unroll
;                     for (int i = 0; i < 16; ++i) k1[i] = (unsigned)__shfl_xor((int)k0[i], msk);
;                     merge16(k0, k1); }
	v_min_u32_e32 v94, v94, v96
	v_max_u32_e32 v96, v84, v93
	v_min_u32_e32 v84, v84, v93
	v_max_u32_e32 v93, v97, v106
	v_min_u32_e32 v97, v97, v106
	v_max_u32_e32 v106, v78, v85
	v_min_u32_e32 v78, v78, v85
	v_max_u32_e32 v85, v81, v90
	v_min_u32_e32 v81, v81, v90
	v_max_u32_e32 v90, v83, v79
	v_min_u32_e32 v79, v83, v79
	v_max_u32_e32 v83, v80, v82
	v_min_u32_e32 v80, v80, v82
	v_max_u32_e32 v99, v100, v103
	v_min_u32_e32 v100, v100, v103
	v_max_u32_e32 v103, v102, v104
	v_min_u32_e32 v102, v102, v104
	v_max_u32_e32 v104, v88, v101
	v_min_u32_e32 v88, v88, v101
	v_max_u32_e32 v101, v105, v115
	v_min_u32_e32 v105, v105, v115
	v_max_u32_e32 v115, v0, v89
	v_min_u32_e32 v0, v0, v89
	v_max_u32_e32 v89, v3, v98
	v_min_u32_e32 v3, v3, v98
	v_max_u32_e32 v98, v87, v1
	v_min_u32_e32 v1, v87, v1
	v_max_u32_e32 v87, v2, v86
	v_min_u32_e32 v2, v2, v86
	v_max_u32_e32 v82, v91, v96
	v_min_u32_e32 v91, v91, v96
	v_max_u32_e32 v96, v95, v93
	v_min_u32_e32 v93, v95, v93
	v_max_u32_e32 v95, v92, v84
	v_min_u32_e32 v84, v92, v84
	v_max_u32_e32 v92, v94, v97
	v_min_u32_e32 v94, v94, v97
	v_max_u32_e32 v97, v106, v90
	v_min_u32_e32 v90, v106, v90
	v_max_u32_e32 v106, v85, v83
	v_min_u32_e32 v83, v85, v83
	v_max_u32_e32 v85, v78, v79
	v_min_u32_e32 v78, v78, v79
	v_max_u32_e32 v79, v81, v80
	v_min_u32_e32 v80, v81, v80
	v_max_u32_e32 v86, v99, v104
	v_min_u32_e32 v99, v99, v104
	v_max_u32_e32 v104, v103, v101
	v_min_u32_e32 v101, v103, v101
	v_max_u32_e32 v103, v100, v88
	v_min_u32_e32 v88, v100, v88
	v_max_u32_e32 v100, v102, v105
	v_min_u32_e32 v102, v102, v105
	v_max_u32_e32 v105, v115, v98
	v_min_u32_e32 v98, v115, v98
	v_max_u32_e32 v115, v89, v87
	v_min_u32_e32 v87, v89, v87
	v_max_u32_e32 v89, v0, v1
	v_min_u32_e32 v0, v0, v1
	v_max_u32_e32 v1, v3, v2
	v_min_u32_e32 v2, v3, v2
	v_min_u32_e32 v81, v82, v96
	v_min_u32_e32 v107, v91, v93
	v_min_u32_e32 v108, v95, v92
	v_min_u32_e32 v109, v84, v94
	v_min_u32_e32 v110, v97, v106
	v_min_u32_e32 v111, v90, v83
	v_min_u32_e32 v112, v85, v79
	v_min_u32_e32 v114, v78, v80
	v_min_u32_e32 v3, v86, v104
	v_min_u32_e32 v116, v99, v101
	v_min_u32_e32 v117, v103, v100
	v_min_u32_e32 v118, v88, v102
	v_min_u32_e32 v119, v105, v115
	v_min_u32_e32 v120, v98, v87
	v_min_u32_e32 v121, v89, v1
	v_min_u32_e32 v122, v0, v2
	v_max3_u32 v82, v82, v96, v122
	v_max3_u32 v0, v81, v0, v2
	v_max3_u32 v2, v91, v93, v121
	v_max3_u32 v1, v107, v89, v1
	v_max3_u32 v81, v95, v92, v120
	v_max3_u32 v87, v108, v98, v87
	v_max3_u32 v84, v84, v94, v119
	v_max3_u32 v89, v109, v105, v115
	v_max3_u32 v91, v97, v106, v118
	v_max3_u32 v88, v110, v88, v102
	v_max3_u32 v83, v90, v83, v117
	v_max3_u32 v90, v111, v103, v100
	v_max3_u32 v79, v85, v79, v116
	v_max3_u32 v85, v112, v99, v101
	v_max3_u32 v3, v78, v80, v3
	v_max3_u32 v78, v114, v86, v104
	v_max_u32_e32 v80, v82, v91
	v_min_u32_e32 v82, v82, v91
	v_max_u32_e32 v86, v0, v88
	v_min_u32_e32 v0, v0, v88
	v_max_u32_e32 v88, v2, v83
	v_min_u32_e32 v2, v2, v83
	v_max_u32_e32 v83, v1, v90
	v_min_u32_e32 v1, v1, v90
	v_max_u32_e32 v90, v81, v79
	v_min_u32_e32 v79, v81, v79
	v_max_u32_e32 v81, v87, v85
	v_min_u32_e32 v85, v87, v85
	v_max_u32_e32 v87, v84, v3
	v_min_u32_e32 v3, v84, v3
	v_max_u32_e32 v84, v89, v78
	v_min_u32_e32 v78, v89, v78
	v_max_u32_e32 v89, v80, v90
	v_min_u32_e32 v80, v80, v90
	v_max_u32_e32 v90, v86, v81
	v_min_u32_e32 v81, v86, v81
	v_max_u32_e32 v86, v88, v87
	v_min_u32_e32 v87, v88, v87
	v_max_u32_e32 v88, v83, v84
	v_min_u32_e32 v83, v83, v84
	v_max_u32_e32 v84, v82, v79
	v_min_u32_e32 v79, v82, v79
	v_max_u32_e32 v82, v0, v85
	v_min_u32_e32 v0, v0, v85
	v_max_u32_e32 v85, v2, v3
	v_min_u32_e32 v2, v2, v3
	v_max_u32_e32 v3, v1, v78
	v_min_u32_e32 v1, v1, v78
	v_max_u32_e32 v78, v89, v86
	v_min_u32_e32 v86, v89, v86
	v_max_u32_e32 v89, v90, v88
	v_min_u32_e32 v88, v90, v88
	v_max_u32_e32 v90, v80, v87
	v_min_u32_e32 v80, v80, v87
	v_max_u32_e32 v87, v81, v83
	v_min_u32_e32 v81, v81, v83
	v_max_u32_e32 v83, v84, v85
	v_min_u32_e32 v84, v84, v85
	v_max_u32_e32 v85, v82, v3
	v_min_u32_e32 v3, v82, v3
	v_max_u32_e32 v82, v79, v2
	v_min_u32_e32 v2, v79, v2
	v_max_u32_e32 v79, v0, v1
	v_min_u32_e32 v0, v0, v1
	v_max_u32_e32 v1, v78, v89
	v_min_u32_e32 v78, v78, v89
	v_max_u32_e32 v89, v86, v88
	v_min_u32_e32 v86, v86, v88
	v_max_u32_e32 v88, v90, v87
	v_min_u32_e32 v87, v90, v87
	v_max_u32_e32 v90, v80, v81
	v_min_u32_e32 v80, v80, v81
	v_max_u32_e32 v81, v83, v85
	v_min_u32_e32 v83, v83, v85
	v_max_u32_e32 v85, v84, v3
	v_min_u32_e32 v3, v84, v3
	v_max_u32_e32 v84, v82, v79
	v_min_u32_e32 v79, v82, v79
	v_max_u32_e32 v82, v2, v0
	v_min_u32_e32 v0, v2, v0
	ds_bpermute_b32 v2, v27, v1
	ds_bpermute_b32 v91, v27, v78
	ds_bpermute_b32 v92, v27, v89
	ds_bpermute_b32 v93, v27, v86
	ds_bpermute_b32 v94, v27, v88
	ds_bpermute_b32 v95, v27, v87
	ds_bpermute_b32 v96, v27, v90
	ds_bpermute_b32 v97, v27, v80
	ds_bpermute_b32 v98, v27, v81
	ds_bpermute_b32 v99, v27, v83
	ds_bpermute_b32 v100, v27, v85
	ds_bpermute_b32 v101, v27, v0
	ds_bpermute_b32 v102, v27, v82
	ds_bpermute_b32 v103, v27, v79
	ds_bpermute_b32 v104, v27, v84
	ds_bpermute_b32 v105, v27, v3
	s_waitcnt lgkmcnt(4)
	v_max_u32_e32 v1, v1, v101
	s_waitcnt lgkmcnt(3)
	v_max_u32_e32 v78, v78, v102
	s_waitcnt lgkmcnt(2)
	v_max_u32_e32 v89, v89, v103
	s_waitcnt lgkmcnt(1)
	v_max_u32_e32 v86, v86, v104
	s_waitcnt lgkmcnt(0)
; #define CE_DESC(a, b) do { const unsigned _mx = (a) > (b) ? (a) : (b), _mn = (a) > (b) ? (b) : (a); (a) = _mx; (b) = _mn; } while (0)
; __device__ __forceinline__ void sort16_desc(unsigned (&k)[16]) {
; #pragma unroll
;     for (int size = 2; size <= 16; size <<= 1)
; #pragma unroll
;         for (int stride = size >> 1; stride > 0; stride >>= 1)
; #pragma unroll
;             for (int i = 0; i < 16; ++i) { const int j = i ^ stride;
;                 if (j > i) { if ((i & size) == 0) CE_DESC(k[i], k[j]); else CE_DESC(k[j], k[i]); } }
; }
; __device__ __forceinline__ void merge16(unsigned (&a)[16], const unsigned (&b)[16]) {
; #pragma unroll
;     for (int i = 0; i < 16; ++i) a[i] = a[i] > b[15 - i] ? a[i] : b[15 - i];
; #pragma unroll
;     for (int stride = 8; stride > 0; stride >>= 1)
; #pragma unroll
;         for (int i = 0; i < 16; ++i) { const int j = i ^ stride; if (j > i) CE_DESC(a[i], a[j]); }
; }
; __device__ __forceinline__ void peer_tile(const Args& A, LAS unsigned char* lds, int tile) {
;     ...
;                 { const bf16_t* sp = QRY + m * 2048 + hp * 128 + 32 * g;
;                   const u32x4 s0 = *(const u32x4*)sp, s1 = *(const u32x4*)(sp + 8), s2 = *(const u32x4*)(sp + 16), s3 = *(const u32x4*)(sp + 24);
;     ...
;                 sort16_desc(k0); sort16_desc(k1); merge16(k0, k1);
; #pragma unroll
;                 for (int msk = 16; msk <= 32; msk <<= 1) {
; #pragma unroll
;                     for (int i = 0; i < 16; ++i) k1[i] = (unsigned)__shfl_xor((int)k0[i], msk);
;                     merge16(k0, k1); }
	v_max_u32_e32 v88, v88, v105
	v_max_u32_e32 v87, v87, v100
	v_max_u32_e32 v90, v90, v99
	v_max_u32_e32 v80, v80, v98
	v_max_u32_e32 v81, v81, v97
	v_max_u32_e32 v83, v83, v96
	v_max_u32_e32 v85, v85, v95
	v_max_u32_e32 v3, v3, v94
	v_max_u32_e32 v84, v84, v93
	v_max_u32_e32 v79, v79, v92
	v_max_u32_e32 v82, v82, v91
	v_max_u32_e32 v0, v0, v2
	v_max_u32_e32 v2, v1, v81
	v_min_u32_e32 v1, v1, v81
	v_max_u32_e32 v81, v78, v83
	v_min_u32_e32 v78, v78, v83
	v_max_u32_e32 v83, v89, v85
	v_min_u32_e32 v85, v89, v85
	v_max_u32_e32 v89, v86, v3
	v_min_u32_e32 v3, v86, v3
	v_max_u32_e32 v86, v88, v84
	v_min_u32_e32 v84, v88, v84
	v_max_u32_e32 v88, v87, v79
	v_min_u32_e32 v79, v87, v79
	v_max_u32_e32 v87, v90, v82
	v_min_u32_e32 v82, v90, v82
	v_max_u32_e32 v90, v80, v0
	v_min_u32_e32 v0, v80, v0
	v_max_u32_e32 v80, v2, v86
	v_min_u32_e32 v2, v2, v86
	v_max_u32_e32 v86, v81, v88
	v_min_u32_e32 v81, v81, v88
	v_max_u32_e32 v88, v83, v87
	v_min_u32_e32 v83, v83, v87
	v_max_u32_e32 v87, v89, v90
	v_min_u32_e32 v89, v89, v90
	v_max_u32_e32 v90, v1, v84
	v_min_u32_e32 v1, v1, v84
	v_max_u32_e32 v84, v78, v79
	v_min_u32_e32 v78, v78, v79
	v_max_u32_e32 v79, v85, v82
	v_min_u32_e32 v82, v85, v82
	v_max_u32_e32 v85, v3, v0
	v_min_u32_e32 v0, v3, v0
	v_max_u32_e32 v3, v80, v88
	v_min_u32_e32 v80, v80, v88
	v_max_u32_e32 v88, v86, v87
	v_min_u32_e32 v86, v86, v87
	v_max_u32_e32 v87, v2, v83
	v_min_u32_e32 v2, v2, v83
	v_max_u32_e32 v83, v81, v89
	v_min_u32_e32 v81, v81, v89
	v_max_u32_e32 v89, v90, v79
	v_min_u32_e32 v79, v90, v79
	v_max_u32_e32 v90, v84, v85
	v_min_u32_e32 v84, v84, v85
	v_max_u32_e32 v85, v1, v82
	v_min_u32_e32 v1, v1, v82
	v_max_u32_e32 v82, v78, v0
	v_min_u32_e32 v0, v78, v0
	v_max_u32_e32 v78, v3, v88
	v_min_u32_e32 v3, v3, v88
	v_max_u32_e32 v88, v80, v86
	v_min_u32_e32 v80, v80, v86
	v_max_u32_e32 v86, v87, v83
	v_min_u32_e32 v83, v87, v83
	v_max_u32_e32 v87, v2, v81
	v_min_u32_e32 v2, v2, v81
	v_max_u32_e32 v81, v89, v90
	v_min_u32_e32 v89, v89, v90
	v_max_u32_e32 v90, v79, v84
	v_min_u32_e32 v79, v79, v84
	v_max_u32_e32 v84, v85, v82
	v_min_u32_e32 v82, v85, v82
	v_max_u32_e32 v85, v1, v0
	v_min_u32_e32 v0, v1, v0
	ds_bpermute_b32 v94, v29, v0
	ds_bpermute_b32 v1, v29, v78
	ds_bpermute_b32 v91, v29, v3
	ds_bpermute_b32 v92, v29, v88
	ds_bpermute_b32 v93, v29, v80
	s_waitcnt lgkmcnt(4)
	v_max_u32_e32 v78, v78, v94
	global_load_dwordx4 v[94:97], v[4:5], off offset:1040
	global_load_dwordx4 v[98:101], v[4:5], off offset:1024
	ds_bpermute_b32 v102, v29, v86
	ds_bpermute_b32 v103, v29, v83
	ds_bpermute_b32 v104, v29, v87
	ds_bpermute_b32 v105, v29, v2
	ds_bpermute_b32 v106, v29, v81
	ds_bpermute_b32 v107, v29, v89
	ds_bpermute_b32 v108, v29, v90
	ds_bpermute_b32 v109, v29, v79
	ds_bpermute_b32 v110, v29, v84
	ds_bpermute_b32 v111, v29, v85
	ds_bpermute_b32 v112, v29, v82
	s_waitcnt lgkmcnt(4)
	v_max_u32_e32 v83, v83, v108
	s_waitcnt lgkmcnt(3)
	v_max_u32_e32 v86, v86, v109
	s_waitcnt lgkmcnt(2)
	v_max_u32_e32 v80, v80, v110
	s_waitcnt lgkmcnt(1)
	v_max_u32_e32 v3, v3, v111
	s_waitcnt lgkmcnt(0)
	v_max_u32_e32 v88, v88, v112
	v_max_u32_e32 v87, v87, v107
	v_max_u32_e32 v2, v2, v106
	v_max_u32_e32 v81, v81, v105
	v_max_u32_e32 v89, v89, v104
	v_max_u32_e32 v90, v90, v103
	v_max_u32_e32 v79, v79, v102
	v_max_u32_e32 v84, v84, v93
	v_max_u32_e32 v82, v82, v92
	v_max_u32_e32 v85, v85, v91
	v_max_u32_e32 v0, v0, v1
	v_max_u32_e32 v1, v78, v81
	v_min_u32_e32 v78, v78, v81
	v_max_u32_e32 v81, v3, v89
	v_min_u32_e32 v3, v3, v89
	v_max_u32_e32 v89, v88, v90
	v_min_u32_e32 v88, v88, v90
	v_max_u32_e32 v90, v80, v79
	v_min_u32_e32 v79, v80, v79
	v_max_u32_e32 v80, v86, v84
	v_min_u32_e32 v84, v86, v84
	v_max_u32_e32 v86, v83, v82
	v_min_u32_e32 v82, v83, v82
	v_max_u32_e32 v83, v87, v85
	v_min_u32_e32 v85, v87, v85
	v_max_u32_e32 v87, v2, v0
	v_min_u32_e32 v0, v2, v0
	v_max_u32_e32 v2, v1, v80
	v_min_u32_e32 v1, v1, v80
	v_max_u32_e32 v80, v81, v86
	v_min_u32_e32 v81, v81, v86
	v_max_u32_e32 v86, v89, v83
	v_min_u32_e32 v83, v89, v83
	v_max_u32_e32 v89, v90, v87
	v_min_u32_e32 v87, v90, v87
	v_max_u32_e32 v90, v78, v84
	v_min_u32_e32 v78, v78, v84
	v_max_u32_e32 v84, v3, v82
	v_min_u32_e32 v3, v3, v82
	v_max_u32_e32 v82, v88, v85
	v_min_u32_e32 v85, v88, v85
	v_max_u32_e32 v88, v79, v0
	v_min_u32_e32 v0, v79, v0
	v_max_u32_e32 v79, v2, v86
	v_min_u32_e32 v2, v2, v86
	v_max_u32_e32 v86, v80, v89
	v_min_u32_e32 v80, v80, v89
	v_max_u32_e32 v102, v1, v83
	v_min_u32_e32 v1, v1, v83
	v_max_u32_e32 v83, v81, v87
	v_min_u32_e32 v81, v81, v87
	v_max_u32_e32 v103, v90, v82
	v_min_u32_e32 v82, v90, v82
	v_max_u32_e32 v104, v84, v88
	v_min_u32_e32 v105, v84, v88
	v_max_u32_e32 v106, v78, v85
	v_min_u32_e32 v78, v78, v85
	v_max_u32_e32 v107, v3, v0
	v_min_u32_e32 v0, v3, v0
	v_max_u32_e32 v93, v79, v86
	v_min_u32_e32 v92, v79, v86
	v_max_u32_e32 v91, v2, v80
	v_min_u32_e32 v90, v2, v80
	v_max_u32_e32 v89, v102, v83
	v_min_u32_e32 v88, v102, v83
	v_max_u32_e32 v87, v1, v81
	v_min_u32_e32 v86, v1, v81
	v_max_u32_e32 v85, v103, v104
	v_min_u32_e32 v84, v103, v104
	v_max_u32_e32 v83, v82, v105
	v_min_u32_e32 v82, v82, v105
	v_max_u32_e32 v79, v78, v0
	v_min_u32_e32 v78, v78, v0
	global_load_dwordx4 v[0:3], v[4:5], off offset:1072
	global_load_dwordx4 v[102:105], v[4:5], off offset:1056
	v_max_u32_e32 v81, v106, v107
	v_min_u32_e32 v80, v106, v107
	s_waitcnt vmcnt(2)
; __device__ __forceinline__ unsigned f2key(float f) { const unsigned u = __float_as_uint(f); return (u & 0x80000000u) ? ~u : (u | 0x80000000u); }
; __device__ __forceinline__ void peer_tile(const Args& A, LAS unsigned char* lds, int tile) {
;     ...
;                 { const bf16_t* sp = QRY + m * 2048 + hp * 128 + 32 * g;
;                   const u32x4 s0 = *(const u32x4*)sp, s1 = *(const u32x4*)(sp + 8), s2 = *(const u32x4*)(sp + 16), s3 = *(const u32x4*)(sp + 24);
;                   const unsigned sw[16] = {s0.x, s0.y, s0.z, s0.w, s1.x, s1.y, s1.z, s1.w, s2.x, s2.y, s2.z, s2.w, s3.x, s3.y, s3.z, s3.w};
; #pragma unroll
;                   for (int i = 0; i < 16; ++i) {
;                       const float lo = (float)__builtin_bit_cast(_Float16, (unsigned short)(sw[i] & 0xffffu)), hi = (float)__builtin_bit_cast(_Float16, (unsigned short)(sw[i] >> 16));
;                       const unsigned klo = (f2key(lo) & ~127u) | (unsigned)(127 - (32 * g + 2 * i)), khi = (f2key(hi) & ~127u) | (unsigned)(127 - (32 * g + 2 * i + 1));
;                       if (i < 8) { k0[2 * i] = klo; k0[2 * i + 1] = khi; } else { k1[2 * (i - 8)] = klo; k1[2 * (i - 8) + 1] = khi; } } }
;     ...
;                 for (int i = 0; i < 16; ++i) L2[p][i] = (g & 2) ? ((g & 1) ? LA[3][p][i] : LA[2][p][i]) : ((g & 1) ? LA[1][p][i] : LA[0][p][i]);
	v_cvt_f32_f16_sdwa v106, v98 dst_sel:DWORD dst_unused:UNUSED_PAD src0_sel:WORD_1
	v_cvt_f32_f16_e32 v98, v98
	v_cndmask_b32_e64 v34, v66, v34, s[0:1]
	v_cndmask_b32_e64 v33, v65, v33, s[0:1]
	v_not_b32_e32 v107, v106
	v_or_b32_e32 v108, 0x80000000, v106
	v_cmp_gt_i32_e32 vcc, 0, v106
	v_cndmask_b32_e64 v32, v64, v32, s[0:1]
	v_cndmask_b32_e64 v31, v63, v31, s[0:1]
	v_cndmask_b32_e32 v106, v108, v107, vcc
	v_not_b32_e32 v107, v98
	v_or_b32_e32 v108, 0x80000000, v98
	v_cmp_gt_i32_e32 vcc, 0, v98
	v_and_b32_e32 v106, 0xffffff80, v106
	v_sub_u32_e32 v106, v106, v15
	v_cndmask_b32_e32 v98, v108, v107, vcc
	v_cvt_f32_f16_sdwa v107, v99 dst_sel:DWORD dst_unused:UNUSED_PAD src0_sel:WORD_1
	v_cvt_f32_f16_e32 v99, v99
	v_and_b32_e32 v98, 0xffffff80, v98
	v_sub_u32_e32 v98, v98, v15
	v_not_b32_e32 v108, v107
	v_or_b32_e32 v109, 0x80000000, v107
	v_cmp_gt_i32_e32 vcc, 0, v107
	v_add_u32_e32 v106, 0x7e, v106
	v_add_u32_e32 v98, 0x7f, v98
	v_cndmask_b32_e32 v107, v109, v108, vcc
	v_not_b32_e32 v108, v99
	v_or_b32_e32 v109, 0x80000000, v99
	v_cmp_gt_i32_e32 vcc, 0, v99
	v_and_b32_e32 v107, 0xffffff80, v107
	v_sub_u32_e32 v107, v107, v14
	v_cndmask_b32_e32 v99, v109, v108, vcc
	v_cvt_f32_f16_sdwa v108, v100 dst_sel:DWORD dst_unused:UNUSED_PAD src0_sel:WORD_1
	v_cvt_f32_f16_e32 v100, v100
	v_and_b32_e32 v99, 0xffffff80, v99
	v_sub_u32_e32 v99, v99, v14
	v_not_b32_e32 v109, v108
	v_or_b32_e32 v110, 0x80000000, v108
	v_cmp_gt_i32_e32 vcc, 0, v108
	v_add_u32_e32 v107, 0x7e, v107
	v_add_u32_e32 v99, 0x7f, v99
	v_cndmask_b32_e32 v108, v110, v109, vcc
	v_not_b32_e32 v109, v100
	v_or_b32_e32 v110, 0x80000000, v100
	v_cmp_gt_i32_e32 vcc, 0, v100
	v_and_b32_e32 v108, 0xffffff80, v108
	v_sub_u32_e32 v108, v108, v12
	v_cndmask_b32_e32 v100, v110, v109, vcc
	v_cvt_f32_f16_sdwa v109, v101 dst_sel:DWORD dst_unused:UNUSED_PAD src0_sel:WORD_1
	v_cvt_f32_f16_e32 v101, v101
	v_and_b32_e32 v100, 0xffffff80, v100
	v_sub_u32_e32 v100, v100, v12
	v_not_b32_e32 v110, v109
	v_or_b32_e32 v111, 0x80000000, v109
	v_cmp_gt_i32_e32 vcc, 0, v109
	v_add_u32_e32 v108, 0x7e, v108
	v_add_u32_e32 v100, 0x7f, v100
	v_cndmask_b32_e32 v109, v111, v110, vcc
	v_not_b32_e32 v110, v101
	v_or_b32_e32 v111, 0x80000000, v101
	v_cmp_gt_i32_e32 vcc, 0, v101
	v_and_b32_e32 v109, 0xffffff80, v109
	v_sub_u32_e32 v109, v109, v10
	v_cndmask_b32_e32 v101, v111, v110, vcc
	v_cvt_f32_f16_sdwa v110, v94 dst_sel:DWORD dst_unused:UNUSED_PAD src0_sel:WORD_1
	v_cvt_f32_f16_e32 v94, v94
	v_and_b32_e32 v101, 0xffffff80, v101
	v_sub_u32_e32 v101, v101, v10
	v_not_b32_e32 v111, v110
	v_or_b32_e32 v112, 0x80000000, v110
	v_cmp_gt_i32_e32 vcc, 0, v110
	v_add_u32_e32 v109, 0x7e, v109
	v_add_u32_e32 v101, 0x7f, v101
	v_cndmask_b32_e32 v110, v112, v111, vcc
	v_not_b32_e32 v111, v94
	v_or_b32_e32 v112, 0x80000000, v94
	v_cmp_gt_i32_e32 vcc, 0, v94
	v_and_b32_e32 v110, 0xffffff80, v110
	v_sub_u32_e32 v110, v110, v8
	v_cndmask_b32_e32 v94, v112, v111, vcc
	v_cvt_f32_f16_sdwa v111, v95 dst_sel:DWORD dst_unused:UNUSED_PAD src0_sel:WORD_1
	v_cvt_f32_f16_e32 v95, v95
	v_and_b32_e32 v94, 0xffffff80, v94
	v_sub_u32_e32 v94, v94, v8
	v_not_b32_e32 v112, v111
	v_or_b32_e32 v114, 0x80000000, v111
	v_cmp_gt_i32_e32 vcc, 0, v111
	v_add_u32_e32 v110, 0x7e, v110
	v_add_u32_e32 v94, 0x7f, v94
	v_cndmask_b32_e32 v111, v114, v112, vcc
	v_not_b32_e32 v112, v95
	v_or_b32_e32 v114, 0x80000000, v95
	v_cmp_gt_i32_e32 vcc, 0, v95
	v_and_b32_e32 v111, 0xffffff80, v111
	v_sub_u32_e32 v111, v111, v16
	v_cndmask_b32_e32 v95, v114, v112, vcc
	v_cvt_f32_f16_sdwa v112, v96 dst_sel:DWORD dst_unused:UNUSED_PAD src0_sel:WORD_1
	v_cvt_f32_f16_e32 v96, v96
	v_and_b32_e32 v95, 0xffffff80, v95
	v_sub_u32_e32 v95, v95, v16
	v_not_b32_e32 v114, v112
	v_or_b32_e32 v115, 0x80000000, v112
	v_cmp_gt_i32_e32 vcc, 0, v112
	v_add_u32_e32 v111, 0x7e, v111
	v_add_u32_e32 v95, 0x7f, v95
	v_cndmask_b32_e32 v112, v115, v114, vcc
	v_not_b32_e32 v114, v96
	v_or_b32_e32 v115, 0x80000000, v96
	v_cmp_gt_i32_e32 vcc, 0, v96
	v_and_b32_e32 v112, 0xffffff80, v112
	v_sub_u32_e32 v112, v112, v17
	v_cndmask_b32_e32 v96, v115, v114, vcc
	v_cvt_f32_f16_sdwa v114, v97 dst_sel:DWORD dst_unused:UNUSED_PAD src0_sel:WORD_1
	v_cvt_f32_f16_e32 v97, v97
	v_and_b32_e32 v96, 0xffffff80, v96
	v_sub_u32_e32 v96, v96, v17
	v_not_b32_e32 v115, v114
	v_or_b32_e32 v116, 0x80000000, v114
	v_cmp_gt_i32_e32 vcc, 0, v114
	v_add_u32_e32 v112, 0x7e, v112
	v_add_u32_e32 v96, 0x7f, v96
	v_cndmask_b32_e32 v114, v116, v115, vcc
	v_not_b32_e32 v115, v97
	v_or_b32_e32 v116, 0x80000000, v97
	v_cmp_gt_i32_e32 vcc, 0, v97
	v_and_b32_e32 v114, 0xffffff80, v114
	v_sub_u32_e32 v114, v114, v18
	v_cndmask_b32_e32 v97, v116, v115, vcc
	s_waitcnt vmcnt(0)
; __device__ __forceinline__ unsigned f2key(float f) { const unsigned u = __float_as_uint(f); return (u & 0x80000000u) ? ~u : (u | 0x80000000u); }
; #define CE_DESC(a, b) do { const unsigned _mx = (a) > (b) ? (a) : (b), _mn = (a) > (b) ? (b) : (a); (a) = _mx; (b) = _mn; } while (0)
; __device__ __forceinline__ void sort16_desc(unsigned (&k)[16]) {
; #pragma unroll
;     for (int size = 2; size <= 16; size <<= 1)
; #pragma unroll
;         for (int stride = size >> 1; stride > 0; stride >>= 1)
; #pragma unroll
;             for (int i = 0; i < 16; ++i) { const int j = i ^ stride;
;                 if (j > i) { if ((i & size) == 0) CE_DESC(k[i], k[j]); else CE_DESC(k[j], k[i]); } }
; }
; __device__ __forceinline__ void peer_tile(const Args& A, LAS unsigned char* lds, int tile) {
;     ...
;                 { const bf16_t* sp = QRY + m * 2048 + hp * 128 + 32 * g;
;                   const u32x4 s0 = *(const u32x4*)sp, s1 = *(const u32x4*)(sp + 8), s2 = *(const u32x4*)(sp + 16), s3 = *(const u32x4*)(sp + 24);
;                   const unsigned sw[16] = {s0.x, s0.y, s0.z, s0.w, s1.x, s1.y, s1.z, s1.w, s2.x, s2.y, s2.z, s2.w, s3.x, s3.y, s3.z, s3.w};
; #pragma unroll
;                   for (int i = 0; i < 16; ++i) {
;                       const float lo = (float)__builtin_bit_cast(_Float16, (unsigned short)(sw[i] & 0xffffu)), hi = (float)__builtin_bit_cast(_Float16, (unsigned short)(sw[i] >> 16));
;                       const unsigned klo = (f2key(lo) & ~127u) | (unsigned)(127 - (32 * g + 2 * i)), khi = (f2key(hi) & ~127u) | (unsigned)(127 - (32 * g + 2 * i + 1));
;                       if (i < 8) { k0[2 * i] = klo; k0[2 * i + 1] = khi; } else { k1[2 * (i - 8)] = klo; k1[2 * (i - 8) + 1] = khi; } } }
	v_cvt_f32_f16_sdwa v115, v102 dst_sel:DWORD dst_unused:UNUSED_PAD src0_sel:WORD_1
	v_cvt_f32_f16_e32 v102, v102
	v_and_b32_e32 v97, 0xffffff80, v97
	v_sub_u32_e32 v97, v97, v18
	v_not_b32_e32 v116, v115
	v_or_b32_e32 v117, 0x80000000, v115
	v_cmp_gt_i32_e32 vcc, 0, v115
	v_add_u32_e32 v114, 0x7e, v114
	v_add_u32_e32 v97, 0x7f, v97
	v_cndmask_b32_e32 v115, v117, v116, vcc
	v_not_b32_e32 v116, v102
	v_or_b32_e32 v117, 0x80000000, v102
	v_cmp_gt_i32_e32 vcc, 0, v102
	v_and_b32_e32 v115, 0xffffff80, v115
	v_sub_u32_e32 v115, v115, v20
	v_cndmask_b32_e32 v102, v117, v116, vcc
	v_cvt_f32_f16_sdwa v116, v103 dst_sel:DWORD dst_unused:UNUSED_PAD src0_sel:WORD_1
	v_cvt_f32_f16_e32 v103, v103
	v_and_b32_e32 v102, 0xffffff80, v102
	v_sub_u32_e32 v102, v102, v20
	v_not_b32_e32 v117, v116
	v_or_b32_e32 v118, 0x80000000, v116
	v_cmp_gt_i32_e32 vcc, 0, v116
	v_add_u32_e32 v115, 0x7e, v115
	v_add_u32_e32 v102, 0x7f, v102
	v_cndmask_b32_e32 v116, v118, v117, vcc
	v_not_b32_e32 v117, v103
	v_or_b32_e32 v118, 0x80000000, v103
	v_cmp_gt_i32_e32 vcc, 0, v103
	v_and_b32_e32 v116, 0xffffff80, v116
	v_sub_u32_e32 v116, v116, v21
	v_cndmask_b32_e32 v103, v118, v117, vcc
	v_cvt_f32_f16_sdwa v117, v104 dst_sel:DWORD dst_unused:UNUSED_PAD src0_sel:WORD_1
	v_cvt_f32_f16_e32 v104, v104
	v_and_b32_e32 v103, 0xffffff80, v103
	v_sub_u32_e32 v103, v103, v21
	v_not_b32_e32 v118, v117
	v_or_b32_e32 v119, 0x80000000, v117
	v_cmp_gt_i32_e32 vcc, 0, v117
	v_add_u32_e32 v116, 0x7e, v116
	v_add_u32_e32 v103, 0x7f, v103
	v_cndmask_b32_e32 v117, v119, v118, vcc
	v_not_b32_e32 v118, v104
	v_or_b32_e32 v119, 0x80000000, v104
	v_cmp_gt_i32_e32 vcc, 0, v104
	v_and_b32_e32 v117, 0xffffff80, v117
	v_sub_u32_e32 v117, v117, v22
	v_cndmask_b32_e32 v104, v119, v118, vcc
	v_cvt_f32_f16_sdwa v118, v105 dst_sel:DWORD dst_unused:UNUSED_PAD src0_sel:WORD_1
	v_cvt_f32_f16_e32 v105, v105
	v_and_b32_e32 v104, 0xffffff80, v104
	v_sub_u32_e32 v104, v104, v22
	v_not_b32_e32 v119, v118
	v_or_b32_e32 v120, 0x80000000, v118
	v_cmp_gt_i32_e32 vcc, 0, v118
	v_add_u32_e32 v117, 0x7e, v117
	v_add_u32_e32 v104, 0x7f, v104
	v_cndmask_b32_e32 v118, v120, v119, vcc
	v_not_b32_e32 v119, v105
	v_or_b32_e32 v120, 0x80000000, v105
	v_cmp_gt_i32_e32 vcc, 0, v105
	v_and_b32_e32 v118, 0xffffff80, v118
	v_sub_u32_e32 v118, v118, v23
	v_cndmask_b32_e32 v105, v120, v119, vcc
	v_cvt_f32_f16_sdwa v119, v0 dst_sel:DWORD dst_unused:UNUSED_PAD src0_sel:WORD_1
	v_cvt_f32_f16_e32 v0, v0
	v_and_b32_e32 v105, 0xffffff80, v105
	v_sub_u32_e32 v105, v105, v23
	v_not_b32_e32 v120, v119
	v_or_b32_e32 v121, 0x80000000, v119
	v_cmp_gt_i32_e32 vcc, 0, v119
	v_add_u32_e32 v118, 0x7e, v118
	v_add_u32_e32 v105, 0x7f, v105
	v_cndmask_b32_e32 v119, v121, v120, vcc
	v_not_b32_e32 v120, v0
	v_or_b32_e32 v121, 0x80000000, v0
	v_cmp_gt_i32_e32 vcc, 0, v0
	v_and_b32_e32 v119, 0xffffff80, v119
	v_sub_u32_e32 v119, v119, v24
	v_cndmask_b32_e32 v0, v121, v120, vcc
	v_cvt_f32_f16_sdwa v120, v1 dst_sel:DWORD dst_unused:UNUSED_PAD src0_sel:WORD_1
	v_cvt_f32_f16_e32 v1, v1
	v_and_b32_e32 v0, 0xffffff80, v0
	v_sub_u32_e32 v0, v0, v24
	v_not_b32_e32 v121, v120
	v_or_b32_e32 v122, 0x80000000, v120
	v_cmp_gt_i32_e32 vcc, 0, v120
	v_add_u32_e32 v119, 0x7e, v119
	v_add_u32_e32 v0, 0x7f, v0
	v_cndmask_b32_e32 v120, v122, v121, vcc
	v_not_b32_e32 v121, v1
	v_or_b32_e32 v122, 0x80000000, v1
	v_cmp_gt_i32_e32 vcc, 0, v1
	v_and_b32_e32 v120, 0xffffff80, v120
	v_sub_u32_e32 v120, v120, v25
	v_cndmask_b32_e32 v1, v122, v121, vcc
	v_cvt_f32_f16_sdwa v121, v2 dst_sel:DWORD dst_unused:UNUSED_PAD src0_sel:WORD_1
	v_cvt_f32_f16_e32 v2, v2
	v_and_b32_e32 v1, 0xffffff80, v1
	v_sub_u32_e32 v1, v1, v25
	v_not_b32_e32 v122, v121
	v_or_b32_e32 v123, 0x80000000, v121
	v_cmp_gt_i32_e32 vcc, 0, v121
	v_add_u32_e32 v120, 0x7e, v120
	v_add_u32_e32 v1, 0x7f, v1
	v_cndmask_b32_e32 v121, v123, v122, vcc
	v_not_b32_e32 v122, v2
	v_or_b32_e32 v123, 0x80000000, v2
	v_cmp_gt_i32_e32 vcc, 0, v2
	v_and_b32_e32 v121, 0xffffff80, v121
	v_sub_u32_e32 v121, v121, v26
	v_cndmask_b32_e32 v2, v123, v122, vcc
	v_cvt_f32_f16_sdwa v122, v3 dst_sel:DWORD dst_unused:UNUSED_PAD src0_sel:WORD_1
	v_cvt_f32_f16_e32 v3, v3
	v_and_b32_e32 v2, 0xffffff80, v2
	v_sub_u32_e32 v2, v2, v26
	v_not_b32_e32 v123, v122
	v_or_b32_e32 v124, 0x80000000, v122
	v_cmp_gt_i32_e32 vcc, 0, v122
	v_add_u32_e32 v121, 0x7e, v121
	v_add_u32_e32 v2, 0x7f, v2
	v_cndmask_b32_e32 v122, v124, v123, vcc
	v_not_b32_e32 v123, v3
	v_or_b32_e32 v124, 0x80000000, v3
	v_cmp_gt_i32_e32 vcc, 0, v3
	v_and_b32_e32 v122, 0xffffff80, v122
	v_sub_u32_e32 v122, v122, v28
	v_cndmask_b32_e32 v3, v124, v123, vcc
	v_and_b32_e32 v3, 0xffffff80, v3
	v_sub_u32_e32 v3, v3, v28
	v_add_u32_e32 v122, 0x7e, v122
	v_add_u32_e32 v3, 0x7f, v3
	v_max_u32_e32 v123, v98, v106
	v_min_u32_e32 v98, v98, v106
	v_max_u32_e32 v106, v107, v99
	v_min_u32_e32 v99, v107, v99
	v_max_u32_e32 v107, v100, v108
	v_min_u32_e32 v100, v100, v108
	v_max_u32_e32 v108, v109, v101
	v_min_u32_e32 v101, v109, v101
	v_max_u32_e32 v109, v94, v110
	v_min_u32_e32 v94, v94, v110
	v_max_u32_e32 v110, v111, v95
	v_min_u32_e32 v95, v111, v95
	v_max_u32_e32 v111, v96, v112
	v_min_u32_e32 v96, v96, v112
	v_max_u32_e32 v112, v114, v97
	v_min_u32_e32 v97, v114, v97
	v_max_u32_e32 v131, v102, v115
	v_min_u32_e32 v102, v102, v115
	v_max_u32_e32 v115, v116, v103
	v_min_u32_e32 v103, v116, v103
	v_max_u32_e32 v116, v104, v117
	v_min_u32_e32 v104, v104, v117
	v_max_u32_e32 v117, v118, v105
	v_min_u32_e32 v105, v118, v105
	v_max_u32_e32 v118, v0, v119
	v_min_u32_e32 v0, v0, v119
	v_max_u32_e32 v119, v120, v1
	v_min_u32_e32 v1, v120, v1
	v_max_u32_e32 v120, v2, v121
	v_min_u32_e32 v2, v2, v121
; #define CE_DESC(a, b) do { const unsigned _mx = (a) > (b) ? (a) : (b), _mn = (a) > (b) ? (b) : (a); (a) = _mx; (b) = _mn; } while (0)
; __device__ __forceinline__ void sort16_desc(unsigned (&k)[16]) {
; #pragma unroll
;     for (int size = 2; size <= 16; size <<= 1)
; #pragma unroll
;         for (int stride = size >> 1; stride > 0; stride >>= 1)
; #pragma unroll
;             for (int i = 0; i < 16; ++i) { const int j = i ^ stride;
;                 if (j > i) { if ((i & size) == 0) CE_DESC(k[i], k[j]); else CE_DESC(k[j], k[i]); } }
; }
	v_max_u32_e32 v121, v122, v3
	v_min_u32_e32 v3, v122, v3
	v_max_u32_e32 v114, v123, v99
	v_min_u32_e32 v99, v123, v99
	v_max_u32_e32 v123, v98, v106
	v_min_u32_e32 v98, v98, v106
	v_max_u32_e32 v106, v101, v107
	v_min_u32_e32 v101, v101, v107
	v_max_u32_e32 v107, v108, v100
	v_min_u32_e32 v100, v108, v100
	v_max_u32_e32 v108, v109, v95
	v_min_u32_e32 v95, v109, v95
	v_max_u32_e32 v109, v94, v110
	v_min_u32_e32 v94, v94, v110
	v_max_u32_e32 v110, v97, v111
	v_min_u32_e32 v97, v97, v111
	v_max_u32_e32 v111, v112, v96
	v_min_u32_e32 v96, v112, v96
	v_max_u32_e32 v122, v131, v103
	v_min_u32_e32 v103, v131, v103
	v_max_u32_e32 v131, v102, v115
	v_min_u32_e32 v102, v102, v115
	v_max_u32_e32 v115, v105, v116
	v_min_u32_e32 v105, v105, v116
	v_max_u32_e32 v116, v117, v104
	v_min_u32_e32 v104, v117, v104
	v_max_u32_e32 v117, v118, v1
	v_min_u32_e32 v1, v118, v1
	v_max_u32_e32 v118, v0, v119
	v_min_u32_e32 v0, v0, v119
	v_max_u32_e32 v119, v3, v120
	v_min_u32_e32 v3, v3, v120
	v_max_u32_e32 v120, v121, v2
	v_min_u32_e32 v2, v121, v2
	v_max_u32_e32 v112, v114, v123
	v_min_u32_e32 v114, v114, v123
	v_max_u32_e32 v123, v99, v98
	v_min_u32_e32 v98, v99, v98
	v_max_u32_e32 v99, v100, v101
	v_min_u32_e32 v100, v100, v101
	v_max_u32_e32 v101, v107, v106
	v_min_u32_e32 v106, v107, v106
	v_max_u32_e32 v107, v108, v109
	v_min_u32_e32 v108, v108, v109
	v_max_u32_e32 v109, v95, v94
	v_min_u32_e32 v94, v95, v94
	v_max_u32_e32 v95, v96, v97
	v_min_u32_e32 v96, v96, v97
	v_max_u32_e32 v97, v111, v110
	v_min_u32_e32 v110, v111, v110
	v_max_u32_e32 v121, v122, v131
	v_min_u32_e32 v122, v122, v131
	v_max_u32_e32 v131, v103, v102
	v_min_u32_e32 v102, v103, v102
	v_max_u32_e32 v103, v104, v105
	v_min_u32_e32 v104, v104, v105
	v_max_u32_e32 v105, v116, v115
	v_min_u32_e32 v115, v116, v115
	v_max_u32_e32 v116, v117, v118
	v_min_u32_e32 v117, v117, v118
	v_max_u32_e32 v118, v1, v0
	v_min_u32_e32 v0, v1, v0
	v_max_u32_e32 v1, v2, v3
	v_min_u32_e32 v2, v2, v3
	v_max_u32_e32 v3, v120, v119
	v_min_u32_e32 v119, v120, v119
	v_max_u32_e32 v111, v112, v100
	v_min_u32_e32 v100, v112, v100
	v_max_u32_e32 v112, v114, v99
	v_min_u32_e32 v99, v114, v99
	v_max_u32_e32 v114, v123, v106
	v_min_u32_e32 v106, v123, v106
	v_max_u32_e32 v123, v98, v101
	v_min_u32_e32 v98, v98, v101
	v_max_u32_e32 v101, v96, v107
	v_min_u32_e32 v96, v96, v107
	v_max_u32_e32 v107, v95, v108
	v_min_u32_e32 v95, v95, v108
	v_max_u32_e32 v108, v110, v109
	v_min_u32_e32 v109, v110, v109
	v_max_u32_e32 v110, v97, v94
	v_min_u32_e32 v94, v97, v94
	v_max_u32_e32 v120, v121, v104
	v_min_u32_e32 v104, v121, v104
	v_max_u32_e32 v121, v122, v103
	v_min_u32_e32 v103, v122, v103
	v_max_u32_e32 v122, v131, v115
	v_min_u32_e32 v115, v131, v115
	v_max_u32_e32 v131, v102, v105
	v_min_u32_e32 v102, v102, v105
	v_max_u32_e32 v105, v2, v116
	v_min_u32_e32 v2, v2, v116
	v_max_u32_e32 v116, v1, v117
	v_min_u32_e32 v1, v1, v117
	v_max_u32_e32 v117, v119, v118
	v_min_u32_e32 v118, v119, v118
	v_max_u32_e32 v119, v3, v0
	v_min_u32_e32 v0, v3, v0
	v_max_u32_e32 v97, v111, v114
	v_min_u32_e32 v111, v111, v114
	v_max_u32_e32 v114, v112, v123
	v_min_u32_e32 v112, v112, v123
	v_max_u32_e32 v123, v100, v106
	v_min_u32_e32 v100, v100, v106
	v_max_u32_e32 v106, v99, v98
	v_min_u32_e32 v98, v99, v98
	v_max_u32_e32 v99, v109, v96
	v_min_u32_e32 v96, v109, v96
	v_max_u32_e32 v109, v94, v95
	v_min_u32_e32 v94, v94, v95
	v_max_u32_e32 v95, v108, v101
	v_min_u32_e32 v101, v108, v101
	v_max_u32_e32 v108, v110, v107
	v_min_u32_e32 v107, v110, v107
	v_max_u32_e32 v3, v120, v122
	v_min_u32_e32 v120, v120, v122
	v_max_u32_e32 v122, v121, v131
	v_min_u32_e32 v121, v121, v131
	v_max_u32_e32 v131, v104, v115
	v_min_u32_e32 v104, v104, v115
	v_max_u32_e32 v115, v103, v102
	v_min_u32_e32 v102, v103, v102
	v_max_u32_e32 v103, v118, v2
	v_min_u32_e32 v2, v118, v2
	v_max_u32_e32 v118, v0, v1
	v_min_u32_e32 v0, v0, v1
	v_max_u32_e32 v1, v117, v105
	v_min_u32_e32 v105, v117, v105
	v_max_u32_e32 v117, v119, v116
	v_min_u32_e32 v116, v119, v116
	v_max_u32_e32 v110, v97, v114
	v_min_u32_e32 v97, v97, v114
	v_max_u32_e32 v114, v111, v112
	v_min_u32_e32 v111, v111, v112
	v_max_u32_e32 v112, v123, v106
	v_min_u32_e32 v106, v123, v106
	v_max_u32_e32 v123, v100, v98
	v_min_u32_e32 v98, v100, v98
	v_max_u32_e32 v100, v94, v96
	v_min_u32_e32 v94, v94, v96
	v_max_u32_e32 v96, v109, v99
	v_min_u32_e32 v99, v109, v99
	v_max_u32_e32 v109, v107, v101
	v_min_u32_e32 v101, v107, v101
	v_max_u32_e32 v107, v108, v95
	v_min_u32_e32 v95, v108, v95
	v_max_u32_e32 v119, v3, v122
	v_min_u32_e32 v3, v3, v122
	v_max_u32_e32 v122, v120, v121
	v_min_u32_e32 v120, v120, v121
	v_max_u32_e32 v121, v131, v115
	v_min_u32_e32 v115, v131, v115
	v_max_u32_e32 v131, v104, v102
	v_min_u32_e32 v102, v104, v102
	v_max_u32_e32 v104, v0, v2
	v_min_u32_e32 v0, v0, v2
	v_max_u32_e32 v2, v118, v103
	v_min_u32_e32 v103, v118, v103
	v_max_u32_e32 v118, v116, v105
	v_min_u32_e32 v105, v116, v105
	v_max_u32_e32 v116, v117, v1
	v_min_u32_e32 v1, v117, v1
	v_max_u32_e32 v108, v110, v94
	v_min_u32_e32 v94, v110, v94
	v_max_u32_e32 v110, v97, v100
	v_min_u32_e32 v97, v97, v100
	v_max_u32_e32 v100, v114, v99
	v_min_u32_e32 v99, v114, v99
	v_max_u32_e32 v114, v111, v96
	v_min_u32_e32 v96, v111, v96
	v_max_u32_e32 v111, v112, v101
	v_min_u32_e32 v101, v112, v101
	v_max_u32_e32 v112, v106, v109
	v_min_u32_e32 v106, v106, v109
	v_max_u32_e32 v109, v123, v95
	v_min_u32_e32 v95, v123, v95
	v_max_u32_e32 v123, v98, v107
	v_min_u32_e32 v98, v98, v107
	v_max_u32_e32 v117, v119, v0
	v_min_u32_e32 v0, v119, v0
	v_max_u32_e32 v119, v3, v104
	v_min_u32_e32 v3, v3, v104
	v_max_u32_e32 v104, v122, v103
	v_min_u32_e32 v103, v122, v103
; #define CE_DESC(a, b) do { const unsigned _mx = (a) > (b) ? (a) : (b), _mn = (a) > (b) ? (b) : (a); (a) = _mx; (b) = _mn; } while (0)
; __device__ __forceinline__ void sort16_desc(unsigned (&k)[16]) {
; #pragma unroll
;     for (int size = 2; size <= 16; size <<= 1)
; #pragma unroll
;         for (int stride = size >> 1; stride > 0; stride >>= 1)
; #pragma unroll
;             for (int i = 0; i < 16; ++i) { const int j = i ^ stride;
;                 if (j > i) { if ((i & size) == 0) CE_DESC(k[i], k[j]); else CE_DESC(k[j], k[i]); } }
; }
; __device__ __forceinline__ void merge16(unsigned (&a)[16], const unsigned (&b)[16]) {
; #pragma unroll
;     for (int i = 0; i < 16; ++i) a[i] = a[i] > b[15 - i] ? a[i] : b[15 - i];
; #pragma unroll
;     for (int stride = 8; stride > 0; stride >>= 1)
; #pragma unroll
;         for (int i = 0; i < 16; ++i) { const int j = i ^ stride; if (j > i) CE_DESC(a[i], a[j]); }
; }
; __device__ __forceinline__ void peer_tile(const Args& A, LAS unsigned char* lds, int tile) {
;     ...
;                 sort16_desc(k0); sort16_desc(k1); merge16(k0, k1);
; #pragma unroll
;                 for (int msk = 16; msk <= 32; msk <<= 1) {
; #pragma unroll
;                     for (int i = 0; i < 16; ++i) k1[i] = (unsigned)__shfl_xor((int)k0[i], msk);
;                     merge16(k0, k1); }
	v_max_u32_e32 v122, v120, v2
	v_min_u32_e32 v2, v120, v2
	v_max_u32_e32 v120, v121, v105
	v_min_u32_e32 v105, v121, v105
	v_max_u32_e32 v121, v115, v118
	v_min_u32_e32 v115, v115, v118
	v_max_u32_e32 v118, v131, v1
	v_min_u32_e32 v1, v131, v1
	v_max_u32_e32 v131, v102, v116
	v_min_u32_e32 v102, v102, v116
	v_max_u32_e32 v107, v108, v111
	v_min_u32_e32 v108, v108, v111
	v_max_u32_e32 v111, v110, v112
	v_min_u32_e32 v110, v110, v112
	v_max_u32_e32 v112, v100, v109
	v_min_u32_e32 v100, v100, v109
	v_max_u32_e32 v109, v114, v123
	v_min_u32_e32 v114, v114, v123
	v_max_u32_e32 v123, v94, v101
	v_min_u32_e32 v94, v94, v101
	v_max_u32_e32 v101, v97, v106
	v_min_u32_e32 v97, v97, v106
	v_max_u32_e32 v106, v99, v95
	v_min_u32_e32 v95, v99, v95
	v_max_u32_e32 v99, v96, v98
	v_min_u32_e32 v96, v96, v98
	v_max_u32_e32 v116, v117, v120
	v_min_u32_e32 v117, v117, v120
	v_max_u32_e32 v120, v119, v121
	v_min_u32_e32 v119, v119, v121
	v_max_u32_e32 v121, v104, v118
	v_min_u32_e32 v104, v104, v118
	v_max_u32_e32 v118, v122, v131
	v_min_u32_e32 v122, v122, v131
	v_max_u32_e32 v131, v0, v105
	v_min_u32_e32 v0, v0, v105
	v_max_u32_e32 v105, v3, v115
	v_min_u32_e32 v3, v3, v115
	v_max_u32_e32 v115, v103, v1
	v_min_u32_e32 v1, v103, v1
	v_max_u32_e32 v103, v2, v102
	v_min_u32_e32 v2, v2, v102
	v_max_u32_e32 v98, v107, v112
	v_min_u32_e32 v107, v107, v112
	v_max_u32_e32 v112, v111, v109
	v_min_u32_e32 v109, v111, v109
	v_max_u32_e32 v111, v108, v100
	v_min_u32_e32 v100, v108, v100
	v_max_u32_e32 v108, v110, v114
	v_min_u32_e32 v110, v110, v114
	v_max_u32_e32 v114, v123, v106
	v_min_u32_e32 v106, v123, v106
	v_max_u32_e32 v123, v101, v99
	v_min_u32_e32 v99, v101, v99
	v_max_u32_e32 v101, v94, v95
	v_min_u32_e32 v94, v94, v95
	v_max_u32_e32 v95, v97, v96
	v_min_u32_e32 v96, v97, v96
	v_max_u32_e32 v102, v116, v121
	v_min_u32_e32 v116, v116, v121
	v_max_u32_e32 v121, v120, v118
	v_min_u32_e32 v118, v120, v118
	v_max_u32_e32 v120, v117, v104
	v_min_u32_e32 v104, v117, v104
	v_max_u32_e32 v117, v119, v122
	v_min_u32_e32 v119, v119, v122
	v_max_u32_e32 v122, v131, v115
	v_min_u32_e32 v115, v131, v115
	v_max_u32_e32 v131, v105, v103
	v_min_u32_e32 v103, v105, v103
	v_max_u32_e32 v105, v0, v1
	v_min_u32_e32 v0, v0, v1
	v_max_u32_e32 v1, v3, v2
	v_min_u32_e32 v2, v3, v2
	v_min_u32_e32 v97, v98, v112
	v_min_u32_e32 v124, v107, v109
	v_min_u32_e32 v125, v111, v108
	v_min_u32_e32 v126, v100, v110
	v_min_u32_e32 v127, v114, v123
	v_min_u32_e32 v128, v106, v99
	v_min_u32_e32 v129, v101, v95
	v_min_u32_e32 v130, v94, v96
	v_min_u32_e32 v3, v102, v121
	v_min_u32_e32 v132, v116, v118
	v_min_u32_e32 v133, v120, v117
	v_min_u32_e32 v134, v104, v119
	v_min_u32_e32 v135, v122, v131
	v_min_u32_e32 v136, v115, v103
	v_min_u32_e32 v137, v105, v1
	v_min_u32_e32 v138, v0, v2
	v_max3_u32 v98, v98, v112, v138
	v_max3_u32 v0, v97, v0, v2
	v_max3_u32 v2, v107, v109, v137
	v_max3_u32 v1, v124, v105, v1
	v_max3_u32 v97, v111, v108, v136
	v_max3_u32 v103, v125, v115, v103
	v_max3_u32 v100, v100, v110, v135
	v_max3_u32 v105, v126, v122, v131
	v_max3_u32 v107, v114, v123, v134
	v_max3_u32 v104, v127, v104, v119
	v_max3_u32 v99, v106, v99, v133
	v_max3_u32 v106, v128, v120, v117
	v_max3_u32 v95, v101, v95, v132
	v_max3_u32 v101, v129, v116, v118
	v_max3_u32 v3, v94, v96, v3
	v_max3_u32 v94, v130, v102, v121
	v_max_u32_e32 v96, v98, v107
	v_min_u32_e32 v98, v98, v107
	v_max_u32_e32 v102, v0, v104
	v_min_u32_e32 v0, v0, v104
	v_max_u32_e32 v104, v2, v99
	v_min_u32_e32 v2, v2, v99
	v_max_u32_e32 v99, v1, v106
	v_min_u32_e32 v1, v1, v106
	v_max_u32_e32 v106, v97, v95
	v_min_u32_e32 v95, v97, v95
	v_max_u32_e32 v97, v103, v101
	v_min_u32_e32 v101, v103, v101
	v_max_u32_e32 v103, v100, v3
	v_min_u32_e32 v3, v100, v3
	v_max_u32_e32 v100, v105, v94
	v_min_u32_e32 v94, v105, v94
	v_max_u32_e32 v105, v96, v106
	v_min_u32_e32 v96, v96, v106
	v_max_u32_e32 v106, v102, v97
	v_min_u32_e32 v97, v102, v97
	v_max_u32_e32 v102, v104, v103
	v_min_u32_e32 v103, v104, v103
	v_max_u32_e32 v104, v99, v100
	v_min_u32_e32 v99, v99, v100
	v_max_u32_e32 v100, v98, v95
	v_min_u32_e32 v95, v98, v95
	v_max_u32_e32 v98, v0, v101
	v_min_u32_e32 v0, v0, v101
	v_max_u32_e32 v101, v2, v3
	v_min_u32_e32 v2, v2, v3
	v_max_u32_e32 v3, v1, v94
	v_min_u32_e32 v1, v1, v94
	v_max_u32_e32 v94, v105, v102
	v_min_u32_e32 v102, v105, v102
	v_max_u32_e32 v105, v106, v104
	v_min_u32_e32 v104, v106, v104
	v_max_u32_e32 v106, v96, v103
	v_min_u32_e32 v96, v96, v103
	v_max_u32_e32 v103, v97, v99
	v_min_u32_e32 v97, v97, v99
	v_max_u32_e32 v99, v100, v101
	v_min_u32_e32 v100, v100, v101
	v_max_u32_e32 v101, v98, v3
	v_min_u32_e32 v3, v98, v3
	v_max_u32_e32 v98, v95, v2
	v_min_u32_e32 v2, v95, v2
	v_max_u32_e32 v95, v0, v1
	v_min_u32_e32 v0, v0, v1
	v_max_u32_e32 v1, v94, v105
	v_min_u32_e32 v94, v94, v105
	v_max_u32_e32 v105, v102, v104
	v_min_u32_e32 v102, v102, v104
	v_max_u32_e32 v104, v106, v103
	v_min_u32_e32 v103, v106, v103
	v_max_u32_e32 v106, v96, v97
	v_min_u32_e32 v96, v96, v97
	v_max_u32_e32 v97, v99, v101
	v_min_u32_e32 v99, v99, v101
	v_max_u32_e32 v101, v100, v3
	v_min_u32_e32 v3, v100, v3
	v_max_u32_e32 v100, v98, v95
	v_min_u32_e32 v95, v98, v95
	v_max_u32_e32 v98, v2, v0
	v_min_u32_e32 v0, v2, v0
	ds_bpermute_b32 v2, v27, v1
	ds_bpermute_b32 v107, v27, v94
	ds_bpermute_b32 v108, v27, v105
	ds_bpermute_b32 v109, v27, v102
	ds_bpermute_b32 v110, v27, v104
	ds_bpermute_b32 v111, v27, v103
	ds_bpermute_b32 v112, v27, v106
	ds_bpermute_b32 v114, v27, v96
	ds_bpermute_b32 v115, v27, v97
	ds_bpermute_b32 v116, v27, v99
	ds_bpermute_b32 v117, v27, v101
	ds_bpermute_b32 v118, v27, v0
	ds_bpermute_b32 v119, v27, v98
	ds_bpermute_b32 v120, v27, v95
	ds_bpermute_b32 v121, v27, v100
	ds_bpermute_b32 v122, v27, v3
	s_waitcnt lgkmcnt(4)
; #define CE_DESC(a, b) do { const unsigned _mx = (a) > (b) ? (a) : (b), _mn = (a) > (b) ? (b) : (a); (a) = _mx; (b) = _mn; } while (0)
; __device__ __forceinline__ void sort16_desc(unsigned (&k)[16]) {
; #pragma unroll
;     for (int size = 2; size <= 16; size <<= 1)
; #pragma unroll
;         for (int stride = size >> 1; stride > 0; stride >>= 1)
; #pragma unroll
;             for (int i = 0; i < 16; ++i) { const int j = i ^ stride;
;                 if (j > i) { if ((i & size) == 0) CE_DESC(k[i], k[j]); else CE_DESC(k[j], k[i]); } }
; }
; __device__ __forceinline__ void merge16(unsigned (&a)[16], const unsigned (&b)[16]) {
; #pragma unroll
;     for (int i = 0; i < 16; ++i) a[i] = a[i] > b[15 - i] ? a[i] : b[15 - i];
; #pragma unroll
;     for (int stride = 8; stride > 0; stride >>= 1)
; #pragma unroll
;         for (int i = 0; i < 16; ++i) { const int j = i ^ stride; if (j > i) CE_DESC(a[i], a[j]); }
; }
; __device__ __forceinline__ void peer_tile(const Args& A, LAS unsigned char* lds, int tile) {
;     ...
;                 { const bf16_t* sp = QRY + m * 2048 + hp * 128 + 32 * g;
;                   const u32x4 s0 = *(const u32x4*)sp, s1 = *(const u32x4*)(sp + 8), s2 = *(const u32x4*)(sp + 16), s3 = *(const u32x4*)(sp + 24);
;     ...
;                 sort16_desc(k0); sort16_desc(k1); merge16(k0, k1);
; #pragma unroll
;                 for (int msk = 16; msk <= 32; msk <<= 1) {
; #pragma unroll
;                     for (int i = 0; i < 16; ++i) k1[i] = (unsigned)__shfl_xor((int)k0[i], msk);
;                     merge16(k0, k1); }
	v_max_u32_e32 v1, v1, v118
	s_waitcnt lgkmcnt(3)
	v_max_u32_e32 v94, v94, v119
	s_waitcnt lgkmcnt(2)
	v_max_u32_e32 v105, v105, v120
	s_waitcnt lgkmcnt(1)
	v_max_u32_e32 v102, v102, v121
	s_waitcnt lgkmcnt(0)
	v_max_u32_e32 v104, v104, v122
	v_max_u32_e32 v103, v103, v117
	v_max_u32_e32 v106, v106, v116
	v_max_u32_e32 v96, v96, v115
	v_max_u32_e32 v97, v97, v114
	v_max_u32_e32 v99, v99, v112
	v_max_u32_e32 v101, v101, v111
	v_max_u32_e32 v3, v3, v110
	v_max_u32_e32 v100, v100, v109
	v_max_u32_e32 v95, v95, v108
	v_max_u32_e32 v98, v98, v107
	v_max_u32_e32 v0, v0, v2
	v_max_u32_e32 v2, v1, v97
	v_min_u32_e32 v1, v1, v97
	v_max_u32_e32 v97, v94, v99
	v_min_u32_e32 v94, v94, v99
	v_max_u32_e32 v99, v105, v101
	v_min_u32_e32 v101, v105, v101
	v_max_u32_e32 v105, v102, v3
	v_min_u32_e32 v3, v102, v3
	v_max_u32_e32 v102, v104, v100
	v_min_u32_e32 v100, v104, v100
	v_max_u32_e32 v104, v103, v95
	v_min_u32_e32 v95, v103, v95
	v_max_u32_e32 v103, v106, v98
	v_min_u32_e32 v98, v106, v98
	v_max_u32_e32 v106, v96, v0
	v_min_u32_e32 v0, v96, v0
	v_max_u32_e32 v96, v2, v102
	v_min_u32_e32 v2, v2, v102
	v_max_u32_e32 v102, v97, v104
	v_min_u32_e32 v97, v97, v104
	v_max_u32_e32 v104, v99, v103
	v_min_u32_e32 v99, v99, v103
	v_max_u32_e32 v103, v105, v106
	v_min_u32_e32 v105, v105, v106
	v_max_u32_e32 v106, v1, v100
	v_min_u32_e32 v1, v1, v100
	v_max_u32_e32 v100, v94, v95
	v_min_u32_e32 v94, v94, v95
	v_max_u32_e32 v95, v101, v98
	v_min_u32_e32 v98, v101, v98
	v_max_u32_e32 v101, v3, v0
	v_min_u32_e32 v0, v3, v0
	v_max_u32_e32 v3, v96, v104
	v_min_u32_e32 v96, v96, v104
	v_max_u32_e32 v104, v102, v103
	v_min_u32_e32 v102, v102, v103
	v_max_u32_e32 v103, v2, v99
	v_min_u32_e32 v2, v2, v99
	v_max_u32_e32 v99, v97, v105
	v_min_u32_e32 v97, v97, v105
	v_max_u32_e32 v105, v106, v95
	v_min_u32_e32 v95, v106, v95
	v_max_u32_e32 v106, v100, v101
	v_min_u32_e32 v100, v100, v101
	v_max_u32_e32 v101, v1, v98
	v_min_u32_e32 v1, v1, v98
	v_max_u32_e32 v98, v94, v0
	v_min_u32_e32 v0, v94, v0
	v_max_u32_e32 v94, v3, v104
	v_min_u32_e32 v3, v3, v104
	v_max_u32_e32 v104, v96, v102
	v_min_u32_e32 v96, v96, v102
	v_max_u32_e32 v102, v103, v99
	v_min_u32_e32 v99, v103, v99
	v_max_u32_e32 v103, v2, v97
	v_min_u32_e32 v2, v2, v97
	v_max_u32_e32 v97, v105, v106
	v_min_u32_e32 v105, v105, v106
	v_max_u32_e32 v106, v95, v100
	v_min_u32_e32 v95, v95, v100
	v_max_u32_e32 v100, v101, v98
	v_min_u32_e32 v98, v101, v98
	v_max_u32_e32 v101, v1, v0
	v_min_u32_e32 v0, v1, v0
	ds_bpermute_b32 v114, v29, v0
	ds_bpermute_b32 v1, v29, v94
	ds_bpermute_b32 v107, v29, v3
	ds_bpermute_b32 v108, v29, v104
	ds_bpermute_b32 v109, v29, v96
	s_waitcnt lgkmcnt(4)
	v_max_u32_e32 v94, v94, v114
	global_load_dwordx4 v[114:117], v[4:5], off offset:1296
	global_load_dwordx4 v[118:121], v[4:5], off offset:1280
	ds_bpermute_b32 v110, v29, v102
	ds_bpermute_b32 v111, v29, v99
	ds_bpermute_b32 v112, v29, v103
	ds_bpermute_b32 v122, v29, v2
	ds_bpermute_b32 v123, v29, v97
	ds_bpermute_b32 v124, v29, v105
	ds_bpermute_b32 v125, v29, v106
	ds_bpermute_b32 v126, v29, v95
	ds_bpermute_b32 v127, v29, v100
	ds_bpermute_b32 v128, v29, v101
	ds_bpermute_b32 v129, v29, v98
	s_waitcnt lgkmcnt(4)
	v_max_u32_e32 v99, v99, v125
	s_waitcnt lgkmcnt(3)
	v_max_u32_e32 v102, v102, v126
	s_waitcnt lgkmcnt(2)
	v_max_u32_e32 v96, v96, v127
	s_waitcnt lgkmcnt(1)
	v_max_u32_e32 v3, v3, v128
	s_waitcnt lgkmcnt(0)
	v_max_u32_e32 v104, v104, v129
	v_max_u32_e32 v103, v103, v124
	v_max_u32_e32 v2, v2, v123
	v_max_u32_e32 v97, v97, v122
	v_max_u32_e32 v105, v105, v112
	v_max_u32_e32 v106, v106, v111
	v_max_u32_e32 v95, v95, v110
	v_max_u32_e32 v100, v100, v109
	v_max_u32_e32 v98, v98, v108
	v_max_u32_e32 v101, v101, v107
	v_max_u32_e32 v0, v0, v1
	v_max_u32_e32 v1, v94, v97
	v_min_u32_e32 v94, v94, v97
	v_max_u32_e32 v97, v3, v105
	v_min_u32_e32 v3, v3, v105
	v_max_u32_e32 v105, v104, v106
	v_min_u32_e32 v104, v104, v106
	v_max_u32_e32 v106, v96, v95
	v_min_u32_e32 v95, v96, v95
	v_max_u32_e32 v96, v102, v100
	v_min_u32_e32 v100, v102, v100
	v_max_u32_e32 v102, v99, v98
	v_min_u32_e32 v98, v99, v98
	v_max_u32_e32 v99, v103, v101
	v_min_u32_e32 v101, v103, v101
	v_max_u32_e32 v103, v2, v0
	v_min_u32_e32 v0, v2, v0
	v_max_u32_e32 v2, v1, v96
	v_min_u32_e32 v1, v1, v96
	v_max_u32_e32 v96, v97, v102
	v_min_u32_e32 v97, v97, v102
	v_max_u32_e32 v102, v105, v99
	v_min_u32_e32 v99, v105, v99
	v_max_u32_e32 v105, v106, v103
	v_min_u32_e32 v103, v106, v103
	v_max_u32_e32 v106, v94, v100
	v_min_u32_e32 v94, v94, v100
	v_max_u32_e32 v100, v3, v98
	v_min_u32_e32 v3, v3, v98
	v_max_u32_e32 v98, v104, v101
	v_min_u32_e32 v101, v104, v101
	v_max_u32_e32 v104, v95, v0
	v_min_u32_e32 v0, v95, v0
	v_max_u32_e32 v95, v2, v102
	v_min_u32_e32 v2, v2, v102
	v_max_u32_e32 v102, v96, v105
	v_min_u32_e32 v96, v96, v105
	v_max_u32_e32 v110, v1, v99
	v_min_u32_e32 v1, v1, v99
	v_max_u32_e32 v99, v97, v103
	v_min_u32_e32 v97, v97, v103
	v_max_u32_e32 v111, v106, v98
	v_min_u32_e32 v98, v106, v98
	v_min_u32_e32 v122, v100, v104
	v_max_u32_e32 v123, v94, v101
	v_min_u32_e32 v94, v94, v101
	v_max_u32_e32 v124, v3, v0
	v_min_u32_e32 v0, v3, v0
	v_max_u32_e32 v112, v100, v104
	v_max_u32_e32 v109, v95, v102
	v_min_u32_e32 v108, v95, v102
	v_max_u32_e32 v107, v2, v96
	v_min_u32_e32 v106, v2, v96
	v_max_u32_e32 v105, v110, v99
	v_min_u32_e32 v104, v110, v99
	v_max_u32_e32 v103, v1, v97
	v_min_u32_e32 v102, v1, v97
	v_max_u32_e32 v99, v98, v122
	v_min_u32_e32 v98, v98, v122
	v_max_u32_e32 v97, v123, v124
	v_min_u32_e32 v96, v123, v124
	v_max_u32_e32 v95, v94, v0
	v_min_u32_e32 v94, v94, v0
	global_load_dwordx4 v[0:3], v[4:5], off offset:1328
	global_load_dwordx4 v[122:125], v[4:5], off offset:1312
	s_waitcnt vmcnt(2)
; __device__ __forceinline__ unsigned f2key(float f) { const unsigned u = __float_as_uint(f); return (u & 0x80000000u) ? ~u : (u | 0x80000000u); }
; __device__ __forceinline__ void peer_tile(const Args& A, LAS unsigned char* lds, int tile) {
;     ...
;                 { const bf16_t* sp = QRY + m * 2048 + hp * 128 + 32 * g;
;                   const u32x4 s0 = *(const u32x4*)sp, s1 = *(const u32x4*)(sp + 8), s2 = *(const u32x4*)(sp + 16), s3 = *(const u32x4*)(sp + 24);
;                   const unsigned sw[16] = {s0.x, s0.y, s0.z, s0.w, s1.x, s1.y, s1.z, s1.w, s2.x, s2.y, s2.z, s2.w, s3.x, s3.y, s3.z, s3.w};
; #pragma unroll
;                   for (int i = 0; i < 16; ++i) {
;                       const float lo = (float)__builtin_bit_cast(_Float16, (unsigned short)(sw[i] & 0xffffu)), hi = (float)__builtin_bit_cast(_Float16, (unsigned short)(sw[i] >> 16));
;                       const unsigned klo = (f2key(lo) & ~127u) | (unsigned)(127 - (32 * g + 2 * i)), khi = (f2key(hi) & ~127u) | (unsigned)(127 - (32 * g + 2 * i + 1));
;                       if (i < 8) { k0[2 * i] = klo; k0[2 * i + 1] = khi; } else { k1[2 * (i - 8)] = klo; k1[2 * (i - 8) + 1] = khi; } } }
;     ...
;                 for (int i = 0; i < 16; ++i) L2[p][i] = (g & 2) ? ((g & 1) ? LA[3][p][i] : LA[2][p][i]) : ((g & 1) ? LA[1][p][i] : LA[0][p][i]);
	v_cvt_f32_f16_sdwa v110, v118 dst_sel:DWORD dst_unused:UNUSED_PAD src0_sel:WORD_1
	v_max_u32_e32 v101, v111, v112
	v_min_u32_e32 v100, v111, v112
	v_cvt_f32_f16_e32 v111, v118
	v_not_b32_e32 v112, v110
	v_or_b32_e32 v118, 0x80000000, v110
	v_cmp_gt_i32_e32 vcc, 0, v110
	v_cndmask_b32_e64 v30, v62, v30, s[0:1]
	s_nop 0
	v_cndmask_b32_e32 v110, v118, v112, vcc
	v_not_b32_e32 v112, v111
	v_or_b32_e32 v118, 0x80000000, v111
	v_cmp_gt_i32_e32 vcc, 0, v111
	v_and_b32_e32 v110, 0xffffff80, v110
	v_sub_u32_e32 v110, v110, v15
	v_cndmask_b32_e32 v111, v118, v112, vcc
	v_cvt_f32_f16_sdwa v112, v119 dst_sel:DWORD dst_unused:UNUSED_PAD src0_sel:WORD_1
	v_cvt_f32_f16_e32 v118, v119
	v_and_b32_e32 v111, 0xffffff80, v111
	v_sub_u32_e32 v111, v111, v15
	v_not_b32_e32 v119, v112
	v_or_b32_e32 v126, 0x80000000, v112
	v_cmp_gt_i32_e32 vcc, 0, v112
	v_add_u32_e32 v110, 0x7e, v110
	v_add_u32_e32 v111, 0x7f, v111
	v_cndmask_b32_e32 v112, v126, v119, vcc
	v_not_b32_e32 v119, v118
	v_or_b32_e32 v126, 0x80000000, v118
	v_cmp_gt_i32_e32 vcc, 0, v118
	v_and_b32_e32 v112, 0xffffff80, v112
	v_sub_u32_e32 v112, v112, v14
	v_cndmask_b32_e32 v118, v126, v119, vcc
	v_cvt_f32_f16_sdwa v119, v120 dst_sel:DWORD dst_unused:UNUSED_PAD src0_sel:WORD_1
	v_cvt_f32_f16_e32 v120, v120
	v_and_b32_e32 v118, 0xffffff80, v118
	v_sub_u32_e32 v118, v118, v14
	v_not_b32_e32 v126, v119
	v_or_b32_e32 v127, 0x80000000, v119
	v_cmp_gt_i32_e32 vcc, 0, v119
	v_add_u32_e32 v112, 0x7e, v112
	v_add_u32_e32 v118, 0x7f, v118
	v_cndmask_b32_e32 v119, v127, v126, vcc
	v_not_b32_e32 v126, v120
	v_or_b32_e32 v127, 0x80000000, v120
	v_cmp_gt_i32_e32 vcc, 0, v120
	v_and_b32_e32 v119, 0xffffff80, v119
	v_sub_u32_e32 v119, v119, v12
	v_cndmask_b32_e32 v120, v127, v126, vcc
	v_cvt_f32_f16_sdwa v126, v121 dst_sel:DWORD dst_unused:UNUSED_PAD src0_sel:WORD_1
	v_cvt_f32_f16_e32 v121, v121
	v_and_b32_e32 v120, 0xffffff80, v120
	v_sub_u32_e32 v120, v120, v12
	v_not_b32_e32 v127, v126
	v_or_b32_e32 v128, 0x80000000, v126
	v_cmp_gt_i32_e32 vcc, 0, v126
	v_add_u32_e32 v119, 0x7e, v119
	v_add_u32_e32 v120, 0x7f, v120
	v_cndmask_b32_e32 v126, v128, v127, vcc
	v_not_b32_e32 v127, v121
	v_or_b32_e32 v128, 0x80000000, v121
	v_cmp_gt_i32_e32 vcc, 0, v121
	v_and_b32_e32 v126, 0xffffff80, v126
	v_sub_u32_e32 v126, v126, v10
	v_cndmask_b32_e32 v121, v128, v127, vcc
	v_cvt_f32_f16_sdwa v127, v114 dst_sel:DWORD dst_unused:UNUSED_PAD src0_sel:WORD_1
	v_cvt_f32_f16_e32 v114, v114
	v_and_b32_e32 v121, 0xffffff80, v121
	v_sub_u32_e32 v121, v121, v10
	v_not_b32_e32 v128, v127
	v_or_b32_e32 v129, 0x80000000, v127
	v_cmp_gt_i32_e32 vcc, 0, v127
	v_add_u32_e32 v126, 0x7e, v126
	v_add_u32_e32 v121, 0x7f, v121
	v_cndmask_b32_e32 v127, v129, v128, vcc
	v_not_b32_e32 v128, v114
	v_or_b32_e32 v129, 0x80000000, v114
	v_cmp_gt_i32_e32 vcc, 0, v114
	v_and_b32_e32 v127, 0xffffff80, v127
	v_sub_u32_e32 v127, v127, v8
	v_cndmask_b32_e32 v114, v129, v128, vcc
	v_cvt_f32_f16_sdwa v128, v115 dst_sel:DWORD dst_unused:UNUSED_PAD src0_sel:WORD_1
	v_cvt_f32_f16_e32 v115, v115
	v_and_b32_e32 v114, 0xffffff80, v114
	v_sub_u32_e32 v114, v114, v8
	v_not_b32_e32 v129, v128
	v_or_b32_e32 v130, 0x80000000, v128
	v_cmp_gt_i32_e32 vcc, 0, v128
	v_add_u32_e32 v127, 0x7e, v127
	v_add_u32_e32 v114, 0x7f, v114
	v_cndmask_b32_e32 v128, v130, v129, vcc
	v_not_b32_e32 v129, v115
	v_or_b32_e32 v130, 0x80000000, v115
	v_cmp_gt_i32_e32 vcc, 0, v115
	v_and_b32_e32 v128, 0xffffff80, v128
	v_sub_u32_e32 v128, v128, v16
	v_cndmask_b32_e32 v115, v130, v129, vcc
	v_cvt_f32_f16_sdwa v129, v116 dst_sel:DWORD dst_unused:UNUSED_PAD src0_sel:WORD_1
	v_cvt_f32_f16_e32 v116, v116
	v_and_b32_e32 v115, 0xffffff80, v115
	v_sub_u32_e32 v115, v115, v16
	v_not_b32_e32 v130, v129
	v_or_b32_e32 v131, 0x80000000, v129
	v_cmp_gt_i32_e32 vcc, 0, v129
	v_add_u32_e32 v128, 0x7e, v128
	v_add_u32_e32 v115, 0x7f, v115
	v_cndmask_b32_e32 v129, v131, v130, vcc
	v_not_b32_e32 v130, v116
	v_or_b32_e32 v131, 0x80000000, v116
	v_cmp_gt_i32_e32 vcc, 0, v116
	v_and_b32_e32 v129, 0xffffff80, v129
	v_sub_u32_e32 v129, v129, v17
	v_cndmask_b32_e32 v116, v131, v130, vcc
	v_cvt_f32_f16_sdwa v130, v117 dst_sel:DWORD dst_unused:UNUSED_PAD src0_sel:WORD_1
	v_cvt_f32_f16_e32 v117, v117
	v_and_b32_e32 v116, 0xffffff80, v116
	v_sub_u32_e32 v116, v116, v17
	v_not_b32_e32 v131, v130
	v_or_b32_e32 v132, 0x80000000, v130
	v_cmp_gt_i32_e32 vcc, 0, v130
	v_add_u32_e32 v129, 0x7e, v129
	v_add_u32_e32 v116, 0x7f, v116
	v_cndmask_b32_e32 v130, v132, v131, vcc
	v_not_b32_e32 v131, v117
	v_or_b32_e32 v132, 0x80000000, v117
	v_cmp_gt_i32_e32 vcc, 0, v117
	v_and_b32_e32 v130, 0xffffff80, v130
	v_sub_u32_e32 v130, v130, v18
	v_cndmask_b32_e32 v117, v132, v131, vcc
	s_waitcnt vmcnt(0)
; __device__ __forceinline__ unsigned f2key(float f) { const unsigned u = __float_as_uint(f); return (u & 0x80000000u) ? ~u : (u | 0x80000000u); }
; #define CE_DESC(a, b) do { const unsigned _mx = (a) > (b) ? (a) : (b), _mn = (a) > (b) ? (b) : (a); (a) = _mx; (b) = _mn; } while (0)
; __device__ __forceinline__ void sort16_desc(unsigned (&k)[16]) {
; #pragma unroll
;     for (int size = 2; size <= 16; size <<= 1)
; #pragma unroll
;         for (int stride = size >> 1; stride > 0; stride >>= 1)
; #pragma unroll
;             for (int i = 0; i < 16; ++i) { const int j = i ^ stride;
;                 if (j > i) { if ((i & size) == 0) CE_DESC(k[i], k[j]); else CE_DESC(k[j], k[i]); } }
; }
; __device__ __forceinline__ void peer_tile(const Args& A, LAS unsigned char* lds, int tile) {
;     ...
;                 { const bf16_t* sp = QRY + m * 2048 + hp * 128 + 32 * g;
;                   const u32x4 s0 = *(const u32x4*)sp, s1 = *(const u32x4*)(sp + 8), s2 = *(const u32x4*)(sp + 16), s3 = *(const u32x4*)(sp + 24);
;                   const unsigned sw[16] = {s0.x, s0.y, s0.z, s0.w, s1.x, s1.y, s1.z, s1.w, s2.x, s2.y, s2.z, s2.w, s3.x, s3.y, s3.z, s3.w};
; #pragma unroll
;                   for (int i = 0; i < 16; ++i) {
;                       const float lo = (float)__builtin_bit_cast(_Float16, (unsigned short)(sw[i] & 0xffffu)), hi = (float)__builtin_bit_cast(_Float16, (unsigned short)(sw[i] >> 16));
;                       const unsigned klo = (f2key(lo) & ~127u) | (unsigned)(127 - (32 * g + 2 * i)), khi = (f2key(hi) & ~127u) | (unsigned)(127 - (32 * g + 2 * i + 1));
;                       if (i < 8) { k0[2 * i] = klo; k0[2 * i + 1] = khi; } else { k1[2 * (i - 8)] = klo; k1[2 * (i - 8) + 1] = khi; } } }
	v_cvt_f32_f16_sdwa v131, v122 dst_sel:DWORD dst_unused:UNUSED_PAD src0_sel:WORD_1
	v_cvt_f32_f16_e32 v122, v122
	v_and_b32_e32 v117, 0xffffff80, v117
	v_sub_u32_e32 v117, v117, v18
	v_not_b32_e32 v132, v131
	v_or_b32_e32 v133, 0x80000000, v131
	v_cmp_gt_i32_e32 vcc, 0, v131
	v_add_u32_e32 v130, 0x7e, v130
	v_add_u32_e32 v117, 0x7f, v117
	v_cndmask_b32_e32 v131, v133, v132, vcc
	v_not_b32_e32 v132, v122
	v_or_b32_e32 v133, 0x80000000, v122
	v_cmp_gt_i32_e32 vcc, 0, v122
	v_and_b32_e32 v131, 0xffffff80, v131
	v_sub_u32_e32 v131, v131, v20
	v_cndmask_b32_e32 v122, v133, v132, vcc
	v_cvt_f32_f16_sdwa v132, v123 dst_sel:DWORD dst_unused:UNUSED_PAD src0_sel:WORD_1
	v_cvt_f32_f16_e32 v123, v123
	v_and_b32_e32 v122, 0xffffff80, v122
	v_sub_u32_e32 v122, v122, v20
	v_not_b32_e32 v133, v132
	v_or_b32_e32 v134, 0x80000000, v132
	v_cmp_gt_i32_e32 vcc, 0, v132
	v_add_u32_e32 v131, 0x7e, v131
	v_add_u32_e32 v122, 0x7f, v122
	v_cndmask_b32_e32 v132, v134, v133, vcc
	v_not_b32_e32 v133, v123
	v_or_b32_e32 v134, 0x80000000, v123
	v_cmp_gt_i32_e32 vcc, 0, v123
	v_and_b32_e32 v132, 0xffffff80, v132
	v_sub_u32_e32 v132, v132, v21
	v_cndmask_b32_e32 v123, v134, v133, vcc
	v_cvt_f32_f16_sdwa v133, v124 dst_sel:DWORD dst_unused:UNUSED_PAD src0_sel:WORD_1
	v_cvt_f32_f16_e32 v124, v124
	v_and_b32_e32 v123, 0xffffff80, v123
	v_sub_u32_e32 v123, v123, v21
	v_not_b32_e32 v134, v133
	v_or_b32_e32 v135, 0x80000000, v133
	v_cmp_gt_i32_e32 vcc, 0, v133
	v_add_u32_e32 v132, 0x7e, v132
	v_add_u32_e32 v123, 0x7f, v123
	v_cndmask_b32_e32 v133, v135, v134, vcc
	v_not_b32_e32 v134, v124
	v_or_b32_e32 v135, 0x80000000, v124
	v_cmp_gt_i32_e32 vcc, 0, v124
	v_and_b32_e32 v133, 0xffffff80, v133
	v_sub_u32_e32 v133, v133, v22
	v_cndmask_b32_e32 v124, v135, v134, vcc
	v_cvt_f32_f16_sdwa v134, v125 dst_sel:DWORD dst_unused:UNUSED_PAD src0_sel:WORD_1
	v_cvt_f32_f16_e32 v125, v125
	v_and_b32_e32 v124, 0xffffff80, v124
	v_sub_u32_e32 v124, v124, v22
	v_not_b32_e32 v135, v134
	v_or_b32_e32 v136, 0x80000000, v134
	v_cmp_gt_i32_e32 vcc, 0, v134
	v_add_u32_e32 v133, 0x7e, v133
	v_add_u32_e32 v124, 0x7f, v124
	v_cndmask_b32_e32 v134, v136, v135, vcc
	v_not_b32_e32 v135, v125
	v_or_b32_e32 v136, 0x80000000, v125
	v_cmp_gt_i32_e32 vcc, 0, v125
	v_and_b32_e32 v134, 0xffffff80, v134
	v_sub_u32_e32 v134, v134, v23
	v_cndmask_b32_e32 v125, v136, v135, vcc
	v_cvt_f32_f16_sdwa v135, v0 dst_sel:DWORD dst_unused:UNUSED_PAD src0_sel:WORD_1
	v_cvt_f32_f16_e32 v0, v0
	v_and_b32_e32 v125, 0xffffff80, v125
	v_sub_u32_e32 v125, v125, v23
	v_not_b32_e32 v136, v135
	v_or_b32_e32 v137, 0x80000000, v135
	v_cmp_gt_i32_e32 vcc, 0, v135
	v_add_u32_e32 v134, 0x7e, v134
	v_add_u32_e32 v125, 0x7f, v125
	v_cndmask_b32_e32 v135, v137, v136, vcc
	v_not_b32_e32 v136, v0
	v_or_b32_e32 v137, 0x80000000, v0
	v_cmp_gt_i32_e32 vcc, 0, v0
	v_and_b32_e32 v135, 0xffffff80, v135
	v_sub_u32_e32 v135, v135, v24
	v_cndmask_b32_e32 v0, v137, v136, vcc
	v_cvt_f32_f16_sdwa v136, v1 dst_sel:DWORD dst_unused:UNUSED_PAD src0_sel:WORD_1
	v_cvt_f32_f16_e32 v1, v1
	v_and_b32_e32 v0, 0xffffff80, v0
	v_sub_u32_e32 v0, v0, v24
	v_not_b32_e32 v137, v136
	v_or_b32_e32 v138, 0x80000000, v136
	v_cmp_gt_i32_e32 vcc, 0, v136
	v_add_u32_e32 v135, 0x7e, v135
	v_add_u32_e32 v0, 0x7f, v0
	v_cndmask_b32_e32 v136, v138, v137, vcc
	v_not_b32_e32 v137, v1
	v_or_b32_e32 v138, 0x80000000, v1
	v_cmp_gt_i32_e32 vcc, 0, v1
	v_and_b32_e32 v136, 0xffffff80, v136
	v_sub_u32_e32 v136, v136, v25
	v_cndmask_b32_e32 v1, v138, v137, vcc
	v_cvt_f32_f16_sdwa v137, v2 dst_sel:DWORD dst_unused:UNUSED_PAD src0_sel:WORD_1
	v_cvt_f32_f16_e32 v2, v2
	v_and_b32_e32 v1, 0xffffff80, v1
	v_sub_u32_e32 v1, v1, v25
	v_not_b32_e32 v138, v137
	v_or_b32_e32 v139, 0x80000000, v137
	v_cmp_gt_i32_e32 vcc, 0, v137
	v_add_u32_e32 v136, 0x7e, v136
	v_add_u32_e32 v1, 0x7f, v1
	v_cndmask_b32_e32 v137, v139, v138, vcc
	v_not_b32_e32 v138, v2
	v_or_b32_e32 v139, 0x80000000, v2
	v_cmp_gt_i32_e32 vcc, 0, v2
	v_and_b32_e32 v137, 0xffffff80, v137
	v_sub_u32_e32 v137, v137, v26
	v_cndmask_b32_e32 v2, v139, v138, vcc
	v_cvt_f32_f16_sdwa v138, v3 dst_sel:DWORD dst_unused:UNUSED_PAD src0_sel:WORD_1
	v_cvt_f32_f16_e32 v3, v3
	v_and_b32_e32 v2, 0xffffff80, v2
	v_sub_u32_e32 v2, v2, v26
	v_not_b32_e32 v139, v138
	v_or_b32_e32 v140, 0x80000000, v138
	v_cmp_gt_i32_e32 vcc, 0, v138
	v_add_u32_e32 v137, 0x7e, v137
	v_add_u32_e32 v2, 0x7f, v2
	v_cndmask_b32_e32 v138, v140, v139, vcc
	v_not_b32_e32 v139, v3
	v_or_b32_e32 v140, 0x80000000, v3
	v_cmp_gt_i32_e32 vcc, 0, v3
	v_and_b32_e32 v138, 0xffffff80, v138
	v_sub_u32_e32 v138, v138, v28
	v_cndmask_b32_e32 v3, v140, v139, vcc
	v_and_b32_e32 v3, 0xffffff80, v3
	v_sub_u32_e32 v3, v3, v28
	v_add_u32_e32 v138, 0x7e, v138
	v_add_u32_e32 v3, 0x7f, v3
	v_max_u32_e32 v139, v111, v110
	v_min_u32_e32 v110, v111, v110
	v_max_u32_e32 v111, v112, v118
	v_min_u32_e32 v112, v112, v118
	v_max_u32_e32 v118, v120, v119
	v_min_u32_e32 v119, v120, v119
	v_max_u32_e32 v120, v126, v121
	v_min_u32_e32 v121, v126, v121
	v_max_u32_e32 v126, v114, v127
	v_min_u32_e32 v114, v114, v127
	v_max_u32_e32 v127, v128, v115
	v_min_u32_e32 v115, v128, v115
	v_max_u32_e32 v128, v116, v129
	v_min_u32_e32 v116, v116, v129
	v_max_u32_e32 v129, v130, v117
	v_min_u32_e32 v117, v130, v117
	v_max_u32_e32 v147, v122, v131
	v_min_u32_e32 v122, v122, v131
	v_max_u32_e32 v131, v132, v123
	v_min_u32_e32 v123, v132, v123
	v_max_u32_e32 v132, v124, v133
	v_min_u32_e32 v124, v124, v133
	v_max_u32_e32 v133, v134, v125
	v_min_u32_e32 v125, v134, v125
	v_max_u32_e32 v134, v0, v135
	v_min_u32_e32 v0, v0, v135
	v_max_u32_e32 v135, v136, v1
	v_min_u32_e32 v1, v136, v1
	v_max_u32_e32 v136, v2, v137
	v_min_u32_e32 v2, v2, v137
; #define CE_DESC(a, b) do { const unsigned _mx = (a) > (b) ? (a) : (b), _mn = (a) > (b) ? (b) : (a); (a) = _mx; (b) = _mn; } while (0)
; __device__ __forceinline__ void sort16_desc(unsigned (&k)[16]) {
; #pragma unroll
;     for (int size = 2; size <= 16; size <<= 1)
; #pragma unroll
;         for (int stride = size >> 1; stride > 0; stride >>= 1)
; #pragma unroll
;             for (int i = 0; i < 16; ++i) { const int j = i ^ stride;
;                 if (j > i) { if ((i & size) == 0) CE_DESC(k[i], k[j]); else CE_DESC(k[j], k[i]); } }
; }
	v_max_u32_e32 v137, v138, v3
	v_min_u32_e32 v3, v138, v3
	v_max_u32_e32 v130, v139, v112
	v_min_u32_e32 v112, v139, v112
	v_max_u32_e32 v139, v110, v111
	v_min_u32_e32 v110, v110, v111
	v_max_u32_e32 v111, v121, v118
	v_min_u32_e32 v118, v121, v118
	v_max_u32_e32 v121, v120, v119
	v_min_u32_e32 v119, v120, v119
	v_max_u32_e32 v120, v126, v115
	v_min_u32_e32 v115, v126, v115
	v_max_u32_e32 v126, v114, v127
	v_min_u32_e32 v114, v114, v127
	v_max_u32_e32 v127, v117, v128
	v_min_u32_e32 v117, v117, v128
	v_max_u32_e32 v128, v129, v116
	v_min_u32_e32 v116, v129, v116
	v_max_u32_e32 v138, v147, v123
	v_min_u32_e32 v123, v147, v123
	v_max_u32_e32 v147, v122, v131
	v_min_u32_e32 v122, v122, v131
	v_max_u32_e32 v131, v125, v132
	v_min_u32_e32 v125, v125, v132
	v_max_u32_e32 v132, v133, v124
	v_min_u32_e32 v124, v133, v124
	v_max_u32_e32 v133, v134, v1
	v_min_u32_e32 v1, v134, v1
	v_max_u32_e32 v134, v0, v135
	v_min_u32_e32 v0, v0, v135
	v_max_u32_e32 v135, v3, v136
	v_min_u32_e32 v3, v3, v136
	v_max_u32_e32 v136, v137, v2
	v_min_u32_e32 v2, v137, v2
	v_max_u32_e32 v129, v130, v139
	v_min_u32_e32 v130, v130, v139
	v_max_u32_e32 v139, v112, v110
	v_min_u32_e32 v110, v112, v110
	v_max_u32_e32 v112, v119, v118
	v_min_u32_e32 v118, v119, v118
	v_max_u32_e32 v119, v121, v111
	v_min_u32_e32 v111, v121, v111
	v_max_u32_e32 v121, v120, v126
	v_min_u32_e32 v120, v120, v126
	v_max_u32_e32 v126, v115, v114
	v_min_u32_e32 v114, v115, v114
	v_max_u32_e32 v115, v116, v117
	v_min_u32_e32 v116, v116, v117
	v_max_u32_e32 v117, v128, v127
	v_min_u32_e32 v127, v128, v127
	v_max_u32_e32 v137, v138, v147
	v_min_u32_e32 v138, v138, v147
	v_max_u32_e32 v147, v123, v122
	v_min_u32_e32 v122, v123, v122
	v_max_u32_e32 v123, v124, v125
	v_min_u32_e32 v124, v124, v125
	v_max_u32_e32 v125, v132, v131
	v_min_u32_e32 v131, v132, v131
	v_max_u32_e32 v132, v133, v134
	v_min_u32_e32 v133, v133, v134
	v_max_u32_e32 v134, v1, v0
	v_min_u32_e32 v0, v1, v0
	v_max_u32_e32 v1, v2, v3
	v_min_u32_e32 v2, v2, v3
	v_max_u32_e32 v3, v136, v135
	v_min_u32_e32 v135, v136, v135
	v_max_u32_e32 v128, v129, v118
	v_min_u32_e32 v118, v129, v118
	v_max_u32_e32 v129, v130, v112
	v_min_u32_e32 v112, v130, v112
	v_max_u32_e32 v130, v139, v111
	v_min_u32_e32 v111, v139, v111
	v_max_u32_e32 v139, v110, v119
	v_min_u32_e32 v110, v110, v119
	v_max_u32_e32 v119, v116, v121
	v_min_u32_e32 v116, v116, v121
	v_max_u32_e32 v121, v115, v120
	v_min_u32_e32 v115, v115, v120
	v_max_u32_e32 v120, v127, v126
	v_min_u32_e32 v126, v127, v126
	v_max_u32_e32 v127, v117, v114
	v_min_u32_e32 v114, v117, v114
	v_max_u32_e32 v136, v137, v124
	v_min_u32_e32 v124, v137, v124
	v_max_u32_e32 v137, v138, v123
	v_min_u32_e32 v123, v138, v123
	v_max_u32_e32 v138, v147, v131
	v_min_u32_e32 v131, v147, v131
	v_max_u32_e32 v147, v122, v125
	v_min_u32_e32 v122, v122, v125
	v_max_u32_e32 v125, v2, v132
	v_min_u32_e32 v2, v2, v132
	v_max_u32_e32 v132, v1, v133
	v_min_u32_e32 v1, v1, v133
	v_max_u32_e32 v133, v135, v134
	v_min_u32_e32 v134, v135, v134
	v_max_u32_e32 v135, v3, v0
	v_min_u32_e32 v0, v3, v0
	v_max_u32_e32 v117, v128, v130
	v_min_u32_e32 v128, v128, v130
	v_max_u32_e32 v130, v129, v139
	v_min_u32_e32 v129, v129, v139
	v_max_u32_e32 v139, v118, v111
	v_min_u32_e32 v111, v118, v111
	v_max_u32_e32 v118, v112, v110
	v_min_u32_e32 v110, v112, v110
	v_max_u32_e32 v112, v126, v116
	v_min_u32_e32 v116, v126, v116
	v_max_u32_e32 v126, v114, v115
	v_min_u32_e32 v114, v114, v115
	v_max_u32_e32 v115, v120, v119
	v_min_u32_e32 v119, v120, v119
	v_max_u32_e32 v120, v127, v121
	v_min_u32_e32 v121, v127, v121
	v_max_u32_e32 v3, v136, v138
	v_min_u32_e32 v136, v136, v138
	v_max_u32_e32 v138, v137, v147
	v_min_u32_e32 v137, v137, v147
	v_max_u32_e32 v147, v124, v131
	v_min_u32_e32 v124, v124, v131
	v_max_u32_e32 v131, v123, v122
	v_min_u32_e32 v122, v123, v122
	v_max_u32_e32 v123, v134, v2
	v_min_u32_e32 v2, v134, v2
	v_max_u32_e32 v134, v0, v1
	v_min_u32_e32 v0, v0, v1
	v_max_u32_e32 v1, v133, v125
	v_min_u32_e32 v125, v133, v125
	v_max_u32_e32 v133, v135, v132
	v_min_u32_e32 v132, v135, v132
	v_max_u32_e32 v127, v117, v130
	v_min_u32_e32 v117, v117, v130
	v_max_u32_e32 v130, v128, v129
	v_min_u32_e32 v128, v128, v129
	v_max_u32_e32 v129, v139, v118
	v_min_u32_e32 v118, v139, v118
	v_max_u32_e32 v139, v111, v110
	v_min_u32_e32 v110, v111, v110
	v_max_u32_e32 v111, v114, v116
	v_min_u32_e32 v114, v114, v116
	v_max_u32_e32 v116, v126, v112
	v_min_u32_e32 v112, v126, v112
	v_max_u32_e32 v126, v121, v119
	v_min_u32_e32 v119, v121, v119
	v_max_u32_e32 v121, v120, v115
	v_min_u32_e32 v115, v120, v115
	v_max_u32_e32 v135, v3, v138
	v_min_u32_e32 v3, v3, v138
	v_max_u32_e32 v138, v136, v137
	v_min_u32_e32 v136, v136, v137
	v_max_u32_e32 v137, v147, v131
	v_min_u32_e32 v131, v147, v131
	v_max_u32_e32 v147, v124, v122
	v_min_u32_e32 v122, v124, v122
	v_max_u32_e32 v124, v0, v2
	v_min_u32_e32 v0, v0, v2
	v_max_u32_e32 v2, v134, v123
	v_min_u32_e32 v123, v134, v123
	v_max_u32_e32 v134, v132, v125
	v_min_u32_e32 v125, v132, v125
	v_max_u32_e32 v132, v133, v1
	v_min_u32_e32 v1, v133, v1
	v_max_u32_e32 v120, v127, v114
	v_min_u32_e32 v114, v127, v114
	v_max_u32_e32 v127, v117, v111
	v_min_u32_e32 v111, v117, v111
	v_max_u32_e32 v117, v130, v112
	v_min_u32_e32 v112, v130, v112
	v_max_u32_e32 v130, v128, v116
	v_min_u32_e32 v116, v128, v116
	v_max_u32_e32 v128, v129, v119
	v_min_u32_e32 v119, v129, v119
	v_max_u32_e32 v129, v118, v126
	v_min_u32_e32 v118, v118, v126
	v_max_u32_e32 v126, v139, v115
	v_min_u32_e32 v115, v139, v115
	v_max_u32_e32 v139, v110, v121
	v_min_u32_e32 v110, v110, v121
	v_max_u32_e32 v133, v135, v0
	v_min_u32_e32 v0, v135, v0
; #define CE_DESC(a, b) do { const unsigned _mx = (a) > (b) ? (a) : (b), _mn = (a) > (b) ? (b) : (a); (a) = _mx; (b) = _mn; } while (0)
; __device__ __forceinline__ void sort16_desc(unsigned (&k)[16]) {
; #pragma unroll
;     for (int size = 2; size <= 16; size <<= 1)
; #pragma unroll
;         for (int stride = size >> 1; stride > 0; stride >>= 1)
; #pragma unroll
;             for (int i = 0; i < 16; ++i) { const int j = i ^ stride;
;                 if (j > i) { if ((i & size) == 0) CE_DESC(k[i], k[j]); else CE_DESC(k[j], k[i]); } }
; }
; __device__ __forceinline__ void merge16(unsigned (&a)[16], const unsigned (&b)[16]) {
; #pragma unroll
;     for (int i = 0; i < 16; ++i) a[i] = a[i] > b[15 - i] ? a[i] : b[15 - i];
; #pragma unroll
;     for (int stride = 8; stride > 0; stride >>= 1)
; #pragma unroll
;         for (int i = 0; i < 16; ++i) { const int j = i ^ stride; if (j > i) CE_DESC(a[i], a[j]); }
; }
; __device__ __forceinline__ void peer_tile(const Args& A, LAS unsigned char* lds, int tile) {
;     ...
;                 sort16_desc(k0); sort16_desc(k1); merge16(k0, k1);
; #pragma unroll
;                 for (int msk = 16; msk <= 32; msk <<= 1) {
; #pragma unroll
;                     for (int i = 0; i < 16; ++i) k1[i] = (unsigned)__shfl_xor((int)k0[i], msk);
;                     merge16(k0, k1); }
	v_max_u32_e32 v135, v3, v124
	v_min_u32_e32 v3, v3, v124
	v_max_u32_e32 v124, v138, v123
	v_min_u32_e32 v123, v138, v123
	v_max_u32_e32 v138, v136, v2
	v_min_u32_e32 v2, v136, v2
	v_max_u32_e32 v136, v137, v125
	v_min_u32_e32 v125, v137, v125
	v_max_u32_e32 v137, v131, v134
	v_min_u32_e32 v131, v131, v134
	v_max_u32_e32 v134, v147, v1
	v_min_u32_e32 v1, v147, v1
	v_max_u32_e32 v147, v122, v132
	v_min_u32_e32 v122, v122, v132
	v_max_u32_e32 v121, v120, v128
	v_min_u32_e32 v120, v120, v128
	v_max_u32_e32 v128, v127, v129
	v_min_u32_e32 v127, v127, v129
	v_max_u32_e32 v129, v117, v126
	v_min_u32_e32 v117, v117, v126
	v_max_u32_e32 v126, v130, v139
	v_min_u32_e32 v130, v130, v139
	v_max_u32_e32 v139, v114, v119
	v_min_u32_e32 v114, v114, v119
	v_max_u32_e32 v119, v111, v118
	v_min_u32_e32 v111, v111, v118
	v_max_u32_e32 v118, v112, v115
	v_min_u32_e32 v112, v112, v115
	v_max_u32_e32 v115, v116, v110
	v_min_u32_e32 v110, v116, v110
	v_max_u32_e32 v132, v133, v136
	v_min_u32_e32 v133, v133, v136
	v_max_u32_e32 v136, v135, v137
	v_min_u32_e32 v135, v135, v137
	v_max_u32_e32 v137, v124, v134
	v_min_u32_e32 v124, v124, v134
	v_max_u32_e32 v134, v138, v147
	v_min_u32_e32 v138, v138, v147
	v_max_u32_e32 v147, v0, v125
	v_min_u32_e32 v0, v0, v125
	v_max_u32_e32 v125, v3, v131
	v_min_u32_e32 v3, v3, v131
	v_max_u32_e32 v131, v123, v1
	v_min_u32_e32 v1, v123, v1
	v_max_u32_e32 v123, v2, v122
	v_min_u32_e32 v2, v2, v122
	v_max_u32_e32 v116, v121, v129
	v_min_u32_e32 v121, v121, v129
	v_max_u32_e32 v129, v128, v126
	v_min_u32_e32 v126, v128, v126
	v_max_u32_e32 v128, v120, v117
	v_min_u32_e32 v117, v120, v117
	v_max_u32_e32 v120, v127, v130
	v_min_u32_e32 v127, v127, v130
	v_max_u32_e32 v130, v139, v118
	v_min_u32_e32 v118, v139, v118
	v_max_u32_e32 v139, v119, v115
	v_min_u32_e32 v115, v119, v115
	v_max_u32_e32 v119, v114, v112
	v_min_u32_e32 v112, v114, v112
	v_max_u32_e32 v114, v111, v110
	v_min_u32_e32 v110, v111, v110
	v_max_u32_e32 v122, v132, v137
	v_min_u32_e32 v132, v132, v137
	v_max_u32_e32 v137, v136, v134
	v_min_u32_e32 v134, v136, v134
	v_max_u32_e32 v136, v133, v124
	v_min_u32_e32 v124, v133, v124
	v_max_u32_e32 v133, v135, v138
	v_min_u32_e32 v135, v135, v138
	v_max_u32_e32 v138, v147, v131
	v_min_u32_e32 v131, v147, v131
	v_max_u32_e32 v147, v125, v123
	v_min_u32_e32 v123, v125, v123
	v_max_u32_e32 v125, v0, v1
	v_min_u32_e32 v0, v0, v1
	v_max_u32_e32 v1, v3, v2
	v_min_u32_e32 v2, v3, v2
	v_min_u32_e32 v111, v116, v129
	v_min_u32_e32 v140, v121, v126
	v_min_u32_e32 v141, v128, v120
	v_min_u32_e32 v142, v117, v127
	v_min_u32_e32 v143, v130, v139
	v_min_u32_e32 v144, v118, v115
	v_min_u32_e32 v145, v119, v114
	v_min_u32_e32 v146, v112, v110
	v_min_u32_e32 v3, v122, v137
	v_min_u32_e32 v148, v132, v134
	v_min_u32_e32 v149, v136, v133
	v_min_u32_e32 v150, v124, v135
	v_min_u32_e32 v151, v138, v147
	v_min_u32_e32 v152, v131, v123
	v_min_u32_e32 v153, v125, v1
	v_min_u32_e32 v154, v0, v2
	v_max3_u32 v116, v116, v129, v154
	v_max3_u32 v0, v111, v0, v2
	v_max3_u32 v2, v121, v126, v153
	v_max3_u32 v1, v140, v125, v1
	v_max3_u32 v111, v128, v120, v152
	v_max3_u32 v120, v141, v131, v123
	v_max3_u32 v117, v117, v127, v151
	v_max3_u32 v121, v142, v138, v147
	v_max3_u32 v123, v130, v139, v150
	v_max3_u32 v124, v143, v124, v135
	v_max3_u32 v115, v118, v115, v149
	v_max3_u32 v118, v144, v136, v133
	v_max3_u32 v114, v119, v114, v148
	v_max3_u32 v119, v145, v132, v134
	v_max3_u32 v3, v112, v110, v3
	v_max3_u32 v110, v146, v122, v137
	v_max_u32_e32 v112, v116, v123
	v_min_u32_e32 v116, v116, v123
	v_max_u32_e32 v122, v0, v124
	v_min_u32_e32 v0, v0, v124
	v_max_u32_e32 v123, v2, v115
	v_min_u32_e32 v2, v2, v115
	v_max_u32_e32 v115, v1, v118
	v_min_u32_e32 v1, v1, v118
	v_max_u32_e32 v118, v111, v114
	v_min_u32_e32 v111, v111, v114
	v_max_u32_e32 v114, v120, v119
	v_min_u32_e32 v119, v120, v119
	v_max_u32_e32 v120, v117, v3
	v_min_u32_e32 v3, v117, v3
	v_max_u32_e32 v117, v121, v110
	v_min_u32_e32 v110, v121, v110
	v_max_u32_e32 v121, v112, v118
	v_min_u32_e32 v112, v112, v118
	v_max_u32_e32 v118, v122, v114
	v_min_u32_e32 v114, v122, v114
	v_max_u32_e32 v122, v123, v120
	v_min_u32_e32 v120, v123, v120
	v_max_u32_e32 v123, v115, v117
	v_min_u32_e32 v115, v115, v117
	v_max_u32_e32 v117, v116, v111
	v_min_u32_e32 v111, v116, v111
	v_max_u32_e32 v116, v0, v119
	v_min_u32_e32 v0, v0, v119
	v_max_u32_e32 v119, v2, v3
	v_min_u32_e32 v2, v2, v3
	v_max_u32_e32 v3, v1, v110
	v_min_u32_e32 v1, v1, v110
	v_max_u32_e32 v110, v121, v122
	v_min_u32_e32 v121, v121, v122
	v_max_u32_e32 v122, v118, v123
	v_min_u32_e32 v118, v118, v123
	v_max_u32_e32 v123, v112, v120
	v_min_u32_e32 v112, v112, v120
	v_max_u32_e32 v120, v114, v115
	v_min_u32_e32 v114, v114, v115
	v_max_u32_e32 v115, v117, v119
	v_min_u32_e32 v117, v117, v119
	v_max_u32_e32 v119, v116, v3
	v_min_u32_e32 v3, v116, v3
	v_max_u32_e32 v116, v111, v2
	v_min_u32_e32 v2, v111, v2
	v_max_u32_e32 v111, v0, v1
	v_min_u32_e32 v0, v0, v1
	v_max_u32_e32 v1, v110, v122
	v_min_u32_e32 v110, v110, v122
	v_max_u32_e32 v122, v121, v118
	v_min_u32_e32 v118, v121, v118
	v_max_u32_e32 v121, v123, v120
	v_min_u32_e32 v120, v123, v120
	v_max_u32_e32 v123, v112, v114
	v_min_u32_e32 v112, v112, v114
	v_max_u32_e32 v114, v115, v119
	v_min_u32_e32 v115, v115, v119
	v_max_u32_e32 v119, v117, v3
	v_min_u32_e32 v3, v117, v3
	v_max_u32_e32 v117, v116, v111
	v_min_u32_e32 v111, v116, v111
	v_max_u32_e32 v116, v2, v0
	v_min_u32_e32 v0, v2, v0
	ds_bpermute_b32 v2, v27, v1
	ds_bpermute_b32 v124, v27, v110
	ds_bpermute_b32 v125, v27, v122
	ds_bpermute_b32 v126, v27, v118
	ds_bpermute_b32 v127, v27, v121
	ds_bpermute_b32 v128, v27, v120
	ds_bpermute_b32 v129, v27, v123
	ds_bpermute_b32 v130, v27, v112
	ds_bpermute_b32 v131, v27, v114
	ds_bpermute_b32 v132, v27, v115
	ds_bpermute_b32 v133, v27, v119
	ds_bpermute_b32 v134, v27, v0
	ds_bpermute_b32 v135, v27, v116
	ds_bpermute_b32 v136, v27, v111
	ds_bpermute_b32 v137, v27, v117
	ds_bpermute_b32 v138, v27, v3
	s_waitcnt lgkmcnt(4)
; #define CE_DESC(a, b) do { const unsigned _mx = (a) > (b) ? (a) : (b), _mn = (a) > (b) ? (b) : (a); (a) = _mx; (b) = _mn; } while (0)
; __device__ __forceinline__ void sort16_desc(unsigned (&k)[16]) {
; #pragma unroll
;     for (int size = 2; size <= 16; size <<= 1)
; #pragma unroll
;         for (int stride = size >> 1; stride > 0; stride >>= 1)
; #pragma unroll
;             for (int i = 0; i < 16; ++i) { const int j = i ^ stride;
;                 if (j > i) { if ((i & size) == 0) CE_DESC(k[i], k[j]); else CE_DESC(k[j], k[i]); } }
; }
; __device__ __forceinline__ void merge16(unsigned (&a)[16], const unsigned (&b)[16]) {
; #pragma unroll
;     for (int i = 0; i < 16; ++i) a[i] = a[i] > b[15 - i] ? a[i] : b[15 - i];
; #pragma unroll
;     for (int stride = 8; stride > 0; stride >>= 1)
; #pragma unroll
;         for (int i = 0; i < 16; ++i) { const int j = i ^ stride; if (j > i) CE_DESC(a[i], a[j]); }
; }
; __device__ __forceinline__ void peer_tile(const Args& A, LAS unsigned char* lds, int tile) {
;     ...
;                 { const bf16_t* sp = QRY + m * 2048 + hp * 128 + 32 * g;
;                   const u32x4 s0 = *(const u32x4*)sp, s1 = *(const u32x4*)(sp + 8), s2 = *(const u32x4*)(sp + 16), s3 = *(const u32x4*)(sp + 24);
;     ...
;                 sort16_desc(k0); sort16_desc(k1); merge16(k0, k1);
; #pragma unroll
;                 for (int msk = 16; msk <= 32; msk <<= 1) {
; #pragma unroll
;                     for (int i = 0; i < 16; ++i) k1[i] = (unsigned)__shfl_xor((int)k0[i], msk);
;                     merge16(k0, k1); }
	v_max_u32_e32 v1, v1, v134
	s_waitcnt lgkmcnt(3)
	v_max_u32_e32 v110, v110, v135
	s_waitcnt lgkmcnt(2)
	v_max_u32_e32 v122, v122, v136
	s_waitcnt lgkmcnt(1)
	v_max_u32_e32 v118, v118, v137
	s_waitcnt lgkmcnt(0)
	v_max_u32_e32 v121, v121, v138
	v_max_u32_e32 v120, v120, v133
	v_max_u32_e32 v123, v123, v132
	v_max_u32_e32 v112, v112, v131
	v_max_u32_e32 v114, v114, v130
	v_max_u32_e32 v115, v115, v129
	v_max_u32_e32 v119, v119, v128
	v_max_u32_e32 v3, v3, v127
	v_max_u32_e32 v117, v117, v126
	v_max_u32_e32 v111, v111, v125
	v_max_u32_e32 v116, v116, v124
	v_max_u32_e32 v0, v0, v2
	v_max_u32_e32 v2, v1, v114
	v_min_u32_e32 v1, v1, v114
	v_max_u32_e32 v114, v110, v115
	v_min_u32_e32 v110, v110, v115
	v_max_u32_e32 v115, v122, v119
	v_min_u32_e32 v119, v122, v119
	v_max_u32_e32 v122, v118, v3
	v_min_u32_e32 v3, v118, v3
	v_max_u32_e32 v118, v121, v117
	v_min_u32_e32 v117, v121, v117
	v_max_u32_e32 v121, v120, v111
	v_min_u32_e32 v111, v120, v111
	v_max_u32_e32 v120, v123, v116
	v_min_u32_e32 v116, v123, v116
	v_max_u32_e32 v123, v112, v0
	v_min_u32_e32 v0, v112, v0
	v_max_u32_e32 v112, v2, v118
	v_min_u32_e32 v2, v2, v118
	v_max_u32_e32 v118, v114, v121
	v_min_u32_e32 v114, v114, v121
	v_max_u32_e32 v121, v115, v120
	v_min_u32_e32 v115, v115, v120
	v_max_u32_e32 v120, v122, v123
	v_min_u32_e32 v122, v122, v123
	v_max_u32_e32 v123, v1, v117
	v_min_u32_e32 v1, v1, v117
	v_max_u32_e32 v117, v110, v111
	v_min_u32_e32 v110, v110, v111
	v_max_u32_e32 v111, v119, v116
	v_min_u32_e32 v116, v119, v116
	v_max_u32_e32 v119, v3, v0
	v_min_u32_e32 v0, v3, v0
	v_max_u32_e32 v3, v112, v121
	v_min_u32_e32 v112, v112, v121
	v_max_u32_e32 v121, v118, v120
	v_min_u32_e32 v118, v118, v120
	v_max_u32_e32 v120, v2, v115
	v_min_u32_e32 v2, v2, v115
	v_max_u32_e32 v115, v114, v122
	v_min_u32_e32 v114, v114, v122
	v_max_u32_e32 v122, v123, v111
	v_min_u32_e32 v111, v123, v111
	v_max_u32_e32 v123, v117, v119
	v_min_u32_e32 v117, v117, v119
	v_max_u32_e32 v119, v1, v116
	v_min_u32_e32 v1, v1, v116
	v_max_u32_e32 v116, v110, v0
	v_min_u32_e32 v0, v110, v0
	v_max_u32_e32 v110, v3, v121
	v_min_u32_e32 v3, v3, v121
	v_max_u32_e32 v121, v112, v118
	v_min_u32_e32 v112, v112, v118
	v_max_u32_e32 v118, v120, v115
	v_min_u32_e32 v115, v120, v115
	v_max_u32_e32 v120, v2, v114
	v_min_u32_e32 v2, v2, v114
	v_max_u32_e32 v114, v122, v123
	v_min_u32_e32 v122, v122, v123
	v_max_u32_e32 v123, v111, v117
	v_min_u32_e32 v111, v111, v117
	v_max_u32_e32 v117, v119, v116
	v_min_u32_e32 v116, v119, v116
	v_max_u32_e32 v119, v1, v0
	v_min_u32_e32 v0, v1, v0
	ds_bpermute_b32 v128, v29, v0
	ds_bpermute_b32 v1, v29, v110
	ds_bpermute_b32 v124, v29, v3
	ds_bpermute_b32 v125, v29, v121
	ds_bpermute_b32 v126, v29, v112
	s_waitcnt lgkmcnt(4)
	v_max_u32_e32 v110, v110, v128
	global_load_dwordx4 v[128:131], v[4:5], off offset:1552
	global_load_dwordx4 v[132:135], v[4:5], off offset:1536
	ds_bpermute_b32 v127, v29, v118
	ds_bpermute_b32 v136, v29, v115
	ds_bpermute_b32 v137, v29, v120
	ds_bpermute_b32 v138, v29, v2
	ds_bpermute_b32 v139, v29, v114
	ds_bpermute_b32 v140, v29, v122
	ds_bpermute_b32 v141, v29, v123
	ds_bpermute_b32 v142, v29, v111
	ds_bpermute_b32 v143, v29, v117
	ds_bpermute_b32 v144, v29, v119
	ds_bpermute_b32 v145, v29, v116
	s_waitcnt lgkmcnt(4)
	v_max_u32_e32 v115, v115, v141
	s_waitcnt lgkmcnt(3)
	v_max_u32_e32 v118, v118, v142
	s_waitcnt lgkmcnt(2)
	v_max_u32_e32 v112, v112, v143
	s_waitcnt lgkmcnt(1)
	v_max_u32_e32 v3, v3, v144
	s_waitcnt lgkmcnt(0)
	v_max_u32_e32 v121, v121, v145
	v_max_u32_e32 v120, v120, v140
	v_max_u32_e32 v2, v2, v139
	v_max_u32_e32 v114, v114, v138
	v_max_u32_e32 v122, v122, v137
	v_max_u32_e32 v123, v123, v136
	v_max_u32_e32 v111, v111, v127
	v_max_u32_e32 v117, v117, v126
	v_max_u32_e32 v116, v116, v125
	v_max_u32_e32 v119, v119, v124
	v_max_u32_e32 v0, v0, v1
	v_max_u32_e32 v1, v110, v114
	v_min_u32_e32 v110, v110, v114
	v_max_u32_e32 v114, v3, v122
	v_min_u32_e32 v3, v3, v122
	v_max_u32_e32 v122, v121, v123
	v_min_u32_e32 v121, v121, v123
	v_max_u32_e32 v123, v112, v111
	v_min_u32_e32 v111, v112, v111
	v_max_u32_e32 v112, v118, v117
	v_min_u32_e32 v117, v118, v117
	v_max_u32_e32 v118, v115, v116
	v_min_u32_e32 v115, v115, v116
	v_max_u32_e32 v116, v120, v119
	v_min_u32_e32 v119, v120, v119
	v_max_u32_e32 v120, v2, v0
	v_min_u32_e32 v0, v2, v0
	v_max_u32_e32 v2, v1, v112
	v_min_u32_e32 v1, v1, v112
	v_max_u32_e32 v112, v114, v118
	v_min_u32_e32 v114, v114, v118
	v_max_u32_e32 v118, v122, v116
	v_min_u32_e32 v116, v122, v116
	v_max_u32_e32 v122, v123, v120
	v_min_u32_e32 v120, v123, v120
	v_max_u32_e32 v123, v110, v117
	v_min_u32_e32 v110, v110, v117
	v_max_u32_e32 v117, v3, v115
	v_min_u32_e32 v3, v3, v115
	v_max_u32_e32 v115, v121, v119
	v_min_u32_e32 v119, v121, v119
	v_max_u32_e32 v121, v111, v0
	v_min_u32_e32 v0, v111, v0
	v_max_u32_e32 v111, v2, v118
	v_min_u32_e32 v2, v2, v118
	v_max_u32_e32 v118, v112, v122
	v_min_u32_e32 v112, v112, v122
	v_max_u32_e32 v127, v1, v116
	v_min_u32_e32 v1, v1, v116
	v_max_u32_e32 v116, v114, v120
	v_min_u32_e32 v114, v114, v120
	v_max_u32_e32 v136, v123, v115
	v_min_u32_e32 v115, v123, v115
	v_max_u32_e32 v137, v117, v121
	v_min_u32_e32 v138, v117, v121
	v_max_u32_e32 v139, v110, v119
	v_min_u32_e32 v110, v110, v119
	v_max_u32_e32 v140, v3, v0
	v_min_u32_e32 v0, v3, v0
	v_max_u32_e32 v126, v111, v118
	v_min_u32_e32 v125, v111, v118
	v_max_u32_e32 v124, v2, v112
	v_min_u32_e32 v123, v2, v112
	v_max_u32_e32 v122, v127, v116
	v_min_u32_e32 v121, v127, v116
	v_max_u32_e32 v120, v1, v114
	v_min_u32_e32 v119, v1, v114
	v_max_u32_e32 v118, v136, v137
	v_min_u32_e32 v117, v136, v137
	v_max_u32_e32 v116, v115, v138
	v_min_u32_e32 v115, v115, v138
	v_max_u32_e32 v114, v139, v140
	v_min_u32_e32 v112, v139, v140
	v_max_u32_e32 v111, v110, v0
	v_min_u32_e32 v110, v110, v0
	global_load_dwordx4 v[0:3], v[4:5], off offset:1584
	global_load_dwordx4 v[136:139], v[4:5], off offset:1568
	s_waitcnt vmcnt(2)
; __device__ __forceinline__ unsigned f2key(float f) { const unsigned u = __float_as_uint(f); return (u & 0x80000000u) ? ~u : (u | 0x80000000u); }
; __device__ __forceinline__ void peer_tile(const Args& A, LAS unsigned char* lds, int tile) {
;     ...
;                 { const bf16_t* sp = QRY + m * 2048 + hp * 128 + 32 * g;
;                   const u32x4 s0 = *(const u32x4*)sp, s1 = *(const u32x4*)(sp + 8), s2 = *(const u32x4*)(sp + 16), s3 = *(const u32x4*)(sp + 24);
;                   const unsigned sw[16] = {s0.x, s0.y, s0.z, s0.w, s1.x, s1.y, s1.z, s1.w, s2.x, s2.y, s2.z, s2.w, s3.x, s3.y, s3.z, s3.w};
; #pragma unroll
;                   for (int i = 0; i < 16; ++i) {
;                       const float lo = (float)__builtin_bit_cast(_Float16, (unsigned short)(sw[i] & 0xffffu)), hi = (float)__builtin_bit_cast(_Float16, (unsigned short)(sw[i] >> 16));
;                       const unsigned klo = (f2key(lo) & ~127u) | (unsigned)(127 - (32 * g + 2 * i)), khi = (f2key(hi) & ~127u) | (unsigned)(127 - (32 * g + 2 * i + 1));
;                       if (i < 8) { k0[2 * i] = klo; k0[2 * i + 1] = khi; } else { k1[2 * (i - 8)] = klo; k1[2 * (i - 8) + 1] = khi; } } }
	v_cvt_f32_f16_sdwa v127, v132 dst_sel:DWORD dst_unused:UNUSED_PAD src0_sel:WORD_1
	v_cvt_f32_f16_e32 v132, v132
	v_not_b32_e32 v140, v127
	v_or_b32_e32 v141, 0x80000000, v127
	v_cmp_gt_i32_e32 vcc, 0, v127
	s_nop 1
	v_cndmask_b32_e32 v127, v141, v140, vcc
	v_not_b32_e32 v140, v132
	v_or_b32_e32 v141, 0x80000000, v132
	v_cmp_gt_i32_e32 vcc, 0, v132
	v_and_b32_e32 v127, 0xffffff80, v127
	v_sub_u32_e32 v127, v127, v15
	v_cndmask_b32_e32 v132, v141, v140, vcc
	v_cvt_f32_f16_sdwa v140, v133 dst_sel:DWORD dst_unused:UNUSED_PAD src0_sel:WORD_1
	v_cvt_f32_f16_e32 v133, v133
	v_and_b32_e32 v132, 0xffffff80, v132
	v_sub_u32_e32 v132, v132, v15
	v_not_b32_e32 v141, v140
	v_or_b32_e32 v142, 0x80000000, v140
	v_cmp_gt_i32_e32 vcc, 0, v140
	v_add_u32_e32 v127, 0x7e, v127
	v_add_u32_e32 v132, 0x7f, v132
	v_cndmask_b32_e32 v140, v142, v141, vcc
	v_not_b32_e32 v141, v133
	v_or_b32_e32 v142, 0x80000000, v133
	v_cmp_gt_i32_e32 vcc, 0, v133
	v_and_b32_e32 v140, 0xffffff80, v140
	v_sub_u32_e32 v140, v140, v14
	v_cndmask_b32_e32 v133, v142, v141, vcc
	v_cvt_f32_f16_sdwa v141, v134 dst_sel:DWORD dst_unused:UNUSED_PAD src0_sel:WORD_1
	v_cvt_f32_f16_e32 v134, v134
	v_and_b32_e32 v133, 0xffffff80, v133
	v_sub_u32_e32 v133, v133, v14
	v_not_b32_e32 v142, v141
	v_or_b32_e32 v143, 0x80000000, v141
	v_cmp_gt_i32_e32 vcc, 0, v141
	v_add_u32_e32 v140, 0x7e, v140
	v_add_u32_e32 v133, 0x7f, v133
	v_cndmask_b32_e32 v141, v143, v142, vcc
	v_not_b32_e32 v142, v134
	v_or_b32_e32 v143, 0x80000000, v134
	v_cmp_gt_i32_e32 vcc, 0, v134
	v_and_b32_e32 v141, 0xffffff80, v141
	v_sub_u32_e32 v141, v141, v12
	v_cndmask_b32_e32 v134, v143, v142, vcc
	v_cvt_f32_f16_sdwa v142, v135 dst_sel:DWORD dst_unused:UNUSED_PAD src0_sel:WORD_1
	v_cvt_f32_f16_e32 v135, v135
	v_and_b32_e32 v134, 0xffffff80, v134
	v_sub_u32_e32 v134, v134, v12
	v_not_b32_e32 v143, v142
	v_or_b32_e32 v144, 0x80000000, v142
	v_cmp_gt_i32_e32 vcc, 0, v142
	v_add_u32_e32 v141, 0x7e, v141
	v_add_u32_e32 v134, 0x7f, v134
	v_cndmask_b32_e32 v142, v144, v143, vcc
	v_not_b32_e32 v143, v135
	v_or_b32_e32 v144, 0x80000000, v135
	v_cmp_gt_i32_e32 vcc, 0, v135
	v_and_b32_e32 v142, 0xffffff80, v142
	v_sub_u32_e32 v142, v142, v10
	v_cndmask_b32_e32 v135, v144, v143, vcc
	v_cvt_f32_f16_sdwa v143, v128 dst_sel:DWORD dst_unused:UNUSED_PAD src0_sel:WORD_1
	v_cvt_f32_f16_e32 v128, v128
	v_and_b32_e32 v135, 0xffffff80, v135
	v_sub_u32_e32 v135, v135, v10
	v_not_b32_e32 v144, v143
	v_or_b32_e32 v145, 0x80000000, v143
	v_cmp_gt_i32_e32 vcc, 0, v143
	v_add_u32_e32 v142, 0x7e, v142
	v_add_u32_e32 v135, 0x7f, v135
	v_cndmask_b32_e32 v143, v145, v144, vcc
	v_not_b32_e32 v144, v128
	v_or_b32_e32 v145, 0x80000000, v128
	v_cmp_gt_i32_e32 vcc, 0, v128
	v_and_b32_e32 v143, 0xffffff80, v143
	v_sub_u32_e32 v143, v143, v8
	v_cndmask_b32_e32 v128, v145, v144, vcc
	v_cvt_f32_f16_sdwa v144, v129 dst_sel:DWORD dst_unused:UNUSED_PAD src0_sel:WORD_1
	v_cvt_f32_f16_e32 v129, v129
	v_and_b32_e32 v128, 0xffffff80, v128
	v_sub_u32_e32 v128, v128, v8
	v_not_b32_e32 v145, v144
	v_or_b32_e32 v146, 0x80000000, v144
	v_cmp_gt_i32_e32 vcc, 0, v144
	v_add_u32_e32 v143, 0x7e, v143
	v_add_u32_e32 v128, 0x7f, v128
	v_cndmask_b32_e32 v144, v146, v145, vcc
	v_not_b32_e32 v145, v129
	v_or_b32_e32 v146, 0x80000000, v129
	v_cmp_gt_i32_e32 vcc, 0, v129
	v_and_b32_e32 v144, 0xffffff80, v144
	v_sub_u32_e32 v144, v144, v16
	v_cndmask_b32_e32 v129, v146, v145, vcc
	v_cvt_f32_f16_sdwa v145, v130 dst_sel:DWORD dst_unused:UNUSED_PAD src0_sel:WORD_1
	v_cvt_f32_f16_e32 v130, v130
	v_and_b32_e32 v129, 0xffffff80, v129
	v_sub_u32_e32 v129, v129, v16
	v_not_b32_e32 v146, v145
	v_or_b32_e32 v147, 0x80000000, v145
	v_cmp_gt_i32_e32 vcc, 0, v145
	v_add_u32_e32 v144, 0x7e, v144
	v_add_u32_e32 v129, 0x7f, v129
	v_cndmask_b32_e32 v145, v147, v146, vcc
	v_not_b32_e32 v146, v130
	v_or_b32_e32 v147, 0x80000000, v130
	v_cmp_gt_i32_e32 vcc, 0, v130
	v_and_b32_e32 v145, 0xffffff80, v145
	v_sub_u32_e32 v145, v145, v17
	v_cndmask_b32_e32 v130, v147, v146, vcc
	v_cvt_f32_f16_sdwa v146, v131 dst_sel:DWORD dst_unused:UNUSED_PAD src0_sel:WORD_1
	v_cvt_f32_f16_e32 v131, v131
	v_and_b32_e32 v130, 0xffffff80, v130
	v_sub_u32_e32 v130, v130, v17
	v_not_b32_e32 v147, v146
	v_or_b32_e32 v148, 0x80000000, v146
	v_cmp_gt_i32_e32 vcc, 0, v146
	v_add_u32_e32 v145, 0x7e, v145
	v_add_u32_e32 v130, 0x7f, v130
	v_cndmask_b32_e32 v146, v148, v147, vcc
	v_not_b32_e32 v147, v131
	v_or_b32_e32 v148, 0x80000000, v131
	v_cmp_gt_i32_e32 vcc, 0, v131
	v_and_b32_e32 v146, 0xffffff80, v146
	v_sub_u32_e32 v146, v146, v18
	v_cndmask_b32_e32 v131, v148, v147, vcc
	s_waitcnt vmcnt(0)
; __device__ __forceinline__ unsigned f2key(float f) { const unsigned u = __float_as_uint(f); return (u & 0x80000000u) ? ~u : (u | 0x80000000u); }
; #define CE_DESC(a, b) do { const unsigned _mx = (a) > (b) ? (a) : (b), _mn = (a) > (b) ? (b) : (a); (a) = _mx; (b) = _mn; } while (0)
; __device__ __forceinline__ void sort16_desc(unsigned (&k)[16]) {
; #pragma unroll
;     for (int size = 2; size <= 16; size <<= 1)
; #pragma unroll
;         for (int stride = size >> 1; stride > 0; stride >>= 1)
; #pragma unroll
;             for (int i = 0; i < 16; ++i) { const int j = i ^ stride;
;                 if (j > i) { if ((i & size) == 0) CE_DESC(k[i], k[j]); else CE_DESC(k[j], k[i]); } }
; }
; __device__ __forceinline__ void peer_tile(const Args& A, LAS unsigned char* lds, int tile) {
;     ...
;                   for (int i = 0; i < 16; ++i) {
;                       const float lo = (float)__builtin_bit_cast(_Float16, (unsigned short)(sw[i] & 0xffffu)), hi = (float)__builtin_bit_cast(_Float16, (unsigned short)(sw[i] >> 16));
;                       const unsigned klo = (f2key(lo) & ~127u) | (unsigned)(127 - (32 * g + 2 * i)), khi = (f2key(hi) & ~127u) | (unsigned)(127 - (32 * g + 2 * i + 1));
;                       if (i < 8) { k0[2 * i] = klo; k0[2 * i + 1] = khi; } else { k1[2 * (i - 8)] = klo; k1[2 * (i - 8) + 1] = khi; } } }
	v_cvt_f32_f16_sdwa v147, v136 dst_sel:DWORD dst_unused:UNUSED_PAD src0_sel:WORD_1
	v_cvt_f32_f16_e32 v136, v136
	v_and_b32_e32 v131, 0xffffff80, v131
	v_sub_u32_e32 v131, v131, v18
	v_not_b32_e32 v148, v147
	v_or_b32_e32 v149, 0x80000000, v147
	v_cmp_gt_i32_e32 vcc, 0, v147
	v_add_u32_e32 v146, 0x7e, v146
	v_add_u32_e32 v131, 0x7f, v131
	v_cndmask_b32_e32 v147, v149, v148, vcc
	v_not_b32_e32 v148, v136
	v_or_b32_e32 v149, 0x80000000, v136
	v_cmp_gt_i32_e32 vcc, 0, v136
	v_and_b32_e32 v147, 0xffffff80, v147
	v_sub_u32_e32 v147, v147, v20
	v_cndmask_b32_e32 v136, v149, v148, vcc
	v_cvt_f32_f16_sdwa v148, v137 dst_sel:DWORD dst_unused:UNUSED_PAD src0_sel:WORD_1
	v_cvt_f32_f16_e32 v137, v137
	v_and_b32_e32 v136, 0xffffff80, v136
	v_sub_u32_e32 v136, v136, v20
	v_not_b32_e32 v149, v148
	v_or_b32_e32 v150, 0x80000000, v148
	v_cmp_gt_i32_e32 vcc, 0, v148
	v_add_u32_e32 v147, 0x7e, v147
	v_add_u32_e32 v136, 0x7f, v136
	v_cndmask_b32_e32 v148, v150, v149, vcc
	v_not_b32_e32 v149, v137
	v_or_b32_e32 v150, 0x80000000, v137
	v_cmp_gt_i32_e32 vcc, 0, v137
	v_and_b32_e32 v148, 0xffffff80, v148
	v_sub_u32_e32 v148, v148, v21
	v_cndmask_b32_e32 v137, v150, v149, vcc
	v_cvt_f32_f16_sdwa v149, v138 dst_sel:DWORD dst_unused:UNUSED_PAD src0_sel:WORD_1
	v_cvt_f32_f16_e32 v138, v138
	v_and_b32_e32 v137, 0xffffff80, v137
	v_sub_u32_e32 v137, v137, v21
	v_not_b32_e32 v150, v149
	v_or_b32_e32 v151, 0x80000000, v149
	v_cmp_gt_i32_e32 vcc, 0, v149
	v_add_u32_e32 v148, 0x7e, v148
	v_add_u32_e32 v137, 0x7f, v137
	v_cndmask_b32_e32 v149, v151, v150, vcc
	v_not_b32_e32 v150, v138
	v_or_b32_e32 v151, 0x80000000, v138
	v_cmp_gt_i32_e32 vcc, 0, v138
	v_and_b32_e32 v149, 0xffffff80, v149
	v_sub_u32_e32 v149, v149, v22
	v_cndmask_b32_e32 v138, v151, v150, vcc
	v_cvt_f32_f16_sdwa v150, v139 dst_sel:DWORD dst_unused:UNUSED_PAD src0_sel:WORD_1
	v_cvt_f32_f16_e32 v139, v139
	v_and_b32_e32 v138, 0xffffff80, v138
	v_sub_u32_e32 v138, v138, v22
	v_not_b32_e32 v151, v150
	v_or_b32_e32 v152, 0x80000000, v150
	v_cmp_gt_i32_e32 vcc, 0, v150
	v_add_u32_e32 v149, 0x7e, v149
	v_add_u32_e32 v138, 0x7f, v138
	v_cndmask_b32_e32 v150, v152, v151, vcc
	v_not_b32_e32 v151, v139
	v_or_b32_e32 v152, 0x80000000, v139
	v_cmp_gt_i32_e32 vcc, 0, v139
	v_and_b32_e32 v150, 0xffffff80, v150
	v_sub_u32_e32 v150, v150, v23
	v_cndmask_b32_e32 v139, v152, v151, vcc
	v_cvt_f32_f16_sdwa v151, v0 dst_sel:DWORD dst_unused:UNUSED_PAD src0_sel:WORD_1
	v_cvt_f32_f16_e32 v0, v0
	v_and_b32_e32 v139, 0xffffff80, v139
	v_sub_u32_e32 v139, v139, v23
	v_not_b32_e32 v152, v151
	v_or_b32_e32 v153, 0x80000000, v151
	v_cmp_gt_i32_e32 vcc, 0, v151
	v_add_u32_e32 v150, 0x7e, v150
	v_add_u32_e32 v139, 0x7f, v139
	v_cndmask_b32_e32 v151, v153, v152, vcc
	v_not_b32_e32 v152, v0
	v_or_b32_e32 v153, 0x80000000, v0
	v_cmp_gt_i32_e32 vcc, 0, v0
	v_and_b32_e32 v151, 0xffffff80, v151
	v_sub_u32_e32 v151, v151, v24
	v_cndmask_b32_e32 v0, v153, v152, vcc
	v_cvt_f32_f16_sdwa v152, v1 dst_sel:DWORD dst_unused:UNUSED_PAD src0_sel:WORD_1
	v_cvt_f32_f16_e32 v1, v1
	v_and_b32_e32 v0, 0xffffff80, v0
	v_sub_u32_e32 v0, v0, v24
	v_not_b32_e32 v153, v152
	v_or_b32_e32 v154, 0x80000000, v152
	v_cmp_gt_i32_e32 vcc, 0, v152
	v_add_u32_e32 v151, 0x7e, v151
	v_add_u32_e32 v0, 0x7f, v0
	v_cndmask_b32_e32 v152, v154, v153, vcc
	v_not_b32_e32 v153, v1
	v_or_b32_e32 v154, 0x80000000, v1
	v_cmp_gt_i32_e32 vcc, 0, v1
	v_and_b32_e32 v152, 0xffffff80, v152
	v_sub_u32_e32 v152, v152, v25
	v_cndmask_b32_e32 v1, v154, v153, vcc
	v_cvt_f32_f16_sdwa v153, v2 dst_sel:DWORD dst_unused:UNUSED_PAD src0_sel:WORD_1
	v_cvt_f32_f16_e32 v2, v2
	v_and_b32_e32 v1, 0xffffff80, v1
	v_sub_u32_e32 v1, v1, v25
	v_not_b32_e32 v154, v153
	v_or_b32_e32 v155, 0x80000000, v153
	v_cmp_gt_i32_e32 vcc, 0, v153
	v_add_u32_e32 v152, 0x7e, v152
	v_add_u32_e32 v1, 0x7f, v1
	v_cndmask_b32_e32 v153, v155, v154, vcc
	v_not_b32_e32 v154, v2
	v_or_b32_e32 v155, 0x80000000, v2
	v_cmp_gt_i32_e32 vcc, 0, v2
	v_and_b32_e32 v153, 0xffffff80, v153
	v_sub_u32_e32 v153, v153, v26
	v_cndmask_b32_e32 v2, v155, v154, vcc
	v_cvt_f32_f16_sdwa v154, v3 dst_sel:DWORD dst_unused:UNUSED_PAD src0_sel:WORD_1
	v_cvt_f32_f16_e32 v3, v3
	v_and_b32_e32 v2, 0xffffff80, v2
	v_sub_u32_e32 v2, v2, v26
	v_not_b32_e32 v155, v154
	v_or_b32_e32 v156, 0x80000000, v154
	v_cmp_gt_i32_e32 vcc, 0, v154
	v_add_u32_e32 v153, 0x7e, v153
	v_add_u32_e32 v2, 0x7f, v2
	v_cndmask_b32_e32 v154, v156, v155, vcc
	v_not_b32_e32 v155, v3
	v_or_b32_e32 v156, 0x80000000, v3
	v_cmp_gt_i32_e32 vcc, 0, v3
	v_and_b32_e32 v154, 0xffffff80, v154
	v_sub_u32_e32 v154, v154, v28
	v_cndmask_b32_e32 v3, v156, v155, vcc
	v_and_b32_e32 v3, 0xffffff80, v3
	v_sub_u32_e32 v3, v3, v28
	v_add_u32_e32 v154, 0x7e, v154
	v_add_u32_e32 v3, 0x7f, v3
	v_max_u32_e32 v155, v132, v127
	v_min_u32_e32 v127, v132, v127
	v_max_u32_e32 v132, v140, v133
	v_min_u32_e32 v133, v140, v133
	v_max_u32_e32 v140, v134, v141
	v_min_u32_e32 v134, v134, v141
	v_max_u32_e32 v141, v142, v135
	v_min_u32_e32 v135, v142, v135
	v_max_u32_e32 v142, v128, v143
	v_min_u32_e32 v128, v128, v143
	v_max_u32_e32 v143, v144, v129
	v_min_u32_e32 v129, v144, v129
	v_max_u32_e32 v144, v130, v145
	v_min_u32_e32 v130, v130, v145
	v_max_u32_e32 v145, v146, v131
	v_min_u32_e32 v131, v146, v131
	v_max_u32_e32 v163, v136, v147
	v_min_u32_e32 v136, v136, v147
	v_max_u32_e32 v147, v148, v137
	v_min_u32_e32 v137, v148, v137
	v_max_u32_e32 v148, v138, v149
	v_min_u32_e32 v138, v138, v149
	v_max_u32_e32 v149, v150, v139
	v_min_u32_e32 v139, v150, v139
	v_max_u32_e32 v150, v0, v151
	v_min_u32_e32 v0, v0, v151
	v_max_u32_e32 v151, v152, v1
	v_min_u32_e32 v1, v152, v1
	v_max_u32_e32 v152, v2, v153
	v_min_u32_e32 v2, v2, v153
; #define CE_DESC(a, b) do { const unsigned _mx = (a) > (b) ? (a) : (b), _mn = (a) > (b) ? (b) : (a); (a) = _mx; (b) = _mn; } while (0)
; __device__ __forceinline__ void sort16_desc(unsigned (&k)[16]) {
; #pragma unroll
;     for (int size = 2; size <= 16; size <<= 1)
; #pragma unroll
;         for (int stride = size >> 1; stride > 0; stride >>= 1)
; #pragma unroll
;             for (int i = 0; i < 16; ++i) { const int j = i ^ stride;
;                 if (j > i) { if ((i & size) == 0) CE_DESC(k[i], k[j]); else CE_DESC(k[j], k[i]); } }
; }
	v_max_u32_e32 v153, v154, v3
	v_min_u32_e32 v3, v154, v3
	v_max_u32_e32 v146, v155, v133
	v_min_u32_e32 v133, v155, v133
	v_max_u32_e32 v155, v127, v132
	v_min_u32_e32 v127, v127, v132
	v_max_u32_e32 v132, v135, v140
	v_min_u32_e32 v135, v135, v140
	v_max_u32_e32 v140, v141, v134
	v_min_u32_e32 v134, v141, v134
	v_max_u32_e32 v141, v142, v129
	v_min_u32_e32 v129, v142, v129
	v_max_u32_e32 v142, v128, v143
	v_min_u32_e32 v128, v128, v143
	v_max_u32_e32 v143, v131, v144
	v_min_u32_e32 v131, v131, v144
	v_max_u32_e32 v144, v145, v130
	v_min_u32_e32 v130, v145, v130
	v_max_u32_e32 v154, v163, v137
	v_min_u32_e32 v137, v163, v137
	v_max_u32_e32 v163, v136, v147
	v_min_u32_e32 v136, v136, v147
	v_max_u32_e32 v147, v139, v148
	v_min_u32_e32 v139, v139, v148
	v_max_u32_e32 v148, v149, v138
	v_min_u32_e32 v138, v149, v138
	v_max_u32_e32 v149, v150, v1
	v_min_u32_e32 v1, v150, v1
	v_max_u32_e32 v150, v0, v151
	v_min_u32_e32 v0, v0, v151
	v_max_u32_e32 v151, v3, v152
	v_min_u32_e32 v3, v3, v152
	v_max_u32_e32 v152, v153, v2
	v_min_u32_e32 v2, v153, v2
	v_max_u32_e32 v145, v146, v155
	v_min_u32_e32 v146, v146, v155
	v_max_u32_e32 v155, v133, v127
	v_min_u32_e32 v127, v133, v127
	v_max_u32_e32 v133, v134, v135
	v_min_u32_e32 v134, v134, v135
	v_max_u32_e32 v135, v140, v132
	v_min_u32_e32 v132, v140, v132
	v_max_u32_e32 v140, v141, v142
	v_min_u32_e32 v141, v141, v142
	v_max_u32_e32 v142, v129, v128
	v_min_u32_e32 v128, v129, v128
	v_max_u32_e32 v129, v130, v131
	v_min_u32_e32 v130, v130, v131
	v_max_u32_e32 v131, v144, v143
	v_min_u32_e32 v143, v144, v143
	v_max_u32_e32 v153, v154, v163
	v_min_u32_e32 v154, v154, v163
	v_max_u32_e32 v163, v137, v136
	v_min_u32_e32 v136, v137, v136
	v_max_u32_e32 v137, v138, v139
	v_min_u32_e32 v138, v138, v139
	v_max_u32_e32 v139, v148, v147
	v_min_u32_e32 v147, v148, v147
	v_max_u32_e32 v148, v149, v150
	v_min_u32_e32 v149, v149, v150
	v_max_u32_e32 v150, v1, v0
	v_min_u32_e32 v0, v1, v0
	v_max_u32_e32 v1, v2, v3
	v_min_u32_e32 v2, v2, v3
	v_max_u32_e32 v3, v152, v151
	v_min_u32_e32 v151, v152, v151
	v_max_u32_e32 v144, v145, v134
	v_min_u32_e32 v134, v145, v134
	v_max_u32_e32 v145, v146, v133
	v_min_u32_e32 v133, v146, v133
	v_max_u32_e32 v146, v155, v132
	v_min_u32_e32 v132, v155, v132
	v_max_u32_e32 v155, v127, v135
	v_min_u32_e32 v127, v127, v135
	v_max_u32_e32 v135, v130, v140
	v_min_u32_e32 v130, v130, v140
	v_max_u32_e32 v140, v129, v141
	v_min_u32_e32 v129, v129, v141
	v_max_u32_e32 v141, v143, v142
	v_min_u32_e32 v142, v143, v142
	v_max_u32_e32 v143, v131, v128
	v_min_u32_e32 v128, v131, v128
	v_max_u32_e32 v152, v153, v138
	v_min_u32_e32 v138, v153, v138
	v_max_u32_e32 v153, v154, v137
	v_min_u32_e32 v137, v154, v137
	v_max_u32_e32 v154, v163, v147
	v_min_u32_e32 v147, v163, v147
	v_max_u32_e32 v163, v136, v139
	v_min_u32_e32 v136, v136, v139
	v_max_u32_e32 v139, v2, v148
	v_min_u32_e32 v2, v2, v148
	v_max_u32_e32 v148, v1, v149
	v_min_u32_e32 v1, v1, v149
	v_max_u32_e32 v149, v151, v150
	v_min_u32_e32 v150, v151, v150
	v_max_u32_e32 v151, v3, v0
	v_min_u32_e32 v0, v3, v0
	v_max_u32_e32 v131, v144, v146
	v_min_u32_e32 v144, v144, v146
	v_max_u32_e32 v146, v145, v155
	v_min_u32_e32 v145, v145, v155
	v_max_u32_e32 v155, v134, v132
	v_min_u32_e32 v132, v134, v132
	v_max_u32_e32 v134, v133, v127
	v_min_u32_e32 v127, v133, v127
	v_max_u32_e32 v133, v142, v130
	v_min_u32_e32 v130, v142, v130
	v_max_u32_e32 v142, v128, v129
	v_min_u32_e32 v128, v128, v129
	v_max_u32_e32 v129, v141, v135
	v_min_u32_e32 v135, v141, v135
	v_max_u32_e32 v141, v143, v140
	v_min_u32_e32 v140, v143, v140
	v_max_u32_e32 v3, v152, v154
	v_min_u32_e32 v152, v152, v154
	v_max_u32_e32 v154, v153, v163
	v_min_u32_e32 v153, v153, v163
	v_max_u32_e32 v163, v138, v147
	v_min_u32_e32 v138, v138, v147
	v_max_u32_e32 v147, v137, v136
	v_min_u32_e32 v136, v137, v136
	v_max_u32_e32 v137, v150, v2
	v_min_u32_e32 v2, v150, v2
	v_max_u32_e32 v150, v0, v1
	v_min_u32_e32 v0, v0, v1
	v_max_u32_e32 v1, v149, v139
	v_min_u32_e32 v139, v149, v139
	v_max_u32_e32 v149, v151, v148
	v_min_u32_e32 v148, v151, v148
	v_max_u32_e32 v143, v131, v146
	v_min_u32_e32 v131, v131, v146
	v_max_u32_e32 v146, v144, v145
	v_min_u32_e32 v144, v144, v145
	v_max_u32_e32 v145, v155, v134
	v_min_u32_e32 v134, v155, v134
	v_max_u32_e32 v155, v132, v127
	v_min_u32_e32 v127, v132, v127
	v_max_u32_e32 v132, v128, v130
	v_min_u32_e32 v128, v128, v130
	v_max_u32_e32 v130, v142, v133
	v_min_u32_e32 v133, v142, v133
	v_max_u32_e32 v142, v140, v135
	v_min_u32_e32 v135, v140, v135
	v_max_u32_e32 v140, v141, v129
	v_min_u32_e32 v129, v141, v129
	v_max_u32_e32 v151, v3, v154
	v_min_u32_e32 v3, v3, v154
	v_max_u32_e32 v154, v152, v153
	v_min_u32_e32 v152, v152, v153
	v_max_u32_e32 v153, v163, v147
	v_min_u32_e32 v147, v163, v147
	v_max_u32_e32 v163, v138, v136
	v_min_u32_e32 v136, v138, v136
	v_max_u32_e32 v138, v0, v2
	v_min_u32_e32 v0, v0, v2
	v_max_u32_e32 v2, v150, v137
	v_min_u32_e32 v137, v150, v137
	v_max_u32_e32 v150, v148, v139
	v_min_u32_e32 v139, v148, v139
	v_max_u32_e32 v148, v149, v1
	v_min_u32_e32 v1, v149, v1
	v_max_u32_e32 v141, v143, v128
	v_min_u32_e32 v128, v143, v128
	v_max_u32_e32 v143, v131, v132
	v_min_u32_e32 v131, v131, v132
	v_max_u32_e32 v132, v146, v133
	v_min_u32_e32 v133, v146, v133
	v_max_u32_e32 v146, v144, v130
	v_min_u32_e32 v130, v144, v130
	v_max_u32_e32 v144, v145, v135
	v_min_u32_e32 v135, v145, v135
	v_max_u32_e32 v145, v134, v142
	v_min_u32_e32 v134, v134, v142
	v_max_u32_e32 v142, v155, v129
	v_min_u32_e32 v129, v155, v129
	v_max_u32_e32 v155, v127, v140
	v_min_u32_e32 v127, v127, v140
	v_max_u32_e32 v149, v151, v0
	v_min_u32_e32 v0, v151, v0
; #define CE_DESC(a, b) do { const unsigned _mx = (a) > (b) ? (a) : (b), _mn = (a) > (b) ? (b) : (a); (a) = _mx; (b) = _mn; } while (0)
; __device__ __forceinline__ void merge16(unsigned (&a)[16], const unsigned (&b)[16]) {
; #pragma unroll
;     for (int i = 0; i < 16; ++i) a[i] = a[i] > b[15 - i] ? a[i] : b[15 - i];
; #pragma unroll
;     for (int stride = 8; stride > 0; stride >>= 1)
; #pragma unroll
;         for (int i = 0; i < 16; ++i) { const int j = i ^ stride; if (j > i) CE_DESC(a[i], a[j]); }
; }
; __device__ __forceinline__ void peer_tile(const Args& A, LAS unsigned char* lds, int tile) {
;     ...
;                 for (int msk = 16; msk <= 32; msk <<= 1) {
; #pragma unroll
;                     for (int i = 0; i < 16; ++i) k1[i] = (unsigned)__shfl_xor((int)k0[i], msk);
;                     merge16(k0, k1); }
	v_max_u32_e32 v151, v3, v138
	v_min_u32_e32 v3, v3, v138
	v_max_u32_e32 v138, v154, v137
	v_min_u32_e32 v137, v154, v137
	v_max_u32_e32 v154, v152, v2
	v_min_u32_e32 v2, v152, v2
	v_max_u32_e32 v152, v153, v139
	v_min_u32_e32 v139, v153, v139
	v_max_u32_e32 v153, v147, v150
	v_min_u32_e32 v147, v147, v150
	v_max_u32_e32 v150, v163, v1
	v_min_u32_e32 v1, v163, v1
	v_max_u32_e32 v163, v136, v148
	v_min_u32_e32 v136, v136, v148
	v_max_u32_e32 v140, v141, v144
	v_min_u32_e32 v141, v141, v144
	v_max_u32_e32 v144, v143, v145
	v_min_u32_e32 v143, v143, v145
	v_max_u32_e32 v145, v132, v142
	v_min_u32_e32 v132, v132, v142
	v_max_u32_e32 v142, v146, v155
	v_min_u32_e32 v146, v146, v155
	v_max_u32_e32 v155, v128, v135
	v_min_u32_e32 v128, v128, v135
	v_max_u32_e32 v135, v131, v134
	v_min_u32_e32 v131, v131, v134
	v_max_u32_e32 v134, v133, v129
	v_min_u32_e32 v129, v133, v129
	v_max_u32_e32 v133, v130, v127
	v_min_u32_e32 v127, v130, v127
	v_max_u32_e32 v148, v149, v152
	v_min_u32_e32 v149, v149, v152
	v_max_u32_e32 v152, v151, v153
	v_min_u32_e32 v151, v151, v153
	v_max_u32_e32 v153, v138, v150
	v_min_u32_e32 v138, v138, v150
	v_max_u32_e32 v150, v154, v163
	v_min_u32_e32 v154, v154, v163
	v_max_u32_e32 v163, v0, v139
	v_min_u32_e32 v0, v0, v139
	v_max_u32_e32 v139, v3, v147
	v_min_u32_e32 v3, v3, v147
	v_max_u32_e32 v147, v137, v1
	v_min_u32_e32 v1, v137, v1
	v_max_u32_e32 v137, v2, v136
	v_min_u32_e32 v2, v2, v136
	v_max_u32_e32 v130, v140, v145
	v_min_u32_e32 v140, v140, v145
	v_max_u32_e32 v145, v144, v142
	v_min_u32_e32 v142, v144, v142
	v_max_u32_e32 v144, v141, v132
	v_min_u32_e32 v132, v141, v132
	v_max_u32_e32 v141, v143, v146
	v_min_u32_e32 v143, v143, v146
	v_max_u32_e32 v146, v155, v134
	v_min_u32_e32 v134, v155, v134
	v_max_u32_e32 v155, v135, v133
	v_min_u32_e32 v133, v135, v133
	v_max_u32_e32 v135, v128, v129
	v_min_u32_e32 v128, v128, v129
	v_max_u32_e32 v129, v131, v127
	v_min_u32_e32 v127, v131, v127
	v_max_u32_e32 v136, v148, v153
	v_min_u32_e32 v148, v148, v153
	v_max_u32_e32 v153, v152, v150
	v_min_u32_e32 v150, v152, v150
	v_max_u32_e32 v152, v149, v138
	v_min_u32_e32 v138, v149, v138
	v_max_u32_e32 v149, v151, v154
	v_min_u32_e32 v151, v151, v154
	v_max_u32_e32 v154, v163, v147
	v_min_u32_e32 v147, v163, v147
	v_max_u32_e32 v163, v139, v137
	v_min_u32_e32 v137, v139, v137
	v_max_u32_e32 v139, v0, v1
	v_min_u32_e32 v0, v0, v1
	v_max_u32_e32 v1, v3, v2
	v_min_u32_e32 v2, v3, v2
	v_min_u32_e32 v131, v130, v145
	v_min_u32_e32 v156, v140, v142
	v_min_u32_e32 v157, v144, v141
	v_min_u32_e32 v158, v132, v143
	v_min_u32_e32 v159, v146, v155
	v_min_u32_e32 v160, v134, v133
	v_min_u32_e32 v161, v135, v129
	v_min_u32_e32 v162, v128, v127
	v_min_u32_e32 v3, v136, v153
	v_min_u32_e32 v164, v148, v150
	v_min_u32_e32 v165, v152, v149
	v_min_u32_e32 v166, v138, v151
	v_min_u32_e32 v167, v154, v163
	v_min_u32_e32 v168, v147, v137
	v_min_u32_e32 v169, v139, v1
	v_min_u32_e32 v170, v0, v2
	v_max3_u32 v130, v130, v145, v170
	v_max3_u32 v0, v131, v0, v2
	v_max3_u32 v2, v140, v142, v169
	v_max3_u32 v1, v156, v139, v1
	v_max3_u32 v131, v144, v141, v168
	v_max3_u32 v137, v157, v147, v137
	v_max3_u32 v132, v132, v143, v167
	v_max3_u32 v139, v158, v154, v163
	v_max3_u32 v140, v146, v155, v166
	v_max3_u32 v138, v159, v138, v151
	v_max3_u32 v133, v134, v133, v165
	v_max3_u32 v134, v160, v152, v149
	v_max3_u32 v129, v135, v129, v164
	v_max3_u32 v135, v161, v148, v150
	v_max3_u32 v3, v128, v127, v3
	v_max3_u32 v127, v162, v136, v153
	v_max_u32_e32 v128, v130, v140
	v_min_u32_e32 v130, v130, v140
	v_max_u32_e32 v136, v0, v138
	v_min_u32_e32 v0, v0, v138
	v_max_u32_e32 v138, v2, v133
	v_min_u32_e32 v2, v2, v133
	v_max_u32_e32 v133, v1, v134
	v_min_u32_e32 v1, v1, v134
	v_max_u32_e32 v134, v131, v129
	v_min_u32_e32 v129, v131, v129
	v_max_u32_e32 v131, v137, v135
	v_min_u32_e32 v135, v137, v135
	v_max_u32_e32 v137, v132, v3
	v_min_u32_e32 v3, v132, v3
	v_max_u32_e32 v132, v139, v127
	v_min_u32_e32 v127, v139, v127
	v_max_u32_e32 v139, v128, v134
	v_min_u32_e32 v128, v128, v134
	v_max_u32_e32 v134, v136, v131
	v_min_u32_e32 v131, v136, v131
	v_max_u32_e32 v136, v138, v137
	v_min_u32_e32 v137, v138, v137
	v_max_u32_e32 v138, v133, v132
	v_min_u32_e32 v132, v133, v132
	v_max_u32_e32 v133, v130, v129
	v_min_u32_e32 v129, v130, v129
	v_max_u32_e32 v130, v0, v135
	v_min_u32_e32 v0, v0, v135
	v_max_u32_e32 v135, v2, v3
	v_min_u32_e32 v2, v2, v3
	v_max_u32_e32 v3, v1, v127
	v_min_u32_e32 v1, v1, v127
	v_max_u32_e32 v127, v139, v136
	v_min_u32_e32 v136, v139, v136
	v_max_u32_e32 v139, v134, v138
	v_min_u32_e32 v134, v134, v138
	v_max_u32_e32 v138, v128, v137
	v_min_u32_e32 v128, v128, v137
	v_max_u32_e32 v137, v131, v132
	v_min_u32_e32 v131, v131, v132
	v_max_u32_e32 v132, v133, v135
	v_min_u32_e32 v133, v133, v135
	v_max_u32_e32 v135, v130, v3
	v_min_u32_e32 v3, v130, v3
	v_max_u32_e32 v130, v129, v2
	v_min_u32_e32 v2, v129, v2
	v_max_u32_e32 v129, v0, v1
	v_min_u32_e32 v0, v0, v1
	v_max_u32_e32 v1, v127, v139
	v_min_u32_e32 v127, v127, v139
	v_max_u32_e32 v139, v136, v134
	v_min_u32_e32 v134, v136, v134
	v_max_u32_e32 v136, v138, v137
	v_min_u32_e32 v137, v138, v137
	v_max_u32_e32 v138, v128, v131
	v_min_u32_e32 v128, v128, v131
	v_max_u32_e32 v131, v132, v135
	v_min_u32_e32 v132, v132, v135
	v_max_u32_e32 v135, v133, v3
	v_min_u32_e32 v3, v133, v3
	v_max_u32_e32 v133, v130, v129
	v_min_u32_e32 v129, v130, v129
	v_max_u32_e32 v130, v2, v0
	v_min_u32_e32 v0, v2, v0
	ds_bpermute_b32 v2, v27, v1
	ds_bpermute_b32 v140, v27, v127
	ds_bpermute_b32 v141, v27, v139
	ds_bpermute_b32 v142, v27, v134
	ds_bpermute_b32 v143, v27, v136
	ds_bpermute_b32 v144, v27, v137
	ds_bpermute_b32 v145, v27, v138
	ds_bpermute_b32 v146, v27, v128
	ds_bpermute_b32 v147, v27, v131
	ds_bpermute_b32 v148, v27, v132
	ds_bpermute_b32 v149, v27, v135
	ds_bpermute_b32 v150, v27, v0
	ds_bpermute_b32 v151, v27, v130
	ds_bpermute_b32 v152, v27, v129
	ds_bpermute_b32 v153, v27, v133
	ds_bpermute_b32 v154, v27, v3
	s_waitcnt lgkmcnt(4)
; #define CE_DESC(a, b) do { const unsigned _mx = (a) > (b) ? (a) : (b), _mn = (a) > (b) ? (b) : (a); (a) = _mx; (b) = _mn; } while (0)
; __device__ __forceinline__ void merge16(unsigned (&a)[16], const unsigned (&b)[16]) {
; #pragma unroll
;     for (int i = 0; i < 16; ++i) a[i] = a[i] > b[15 - i] ? a[i] : b[15 - i];
; #pragma unroll
;     for (int stride = 8; stride > 0; stride >>= 1)
; #pragma unroll
;         for (int i = 0; i < 16; ++i) { const int j = i ^ stride; if (j > i) CE_DESC(a[i], a[j]); }
; }
; __device__ __forceinline__ void peer_tile(const Args& A, LAS unsigned char* lds, int tile) {
;     ...
;                 { const bf16_t* sp = QRY + m * 2048 + hp * 128 + 32 * g;
;                   const u32x4 s0 = *(const u32x4*)sp, s1 = *(const u32x4*)(sp + 8), s2 = *(const u32x4*)(sp + 16), s3 = *(const u32x4*)(sp + 24);
;                   const unsigned sw[16] = {s0.x, s0.y, s0.z, s0.w, s1.x, s1.y, s1.z, s1.w, s2.x, s2.y, s2.z, s2.w, s3.x, s3.y, s3.z, s3.w};
;     ...
;                 for (int msk = 16; msk <= 32; msk <<= 1) {
; #pragma unroll
;                     for (int i = 0; i < 16; ++i) k1[i] = (unsigned)__shfl_xor((int)k0[i], msk);
;                     merge16(k0, k1); }
	v_max_u32_e32 v1, v1, v150
	s_waitcnt lgkmcnt(3)
	v_max_u32_e32 v127, v127, v151
	s_waitcnt lgkmcnt(2)
	v_max_u32_e32 v139, v139, v152
	s_waitcnt lgkmcnt(1)
	v_max_u32_e32 v134, v134, v153
	s_waitcnt lgkmcnt(0)
	v_max_u32_e32 v136, v136, v154
	v_max_u32_e32 v137, v137, v149
	v_max_u32_e32 v138, v138, v148
	v_max_u32_e32 v128, v128, v147
	v_max_u32_e32 v131, v131, v146
	v_max_u32_e32 v132, v132, v145
	v_max_u32_e32 v135, v135, v144
	v_max_u32_e32 v3, v3, v143
	v_max_u32_e32 v133, v133, v142
	v_max_u32_e32 v129, v129, v141
	v_max_u32_e32 v130, v130, v140
	v_max_u32_e32 v0, v0, v2
	v_max_u32_e32 v2, v1, v131
	v_min_u32_e32 v1, v1, v131
	v_max_u32_e32 v131, v127, v132
	v_min_u32_e32 v127, v127, v132
	v_max_u32_e32 v132, v139, v135
	v_min_u32_e32 v135, v139, v135
	v_max_u32_e32 v139, v134, v3
	v_min_u32_e32 v3, v134, v3
	v_max_u32_e32 v134, v136, v133
	v_min_u32_e32 v133, v136, v133
	v_max_u32_e32 v136, v137, v129
	v_min_u32_e32 v129, v137, v129
	v_max_u32_e32 v137, v138, v130
	v_min_u32_e32 v130, v138, v130
	v_max_u32_e32 v138, v128, v0
	v_min_u32_e32 v0, v128, v0
	v_max_u32_e32 v128, v2, v134
	v_min_u32_e32 v2, v2, v134
	v_max_u32_e32 v134, v131, v136
	v_min_u32_e32 v131, v131, v136
	v_max_u32_e32 v136, v132, v137
	v_min_u32_e32 v132, v132, v137
	v_max_u32_e32 v137, v139, v138
	v_min_u32_e32 v138, v139, v138
	v_max_u32_e32 v139, v1, v133
	v_min_u32_e32 v1, v1, v133
	v_max_u32_e32 v133, v127, v129
	v_min_u32_e32 v127, v127, v129
	v_max_u32_e32 v129, v135, v130
	v_min_u32_e32 v130, v135, v130
	v_max_u32_e32 v135, v3, v0
	v_min_u32_e32 v0, v3, v0
	v_max_u32_e32 v3, v128, v136
	v_min_u32_e32 v128, v128, v136
	v_max_u32_e32 v136, v134, v137
	v_min_u32_e32 v134, v134, v137
	v_max_u32_e32 v137, v2, v132
	v_min_u32_e32 v2, v2, v132
	v_max_u32_e32 v132, v131, v138
	v_min_u32_e32 v131, v131, v138
	v_max_u32_e32 v138, v139, v129
	v_min_u32_e32 v129, v139, v129
	v_max_u32_e32 v139, v133, v135
	v_min_u32_e32 v133, v133, v135
	v_max_u32_e32 v135, v1, v130
	v_min_u32_e32 v1, v1, v130
	v_max_u32_e32 v130, v127, v0
	v_min_u32_e32 v0, v127, v0
	v_max_u32_e32 v127, v3, v136
	v_min_u32_e32 v3, v3, v136
	v_max_u32_e32 v136, v128, v134
	v_min_u32_e32 v128, v128, v134
	v_max_u32_e32 v134, v137, v132
	v_min_u32_e32 v132, v137, v132
	v_max_u32_e32 v137, v2, v131
	v_min_u32_e32 v2, v2, v131
	v_max_u32_e32 v131, v138, v139
	v_min_u32_e32 v138, v138, v139
	v_max_u32_e32 v139, v129, v133
	v_min_u32_e32 v129, v129, v133
	v_max_u32_e32 v133, v135, v130
	v_min_u32_e32 v130, v135, v130
	v_max_u32_e32 v135, v1, v0
	v_min_u32_e32 v0, v1, v0
	ds_bpermute_b32 v144, v29, v0
	ds_bpermute_b32 v1, v29, v127
	ds_bpermute_b32 v140, v29, v3
	ds_bpermute_b32 v141, v29, v136
	ds_bpermute_b32 v142, v29, v128
	s_waitcnt lgkmcnt(4)
	v_max_u32_e32 v127, v127, v144
	global_load_dwordx4 v[144:147], v[4:5], off offset:1808
	global_load_dwordx4 v[148:151], v[4:5], off offset:1792
	ds_bpermute_b32 v143, v29, v134
	ds_bpermute_b32 v152, v29, v132
	ds_bpermute_b32 v153, v29, v137
	ds_bpermute_b32 v154, v29, v2
	ds_bpermute_b32 v155, v29, v131
	ds_bpermute_b32 v156, v29, v138
	ds_bpermute_b32 v157, v29, v139
	ds_bpermute_b32 v158, v29, v129
	ds_bpermute_b32 v159, v29, v133
	ds_bpermute_b32 v160, v29, v135
	ds_bpermute_b32 v161, v29, v130
	s_waitcnt lgkmcnt(4)
	v_max_u32_e32 v132, v132, v157
	s_waitcnt lgkmcnt(3)
	v_max_u32_e32 v134, v134, v158
	s_waitcnt lgkmcnt(2)
	v_max_u32_e32 v128, v128, v159
	s_waitcnt lgkmcnt(1)
	v_max_u32_e32 v3, v3, v160
	s_waitcnt lgkmcnt(0)
	v_max_u32_e32 v136, v136, v161
	v_max_u32_e32 v137, v137, v156
	v_max_u32_e32 v2, v2, v155
	v_max_u32_e32 v131, v131, v154
	v_max_u32_e32 v138, v138, v153
	v_max_u32_e32 v139, v139, v152
	v_max_u32_e32 v129, v129, v143
	v_max_u32_e32 v133, v133, v142
	v_max_u32_e32 v130, v130, v141
	v_max_u32_e32 v135, v135, v140
	v_max_u32_e32 v0, v0, v1
	v_max_u32_e32 v1, v127, v131
	v_min_u32_e32 v127, v127, v131
	v_max_u32_e32 v131, v3, v138
	v_min_u32_e32 v3, v3, v138
	v_max_u32_e32 v138, v136, v139
	v_min_u32_e32 v136, v136, v139
	v_max_u32_e32 v139, v128, v129
	v_min_u32_e32 v128, v128, v129
	v_max_u32_e32 v129, v134, v133
	v_min_u32_e32 v133, v134, v133
	v_max_u32_e32 v134, v132, v130
	v_min_u32_e32 v130, v132, v130
	v_max_u32_e32 v132, v137, v135
	v_min_u32_e32 v135, v137, v135
	v_max_u32_e32 v137, v2, v0
	v_min_u32_e32 v0, v2, v0
	v_max_u32_e32 v2, v1, v129
	v_min_u32_e32 v1, v1, v129
	v_max_u32_e32 v129, v131, v134
	v_min_u32_e32 v131, v131, v134
	v_max_u32_e32 v134, v138, v132
	v_min_u32_e32 v132, v138, v132
	v_max_u32_e32 v138, v139, v137
	v_min_u32_e32 v137, v139, v137
	v_max_u32_e32 v139, v127, v133
	v_min_u32_e32 v127, v127, v133
	v_max_u32_e32 v133, v3, v130
	v_min_u32_e32 v3, v3, v130
	v_max_u32_e32 v130, v136, v135
	v_min_u32_e32 v135, v136, v135
	v_max_u32_e32 v136, v128, v0
	v_min_u32_e32 v0, v128, v0
	v_max_u32_e32 v128, v2, v134
	v_min_u32_e32 v2, v2, v134
	v_max_u32_e32 v134, v129, v138
	v_min_u32_e32 v129, v129, v138
	v_max_u32_e32 v143, v1, v132
	v_min_u32_e32 v1, v1, v132
	v_max_u32_e32 v132, v131, v137
	v_min_u32_e32 v131, v131, v137
	v_max_u32_e32 v152, v139, v130
	v_min_u32_e32 v130, v139, v130
	v_max_u32_e32 v153, v133, v136
	v_min_u32_e32 v154, v133, v136
	v_max_u32_e32 v155, v127, v135
	v_min_u32_e32 v127, v127, v135
	v_max_u32_e32 v156, v3, v0
	v_min_u32_e32 v0, v3, v0
	v_max_u32_e32 v142, v128, v134
	v_min_u32_e32 v141, v128, v134
	v_max_u32_e32 v140, v2, v129
	v_min_u32_e32 v139, v2, v129
	v_max_u32_e32 v138, v143, v132
	v_min_u32_e32 v137, v143, v132
	v_max_u32_e32 v136, v1, v131
	v_min_u32_e32 v135, v1, v131
	v_max_u32_e32 v134, v152, v153
	v_min_u32_e32 v133, v152, v153
	v_max_u32_e32 v132, v130, v154
	v_min_u32_e32 v131, v130, v154
	v_max_u32_e32 v130, v155, v156
	v_min_u32_e32 v129, v155, v156
	v_max_u32_e32 v128, v127, v0
	v_min_u32_e32 v127, v127, v0
	global_load_dwordx4 v[0:3], v[4:5], off offset:1840
	global_load_dwordx4 v[152:155], v[4:5], off offset:1824
	s_waitcnt vmcnt(2)
; __device__ __forceinline__ unsigned f2key(float f) { const unsigned u = __float_as_uint(f); return (u & 0x80000000u) ? ~u : (u | 0x80000000u); }
; __device__ __forceinline__ void peer_tile(const Args& A, LAS unsigned char* lds, int tile) {
;     ...
;                 { const bf16_t* sp = QRY + m * 2048 + hp * 128 + 32 * g;
;                   const u32x4 s0 = *(const u32x4*)sp, s1 = *(const u32x4*)(sp + 8), s2 = *(const u32x4*)(sp + 16), s3 = *(const u32x4*)(sp + 24);
;                   const unsigned sw[16] = {s0.x, s0.y, s0.z, s0.w, s1.x, s1.y, s1.z, s1.w, s2.x, s2.y, s2.z, s2.w, s3.x, s3.y, s3.z, s3.w};
; #pragma unroll
;                   for (int i = 0; i < 16; ++i) {
;                       const float lo = (float)__builtin_bit_cast(_Float16, (unsigned short)(sw[i] & 0xffffu)), hi = (float)__builtin_bit_cast(_Float16, (unsigned short)(sw[i] >> 16));
;                       const unsigned klo = (f2key(lo) & ~127u) | (unsigned)(127 - (32 * g + 2 * i)), khi = (f2key(hi) & ~127u) | (unsigned)(127 - (32 * g + 2 * i + 1));
;                       if (i < 8) { k0[2 * i] = klo; k0[2 * i + 1] = khi; } else { k1[2 * (i - 8)] = klo; k1[2 * (i - 8) + 1] = khi; } } }
	v_cvt_f32_f16_sdwa v143, v148 dst_sel:DWORD dst_unused:UNUSED_PAD src0_sel:WORD_1
	v_cvt_f32_f16_e32 v4, v148
	v_not_b32_e32 v5, v143
	v_or_b32_e32 v148, 0x80000000, v143
	v_cmp_gt_i32_e32 vcc, 0, v143
	v_not_b32_e32 v143, v4
	s_nop 0
	v_cndmask_b32_e32 v5, v148, v5, vcc
	v_or_b32_e32 v148, 0x80000000, v4
	v_cmp_gt_i32_e32 vcc, 0, v4
	v_and_b32_e32 v5, 0xffffff80, v5
	v_sub_u32_e32 v5, v5, v15
	v_cndmask_b32_e32 v4, v148, v143, vcc
	v_and_b32_e32 v4, 0xffffff80, v4
	v_cvt_f32_f16_sdwa v143, v149 dst_sel:DWORD dst_unused:UNUSED_PAD src0_sel:WORD_1
	v_sub_u32_e32 v4, v4, v15
	v_cvt_f32_f16_e32 v15, v149
	v_add_u32_e32 v5, 0x7e, v5
	v_not_b32_e32 v148, v143
	v_or_b32_e32 v149, 0x80000000, v143
	v_cmp_gt_i32_e32 vcc, 0, v143
	v_add_u32_e32 v4, 0x7f, v4
	s_nop 0
	v_cndmask_b32_e32 v143, v149, v148, vcc
	v_not_b32_e32 v148, v15
	v_or_b32_e32 v149, 0x80000000, v15
	v_cmp_gt_i32_e32 vcc, 0, v15
	v_and_b32_e32 v143, 0xffffff80, v143
	v_sub_u32_e32 v143, v143, v14
	v_cndmask_b32_e32 v15, v149, v148, vcc
	v_and_b32_e32 v15, 0xffffff80, v15
	v_cvt_f32_f16_sdwa v148, v150 dst_sel:DWORD dst_unused:UNUSED_PAD src0_sel:WORD_1
	v_sub_u32_e32 v14, v15, v14
	v_cvt_f32_f16_e32 v15, v150
	v_add_u32_e32 v143, 0x7e, v143
	v_not_b32_e32 v149, v148
	v_or_b32_e32 v150, 0x80000000, v148
	v_cmp_gt_i32_e32 vcc, 0, v148
	v_add_u32_e32 v14, 0x7f, v14
	s_nop 0
	v_cndmask_b32_e32 v148, v150, v149, vcc
	v_not_b32_e32 v149, v15
	v_or_b32_e32 v150, 0x80000000, v15
	v_cmp_gt_i32_e32 vcc, 0, v15
	v_and_b32_e32 v148, 0xffffff80, v148
	v_sub_u32_e32 v148, v148, v12
	v_cndmask_b32_e32 v15, v150, v149, vcc
	v_and_b32_e32 v15, 0xffffff80, v15
	v_cvt_f32_f16_sdwa v149, v151 dst_sel:DWORD dst_unused:UNUSED_PAD src0_sel:WORD_1
	v_sub_u32_e32 v12, v15, v12
	v_cvt_f32_f16_e32 v15, v151
	v_add_u32_e32 v148, 0x7e, v148
	v_not_b32_e32 v150, v149
	v_or_b32_e32 v151, 0x80000000, v149
	v_cmp_gt_i32_e32 vcc, 0, v149
	v_add_u32_e32 v12, 0x7f, v12
	s_nop 0
	v_cndmask_b32_e32 v149, v151, v150, vcc
	v_not_b32_e32 v150, v15
	v_or_b32_e32 v151, 0x80000000, v15
	v_cmp_gt_i32_e32 vcc, 0, v15
	v_and_b32_e32 v149, 0xffffff80, v149
	v_sub_u32_e32 v149, v149, v10
	v_cndmask_b32_e32 v15, v151, v150, vcc
	v_and_b32_e32 v15, 0xffffff80, v15
	v_cvt_f32_f16_sdwa v150, v144 dst_sel:DWORD dst_unused:UNUSED_PAD src0_sel:WORD_1
	v_sub_u32_e32 v10, v15, v10
	v_cvt_f32_f16_e32 v15, v144
	v_add_u32_e32 v149, 0x7e, v149
	v_not_b32_e32 v144, v150
	v_or_b32_e32 v151, 0x80000000, v150
	v_cmp_gt_i32_e32 vcc, 0, v150
	v_not_b32_e32 v150, v15
	v_add_u32_e32 v10, 0x7f, v10
	v_cndmask_b32_e32 v144, v151, v144, vcc
	v_or_b32_e32 v151, 0x80000000, v15
	v_cmp_gt_i32_e32 vcc, 0, v15
	v_and_b32_e32 v144, 0xffffff80, v144
	v_sub_u32_e32 v144, v144, v8
	v_cndmask_b32_e32 v15, v151, v150, vcc
	v_and_b32_e32 v15, 0xffffff80, v15
	v_cvt_f32_f16_sdwa v150, v145 dst_sel:DWORD dst_unused:UNUSED_PAD src0_sel:WORD_1
	v_sub_u32_e32 v8, v15, v8
	v_cvt_f32_f16_e32 v15, v145
	v_add_u32_e32 v144, 0x7e, v144
	v_not_b32_e32 v145, v150
	v_or_b32_e32 v151, 0x80000000, v150
	v_cmp_gt_i32_e32 vcc, 0, v150
	v_not_b32_e32 v150, v15
	v_add_u32_e32 v8, 0x7f, v8
	v_cndmask_b32_e32 v145, v151, v145, vcc
	v_or_b32_e32 v151, 0x80000000, v15
	v_cmp_gt_i32_e32 vcc, 0, v15
	v_and_b32_e32 v145, 0xffffff80, v145
	v_sub_u32_e32 v145, v145, v16
	v_cndmask_b32_e32 v15, v151, v150, vcc
	v_and_b32_e32 v15, 0xffffff80, v15
	v_cvt_f32_f16_sdwa v150, v146 dst_sel:DWORD dst_unused:UNUSED_PAD src0_sel:WORD_1
	v_sub_u32_e32 v15, v15, v16
	v_cvt_f32_f16_e32 v16, v146
	v_add_u32_e32 v145, 0x7e, v145
	v_not_b32_e32 v146, v150
	v_or_b32_e32 v151, 0x80000000, v150
	v_cmp_gt_i32_e32 vcc, 0, v150
	v_not_b32_e32 v150, v16
	v_add_u32_e32 v15, 0x7f, v15
	v_cndmask_b32_e32 v146, v151, v146, vcc
	v_or_b32_e32 v151, 0x80000000, v16
	v_cmp_gt_i32_e32 vcc, 0, v16
	v_and_b32_e32 v146, 0xffffff80, v146
	v_sub_u32_e32 v146, v146, v17
	v_cndmask_b32_e32 v16, v151, v150, vcc
	v_and_b32_e32 v16, 0xffffff80, v16
	v_cvt_f32_f16_sdwa v150, v147 dst_sel:DWORD dst_unused:UNUSED_PAD src0_sel:WORD_1
	v_sub_u32_e32 v16, v16, v17
	v_cvt_f32_f16_e32 v17, v147
	v_add_u32_e32 v146, 0x7e, v146
	v_not_b32_e32 v147, v150
	v_or_b32_e32 v151, 0x80000000, v150
	v_cmp_gt_i32_e32 vcc, 0, v150
	v_not_b32_e32 v150, v17
	v_add_u32_e32 v16, 0x7f, v16
	v_cndmask_b32_e32 v147, v151, v147, vcc
	v_or_b32_e32 v151, 0x80000000, v17
	v_cmp_gt_i32_e32 vcc, 0, v17
	v_and_b32_e32 v147, 0xffffff80, v147
	v_sub_u32_e32 v147, v147, v18
	v_cndmask_b32_e32 v17, v151, v150, vcc
	v_and_b32_e32 v17, 0xffffff80, v17
	s_waitcnt vmcnt(0)
; __device__ __forceinline__ unsigned f2key(float f) { const unsigned u = __float_as_uint(f); return (u & 0x80000000u) ? ~u : (u | 0x80000000u); }
; #define CE_DESC(a, b) do { const unsigned _mx = (a) > (b) ? (a) : (b), _mn = (a) > (b) ? (b) : (a); (a) = _mx; (b) = _mn; } while (0)
; __device__ __forceinline__ void sort16_desc(unsigned (&k)[16]) {
; #pragma unroll
;     for (int size = 2; size <= 16; size <<= 1)
; #pragma unroll
;         for (int stride = size >> 1; stride > 0; stride >>= 1)
; #pragma unroll
;             for (int i = 0; i < 16; ++i) { const int j = i ^ stride;
;                 if (j > i) { if ((i & size) == 0) CE_DESC(k[i], k[j]); else CE_DESC(k[j], k[i]); } }
; }
; __device__ __forceinline__ void peer_tile(const Args& A, LAS unsigned char* lds, int tile) {
;     ...
;                   for (int i = 0; i < 16; ++i) {
;                       const float lo = (float)__builtin_bit_cast(_Float16, (unsigned short)(sw[i] & 0xffffu)), hi = (float)__builtin_bit_cast(_Float16, (unsigned short)(sw[i] >> 16));
;                       const unsigned klo = (f2key(lo) & ~127u) | (unsigned)(127 - (32 * g + 2 * i)), khi = (f2key(hi) & ~127u) | (unsigned)(127 - (32 * g + 2 * i + 1));
;                       if (i < 8) { k0[2 * i] = klo; k0[2 * i + 1] = khi; } else { k1[2 * (i - 8)] = klo; k1[2 * (i - 8) + 1] = khi; } } }
	v_cvt_f32_f16_sdwa v150, v152 dst_sel:DWORD dst_unused:UNUSED_PAD src0_sel:WORD_1
	v_sub_u32_e32 v17, v17, v18
	v_cvt_f32_f16_e32 v18, v152
	v_add_u32_e32 v147, 0x7e, v147
	v_not_b32_e32 v151, v150
	v_or_b32_e32 v152, 0x80000000, v150
	v_cmp_gt_i32_e32 vcc, 0, v150
	v_add_u32_e32 v17, 0x7f, v17
	s_nop 0
	v_cndmask_b32_e32 v150, v152, v151, vcc
	v_not_b32_e32 v151, v18
	v_or_b32_e32 v152, 0x80000000, v18
	v_cmp_gt_i32_e32 vcc, 0, v18
	v_and_b32_e32 v150, 0xffffff80, v150
	v_sub_u32_e32 v150, v150, v20
	v_cndmask_b32_e32 v18, v152, v151, vcc
	v_and_b32_e32 v18, 0xffffff80, v18
	v_cvt_f32_f16_sdwa v151, v153 dst_sel:DWORD dst_unused:UNUSED_PAD src0_sel:WORD_1
	v_sub_u32_e32 v18, v18, v20
	v_cvt_f32_f16_e32 v20, v153
	v_add_u32_e32 v150, 0x7e, v150
	v_not_b32_e32 v152, v151
	v_or_b32_e32 v153, 0x80000000, v151
	v_cmp_gt_i32_e32 vcc, 0, v151
	v_add_u32_e32 v18, 0x7f, v18
	v_max_u32_e32 v161, v18, v150
	v_cndmask_b32_e32 v151, v153, v152, vcc
	v_not_b32_e32 v152, v20
	v_or_b32_e32 v153, 0x80000000, v20
	v_cmp_gt_i32_e32 vcc, 0, v20
	v_and_b32_e32 v151, 0xffffff80, v151
	v_sub_u32_e32 v151, v151, v21
	v_cndmask_b32_e32 v20, v153, v152, vcc
	v_and_b32_e32 v20, 0xffffff80, v20
	v_cvt_f32_f16_sdwa v152, v154 dst_sel:DWORD dst_unused:UNUSED_PAD src0_sel:WORD_1
	v_sub_u32_e32 v20, v20, v21
	v_cvt_f32_f16_e32 v21, v154
	v_add_u32_e32 v151, 0x7e, v151
	v_not_b32_e32 v153, v152
	v_or_b32_e32 v154, 0x80000000, v152
	v_cmp_gt_i32_e32 vcc, 0, v152
	v_add_u32_e32 v20, 0x7f, v20
	v_min_u32_e32 v18, v18, v150
	v_cndmask_b32_e32 v152, v154, v153, vcc
	v_not_b32_e32 v153, v21
	v_or_b32_e32 v154, 0x80000000, v21
	v_cmp_gt_i32_e32 vcc, 0, v21
	v_and_b32_e32 v152, 0xffffff80, v152
	v_sub_u32_e32 v152, v152, v22
	v_cndmask_b32_e32 v21, v154, v153, vcc
	v_and_b32_e32 v21, 0xffffff80, v21
	v_cvt_f32_f16_sdwa v153, v155 dst_sel:DWORD dst_unused:UNUSED_PAD src0_sel:WORD_1
	v_sub_u32_e32 v21, v21, v22
	v_cvt_f32_f16_e32 v22, v155
	v_add_u32_e32 v152, 0x7e, v152
	v_not_b32_e32 v154, v153
	v_or_b32_e32 v155, 0x80000000, v153
	v_cmp_gt_i32_e32 vcc, 0, v153
	v_add_u32_e32 v21, 0x7f, v21
	v_max_u32_e32 v150, v151, v20
	v_cndmask_b32_e32 v153, v155, v154, vcc
	v_not_b32_e32 v154, v22
	v_or_b32_e32 v155, 0x80000000, v22
	v_cmp_gt_i32_e32 vcc, 0, v22
	v_and_b32_e32 v153, 0xffffff80, v153
	v_sub_u32_e32 v153, v153, v23
	v_cndmask_b32_e32 v22, v155, v154, vcc
	v_cvt_f32_f16_sdwa v154, v0 dst_sel:DWORD dst_unused:UNUSED_PAD src0_sel:WORD_1
	v_cvt_f32_f16_e32 v0, v0
	v_and_b32_e32 v22, 0xffffff80, v22
	v_sub_u32_e32 v22, v22, v23
	v_not_b32_e32 v23, v154
	v_or_b32_e32 v155, 0x80000000, v154
	v_cmp_gt_i32_e32 vcc, 0, v154
	v_not_b32_e32 v154, v0
	v_add_u32_e32 v153, 0x7e, v153
	v_cndmask_b32_e32 v23, v155, v23, vcc
	v_or_b32_e32 v155, 0x80000000, v0
	v_cmp_gt_i32_e32 vcc, 0, v0
	v_and_b32_e32 v23, 0xffffff80, v23
	v_sub_u32_e32 v23, v23, v24
	v_cndmask_b32_e32 v0, v155, v154, vcc
	v_cvt_f32_f16_sdwa v154, v1 dst_sel:DWORD dst_unused:UNUSED_PAD src0_sel:WORD_1
	v_cvt_f32_f16_e32 v1, v1
	v_and_b32_e32 v0, 0xffffff80, v0
	v_sub_u32_e32 v0, v0, v24
	v_not_b32_e32 v24, v154
	v_or_b32_e32 v155, 0x80000000, v154
	v_cmp_gt_i32_e32 vcc, 0, v154
	v_not_b32_e32 v154, v1
	v_add_u32_e32 v22, 0x7f, v22
	v_cndmask_b32_e32 v24, v155, v24, vcc
	v_or_b32_e32 v155, 0x80000000, v1
	v_cmp_gt_i32_e32 vcc, 0, v1
	v_and_b32_e32 v24, 0xffffff80, v24
	v_sub_u32_e32 v24, v24, v25
	v_cndmask_b32_e32 v1, v155, v154, vcc
	v_cvt_f32_f16_sdwa v154, v2 dst_sel:DWORD dst_unused:UNUSED_PAD src0_sel:WORD_1
	v_cvt_f32_f16_e32 v2, v2
	v_and_b32_e32 v1, 0xffffff80, v1
	v_sub_u32_e32 v1, v1, v25
	v_not_b32_e32 v25, v154
	v_or_b32_e32 v155, 0x80000000, v154
	v_cmp_gt_i32_e32 vcc, 0, v154
	v_not_b32_e32 v154, v2
	v_add_u32_e32 v23, 0x7e, v23
	v_cndmask_b32_e32 v25, v155, v25, vcc
	v_or_b32_e32 v155, 0x80000000, v2
	v_cmp_gt_i32_e32 vcc, 0, v2
	v_and_b32_e32 v25, 0xffffff80, v25
	v_sub_u32_e32 v25, v25, v26
	v_cndmask_b32_e32 v2, v155, v154, vcc
	v_cvt_f32_f16_sdwa v154, v3 dst_sel:DWORD dst_unused:UNUSED_PAD src0_sel:WORD_1
	v_cvt_f32_f16_e32 v3, v3
	v_and_b32_e32 v2, 0xffffff80, v2
	v_sub_u32_e32 v2, v2, v26
	v_not_b32_e32 v26, v154
	v_or_b32_e32 v155, 0x80000000, v154
	v_cmp_gt_i32_e32 vcc, 0, v154
	v_not_b32_e32 v154, v3
	v_add_u32_e32 v0, 0x7f, v0
	v_cndmask_b32_e32 v26, v155, v26, vcc
	v_or_b32_e32 v155, 0x80000000, v3
	v_cmp_gt_i32_e32 vcc, 0, v3
	v_and_b32_e32 v26, 0xffffff80, v26
	v_sub_u32_e32 v26, v26, v28
	v_cndmask_b32_e32 v3, v155, v154, vcc
	v_and_b32_e32 v3, 0xffffff80, v3
	v_sub_u32_e32 v3, v3, v28
	v_add_u32_e32 v24, 0x7e, v24
	v_add_u32_e32 v1, 0x7f, v1
	v_add_u32_e32 v25, 0x7e, v25
	v_add_u32_e32 v2, 0x7f, v2
	v_add_u32_e32 v26, 0x7e, v26
	v_add_u32_e32 v3, 0x7f, v3
	v_max_u32_e32 v28, v4, v5
	v_min_u32_e32 v4, v4, v5
	v_max_u32_e32 v5, v143, v14
	v_min_u32_e32 v14, v143, v14
	v_max_u32_e32 v143, v12, v148
	v_min_u32_e32 v12, v12, v148
	v_max_u32_e32 v148, v149, v10
	v_min_u32_e32 v10, v149, v10
	v_max_u32_e32 v149, v8, v144
	v_min_u32_e32 v8, v8, v144
	v_max_u32_e32 v144, v145, v15
	v_min_u32_e32 v15, v145, v15
	v_max_u32_e32 v145, v16, v146
	v_min_u32_e32 v16, v16, v146
	v_max_u32_e32 v146, v147, v17
	v_min_u32_e32 v17, v147, v17
	v_min_u32_e32 v20, v151, v20
	v_max_u32_e32 v151, v21, v152
	v_min_u32_e32 v21, v21, v152
	v_max_u32_e32 v152, v153, v22
	v_min_u32_e32 v22, v153, v22
	v_max_u32_e32 v153, v0, v23
	v_min_u32_e32 v0, v0, v23
	v_max_u32_e32 v23, v24, v1
	v_min_u32_e32 v1, v24, v1
	v_max_u32_e32 v24, v2, v25
	v_min_u32_e32 v2, v2, v25
	v_max_u32_e32 v25, v26, v3
	v_min_u32_e32 v3, v26, v3
	v_max_u32_e32 v147, v28, v14
	v_min_u32_e32 v14, v28, v14
	v_max_u32_e32 v28, v4, v5
	v_min_u32_e32 v4, v4, v5
; #define CE_DESC(a, b) do { const unsigned _mx = (a) > (b) ? (a) : (b), _mn = (a) > (b) ? (b) : (a); (a) = _mx; (b) = _mn; } while (0)
; __device__ __forceinline__ void sort16_desc(unsigned (&k)[16]) {
; #pragma unroll
;     for (int size = 2; size <= 16; size <<= 1)
; #pragma unroll
;         for (int stride = size >> 1; stride > 0; stride >>= 1)
; #pragma unroll
;             for (int i = 0; i < 16; ++i) { const int j = i ^ stride;
;                 if (j > i) { if ((i & size) == 0) CE_DESC(k[i], k[j]); else CE_DESC(k[j], k[i]); } }
; }
	v_max_u32_e32 v5, v10, v143
	v_min_u32_e32 v10, v10, v143
	v_max_u32_e32 v143, v148, v12
	v_min_u32_e32 v12, v148, v12
	v_max_u32_e32 v148, v149, v15
	v_min_u32_e32 v15, v149, v15
	v_max_u32_e32 v149, v8, v144
	v_min_u32_e32 v8, v8, v144
	v_max_u32_e32 v144, v17, v145
	v_min_u32_e32 v17, v17, v145
	v_max_u32_e32 v145, v146, v16
	v_min_u32_e32 v16, v146, v16
	v_max_u32_e32 v26, v161, v20
	v_min_u32_e32 v20, v161, v20
	v_max_u32_e32 v161, v18, v150
	v_min_u32_e32 v18, v18, v150
	v_max_u32_e32 v150, v22, v151
	v_min_u32_e32 v22, v22, v151
	v_max_u32_e32 v151, v152, v21
	v_min_u32_e32 v21, v152, v21
	v_max_u32_e32 v152, v153, v1
	v_min_u32_e32 v1, v153, v1
	v_max_u32_e32 v153, v0, v23
	v_min_u32_e32 v0, v0, v23
	v_max_u32_e32 v23, v3, v24
	v_min_u32_e32 v3, v3, v24
	v_max_u32_e32 v24, v25, v2
	v_min_u32_e32 v2, v25, v2
	v_max_u32_e32 v146, v147, v28
	v_min_u32_e32 v28, v147, v28
	v_max_u32_e32 v147, v14, v4
	v_min_u32_e32 v4, v14, v4
	v_max_u32_e32 v14, v12, v10
	v_min_u32_e32 v10, v12, v10
	v_max_u32_e32 v12, v143, v5
	v_min_u32_e32 v5, v143, v5
	v_max_u32_e32 v143, v148, v149
	v_min_u32_e32 v148, v148, v149
	v_max_u32_e32 v149, v15, v8
	v_min_u32_e32 v8, v15, v8
	v_max_u32_e32 v15, v16, v17
	v_min_u32_e32 v16, v16, v17
	v_max_u32_e32 v17, v145, v144
	v_min_u32_e32 v144, v145, v144
	v_max_u32_e32 v25, v26, v161
	v_min_u32_e32 v26, v26, v161
	v_max_u32_e32 v161, v20, v18
	v_min_u32_e32 v18, v20, v18
	v_max_u32_e32 v20, v21, v22
	v_min_u32_e32 v21, v21, v22
	v_max_u32_e32 v22, v151, v150
	v_min_u32_e32 v150, v151, v150
	v_max_u32_e32 v151, v152, v153
	v_min_u32_e32 v152, v152, v153
	v_max_u32_e32 v153, v1, v0
	v_min_u32_e32 v0, v1, v0
	v_max_u32_e32 v1, v2, v3
	v_min_u32_e32 v2, v2, v3
	v_max_u32_e32 v3, v24, v23
	v_min_u32_e32 v23, v24, v23
	v_max_u32_e32 v145, v146, v10
	v_min_u32_e32 v10, v146, v10
	v_max_u32_e32 v146, v28, v14
	v_min_u32_e32 v14, v28, v14
	v_max_u32_e32 v28, v147, v5
	v_min_u32_e32 v5, v147, v5
	v_max_u32_e32 v147, v4, v12
	v_min_u32_e32 v4, v4, v12
	v_max_u32_e32 v12, v16, v143
	v_min_u32_e32 v16, v16, v143
	v_max_u32_e32 v143, v15, v148
	v_min_u32_e32 v15, v15, v148
	v_max_u32_e32 v148, v144, v149
	v_min_u32_e32 v144, v144, v149
	v_max_u32_e32 v149, v17, v8
	v_min_u32_e32 v8, v17, v8
	v_max_u32_e32 v24, v25, v21
	v_min_u32_e32 v21, v25, v21
	v_max_u32_e32 v25, v26, v20
	v_min_u32_e32 v20, v26, v20
	v_max_u32_e32 v26, v161, v150
	v_min_u32_e32 v150, v161, v150
	v_max_u32_e32 v161, v18, v22
	v_min_u32_e32 v18, v18, v22
	v_max_u32_e32 v22, v2, v151
	v_min_u32_e32 v2, v2, v151
	v_max_u32_e32 v151, v1, v152
	v_min_u32_e32 v1, v1, v152
	v_max_u32_e32 v152, v23, v153
	v_min_u32_e32 v23, v23, v153
	v_max_u32_e32 v153, v3, v0
	v_min_u32_e32 v0, v3, v0
	v_max_u32_e32 v17, v145, v28
	v_min_u32_e32 v28, v145, v28
	v_max_u32_e32 v145, v146, v147
	v_min_u32_e32 v146, v146, v147
	v_max_u32_e32 v147, v10, v5
	v_min_u32_e32 v5, v10, v5
	v_max_u32_e32 v10, v14, v4
	v_min_u32_e32 v4, v14, v4
	v_max_u32_e32 v14, v144, v16
	v_min_u32_e32 v16, v144, v16
	v_max_u32_e32 v144, v8, v15
	v_min_u32_e32 v8, v8, v15
	v_max_u32_e32 v15, v148, v12
	v_min_u32_e32 v12, v148, v12
	v_max_u32_e32 v148, v149, v143
	v_min_u32_e32 v143, v149, v143
	v_max_u32_e32 v3, v24, v26
	v_min_u32_e32 v24, v24, v26
	v_max_u32_e32 v26, v25, v161
	v_min_u32_e32 v25, v25, v161
	v_max_u32_e32 v161, v21, v150
	v_min_u32_e32 v21, v21, v150
	v_max_u32_e32 v150, v20, v18
	v_min_u32_e32 v18, v20, v18
	v_max_u32_e32 v20, v23, v2
	v_min_u32_e32 v2, v23, v2
	v_max_u32_e32 v23, v0, v1
	v_min_u32_e32 v0, v0, v1
	v_max_u32_e32 v1, v152, v22
	v_min_u32_e32 v22, v152, v22
	v_max_u32_e32 v152, v153, v151
	v_min_u32_e32 v151, v153, v151
	v_max_u32_e32 v149, v17, v145
	v_min_u32_e32 v17, v17, v145
	v_max_u32_e32 v145, v28, v146
	v_min_u32_e32 v28, v28, v146
	v_max_u32_e32 v146, v147, v10
	v_min_u32_e32 v10, v147, v10
	v_max_u32_e32 v147, v5, v4
	v_min_u32_e32 v4, v5, v4
	v_max_u32_e32 v5, v8, v16
	v_min_u32_e32 v8, v8, v16
	v_max_u32_e32 v16, v144, v14
	v_min_u32_e32 v14, v144, v14
	v_max_u32_e32 v144, v143, v12
	v_min_u32_e32 v12, v143, v12
	v_max_u32_e32 v143, v148, v15
	v_min_u32_e32 v15, v148, v15
	v_max_u32_e32 v153, v3, v26
	v_min_u32_e32 v3, v3, v26
	v_max_u32_e32 v26, v24, v25
	v_min_u32_e32 v24, v24, v25
	v_max_u32_e32 v25, v161, v150
	v_min_u32_e32 v150, v161, v150
	v_max_u32_e32 v161, v21, v18
	v_min_u32_e32 v18, v21, v18
	v_max_u32_e32 v21, v0, v2
	v_min_u32_e32 v0, v0, v2
	v_max_u32_e32 v2, v23, v20
	v_min_u32_e32 v20, v23, v20
	v_max_u32_e32 v23, v151, v22
	v_min_u32_e32 v22, v151, v22
	v_max_u32_e32 v151, v152, v1
	v_min_u32_e32 v1, v152, v1
	v_max_u32_e32 v148, v149, v8
	v_min_u32_e32 v8, v149, v8
	v_max_u32_e32 v149, v17, v5
	v_min_u32_e32 v5, v17, v5
	v_max_u32_e32 v17, v145, v14
	v_min_u32_e32 v14, v145, v14
	v_max_u32_e32 v145, v28, v16
	v_min_u32_e32 v16, v28, v16
	v_max_u32_e32 v28, v146, v12
	v_min_u32_e32 v12, v146, v12
	v_max_u32_e32 v146, v10, v144
	v_min_u32_e32 v10, v10, v144
	v_max_u32_e32 v144, v147, v15
	v_min_u32_e32 v15, v147, v15
	v_max_u32_e32 v147, v4, v143
	v_min_u32_e32 v4, v4, v143
	v_max_u32_e32 v152, v153, v0
	v_min_u32_e32 v0, v153, v0
	v_max_u32_e32 v153, v3, v21
	v_min_u32_e32 v3, v3, v21
	v_max_u32_e32 v21, v26, v20
	v_min_u32_e32 v20, v26, v20
	v_max_u32_e32 v26, v24, v2
	v_min_u32_e32 v2, v24, v2
	v_max_u32_e32 v24, v25, v22
	v_min_u32_e32 v22, v25, v22
	v_max_u32_e32 v25, v150, v23
	v_min_u32_e32 v23, v150, v23
	v_max_u32_e32 v150, v161, v1
	v_min_u32_e32 v1, v161, v1
	v_max_u32_e32 v161, v18, v151
	v_min_u32_e32 v18, v18, v151
	v_max_u32_e32 v143, v148, v28
	v_min_u32_e32 v28, v148, v28
	v_max_u32_e32 v148, v149, v146
	v_min_u32_e32 v146, v149, v146
; #define CE_DESC(a, b) do { const unsigned _mx = (a) > (b) ? (a) : (b), _mn = (a) > (b) ? (b) : (a); (a) = _mx; (b) = _mn; } while (0)
; __device__ __forceinline__ void merge16(unsigned (&a)[16], const unsigned (&b)[16]) {
; #pragma unroll
;     for (int i = 0; i < 16; ++i) a[i] = a[i] > b[15 - i] ? a[i] : b[15 - i];
; #pragma unroll
;     for (int stride = 8; stride > 0; stride >>= 1)
; #pragma unroll
;         for (int i = 0; i < 16; ++i) { const int j = i ^ stride; if (j > i) CE_DESC(a[i], a[j]); }
; }
; __device__ __forceinline__ void peer_tile(const Args& A, LAS unsigned char* lds, int tile) {
;     ...
;                 sort16_desc(k0); sort16_desc(k1); merge16(k0, k1);
; #pragma unroll
;                 for (int msk = 16; msk <= 32; msk <<= 1) {
; #pragma unroll
;                     for (int i = 0; i < 16; ++i) k1[i] = (unsigned)__shfl_xor((int)k0[i], msk);
;                     merge16(k0, k1); }
	v_max_u32_e32 v149, v17, v144
	v_min_u32_e32 v17, v17, v144
	v_max_u32_e32 v144, v145, v147
	v_min_u32_e32 v145, v145, v147
	v_max_u32_e32 v147, v8, v12
	v_min_u32_e32 v8, v8, v12
	v_max_u32_e32 v12, v5, v10
	v_min_u32_e32 v5, v5, v10
	v_max_u32_e32 v10, v14, v15
	v_min_u32_e32 v14, v14, v15
	v_max_u32_e32 v15, v16, v4
	v_min_u32_e32 v4, v16, v4
	v_max_u32_e32 v151, v152, v24
	v_min_u32_e32 v24, v152, v24
	v_max_u32_e32 v152, v153, v25
	v_min_u32_e32 v25, v153, v25
	v_max_u32_e32 v153, v21, v150
	v_min_u32_e32 v21, v21, v150
	v_max_u32_e32 v150, v26, v161
	v_min_u32_e32 v26, v26, v161
	v_max_u32_e32 v161, v0, v22
	v_min_u32_e32 v0, v0, v22
	v_max_u32_e32 v22, v3, v23
	v_min_u32_e32 v3, v3, v23
	v_max_u32_e32 v23, v20, v1
	v_min_u32_e32 v1, v20, v1
	v_max_u32_e32 v20, v2, v18
	v_min_u32_e32 v2, v2, v18
	v_max_u32_e32 v16, v143, v149
	v_min_u32_e32 v143, v143, v149
	v_max_u32_e32 v149, v148, v144
	v_min_u32_e32 v144, v148, v144
	v_max_u32_e32 v148, v28, v17
	v_min_u32_e32 v17, v28, v17
	v_max_u32_e32 v28, v146, v145
	v_min_u32_e32 v145, v146, v145
	v_max_u32_e32 v146, v147, v10
	v_min_u32_e32 v10, v147, v10
	v_max_u32_e32 v147, v12, v15
	v_min_u32_e32 v12, v12, v15
	v_max_u32_e32 v15, v8, v14
	v_min_u32_e32 v8, v8, v14
	v_max_u32_e32 v14, v5, v4
	v_min_u32_e32 v4, v5, v4
	v_max_u32_e32 v18, v151, v153
	v_min_u32_e32 v151, v151, v153
	v_max_u32_e32 v153, v152, v150
	v_min_u32_e32 v150, v152, v150
	v_max_u32_e32 v152, v24, v21
	v_min_u32_e32 v21, v24, v21
	v_max_u32_e32 v24, v25, v26
	v_min_u32_e32 v25, v25, v26
	v_max_u32_e32 v26, v161, v23
	v_min_u32_e32 v23, v161, v23
	v_max_u32_e32 v161, v22, v20
	v_min_u32_e32 v20, v22, v20
	v_max_u32_e32 v22, v0, v1
	v_min_u32_e32 v0, v0, v1
	v_max_u32_e32 v1, v3, v2
	v_min_u32_e32 v2, v3, v2
	v_min_u32_e32 v5, v16, v149
	v_min_u32_e32 v154, v143, v144
	v_min_u32_e32 v155, v148, v28
	v_min_u32_e32 v156, v17, v145
	v_min_u32_e32 v157, v146, v147
	v_min_u32_e32 v158, v10, v12
	v_min_u32_e32 v159, v15, v14
	v_min_u32_e32 v160, v8, v4
	v_min_u32_e32 v3, v18, v153
	v_min_u32_e32 v162, v151, v150
	v_min_u32_e32 v163, v152, v24
	v_min_u32_e32 v164, v21, v25
	v_min_u32_e32 v165, v26, v161
	v_min_u32_e32 v166, v23, v20
	v_min_u32_e32 v167, v22, v1
	v_min_u32_e32 v168, v0, v2
	v_max3_u32 v16, v16, v149, v168
	v_max3_u32 v0, v5, v0, v2
	v_max3_u32 v2, v143, v144, v167
	v_max3_u32 v1, v154, v22, v1
	v_max3_u32 v5, v148, v28, v166
	v_max3_u32 v20, v155, v23, v20
	v_max3_u32 v17, v17, v145, v165
	v_max3_u32 v22, v156, v26, v161
	v_max3_u32 v23, v146, v147, v164
	v_max3_u32 v21, v157, v21, v25
	v_max3_u32 v10, v10, v12, v163
	v_max3_u32 v12, v158, v152, v24
	v_max3_u32 v14, v15, v14, v162
	v_max3_u32 v15, v159, v151, v150
	v_max3_u32 v3, v8, v4, v3
	v_max3_u32 v4, v160, v18, v153
	v_max_u32_e32 v8, v16, v23
	v_min_u32_e32 v16, v16, v23
	v_max_u32_e32 v18, v0, v21
	v_min_u32_e32 v0, v0, v21
	v_max_u32_e32 v21, v2, v10
	v_min_u32_e32 v2, v2, v10
	v_max_u32_e32 v10, v1, v12
	v_min_u32_e32 v1, v1, v12
	v_max_u32_e32 v12, v5, v14
	v_min_u32_e32 v5, v5, v14
	v_max_u32_e32 v14, v20, v15
	v_min_u32_e32 v15, v20, v15
	v_max_u32_e32 v20, v17, v3
	v_min_u32_e32 v3, v17, v3
	v_max_u32_e32 v17, v22, v4
	v_min_u32_e32 v4, v22, v4
	v_max_u32_e32 v22, v8, v12
	v_min_u32_e32 v8, v8, v12
	v_max_u32_e32 v12, v18, v14
	v_min_u32_e32 v14, v18, v14
	v_max_u32_e32 v18, v21, v20
	v_min_u32_e32 v20, v21, v20
	v_max_u32_e32 v21, v10, v17
	v_min_u32_e32 v10, v10, v17
	v_max_u32_e32 v17, v16, v5
	v_min_u32_e32 v5, v16, v5
	v_max_u32_e32 v16, v0, v15
	v_min_u32_e32 v0, v0, v15
	v_max_u32_e32 v15, v2, v3
	v_min_u32_e32 v2, v2, v3
	v_max_u32_e32 v3, v1, v4
	v_min_u32_e32 v1, v1, v4
	v_max_u32_e32 v4, v22, v18
	v_min_u32_e32 v18, v22, v18
	v_max_u32_e32 v22, v12, v21
	v_min_u32_e32 v12, v12, v21
	v_max_u32_e32 v21, v8, v20
	v_min_u32_e32 v8, v8, v20
	v_max_u32_e32 v20, v14, v10
	v_min_u32_e32 v10, v14, v10
	v_max_u32_e32 v14, v17, v15
	v_min_u32_e32 v15, v17, v15
	v_max_u32_e32 v17, v16, v3
	v_min_u32_e32 v3, v16, v3
	v_max_u32_e32 v16, v5, v2
	v_min_u32_e32 v2, v5, v2
	v_max_u32_e32 v5, v0, v1
	v_min_u32_e32 v0, v0, v1
	v_max_u32_e32 v1, v4, v22
	v_min_u32_e32 v4, v4, v22
	v_max_u32_e32 v22, v18, v12
	v_min_u32_e32 v12, v18, v12
	v_max_u32_e32 v18, v21, v20
	v_min_u32_e32 v20, v21, v20
	v_max_u32_e32 v21, v8, v10
	v_min_u32_e32 v8, v8, v10
	v_max_u32_e32 v10, v14, v17
	v_min_u32_e32 v14, v14, v17
	v_max_u32_e32 v17, v15, v3
	v_min_u32_e32 v3, v15, v3
	v_max_u32_e32 v15, v16, v5
	v_min_u32_e32 v5, v16, v5
	v_max_u32_e32 v16, v2, v0
	v_min_u32_e32 v0, v2, v0
	ds_bpermute_b32 v2, v27, v1
	ds_bpermute_b32 v23, v27, v4
	ds_bpermute_b32 v24, v27, v22
	ds_bpermute_b32 v25, v27, v12
	ds_bpermute_b32 v26, v27, v18
	ds_bpermute_b32 v28, v27, v20
	ds_bpermute_b32 v143, v27, v21
	ds_bpermute_b32 v144, v27, v8
	ds_bpermute_b32 v145, v27, v10
	ds_bpermute_b32 v146, v27, v14
	ds_bpermute_b32 v147, v27, v17
	ds_bpermute_b32 v148, v27, v0
	ds_bpermute_b32 v149, v27, v16
	ds_bpermute_b32 v150, v27, v5
	ds_bpermute_b32 v151, v27, v15
	ds_bpermute_b32 v27, v27, v3
	s_waitcnt lgkmcnt(4)
	v_max_u32_e32 v1, v1, v148
	s_waitcnt lgkmcnt(3)
	v_max_u32_e32 v4, v4, v149
	s_waitcnt lgkmcnt(2)
	v_max_u32_e32 v22, v22, v150
	s_waitcnt lgkmcnt(1)
	v_max_u32_e32 v12, v12, v151
	s_waitcnt lgkmcnt(0)
; __device__ __forceinline__ void peer_tile(const Args& A, LAS unsigned char* lds, int tile) {
;     ...
;                 for (int msk = 16; msk <= 32; msk <<= 1) {
; #pragma unroll
;                     for (int i = 0; i < 16; ++i) k1[i] = (unsigned)__shfl_xor((int)k0[i], msk);
;                     merge16(k0, k1); }
; #pragma unroll
;                 for (int i = 0; i < 16; ++i) LA[hh][p][i] = k0[i];
;     ...
;                 for (int i = 0; i < 16; ++i) L2[p][i] = (g & 2) ? ((g & 1) ? LA[3][p][i] : LA[2][p][i]) : ((g & 1) ? LA[1][p][i] : LA[0][p][i]);
	v_max_u32_e32 v18, v18, v27
	v_max_u32_e32 v20, v20, v147
	v_max_u32_e32 v21, v21, v146
	v_max_u32_e32 v8, v8, v145
	v_max_u32_e32 v10, v10, v144
	v_max_u32_e32 v14, v14, v143
	v_max_u32_e32 v17, v17, v28
	v_max_u32_e32 v3, v3, v26
	v_max_u32_e32 v15, v15, v25
	v_max_u32_e32 v5, v5, v24
	v_max_u32_e32 v16, v16, v23
	v_max_u32_e32 v0, v0, v2
	v_max_u32_e32 v2, v1, v10
	v_min_u32_e32 v1, v1, v10
	v_max_u32_e32 v10, v4, v14
	v_min_u32_e32 v4, v4, v14
	v_max_u32_e32 v14, v22, v17
	v_min_u32_e32 v17, v22, v17
	v_max_u32_e32 v22, v12, v3
	v_min_u32_e32 v3, v12, v3
	v_max_u32_e32 v12, v18, v15
	v_min_u32_e32 v15, v18, v15
	v_max_u32_e32 v18, v20, v5
	v_min_u32_e32 v5, v20, v5
	v_max_u32_e32 v20, v21, v16
	v_min_u32_e32 v16, v21, v16
	v_max_u32_e32 v21, v8, v0
	v_min_u32_e32 v0, v8, v0
	v_max_u32_e32 v8, v2, v12
	v_min_u32_e32 v2, v2, v12
	v_max_u32_e32 v12, v10, v18
	v_min_u32_e32 v10, v10, v18
	v_max_u32_e32 v18, v14, v20
	v_min_u32_e32 v14, v14, v20
	v_max_u32_e32 v20, v22, v21
	v_min_u32_e32 v21, v22, v21
	v_max_u32_e32 v22, v1, v15
	v_min_u32_e32 v1, v1, v15
	v_max_u32_e32 v15, v4, v5
	v_min_u32_e32 v4, v4, v5
	v_max_u32_e32 v5, v17, v16
	v_min_u32_e32 v16, v17, v16
	v_max_u32_e32 v17, v3, v0
	v_min_u32_e32 v0, v3, v0
	v_max_u32_e32 v3, v8, v18
	v_min_u32_e32 v8, v8, v18
	v_max_u32_e32 v18, v12, v20
	v_min_u32_e32 v12, v12, v20
	v_max_u32_e32 v20, v2, v14
	v_min_u32_e32 v2, v2, v14
	v_max_u32_e32 v14, v10, v21
	v_min_u32_e32 v10, v10, v21
	v_max_u32_e32 v21, v22, v5
	v_min_u32_e32 v5, v22, v5
	v_max_u32_e32 v22, v15, v17
	v_min_u32_e32 v15, v15, v17
	v_max_u32_e32 v17, v1, v16
	v_min_u32_e32 v1, v1, v16
	v_max_u32_e32 v16, v4, v0
	v_min_u32_e32 v0, v4, v0
	v_max_u32_e32 v4, v3, v18
	v_min_u32_e32 v3, v3, v18
	v_max_u32_e32 v18, v8, v12
	v_min_u32_e32 v8, v8, v12
	v_max_u32_e32 v12, v20, v14
	v_min_u32_e32 v14, v20, v14
	v_max_u32_e32 v20, v2, v10
	v_min_u32_e32 v2, v2, v10
	v_max_u32_e32 v10, v21, v22
	v_min_u32_e32 v21, v21, v22
	v_max_u32_e32 v22, v5, v15
	v_min_u32_e32 v5, v5, v15
	v_max_u32_e32 v15, v17, v16
	v_min_u32_e32 v16, v17, v16
	v_max_u32_e32 v17, v1, v0
	v_min_u32_e32 v0, v1, v0
	ds_bpermute_b32 v1, v29, v4
	ds_bpermute_b32 v23, v29, v3
	ds_bpermute_b32 v24, v29, v18
	ds_bpermute_b32 v25, v29, v8
	ds_bpermute_b32 v26, v29, v12
	ds_bpermute_b32 v27, v29, v14
	ds_bpermute_b32 v28, v29, v20
	ds_bpermute_b32 v143, v29, v2
	ds_bpermute_b32 v144, v29, v10
	ds_bpermute_b32 v145, v29, v21
	ds_bpermute_b32 v146, v29, v22
	ds_bpermute_b32 v147, v29, v0
	ds_bpermute_b32 v148, v29, v17
	ds_bpermute_b32 v149, v29, v16
	ds_bpermute_b32 v150, v29, v15
	ds_bpermute_b32 v29, v29, v5
	s_waitcnt lgkmcnt(4)
	v_max_u32_e32 v4, v4, v147
	s_waitcnt lgkmcnt(3)
	v_max_u32_e32 v3, v3, v148
	s_waitcnt lgkmcnt(2)
	v_max_u32_e32 v18, v18, v149
	s_waitcnt lgkmcnt(1)
	v_max_u32_e32 v8, v8, v150
	s_waitcnt lgkmcnt(0)
	v_max_u32_e32 v12, v12, v29
	v_max_u32_e32 v14, v14, v146
	v_max_u32_e32 v20, v20, v145
	v_max_u32_e32 v2, v2, v144
	v_max_u32_e32 v10, v10, v143
	v_max_u32_e32 v21, v21, v28
	v_max_u32_e32 v22, v22, v27
	v_max_u32_e32 v5, v5, v26
	v_max_u32_e32 v15, v15, v25
	v_max_u32_e32 v16, v16, v24
	v_max_u32_e32 v17, v17, v23
	v_max_u32_e32 v0, v0, v1
	v_max_u32_e32 v1, v4, v10
	v_min_u32_e32 v4, v4, v10
	v_max_u32_e32 v10, v3, v21
	v_min_u32_e32 v3, v3, v21
	v_max_u32_e32 v21, v18, v22
	v_min_u32_e32 v18, v18, v22
	v_max_u32_e32 v22, v8, v5
	v_min_u32_e32 v5, v8, v5
	v_max_u32_e32 v8, v12, v15
	v_min_u32_e32 v12, v12, v15
	v_max_u32_e32 v15, v14, v16
	v_min_u32_e32 v14, v14, v16
	v_max_u32_e32 v16, v20, v17
	v_min_u32_e32 v17, v20, v17
	v_max_u32_e32 v20, v2, v0
	v_min_u32_e32 v0, v2, v0
	v_max_u32_e32 v2, v1, v8
	v_min_u32_e32 v1, v1, v8
	v_max_u32_e32 v8, v10, v15
	v_min_u32_e32 v10, v10, v15
	v_max_u32_e32 v15, v21, v16
	v_min_u32_e32 v16, v21, v16
	v_max_u32_e32 v21, v22, v20
	v_min_u32_e32 v20, v22, v20
	v_max_u32_e32 v22, v4, v12
	v_min_u32_e32 v4, v4, v12
	v_max_u32_e32 v12, v3, v14
	v_min_u32_e32 v3, v3, v14
	v_max_u32_e32 v14, v18, v17
	v_min_u32_e32 v17, v18, v17
	v_max_u32_e32 v18, v5, v0
	v_min_u32_e32 v0, v5, v0
	v_max_u32_e32 v5, v2, v15
	v_min_u32_e32 v2, v2, v15
	v_max_u32_e32 v15, v8, v21
	v_min_u32_e32 v8, v8, v21
	v_max_u32_e32 v21, v1, v16
	v_min_u32_e32 v1, v1, v16
	v_max_u32_e32 v16, v10, v20
	v_min_u32_e32 v10, v10, v20
	v_max_u32_e32 v20, v22, v14
	v_min_u32_e32 v14, v22, v14
	v_max_u32_e32 v22, v12, v18
	v_min_u32_e32 v12, v12, v18
	v_max_u32_e32 v18, v4, v17
	v_min_u32_e32 v4, v4, v17
	v_max_u32_e32 v17, v3, v0
	v_min_u32_e32 v0, v3, v0
	v_max_u32_e32 v3, v5, v15
	v_min_u32_e32 v5, v5, v15
	v_max_u32_e32 v15, v2, v8
	v_min_u32_e32 v2, v2, v8
	v_max_u32_e32 v8, v21, v16
	v_min_u32_e32 v16, v21, v16
	v_max_u32_e32 v21, v1, v10
	v_min_u32_e32 v1, v1, v10
	v_max_u32_e32 v10, v20, v22
	v_min_u32_e32 v20, v20, v22
	v_max_u32_e32 v22, v14, v12
	v_min_u32_e32 v12, v14, v12
	v_max_u32_e32 v14, v18, v17
	v_min_u32_e32 v17, v18, v17
	v_max_u32_e32 v18, v4, v0
	v_min_u32_e32 v0, v4, v0
	v_and_b32_e32 v4, 16, v19
	v_cmp_eq_u32_e32 vcc, 0, v4
	v_cndmask_b32_e64 v23, v77, v45, s[0:1]
	v_cndmask_b32_e64 v24, v76, v44, s[0:1]
	v_cndmask_b32_e32 v4, v142, v109, vcc
	v_cndmask_b32_e64 v4, v4, v23, s[4:5]
	v_cndmask_b32_e32 v23, v141, v108, vcc
	v_cndmask_b32_e64 v23, v23, v24, s[4:5]
	v_cndmask_b32_e32 v24, v140, v107, vcc
	v_cndmask_b32_e64 v25, v75, v43, s[0:1]
	v_cndmask_b32_e64 v24, v24, v25, s[4:5]
	v_cndmask_b32_e32 v25, v139, v106, vcc
	v_cndmask_b32_e64 v26, v74, v42, s[0:1]
	v_cndmask_b32_e64 v25, v25, v26, s[4:5]
	v_cndmask_b32_e32 v26, v138, v105, vcc
	v_cndmask_b32_e64 v27, v73, v41, s[0:1]
	v_cndmask_b32_e64 v26, v26, v27, s[4:5]
; __device__ __forceinline__ float key2f(unsigned k) { const unsigned u = (k & 0x80000000u) ? (k & 0x7fffffffu) : ~k; return __uint_as_float(u); }
; __device__ __forceinline__ void peer_tile(const Args& A, LAS unsigned char* lds, int tile) {
;     ...
;                 for (int i = 0; i < 16; ++i) L2[p][i] = (g & 2) ? ((g & 1) ? LA[3][p][i] : LA[2][p][i]) : ((g & 1) ? LA[1][p][i] : LA[0][p][i]);
;             float va[16], vb[16];
; #pragma unroll
;             for (int i = 0; i < 16; ++i) { va[i] = key2f(L2[0][i] & ~127u); vb[i] = key2f(L2[1][i] & ~127u); idx[i] = 127u - (L2[0][i] & 127u); idx[16 + i] = 127u - (L2[1][i] & 127u); }
	v_cndmask_b32_e32 v27, v137, v104, vcc
	v_cndmask_b32_e64 v28, v72, v40, s[0:1]
	v_cndmask_b32_e64 v27, v27, v28, s[4:5]
	v_cndmask_b32_e32 v28, v136, v103, vcc
	v_cndmask_b32_e64 v29, v71, v39, s[0:1]
	v_cndmask_b32_e64 v28, v28, v29, s[4:5]
	v_cndmask_b32_e32 v29, v135, v102, vcc
	v_cndmask_b32_e64 v29, v29, v38, s[4:5]
	v_cndmask_b32_e32 v38, v134, v101, vcc
	v_cndmask_b32_e64 v37, v38, v37, s[4:5]
	v_cndmask_b32_e32 v38, v133, v100, vcc
	v_cndmask_b32_e64 v36, v38, v36, s[4:5]
	v_cndmask_b32_e32 v38, v132, v99, vcc
	v_cndmask_b32_e64 v38, v38, v35, s[4:5]
	v_cndmask_b32_e32 v35, v131, v98, vcc
	v_cndmask_b32_e64 v39, v35, v34, s[4:5]
	v_cndmask_b32_e32 v34, v130, v97, vcc
	v_cndmask_b32_e64 v33, v34, v33, s[4:5]
	v_cndmask_b32_e32 v34, v129, v96, vcc
	v_cndmask_b32_e64 v40, v34, v32, s[4:5]
	v_cndmask_b32_e32 v32, v128, v95, vcc
	v_cndmask_b32_e64 v42, v32, v31, s[4:5]
	v_cndmask_b32_e32 v31, v127, v94, vcc
	v_cndmask_b32_e64 v43, v31, v30, s[4:5]
	v_cndmask_b32_e32 v3, v3, v126, vcc
	v_cndmask_b32_e64 v30, v93, v61, s[0:1]
	v_cndmask_b32_e64 v3, v3, v30, s[4:5]
	v_cndmask_b32_e32 v5, v5, v125, vcc
	v_cndmask_b32_e64 v30, v92, v60, s[0:1]
	v_cndmask_b32_e64 v30, v5, v30, s[4:5]
	v_cndmask_b32_e32 v5, v15, v124, vcc
	v_cndmask_b32_e64 v15, v91, v59, s[0:1]
	v_cndmask_b32_e64 v15, v5, v15, s[4:5]
	v_cndmask_b32_e32 v2, v2, v123, vcc
	v_cndmask_b32_e64 v5, v90, v58, s[0:1]
	v_cndmask_b32_e64 v31, v2, v5, s[4:5]
	v_cndmask_b32_e32 v2, v8, v122, vcc
	v_cndmask_b32_e64 v5, v89, v57, s[0:1]
	v_cndmask_b32_e64 v8, v2, v5, s[4:5]
	v_cndmask_b32_e32 v2, v16, v121, vcc
	v_cndmask_b32_e64 v5, v88, v56, s[0:1]
	v_cndmask_b32_e64 v32, v2, v5, s[4:5]
	v_cndmask_b32_e32 v2, v21, v120, vcc
	v_cndmask_b32_e64 v5, v87, v55, s[0:1]
	v_cndmask_b32_e64 v21, v2, v5, s[4:5]
	v_cndmask_b32_e32 v1, v1, v119, vcc
	v_cndmask_b32_e64 v2, v86, v54, s[0:1]
	v_cndmask_b32_e64 v34, v1, v2, s[4:5]
	v_cndmask_b32_e32 v1, v10, v118, vcc
	v_cndmask_b32_e64 v2, v85, v53, s[0:1]
	v_cndmask_b32_e64 v41, v1, v2, s[4:5]
	v_cndmask_b32_e32 v1, v20, v117, vcc
	v_cndmask_b32_e64 v2, v84, v52, s[0:1]
	v_cndmask_b32_e64 v44, v1, v2, s[4:5]
	v_cndmask_b32_e32 v1, v22, v116, vcc
	v_cndmask_b32_e64 v2, v83, v51, s[0:1]
	v_cndmask_b32_e64 v45, v1, v2, s[4:5]
	v_cndmask_b32_e32 v1, v12, v115, vcc
	v_cndmask_b32_e64 v2, v82, v50, s[0:1]
	v_cndmask_b32_e64 v50, v1, v2, s[4:5]
	v_cndmask_b32_e32 v1, v14, v114, vcc
	v_cndmask_b32_e64 v2, v81, v49, s[0:1]
	v_cndmask_b32_e64 v49, v1, v2, s[4:5]
	v_cndmask_b32_e32 v1, v17, v112, vcc
	v_cndmask_b32_e64 v2, v80, v48, s[0:1]
	v_cndmask_b32_e64 v48, v1, v2, s[4:5]
	v_cndmask_b32_e32 v1, v18, v111, vcc
	v_cndmask_b32_e64 v2, v79, v47, s[0:1]
	v_cndmask_b32_e64 v47, v1, v2, s[4:5]
	v_cndmask_b32_e32 v0, v0, v110, vcc
	v_cndmask_b32_e64 v1, v78, v46, s[0:1]
	v_cndmask_b32_e64 v46, v0, v1, s[4:5]
	v_and_b32_e32 v0, 0x7fffff80, v4
	v_bitop3_b32 v1, v4, s19, v4 bitop3:0xcf
	v_cmp_gt_i32_e32 vcc, 0, v4
	v_bitop3_b32 v2, v4, s19, v4 bitop3:0xc
	v_bitop3_b32 v4, v23, s19, v23 bitop3:0xcf
	v_cndmask_b32_e32 v20, v1, v0, vcc
	v_and_b32_e32 v0, 0x7fffff80, v3
	v_bitop3_b32 v1, v3, s19, v3 bitop3:0xcf
	v_cmp_gt_i32_e32 vcc, 0, v3
	v_add_u32_e32 v5, 0, v6
	v_bitop3_b32 v3, v3, s19, v3 bitop3:0xc
	v_cndmask_b32_e32 v1, v1, v0, vcc
	v_and_b32_e32 v0, 0x7fffff80, v23
	v_cmp_gt_i32_e32 vcc, 0, v23
	v_bitop3_b32 v14, v31, s19, v31 bitop3:0xcf
	v_bitop3_b32 v6, v24, s19, v24 bitop3:0xc
	v_cndmask_b32_e32 v18, v4, v0, vcc
	v_and_b32_e32 v0, 0x7fffff80, v30
	v_bitop3_b32 v4, v30, s19, v30 bitop3:0xcf
	v_cmp_gt_i32_e32 vcc, 0, v30
	v_bitop3_b32 v10, v15, s19, v15 bitop3:0xc
	v_bitop3_b32 v16, v32, s19, v32 bitop3:0xcf
	v_cndmask_b32_e32 v0, v4, v0, vcc
	v_bitop3_b32 v4, v23, s19, v23 bitop3:0xc
	ds_write2_b32 v5, v2, v4 offset1:1
	v_bitop3_b32 v2, v30, s19, v30 bitop3:0xc
	ds_write2_b32 v5, v3, v2 offset0:16 offset1:17
	v_and_b32_e32 v2, 0x7fffff80, v24
	v_bitop3_b32 v3, v24, s19, v24 bitop3:0xcf
	v_cmp_gt_i32_e32 vcc, 0, v24
	v_bitop3_b32 v4, v25, s19, v25 bitop3:0xcf
	v_bitop3_b32 v22, v29, s19, v29 bitop3:0xcf
	v_cndmask_b32_e32 v12, v3, v2, vcc
	v_and_b32_e32 v2, 0x7fffff80, v15
	v_bitop3_b32 v3, v15, s19, v15 bitop3:0xcf
	v_cmp_gt_i32_e32 vcc, 0, v15
	v_bitop3_b32 v15, v27, s19, v27 bitop3:0xcf
	v_bitop3_b32 v24, v34, s19, v34 bitop3:0xcf
	v_cndmask_b32_e32 v3, v3, v2, vcc
	v_and_b32_e32 v2, 0x7fffff80, v25
	v_cmp_gt_i32_e32 vcc, 0, v25
	s_nop 1
	v_cndmask_b32_e32 v4, v4, v2, vcc
	v_and_b32_e32 v2, 0x7fffff80, v31
	v_cmp_gt_i32_e32 vcc, 0, v31
	s_nop 1
	v_cndmask_b32_e32 v2, v14, v2, vcc
	v_bitop3_b32 v14, v25, s19, v25 bitop3:0xc
	ds_write2_b32 v5, v6, v14 offset0:2 offset1:3
	v_bitop3_b32 v6, v31, s19, v31 bitop3:0xc
	ds_write2_b32 v5, v10, v6 offset0:18 offset1:19
	v_and_b32_e32 v6, 0x7fffff80, v26
	v_bitop3_b32 v10, v26, s19, v26 bitop3:0xcf
	v_cmp_gt_i32_e32 vcc, 0, v26
	v_bitop3_b32 v25, v36, s19, v36 bitop3:0xcf
	s_nop 0
	v_cndmask_b32_e32 v14, v10, v6, vcc
	v_and_b32_e32 v6, 0x7fffff80, v8
	v_bitop3_b32 v10, v8, s19, v8 bitop3:0xcf
	v_cmp_gt_i32_e32 vcc, 0, v8
	v_bitop3_b32 v8, v8, s19, v8 bitop3:0xc
	s_nop 0
	v_cndmask_b32_e32 v17, v10, v6, vcc
	v_and_b32_e32 v10, 0x7fffff80, v27
	v_cmp_gt_i32_e32 vcc, 0, v27
	v_bitop3_b32 v6, v26, s19, v26 bitop3:0xc
	v_bitop3_b32 v26, v43, s19, v43 bitop3:0xcf
	v_cndmask_b32_e32 v10, v15, v10, vcc
	v_and_b32_e32 v15, 0x7fffff80, v32
	v_cmp_gt_i32_e32 vcc, 0, v32
	s_nop 1
	v_cndmask_b32_e32 v16, v16, v15, vcc
	v_bitop3_b32 v15, v27, s19, v27 bitop3:0xc
	ds_write2_b32 v5, v6, v15 offset0:4 offset1:5
	v_bitop3_b32 v6, v32, s19, v32 bitop3:0xc
	ds_write2_b32 v5, v8, v6 offset0:20 offset1:21
	v_and_b32_e32 v6, 0x7fffff80, v28
; __device__ __forceinline__ float key2f(unsigned k) { const unsigned u = (k & 0x80000000u) ? (k & 0x7fffffffu) : ~k; return __uint_as_float(u); }
; #define CK(i, j) ((f2key(va[i] + vb[j]) & ~255u) | (unsigned)(255 - (16 * (i) + (j))))
; __device__ __forceinline__ void peer_tile(const Args& A, LAS unsigned char* lds, int tile) {
;     ...
;             for (int i = 0; i < 16; ++i) { va[i] = key2f(L2[0][i] & ~127u); vb[i] = key2f(L2[1][i] & ~127u); idx[i] = 127u - (L2[0][i] & 127u); idx[16 + i] = 127u - (L2[1][i] & 127u); }
;     ...
;             unsigned Lf[16], Bt[16];
; #pragma unroll
;             for (int j = 0; j < 16; ++j) Lf[j] = CK(0, j);
	v_bitop3_b32 v8, v28, s19, v28 bitop3:0xcf
	v_cmp_gt_i32_e32 vcc, 0, v28
	v_bitop3_b32 v15, v21, s19, v21 bitop3:0xcf
	s_nop 0
	v_cndmask_b32_e32 v8, v8, v6, vcc
	v_and_b32_e32 v6, 0x7fffff80, v21
	v_cmp_gt_i32_e32 vcc, 0, v21
	v_bitop3_b32 v21, v21, s19, v21 bitop3:0xc
	s_nop 0
	v_cndmask_b32_e32 v23, v15, v6, vcc
	v_and_b32_e32 v6, 0x7fffff80, v29
	v_cmp_gt_i32_e32 vcc, 0, v29
	v_bitop3_b32 v15, v28, s19, v28 bitop3:0xc
	s_nop 0
	v_cndmask_b32_e32 v6, v22, v6, vcc
	v_and_b32_e32 v22, 0x7fffff80, v34
	v_cmp_gt_i32_e32 vcc, 0, v34
	s_nop 1
	v_cndmask_b32_e32 v22, v24, v22, vcc
	v_bitop3_b32 v24, v29, s19, v29 bitop3:0xc
	ds_write2_b32 v5, v15, v24 offset0:6 offset1:7
	v_bitop3_b32 v15, v34, s19, v34 bitop3:0xc
	ds_write2_b32 v5, v21, v15 offset0:22 offset1:23
	v_and_b32_e32 v15, 0x7fffff80, v37
	v_bitop3_b32 v21, v37, s19, v37 bitop3:0xcf
	v_cmp_gt_i32_e32 vcc, 0, v37
	v_and_b32_e32 v24, 0x7fffff80, v36
	s_nop 0
	v_cndmask_b32_e32 v27, v21, v15, vcc
	v_and_b32_e32 v15, 0x7fffff80, v41
	v_bitop3_b32 v21, v41, s19, v41 bitop3:0xcf
	v_cmp_gt_i32_e32 vcc, 0, v41
	s_nop 1
	v_cndmask_b32_e32 v35, v21, v15, vcc
	v_cmp_gt_i32_e32 vcc, 0, v36
	v_bitop3_b32 v15, v37, s19, v37 bitop3:0xc
	v_bitop3_b32 v21, v41, s19, v41 bitop3:0xc
	v_cndmask_b32_e32 v28, v25, v24, vcc
	v_and_b32_e32 v24, 0x7fffff80, v44
	v_bitop3_b32 v25, v44, s19, v44 bitop3:0xcf
	v_cmp_gt_i32_e32 vcc, 0, v44
	s_nop 1
	v_cndmask_b32_e32 v34, v25, v24, vcc
	v_bitop3_b32 v24, v36, s19, v36 bitop3:0xc
	ds_write2_b32 v5, v15, v24 offset0:8 offset1:9
	v_bitop3_b32 v15, v44, s19, v44 bitop3:0xc
	ds_write2_b32 v5, v21, v15 offset0:24 offset1:25
	v_and_b32_e32 v15, 0x7fffff80, v38
	v_bitop3_b32 v21, v38, s19, v38 bitop3:0xcf
	v_cmp_gt_i32_e32 vcc, 0, v38
	v_and_b32_e32 v24, 0x7fffff80, v39
	v_bitop3_b32 v25, v39, s19, v39 bitop3:0xcf
	v_cndmask_b32_e32 v29, v21, v15, vcc
	v_and_b32_e32 v15, 0x7fffff80, v45
	v_bitop3_b32 v21, v45, s19, v45 bitop3:0xcf
	v_cmp_gt_i32_e32 vcc, 0, v45
	s_nop 1
	v_cndmask_b32_e32 v37, v21, v15, vcc
	v_cmp_gt_i32_e32 vcc, 0, v39
	v_bitop3_b32 v15, v38, s19, v38 bitop3:0xc
	v_bitop3_b32 v21, v45, s19, v45 bitop3:0xc
	v_cndmask_b32_e32 v30, v25, v24, vcc
	v_and_b32_e32 v24, 0x7fffff80, v50
	v_bitop3_b32 v25, v50, s19, v50 bitop3:0xcf
	v_cmp_gt_i32_e32 vcc, 0, v50
	s_nop 1
	v_cndmask_b32_e32 v36, v25, v24, vcc
	v_bitop3_b32 v24, v39, s19, v39 bitop3:0xc
	ds_write2_b32 v5, v15, v24 offset0:10 offset1:11
	v_bitop3_b32 v15, v50, s19, v50 bitop3:0xc
	ds_write2_b32 v5, v21, v15 offset0:26 offset1:27
	v_and_b32_e32 v15, 0x7fffff80, v33
	v_bitop3_b32 v21, v33, s19, v33 bitop3:0xcf
	v_cmp_gt_i32_e32 vcc, 0, v33
	v_and_b32_e32 v24, 0x7fffff80, v40
	v_bitop3_b32 v25, v40, s19, v40 bitop3:0xcf
	v_cndmask_b32_e32 v31, v21, v15, vcc
	v_and_b32_e32 v15, 0x7fffff80, v49
	v_bitop3_b32 v21, v49, s19, v49 bitop3:0xcf
	v_cmp_gt_i32_e32 vcc, 0, v49
	s_nop 1
	v_cndmask_b32_e32 v39, v21, v15, vcc
	v_cmp_gt_i32_e32 vcc, 0, v40
	v_bitop3_b32 v15, v33, s19, v33 bitop3:0xc
	v_bitop3_b32 v21, v49, s19, v49 bitop3:0xc
	v_cndmask_b32_e32 v32, v25, v24, vcc
	v_and_b32_e32 v24, 0x7fffff80, v48
	v_bitop3_b32 v25, v48, s19, v48 bitop3:0xcf
	v_cmp_gt_i32_e32 vcc, 0, v48
	v_bitop3_b32 v33, v46, s19, v46 bitop3:0xcf
	s_nop 0
	v_cndmask_b32_e32 v38, v25, v24, vcc
	v_bitop3_b32 v24, v40, s19, v40 bitop3:0xc
	ds_write2_b32 v5, v15, v24 offset0:12 offset1:13
	v_bitop3_b32 v15, v48, s19, v48 bitop3:0xc
	ds_write2_b32 v5, v21, v15 offset0:28 offset1:29
	v_and_b32_e32 v15, 0x7fffff80, v42
	v_bitop3_b32 v21, v42, s19, v42 bitop3:0xcf
	v_cmp_gt_i32_e32 vcc, 0, v42
	v_and_b32_e32 v24, 0x7fffff80, v43
	s_nop 0
	v_cndmask_b32_e32 v25, v21, v15, vcc
	v_and_b32_e32 v15, 0x7fffff80, v47
	v_bitop3_b32 v21, v47, s19, v47 bitop3:0xcf
	v_cmp_gt_i32_e32 vcc, 0, v47
	s_nop 1
	v_cndmask_b32_e32 v41, v21, v15, vcc
	v_cmp_gt_i32_e32 vcc, 0, v43
	v_bitop3_b32 v21, v47, s19, v47 bitop3:0xc
	v_bitop3_b32 v15, v42, s19, v42 bitop3:0xc
	v_cndmask_b32_e32 v26, v26, v24, vcc
	v_and_b32_e32 v24, 0x7fffff80, v46
	v_cmp_gt_i32_e32 vcc, 0, v46
	v_pk_add_f32 v[34:35], v[20:21], v[34:35] op_sel_hi:[0,1]
	s_nop 0
	v_cndmask_b32_e32 v40, v33, v24, vcc
	v_bitop3_b32 v24, v43, s19, v43 bitop3:0xc
	v_pk_add_f32 v[42:43], v[20:21], v[0:1] op_sel_hi:[0,1]
	ds_write2_b32 v5, v15, v24 offset0:14 offset1:15
	v_not_b32_e32 v15, v43
	v_or_b32_e32 v33, 0x80000000, v43
	v_cmp_gt_i32_e32 vcc, 0, v43
	v_or_b32_e32 v43, 0x80000000, v42
	v_bitop3_b32 v24, v46, s19, v46 bitop3:0xc
	v_cndmask_b32_e32 v15, v33, v15, vcc
	v_or_b32_e32 v33, 0xff, v15
	v_not_b32_e32 v15, v42
	v_cmp_gt_i32_e32 vcc, 0, v42
	ds_write2_b32 v5, v21, v24 offset0:30 offset1:31
	s_waitcnt lgkmcnt(0)
; #define CK(i, j) ((f2key(va[i] + vb[j]) & ~255u) | (unsigned)(255 - (16 * (i) + (j))))
; __device__ __forceinline__ void peer_tile(const Args& A, LAS unsigned char* lds, int tile) {
;     ...
;             unsigned Lf[16], Bt[16];
; #pragma unroll
;             for (int j = 0; j < 16; ++j) Lf[j] = CK(0, j);
; #pragma unroll
;             for (int j = 0; j < 8; ++j) Bt[j] = CK(1, j);
; #pragma unroll
;             for (int j = 0; j < 5; ++j) Bt[8 + j] = CK(2, j);
; #pragma unroll
;             for (int j = 0; j < 3; ++j) Bt[13 + j] = CK(4, j);
	s_nop 0
	v_cndmask_b32_e32 v15, v43, v15, vcc
	v_and_b32_e32 v15, 0xffffff00, v15
	v_pk_add_f32 v[42:43], v[20:21], v[2:3] op_sel_hi:[0,1]
	v_or_b32_e32 v44, 0xfe, v15
	v_not_b32_e32 v15, v43
	v_or_b32_e32 v45, 0x80000000, v43
	v_cmp_gt_i32_e32 vcc, 0, v43
	v_or_b32_e32 v43, 0x80000000, v42
	s_nop 0
	v_cndmask_b32_e32 v15, v45, v15, vcc
	v_and_b32_e32 v15, 0xffffff00, v15
	v_or_b32_e32 v45, 0xfd, v15
	v_not_b32_e32 v15, v42
	v_cmp_gt_i32_e32 vcc, 0, v42
	s_nop 1
	v_cndmask_b32_e32 v15, v43, v15, vcc
	v_and_b32_e32 v15, 0xffffff00, v15
	v_pk_add_f32 v[42:43], v[20:21], v[16:17] op_sel_hi:[0,1]
	v_or_b32_e32 v46, 0xfc, v15
	v_not_b32_e32 v15, v43
	v_or_b32_e32 v47, 0x80000000, v43
	v_cmp_gt_i32_e32 vcc, 0, v43
	v_or_b32_e32 v43, 0x80000000, v42
	s_nop 0
	v_cndmask_b32_e32 v15, v47, v15, vcc
	v_and_b32_e32 v15, 0xffffff00, v15
	v_or_b32_e32 v47, 0xfb, v15
	v_not_b32_e32 v15, v42
	v_cmp_gt_i32_e32 vcc, 0, v42
	s_nop 1
	v_cndmask_b32_e32 v15, v43, v15, vcc
	v_and_b32_e32 v15, 0xffffff00, v15
	v_pk_add_f32 v[42:43], v[20:21], v[22:23] op_sel_hi:[0,1]
	v_or_b32_e32 v48, 0xfa, v15
	v_not_b32_e32 v15, v43
	v_or_b32_e32 v49, 0x80000000, v43
	v_cmp_gt_i32_e32 vcc, 0, v43
	v_pk_add_f32 v[22:23], v[18:19], v[22:23] op_sel_hi:[0,1]
	s_nop 0
	v_cndmask_b32_e32 v15, v49, v15, vcc
	v_and_b32_e32 v15, 0xffffff00, v15
	v_or_b32_e32 v43, 0xf9, v15
	v_not_b32_e32 v15, v42
	v_or_b32_e32 v49, 0x80000000, v42
	v_cmp_gt_i32_e32 vcc, 0, v42
	s_nop 1
	v_cndmask_b32_e32 v15, v49, v15, vcc
	v_and_b32_e32 v15, 0xffffff00, v15
	v_or_b32_e32 v42, 0xf8, v15
	v_not_b32_e32 v15, v35
	v_or_b32_e32 v49, 0x80000000, v35
	v_cmp_gt_i32_e32 vcc, 0, v35
	v_or_b32_e32 v35, 0x80000000, v34
	s_nop 0
	v_cndmask_b32_e32 v15, v49, v15, vcc
	v_and_b32_e32 v15, 0xffffff00, v15
	v_or_b32_e32 v49, 0xf7, v15
	v_not_b32_e32 v15, v34
	v_cmp_gt_i32_e32 vcc, 0, v34
	s_nop 1
	v_cndmask_b32_e32 v15, v35, v15, vcc
	v_and_b32_e32 v15, 0xffffff00, v15
	v_pk_add_f32 v[34:35], v[20:21], v[36:37] op_sel_hi:[0,1]
	v_or_b32_e32 v50, 0xf6, v15
	v_not_b32_e32 v15, v35
	v_or_b32_e32 v36, 0x80000000, v35
	v_cmp_gt_i32_e32 vcc, 0, v35
	v_or_b32_e32 v35, 0x80000000, v34
	s_nop 0
	v_cndmask_b32_e32 v15, v36, v15, vcc
	v_and_b32_e32 v15, 0xffffff00, v15
	v_or_b32_e32 v36, 0xf5, v15
	v_not_b32_e32 v15, v34
	v_cmp_gt_i32_e32 vcc, 0, v34
	s_nop 1
	v_cndmask_b32_e32 v15, v35, v15, vcc
	v_and_b32_e32 v15, 0xffffff00, v15
	v_pk_add_f32 v[34:35], v[20:21], v[38:39] op_sel_hi:[0,1]
	v_or_b32_e32 v37, 0xf4, v15
	v_not_b32_e32 v15, v35
	v_or_b32_e32 v38, 0x80000000, v35
	v_cmp_gt_i32_e32 vcc, 0, v35
	v_or_b32_e32 v35, 0x80000000, v34
	s_nop 0
	v_cndmask_b32_e32 v15, v38, v15, vcc
	v_and_b32_e32 v15, 0xffffff00, v15
	v_or_b32_e32 v38, 0xf3, v15
	v_not_b32_e32 v15, v34
	v_cmp_gt_i32_e32 vcc, 0, v34
	s_nop 1
	v_cndmask_b32_e32 v15, v35, v15, vcc
	v_and_b32_e32 v15, 0xffffff00, v15
	v_pk_add_f32 v[34:35], v[20:21], v[40:41] op_sel_hi:[0,1]
	v_or_b32_e32 v39, 0xf2, v15
	v_not_b32_e32 v15, v35
	v_or_b32_e32 v20, 0x80000000, v35
	v_cmp_gt_i32_e32 vcc, 0, v35
	v_or_b32_e32 v35, 0x80000000, v34
	s_nop 0
	v_cndmask_b32_e32 v15, v20, v15, vcc
	v_and_b32_e32 v15, 0xffffff00, v15
	v_or_b32_e32 v20, 0xf1, v15
	v_not_b32_e32 v15, v34
	v_cmp_gt_i32_e32 vcc, 0, v34
	s_nop 1
	v_cndmask_b32_e32 v15, v35, v15, vcc
	v_and_b32_e32 v15, 0xffffff00, v15
	v_pk_add_f32 v[34:35], v[18:19], v[0:1] op_sel_hi:[0,1]
	v_or_b32_e32 v40, 0xf0, v15
	v_not_b32_e32 v15, v35
	v_or_b32_e32 v41, 0x80000000, v35
	v_cmp_gt_i32_e32 vcc, 0, v35
	v_or_b32_e32 v35, 0x80000000, v34
	s_nop 0
	v_cndmask_b32_e32 v15, v41, v15, vcc
	v_and_b32_e32 v15, 0xffffff00, v15
	v_or_b32_e32 v41, 0xef, v15
	v_not_b32_e32 v15, v34
	v_cmp_gt_i32_e32 vcc, 0, v34
	s_nop 1
	v_cndmask_b32_e32 v15, v35, v15, vcc
	v_and_b32_e32 v15, 0xffffff00, v15
	v_pk_add_f32 v[34:35], v[18:19], v[2:3] op_sel_hi:[0,1]
	v_or_b32_e32 v51, 0xee, v15
	v_not_b32_e32 v15, v35
	v_or_b32_e32 v52, 0x80000000, v35
	v_cmp_gt_i32_e32 vcc, 0, v35
	v_or_b32_e32 v35, 0x80000000, v34
	s_nop 0
	v_cndmask_b32_e32 v15, v52, v15, vcc
	v_and_b32_e32 v15, 0xffffff00, v15
	v_or_b32_e32 v52, 0xed, v15
	v_not_b32_e32 v15, v34
	v_cmp_gt_i32_e32 vcc, 0, v34
	s_nop 1
	v_cndmask_b32_e32 v15, v35, v15, vcc
	v_and_b32_e32 v15, 0xffffff00, v15
	v_pk_add_f32 v[34:35], v[18:19], v[16:17] op_sel_hi:[0,1]
	v_or_b32_e32 v53, 0xec, v15
	v_not_b32_e32 v15, v35
	v_or_b32_e32 v16, 0x80000000, v35
	v_cmp_gt_i32_e32 vcc, 0, v35
	s_nop 1
	v_cndmask_b32_e32 v15, v16, v15, vcc
	v_and_b32_e32 v15, 0xffffff00, v15
	v_or_b32_e32 v35, 0xeb, v15
	v_not_b32_e32 v15, v34
	v_or_b32_e32 v16, 0x80000000, v34
	v_cmp_gt_i32_e32 vcc, 0, v34
	s_nop 1
	v_cndmask_b32_e32 v15, v16, v15, vcc
	v_and_b32_e32 v15, 0xffffff00, v15
	v_or_b32_e32 v34, 0xea, v15
	v_not_b32_e32 v15, v23
	v_or_b32_e32 v16, 0x80000000, v23
	v_cmp_gt_i32_e32 vcc, 0, v23
	s_nop 1
	v_cndmask_b32_e32 v15, v16, v15, vcc
	v_and_b32_e32 v15, 0xffffff00, v15
	v_or_b32_e32 v18, 0xe9, v15
	v_not_b32_e32 v15, v22
	v_or_b32_e32 v16, 0x80000000, v22
	v_cmp_gt_i32_e32 vcc, 0, v22
	v_pk_add_f32 v[22:23], v[12:13], v[0:1] op_sel_hi:[0,1]
	s_nop 0
	v_cndmask_b32_e32 v15, v16, v15, vcc
	v_and_b32_e32 v15, 0xffffff00, v15
	v_or_b32_e32 v54, 0xe8, v15
	v_not_b32_e32 v15, v23
	v_or_b32_e32 v16, 0x80000000, v23
	v_cmp_gt_i32_e32 vcc, 0, v23
	s_nop 1
	v_cndmask_b32_e32 v15, v16, v15, vcc
	v_and_b32_e32 v15, 0xffffff00, v15
	v_or_b32_e32 v55, 0xdf, v15
	v_not_b32_e32 v15, v22
	v_or_b32_e32 v16, 0x80000000, v22
	v_cmp_gt_i32_e32 vcc, 0, v22
	v_pk_add_f32 v[22:23], v[12:13], v[2:3] op_sel_hi:[0,1]
	v_lshl_add_u32 v13, v13, 10, s35
	v_cndmask_b32_e32 v15, v16, v15, vcc
	v_and_b32_e32 v15, 0xffffff00, v15
; #define CK(i, j) ((f2key(va[i] + vb[j]) & ~255u) | (unsigned)(255 - (16 * (i) + (j))))
; __device__ __forceinline__ void peer_tile(const Args& A, LAS unsigned char* lds, int tile) {
;     ...
;             unsigned Lf[16], Bt[16];
; #pragma unroll
;             for (int j = 0; j < 16; ++j) Lf[j] = CK(0, j);
; #pragma unroll
;             for (int j = 0; j < 8; ++j) Bt[j] = CK(1, j);
; #pragma unroll
;             for (int j = 0; j < 5; ++j) Bt[8 + j] = CK(2, j);
; #pragma unroll
;             for (int j = 0; j < 3; ++j) Bt[13 + j] = CK(4, j);
;             sort16_desc(Bt); merge16(Lf, Bt);
; #pragma unroll
;             for (int j = 0; j < 4; ++j) Bt[j] = CK(3, j);
;             Bt[4] = CK(5, 0); Bt[5] = CK(5, 1); Bt[6] = CK(6, 0); Bt[7] = CK(6, 1); Bt[8] = CK(7, 0); Bt[9] = CK(7, 1);
;             Bt[10] = CK(8, 0); Bt[11] = CK(9, 0); Bt[12] = CK(10, 0); Bt[13] = CK(11, 0); Bt[14] = CK(12, 0); Bt[15] = CK(13, 0);
;             sort16_desc(Bt); merge16(Lf, Bt);
	v_or_b32_e32 v56, 0xde, v15
	v_not_b32_e32 v15, v23
	v_or_b32_e32 v16, 0x80000000, v23
	v_cmp_gt_i32_e32 vcc, 0, v23
	s_nop 1
	v_cndmask_b32_e32 v15, v16, v15, vcc
	v_and_b32_e32 v15, 0xffffff00, v15
	v_or_b32_e32 v23, 0xdd, v15
	v_not_b32_e32 v15, v22
	v_or_b32_e32 v16, 0x80000000, v22
	v_cmp_gt_i32_e32 vcc, 0, v22
	s_nop 1
	v_cndmask_b32_e32 v15, v16, v15, vcc
	v_and_b32_e32 v15, 0xffffff00, v15
	v_or_b32_e32 v22, 0xdc, v15
	v_mov_b32_e32 v15, v12
	v_mov_b32_e32 v16, v1
	v_pk_add_f32 v[16:17], v[14:15], v[16:17]
	s_nop 0
	v_not_b32_e32 v12, v17
	v_or_b32_e32 v15, 0x80000000, v17
	v_cmp_gt_i32_e32 vcc, 0, v17
	v_or_b32_e32 v17, 0x80000000, v16
	s_nop 0
	v_cndmask_b32_e32 v12, v15, v12, vcc
	v_not_b32_e32 v15, v16
	v_cmp_gt_i32_e32 vcc, 0, v16
	v_mov_b32_e32 v16, v3
	v_and_b32_e32 v12, 0xffffff00, v12
	v_cndmask_b32_e32 v15, v17, v15, vcc
	v_and_b32_e32 v15, 0xffffff00, v15
	v_mov_b32_e32 v17, v0
	v_or_b32_e32 v57, 0xbf, v15
	v_pk_add_f32 v[14:15], v[14:15], v[16:17] op_sel_hi:[0,1]
	v_not_b32_e32 v16, v15
	v_or_b32_e32 v17, 0x80000000, v15
	v_cmp_gt_i32_e32 vcc, 0, v15
	v_or_b32_e32 v12, 0xdb, v12
	v_pk_add_f32 v[2:3], v[4:5], v[2:3] op_sel_hi:[0,1]
	v_cndmask_b32_e32 v15, v17, v16, vcc
	v_not_b32_e32 v16, v14
	v_or_b32_e32 v17, 0x80000000, v14
	v_cmp_gt_i32_e32 vcc, 0, v14
	v_and_b32_e32 v15, 0xffffff00, v15
	v_or_b32_e32 v15, 0xbe, v15
	v_cndmask_b32_e32 v14, v17, v16, vcc
	v_and_b32_e32 v14, 0xffffff00, v14
	v_or_b32_e32 v14, 0xbd, v14
	v_max_u32_e32 v16, v41, v51
	v_min_u32_e32 v17, v41, v51
	v_max_u32_e32 v41, v53, v52
	v_min_u32_e32 v51, v53, v52
	v_max_u32_e32 v52, v35, v34
	v_min_u32_e32 v34, v35, v34
	v_max_u32_e32 v35, v54, v18
	v_min_u32_e32 v18, v54, v18
	v_max_u32_e32 v53, v55, v56
	v_min_u32_e32 v54, v55, v56
	v_max_u32_e32 v55, v22, v23
	v_min_u32_e32 v22, v22, v23
	v_max_u32_e32 v23, v12, v57
	v_min_u32_e32 v12, v12, v57
	v_max_u32_e32 v56, v14, v15
	v_min_u32_e32 v14, v14, v15
	v_max_u32_e32 v15, v16, v51
	v_min_u32_e32 v16, v16, v51
	v_max_u32_e32 v51, v17, v41
	v_min_u32_e32 v17, v17, v41
	v_max_u32_e32 v41, v18, v52
	v_min_u32_e32 v18, v18, v52
	v_max_u32_e32 v52, v35, v34
	v_min_u32_e32 v34, v35, v34
	v_max_u32_e32 v35, v53, v22
	v_min_u32_e32 v22, v53, v22
	v_max_u32_e32 v53, v54, v55
	v_min_u32_e32 v54, v54, v55
	v_max_u32_e32 v55, v14, v23
	v_min_u32_e32 v14, v14, v23
	v_max_u32_e32 v23, v56, v12
	v_min_u32_e32 v12, v56, v12
	v_max_u32_e32 v56, v15, v51
	v_min_u32_e32 v15, v15, v51
	v_max_u32_e32 v51, v16, v17
	v_min_u32_e32 v16, v16, v17
	v_max_u32_e32 v17, v34, v18
	v_min_u32_e32 v18, v34, v18
	v_max_u32_e32 v34, v52, v41
	v_min_u32_e32 v41, v52, v41
	v_max_u32_e32 v52, v35, v53
	v_min_u32_e32 v35, v35, v53
	v_max_u32_e32 v53, v22, v54
	v_min_u32_e32 v22, v22, v54
	v_max_u32_e32 v54, v12, v14
	v_min_u32_e32 v12, v12, v14
	v_max_u32_e32 v14, v23, v55
	v_min_u32_e32 v23, v23, v55
	v_max_u32_e32 v55, v56, v18
	v_min_u32_e32 v18, v56, v18
	v_max_u32_e32 v56, v15, v17
	v_min_u32_e32 v15, v15, v17
	v_max_u32_e32 v17, v51, v41
	v_min_u32_e32 v41, v51, v41
	v_max_u32_e32 v51, v16, v34
	v_min_u32_e32 v16, v16, v34
	v_max_u32_e32 v34, v12, v52
	v_min_u32_e32 v12, v12, v52
	v_max_u32_e32 v52, v54, v35
	v_min_u32_e32 v35, v54, v35
	v_max_u32_e32 v54, v23, v53
	v_min_u32_e32 v23, v23, v53
	v_max_u32_e32 v53, v14, v22
	v_min_u32_e32 v14, v14, v22
	v_max_u32_e32 v22, v55, v17
	v_min_u32_e32 v17, v55, v17
	v_max_u32_e32 v55, v56, v51
	v_min_u32_e32 v51, v56, v51
	v_max_u32_e32 v56, v18, v41
	v_min_u32_e32 v18, v18, v41
	v_max_u32_e32 v41, v15, v16
	v_min_u32_e32 v15, v15, v16
	v_max_u32_e32 v16, v23, v12
	v_min_u32_e32 v12, v23, v12
	v_max_u32_e32 v23, v14, v35
	v_min_u32_e32 v14, v14, v35
	v_max_u32_e32 v35, v54, v34
	v_min_u32_e32 v34, v54, v34
	v_max_u32_e32 v54, v53, v52
	v_min_u32_e32 v52, v53, v52
	v_max_u32_e32 v53, v22, v55
	v_min_u32_e32 v22, v22, v55
	v_max_u32_e32 v55, v17, v51
	v_min_u32_e32 v17, v17, v51
	v_max_u32_e32 v51, v56, v41
	v_min_u32_e32 v41, v56, v41
	v_max_u32_e32 v56, v18, v15
	v_min_u32_e32 v15, v18, v15
	v_max_u32_e32 v18, v14, v12
	v_min_u32_e32 v12, v14, v12
	v_max_u32_e32 v14, v23, v16
	v_min_u32_e32 v16, v23, v16
	v_max_u32_e32 v23, v52, v34
	v_min_u32_e32 v34, v52, v34
	v_max_u32_e32 v52, v54, v35
	v_min_u32_e32 v35, v54, v35
	v_max_u32_e32 v54, v53, v12
	v_min_u32_e32 v12, v53, v12
	v_max_u32_e32 v53, v22, v18
	v_min_u32_e32 v18, v22, v18
	v_max_u32_e32 v22, v55, v16
	v_min_u32_e32 v16, v55, v16
	v_max_u32_e32 v55, v17, v14
	v_min_u32_e32 v14, v17, v14
	v_max_u32_e32 v17, v51, v34
	v_min_u32_e32 v34, v51, v34
	v_max_u32_e32 v51, v41, v23
	v_min_u32_e32 v23, v41, v23
	v_max_u32_e32 v41, v56, v35
	v_min_u32_e32 v35, v56, v35
	v_max_u32_e32 v56, v15, v52
	v_min_u32_e32 v15, v15, v52
	v_max_u32_e32 v52, v54, v17
	v_min_u32_e32 v17, v54, v17
	v_max_u32_e32 v54, v53, v51
	v_min_u32_e32 v51, v53, v51
	v_max_u32_e32 v53, v22, v41
	v_min_u32_e32 v22, v22, v41
	v_max_u32_e32 v41, v55, v56
	v_min_u32_e32 v55, v55, v56
	v_max_u32_e32 v56, v12, v34
	v_min_u32_e32 v12, v12, v34
	v_max_u32_e32 v34, v18, v23
	v_min_u32_e32 v18, v18, v23
	v_max_u32_e32 v23, v16, v35
	v_min_u32_e32 v16, v16, v35
	v_max_u32_e32 v35, v14, v15
	v_min_u32_e32 v14, v14, v15
	v_max_u32_e32 v15, v52, v53
	v_min_u32_e32 v52, v52, v53
	v_max_u32_e32 v53, v54, v41
	v_min_u32_e32 v41, v54, v41
	v_max_u32_e32 v54, v17, v22
	v_min_u32_e32 v17, v17, v22
	v_max_u32_e32 v22, v51, v55
	v_min_u32_e32 v51, v51, v55
	v_max_u32_e32 v55, v56, v23
	v_min_u32_e32 v23, v56, v23
	v_max_u32_e32 v56, v34, v35
	v_min_u32_e32 v34, v34, v35
	v_max_u32_e32 v35, v12, v16
	v_min_u32_e32 v12, v12, v16
	v_max_u32_e32 v16, v18, v14
	v_min_u32_e32 v14, v18, v14
; #define CK(i, j) ((f2key(va[i] + vb[j]) & ~255u) | (unsigned)(255 - (16 * (i) + (j))))
; __device__ __forceinline__ void peer_tile(const Args& A, LAS unsigned char* lds, int tile) {
;     ...
;             sort16_desc(Bt); merge16(Lf, Bt);
; #pragma unroll
;             for (int j = 0; j < 4; ++j) Bt[j] = CK(3, j);
;             Bt[4] = CK(5, 0); Bt[5] = CK(5, 1); Bt[6] = CK(6, 0); Bt[7] = CK(6, 1); Bt[8] = CK(7, 0); Bt[9] = CK(7, 1);
;             Bt[10] = CK(8, 0); Bt[11] = CK(9, 0); Bt[12] = CK(10, 0); Bt[13] = CK(11, 0); Bt[14] = CK(12, 0); Bt[15] = CK(13, 0);
	v_min_u32_e32 v18, v15, v53
	v_min_u32_e32 v57, v52, v41
	v_min_u32_e32 v58, v54, v22
	v_min_u32_e32 v59, v17, v51
	v_min_u32_e32 v60, v55, v56
	v_min_u32_e32 v61, v23, v34
	v_min_u32_e32 v62, v35, v16
	v_min_u32_e32 v63, v12, v14
	v_max_u32_e32 v33, v33, v63
	v_max3_u32 v12, v44, v12, v14
	v_max_u32_e32 v14, v45, v62
	v_max3_u32 v16, v46, v35, v16
	v_max_u32_e32 v35, v47, v61
	v_max3_u32 v23, v48, v23, v34
	v_max_u32_e32 v34, v43, v60
	v_max3_u32 v42, v42, v55, v56
	v_max_u32_e32 v43, v49, v59
	v_max3_u32 v17, v50, v17, v51
	v_max_u32_e32 v36, v36, v58
	v_max3_u32 v22, v37, v54, v22
	v_max_u32_e32 v37, v38, v57
	v_max3_u32 v38, v39, v52, v41
	v_max_u32_e32 v18, v20, v18
	v_max3_u32 v15, v40, v15, v53
	v_max_u32_e32 v20, v33, v43
	v_min_u32_e32 v33, v33, v43
	v_max_u32_e32 v39, v12, v17
	v_min_u32_e32 v12, v12, v17
	v_max_u32_e32 v17, v14, v36
	v_min_u32_e32 v14, v14, v36
	v_max_u32_e32 v36, v16, v22
	v_min_u32_e32 v16, v16, v22
	v_max_u32_e32 v22, v35, v37
	v_min_u32_e32 v35, v35, v37
	v_max_u32_e32 v37, v23, v38
	v_min_u32_e32 v23, v23, v38
	v_max_u32_e32 v38, v34, v18
	v_min_u32_e32 v18, v34, v18
	v_max_u32_e32 v34, v42, v15
	v_min_u32_e32 v15, v42, v15
	v_max_u32_e32 v40, v20, v22
	v_min_u32_e32 v20, v20, v22
	v_max_u32_e32 v22, v39, v37
	v_min_u32_e32 v37, v39, v37
	v_max_u32_e32 v39, v17, v38
	v_min_u32_e32 v17, v17, v38
	v_max_u32_e32 v38, v36, v34
	v_min_u32_e32 v34, v36, v34
	v_max_u32_e32 v36, v33, v35
	v_min_u32_e32 v33, v33, v35
	v_max_u32_e32 v35, v12, v23
	v_min_u32_e32 v12, v12, v23
	v_max_u32_e32 v23, v14, v18
	v_min_u32_e32 v14, v14, v18
	v_max_u32_e32 v18, v16, v15
	v_min_u32_e32 v15, v16, v15
	v_max_u32_e32 v16, v40, v39
	v_min_u32_e32 v39, v40, v39
	v_max_u32_e32 v40, v22, v38
	v_min_u32_e32 v22, v22, v38
	v_max_u32_e32 v38, v20, v17
	v_min_u32_e32 v17, v20, v17
	v_max_u32_e32 v20, v37, v34
	v_min_u32_e32 v34, v37, v34
	v_max_u32_e32 v37, v36, v23
	v_min_u32_e32 v23, v36, v23
	v_max_u32_e32 v36, v35, v18
	v_min_u32_e32 v18, v35, v18
	v_max_u32_e32 v35, v33, v14
	v_min_u32_e32 v33, v33, v14
	v_max_u32_e32 v41, v12, v15
	v_min_u32_e32 v12, v12, v15
	v_pk_add_f32 v[14:15], v[4:5], v[0:1] op_sel_hi:[0,1]
	v_not_b32_e32 v50, v15
	v_or_b32_e32 v51, 0x80000000, v15
	v_cmp_gt_i32_e32 vcc, 0, v15
	v_not_b32_e32 v4, v3
	v_min_u32_e32 v42, v16, v40
	v_cndmask_b32_e32 v15, v51, v50, vcc
	v_not_b32_e32 v50, v14
	v_or_b32_e32 v51, 0x80000000, v14
	v_cmp_gt_i32_e32 vcc, 0, v14
	v_and_b32_e32 v15, 0xffffff00, v15
	v_or_b32_e32 v15, 0xcf, v15
	v_cndmask_b32_e32 v14, v51, v50, vcc
	v_or_b32_e32 v50, 0x80000000, v3
	v_cmp_gt_i32_e32 vcc, 0, v3
	v_and_b32_e32 v14, 0xffffff00, v14
	v_or_b32_e32 v14, 0xce, v14
	v_cndmask_b32_e32 v3, v50, v4, vcc
	v_and_b32_e32 v3, 0xffffff00, v3
	v_or_b32_e32 v4, 0xcd, v3
	v_not_b32_e32 v3, v2
	v_or_b32_e32 v50, 0x80000000, v2
	v_cmp_gt_i32_e32 vcc, 0, v2
	v_min_u32_e32 v43, v39, v22
	v_min_u32_e32 v44, v38, v20
	v_cndmask_b32_e32 v2, v50, v3, vcc
	v_and_b32_e32 v2, 0xffffff00, v2
	v_or_b32_e32 v50, 0xcc, v2
	v_pk_add_f32 v[2:3], v[10:11], v[0:1] op_sel_hi:[0,1]
	v_not_b32_e32 v10, v3
	v_or_b32_e32 v51, 0x80000000, v3
	v_cmp_gt_i32_e32 vcc, 0, v3
	v_min_u32_e32 v45, v17, v34
	v_min_u32_e32 v46, v37, v36
	v_cndmask_b32_e32 v3, v51, v10, vcc
	v_and_b32_e32 v3, 0xffffff00, v3
	v_or_b32_e32 v10, 0xaf, v3
	v_not_b32_e32 v3, v2
	v_or_b32_e32 v51, 0x80000000, v2
	v_cmp_gt_i32_e32 vcc, 0, v2
	v_min_u32_e32 v47, v23, v18
	v_min_u32_e32 v48, v35, v41
	v_cndmask_b32_e32 v2, v51, v3, vcc
	v_and_b32_e32 v2, 0xffffff00, v2
	v_or_b32_e32 v51, 0xae, v2
	v_pk_add_f32 v[2:3], v[8:9], v[0:1] op_sel_hi:[0,1]
	v_not_b32_e32 v8, v3
	v_or_b32_e32 v52, 0x80000000, v3
	v_cmp_gt_i32_e32 vcc, 0, v3
	v_min_u32_e32 v49, v33, v12
	v_lshlrev_b32_e32 v11, 9, v11
	v_cndmask_b32_e32 v3, v52, v8, vcc
	v_and_b32_e32 v3, 0xffffff00, v3
	v_or_b32_e32 v8, 0x9f, v3
	v_not_b32_e32 v3, v2
	v_or_b32_e32 v52, 0x80000000, v2
	v_cmp_gt_i32_e32 vcc, 0, v2
	s_nop 1
	v_cndmask_b32_e32 v2, v52, v3, vcc
	v_and_b32_e32 v2, 0xffffff00, v2
	v_or_b32_e32 v52, 0x9e, v2
	v_pk_add_f32 v[2:3], v[6:7], v[0:1] op_sel_hi:[0,1]
	v_not_b32_e32 v0, v3
	v_or_b32_e32 v6, 0x80000000, v3
	v_cmp_gt_i32_e32 vcc, 0, v3
	v_not_b32_e32 v3, v2
	s_nop 0
	v_cndmask_b32_e32 v0, v6, v0, vcc
	v_or_b32_e32 v6, 0x80000000, v2
	v_cmp_gt_i32_e32 vcc, 0, v2
	v_and_b32_e32 v0, 0xffffff00, v0
	v_or_b32_e32 v0, 0x8f, v0
	v_cndmask_b32_e32 v2, v6, v3, vcc
	v_add_f32_e32 v3, v27, v1
	v_not_b32_e32 v6, v3
	v_or_b32_e32 v27, 0x80000000, v3
	v_cmp_gt_i32_e32 vcc, 0, v3
	v_and_b32_e32 v2, 0xffffff00, v2
	v_or_b32_e32 v2, 0x8e, v2
	v_cndmask_b32_e32 v3, v27, v6, vcc
	v_add_f32_e32 v6, v28, v1
	v_not_b32_e32 v27, v6
	v_or_b32_e32 v28, 0x80000000, v6
	v_cmp_gt_i32_e32 vcc, 0, v6
	v_and_b32_e32 v3, 0xffffff00, v3
	v_or_b32_e32 v3, 0x7f, v3
	v_cndmask_b32_e32 v6, v28, v27, vcc
	v_add_f32_e32 v27, v29, v1
	v_not_b32_e32 v28, v27
	v_or_b32_e32 v29, 0x80000000, v27
	v_cmp_gt_i32_e32 vcc, 0, v27
	v_and_b32_e32 v6, 0xffffff00, v6
	v_or_b32_e32 v6, 0x6f, v6
	v_cndmask_b32_e32 v27, v29, v28, vcc
	v_add_f32_e32 v28, v30, v1
	v_not_b32_e32 v29, v28
	v_or_b32_e32 v30, 0x80000000, v28
	v_cmp_gt_i32_e32 vcc, 0, v28
	v_and_b32_e32 v27, 0xffffff00, v27
	v_or_b32_e32 v27, 0x5f, v27
	v_cndmask_b32_e32 v28, v30, v29, vcc
	v_add_f32_e32 v29, v31, v1
	v_not_b32_e32 v30, v29
	v_or_b32_e32 v31, 0x80000000, v29
	v_cmp_gt_i32_e32 vcc, 0, v29
	v_and_b32_e32 v28, 0xffffff00, v28
	v_or_b32_e32 v28, 0x4f, v28
	v_cndmask_b32_e32 v29, v31, v30, vcc
	v_add_f32_e32 v30, v32, v1
	v_not_b32_e32 v31, v30
	v_or_b32_e32 v32, 0x80000000, v30
	v_cmp_gt_i32_e32 vcc, 0, v30
	v_and_or_b32 v29, v29, s34, 63
	s_nop 0
	v_cndmask_b32_e32 v30, v32, v31, vcc
; #define CE_DESC(a, b) do { const unsigned _mx = (a) > (b) ? (a) : (b), _mn = (a) > (b) ? (b) : (a); (a) = _mx; (b) = _mn; } while (0)
; __device__ __forceinline__ void sort16_desc(unsigned (&k)[16]) {
; #pragma unroll
;     for (int size = 2; size <= 16; size <<= 1)
; #pragma unroll
;         for (int stride = size >> 1; stride > 0; stride >>= 1)
; #pragma unroll
;             for (int i = 0; i < 16; ++i) { const int j = i ^ stride;
;                 if (j > i) { if ((i & size) == 0) CE_DESC(k[i], k[j]); else CE_DESC(k[j], k[i]); } }
; }
; __device__ __forceinline__ void merge16(unsigned (&a)[16], const unsigned (&b)[16]) {
; #pragma unroll
;     for (int i = 0; i < 16; ++i) a[i] = a[i] > b[15 - i] ? a[i] : b[15 - i];
; #pragma unroll
;     for (int stride = 8; stride > 0; stride >>= 1)
; #pragma unroll
;         for (int i = 0; i < 16; ++i) { const int j = i ^ stride; if (j > i) CE_DESC(a[i], a[j]); }
; }
; __device__ __forceinline__ void peer_tile(const Args& A, LAS unsigned char* lds, int tile) {
;     ...
;             sort16_desc(Bt); merge16(Lf, Bt);
	v_and_or_b32 v30, v30, s34, 47
	v_max_u32_e32 v31, v15, v14
	v_min_u32_e32 v14, v15, v14
	v_max_u32_e32 v15, v50, v4
	v_min_u32_e32 v4, v50, v4
	v_max_u32_e32 v32, v10, v51
	v_min_u32_e32 v10, v10, v51
	v_max_u32_e32 v50, v52, v8
	v_min_u32_e32 v8, v52, v8
	v_max_u32_e32 v51, v0, v2
	v_min_u32_e32 v0, v0, v2
	v_max_u32_e32 v2, v6, v3
	v_min_u32_e32 v3, v6, v3
	v_max_u32_e32 v6, v27, v28
	v_min_u32_e32 v27, v27, v28
	v_max_u32_e32 v28, v30, v29
	v_min_u32_e32 v29, v30, v29
	v_max_u32_e32 v30, v31, v4
	v_min_u32_e32 v4, v31, v4
	v_max_u32_e32 v31, v14, v15
	v_min_u32_e32 v14, v14, v15
	v_max_u32_e32 v15, v8, v32
	v_min_u32_e32 v8, v8, v32
	v_max_u32_e32 v32, v50, v10
	v_min_u32_e32 v10, v50, v10
	v_max_u32_e32 v50, v51, v3
	v_min_u32_e32 v3, v51, v3
	v_max_u32_e32 v51, v0, v2
	v_min_u32_e32 v0, v0, v2
	v_max_u32_e32 v2, v29, v6
	v_min_u32_e32 v6, v29, v6
	v_max_u32_e32 v29, v28, v27
	v_min_u32_e32 v27, v28, v27
	v_max_u32_e32 v28, v30, v31
	v_min_u32_e32 v30, v30, v31
	v_max_u32_e32 v31, v4, v14
	v_min_u32_e32 v4, v4, v14
	v_max_u32_e32 v14, v10, v8
	v_min_u32_e32 v8, v10, v8
	v_max_u32_e32 v10, v32, v15
	v_min_u32_e32 v15, v32, v15
	v_max_u32_e32 v32, v50, v51
	v_min_u32_e32 v50, v50, v51
	v_max_u32_e32 v51, v3, v0
	v_min_u32_e32 v0, v3, v0
	v_max_u32_e32 v3, v27, v6
	v_min_u32_e32 v6, v27, v6
	v_max_u32_e32 v27, v29, v2
	v_min_u32_e32 v2, v29, v2
	v_max_u32_e32 v29, v28, v8
	v_min_u32_e32 v8, v28, v8
	v_max_u32_e32 v28, v30, v14
	v_min_u32_e32 v14, v30, v14
	v_max_u32_e32 v30, v31, v15
	v_min_u32_e32 v15, v31, v15
	v_max_u32_e32 v31, v4, v10
	v_min_u32_e32 v4, v4, v10
	v_max_u32_e32 v10, v6, v32
	v_min_u32_e32 v6, v6, v32
	v_max_u32_e32 v32, v3, v50
	v_min_u32_e32 v3, v3, v50
	v_max_u32_e32 v50, v2, v51
	v_min_u32_e32 v2, v2, v51
	v_max_u32_e32 v51, v27, v0
	v_min_u32_e32 v0, v27, v0
	v_max_u32_e32 v27, v29, v30
	v_min_u32_e32 v29, v29, v30
	v_max_u32_e32 v30, v28, v31
	v_min_u32_e32 v28, v28, v31
	v_max_u32_e32 v31, v8, v15
	v_min_u32_e32 v8, v8, v15
	v_max_u32_e32 v15, v14, v4
	v_min_u32_e32 v4, v14, v4
	v_max_u32_e32 v14, v2, v6
	v_min_u32_e32 v2, v2, v6
	v_max_u32_e32 v6, v0, v3
	v_min_u32_e32 v0, v0, v3
	v_max_u32_e32 v3, v50, v10
	v_min_u32_e32 v10, v50, v10
	v_max_u32_e32 v50, v51, v32
	v_min_u32_e32 v32, v51, v32
	v_max_u32_e32 v51, v27, v30
	v_min_u32_e32 v27, v27, v30
	v_max_u32_e32 v30, v29, v28
	v_min_u32_e32 v28, v29, v28
	v_max_u32_e32 v29, v31, v15
	v_min_u32_e32 v15, v31, v15
	v_max_u32_e32 v31, v8, v4
	v_min_u32_e32 v4, v8, v4
	v_max_u32_e32 v8, v0, v2
	v_min_u32_e32 v0, v0, v2
	v_max_u32_e32 v2, v6, v14
	v_min_u32_e32 v6, v6, v14
	v_max_u32_e32 v14, v32, v10
	v_min_u32_e32 v10, v32, v10
	v_max_u32_e32 v32, v50, v3
	v_min_u32_e32 v3, v50, v3
	v_max_u32_e32 v50, v51, v0
	v_min_u32_e32 v0, v51, v0
	v_max_u32_e32 v51, v27, v8
	v_min_u32_e32 v8, v27, v8
	v_max_u32_e32 v27, v30, v6
	v_min_u32_e32 v6, v30, v6
	v_max_u32_e32 v30, v28, v2
	v_min_u32_e32 v2, v28, v2
	v_max_u32_e32 v28, v29, v10
	v_min_u32_e32 v10, v29, v10
	v_max_u32_e32 v29, v15, v14
	v_min_u32_e32 v14, v15, v14
	v_max_u32_e32 v15, v31, v3
	v_min_u32_e32 v3, v31, v3
	v_max_u32_e32 v31, v4, v32
	v_min_u32_e32 v4, v4, v32
	v_max_u32_e32 v32, v50, v28
	v_min_u32_e32 v28, v50, v28
	v_max_u32_e32 v50, v51, v29
	v_min_u32_e32 v29, v51, v29
	v_max_u32_e32 v51, v27, v15
	v_min_u32_e32 v15, v27, v15
	v_max_u32_e32 v27, v30, v31
	v_min_u32_e32 v30, v30, v31
	v_max_u32_e32 v31, v0, v10
	v_min_u32_e32 v0, v0, v10
	v_max_u32_e32 v10, v8, v14
	v_min_u32_e32 v8, v8, v14
	v_max_u32_e32 v14, v6, v3
	v_min_u32_e32 v3, v6, v3
	v_max_u32_e32 v6, v2, v4
	v_min_u32_e32 v2, v2, v4
	v_max_u32_e32 v4, v32, v51
	v_min_u32_e32 v32, v32, v51
	v_max_u32_e32 v51, v50, v27
	v_min_u32_e32 v27, v50, v27
	v_max_u32_e32 v50, v28, v15
	v_min_u32_e32 v15, v28, v15
	v_max_u32_e32 v28, v29, v30
	v_min_u32_e32 v29, v29, v30
	v_max_u32_e32 v30, v31, v14
	v_min_u32_e32 v14, v31, v14
	v_max_u32_e32 v31, v10, v6
	v_min_u32_e32 v6, v10, v6
	v_max_u32_e32 v10, v0, v3
	v_min_u32_e32 v0, v0, v3
	v_max_u32_e32 v3, v8, v2
	v_min_u32_e32 v2, v8, v2
	v_min_u32_e32 v8, v4, v51
	v_min_u32_e32 v52, v32, v27
	v_min_u32_e32 v53, v50, v28
	v_min_u32_e32 v54, v15, v29
	v_min_u32_e32 v55, v30, v31
	v_min_u32_e32 v56, v14, v6
	v_min_u32_e32 v57, v10, v3
	v_min_u32_e32 v58, v0, v2
	v_max3_u32 v16, v16, v40, v58
	v_max3_u32 v0, v42, v0, v2
	v_max3_u32 v2, v39, v22, v57
	v_max3_u32 v3, v43, v10, v3
	v_max3_u32 v10, v38, v20, v56
	v_max3_u32 v6, v44, v14, v6
	v_max3_u32 v14, v17, v34, v55
	v_max3_u32 v17, v45, v30, v31
	v_max3_u32 v20, v37, v36, v54
	v_max3_u32 v15, v46, v15, v29
	v_max3_u32 v18, v23, v18, v53
	v_max3_u32 v22, v47, v50, v28
	v_max3_u32 v23, v35, v41, v52
	v_max3_u32 v27, v48, v32, v27
	v_max3_u32 v8, v33, v12, v8
	v_max3_u32 v4, v49, v4, v51
	v_max_u32_e32 v12, v16, v20
	v_min_u32_e32 v16, v16, v20
	v_max_u32_e32 v20, v0, v15
	v_min_u32_e32 v0, v0, v15
	v_max_u32_e32 v15, v2, v18
	v_min_u32_e32 v2, v2, v18
	v_max_u32_e32 v18, v3, v22
	v_min_u32_e32 v3, v3, v22
	v_max_u32_e32 v22, v10, v23
	v_min_u32_e32 v10, v10, v23
	v_max_u32_e32 v23, v6, v27
	v_min_u32_e32 v6, v6, v27
	v_max_u32_e32 v27, v14, v8
	v_min_u32_e32 v8, v14, v8
	v_max_u32_e32 v14, v17, v4
	v_min_u32_e32 v4, v17, v4
	v_max_u32_e32 v17, v12, v22
	v_min_u32_e32 v12, v12, v22
	v_max_u32_e32 v22, v20, v23
	v_min_u32_e32 v20, v20, v23
	v_max_u32_e32 v23, v15, v27
	v_min_u32_e32 v15, v15, v27
	v_max_u32_e32 v27, v18, v14
	v_min_u32_e32 v14, v18, v14
	v_max_u32_e32 v18, v16, v10
	v_min_u32_e32 v10, v16, v10
	v_max_u32_e32 v16, v0, v6
	v_min_u32_e32 v0, v0, v6
	v_max_u32_e32 v6, v2, v8
	v_min_u32_e32 v2, v2, v8
	v_max_u32_e32 v8, v3, v4
; __device__ __forceinline__ float key2f(unsigned k) { const unsigned u = (k & 0x80000000u) ? (k & 0x7fffffffu) : ~k; return __uint_as_float(u); }
; #define CE_DESC(a, b) do { const unsigned _mx = (a) > (b) ? (a) : (b), _mn = (a) > (b) ? (b) : (a); (a) = _mx; (b) = _mn; } while (0)
; #define CK(i, j) ((f2key(va[i] + vb[j]) & ~255u) | (unsigned)(255 - (16 * (i) + (j))))
; __device__ __forceinline__ void peer_tile(const Args& A, LAS unsigned char* lds, int tile) {
;     ...
;             { unsigned x0 = CK(14, 0), x1 = CK(15, 0);
; #pragma unroll
;               for (int i = 0; i < 16; ++i) CE_DESC(Lf[i], x0);
; #pragma unroll
;               for (int i = 0; i < 16; ++i) CE_DESC(Lf[i], x1); }
;     ...
;             float fv[16], den = 0.f; const float f0 = key2f(Lf[0] & ~255u);
; #pragma unroll
;             for (int k = 0; k < 16; ++k) { fv[k] = __expf(key2f(Lf[k] & ~255u) - f0); den += fv[k]; }
;             const float rden = 1.f / den;
	v_min_u32_e32 v3, v3, v4
	v_max_u32_e32 v4, v17, v23
	v_min_u32_e32 v17, v17, v23
	v_max_u32_e32 v23, v22, v27
	v_min_u32_e32 v22, v22, v27
	v_max_u32_e32 v27, v12, v15
	v_min_u32_e32 v12, v12, v15
	v_max_u32_e32 v15, v20, v14
	v_min_u32_e32 v14, v20, v14
	v_max_u32_e32 v20, v18, v6
	v_min_u32_e32 v6, v18, v6
	v_max_u32_e32 v18, v16, v8
	v_min_u32_e32 v8, v16, v8
	v_max_u32_e32 v16, v10, v2
	v_min_u32_e32 v2, v10, v2
	v_max_u32_e32 v10, v0, v3
	v_min_u32_e32 v0, v0, v3
	v_max_u32_e32 v41, v2, v0
	v_min_u32_e32 v0, v2, v0
	v_add_f32_e32 v2, v25, v1
	v_not_b32_e32 v25, v2
	v_or_b32_e32 v42, 0x80000000, v2
	v_cmp_gt_i32_e32 vcc, 0, v2
	v_add_f32_e32 v1, v26, v1
	v_max_u32_e32 v3, v4, v23
	v_cndmask_b32_e32 v2, v42, v25, vcc
	v_and_or_b32 v2, v2, s34, 31
	v_not_b32_e32 v25, v1
	v_or_b32_e32 v26, 0x80000000, v1
	v_cmp_gt_i32_e32 vcc, 0, v1
	v_min_u32_e32 v28, v4, v23
	v_max_u32_e32 v29, v17, v22
	v_cndmask_b32_e32 v1, v26, v25, vcc
	v_max_u32_e32 v25, v3, v2
	v_min_u32_e32 v3, v3, v2
	v_min_u32_e32 v3, v28, v3
	v_min_u32_e32 v30, v17, v22
	v_med3_u32 v2, v4, v23, v2
	v_min_u32_e32 v23, v29, v3
	v_max_u32_e32 v31, v27, v15
	v_max_u32_e32 v4, v29, v3
	v_med3_u32 v3, v17, v22, v3
	v_min_u32_e32 v17, v30, v23
	v_min_u32_e32 v32, v27, v15
	v_min_u32_e32 v23, v31, v17
	v_max_u32_e32 v33, v12, v14
	v_max_u32_e32 v22, v31, v17
	v_med3_u32 v15, v27, v15, v17
	v_min_u32_e32 v17, v32, v23
	v_min_u32_e32 v34, v12, v14
	v_min_u32_e32 v26, v33, v17
	v_max_u32_e32 v35, v20, v18
	v_med3_u32 v12, v12, v14, v17
	v_min_u32_e32 v14, v34, v26
	v_min_u32_e32 v36, v20, v18
	v_min_u32_e32 v26, v35, v14
	v_max_u32_e32 v37, v6, v8
	v_max_u32_e32 v23, v33, v17
	v_max_u32_e32 v17, v35, v14
	v_med3_u32 v14, v20, v18, v14
	v_min_u32_e32 v18, v36, v26
	v_min_u32_e32 v38, v6, v8
	v_min_u32_e32 v26, v37, v18
	v_max_u32_e32 v39, v16, v10
	v_med3_u32 v6, v6, v8, v18
	v_min_u32_e32 v8, v38, v26
	v_min_u32_e32 v40, v16, v10
	v_min_u32_e32 v26, v39, v8
	v_and_or_b32 v1, v1, s34, 15
	v_max_u32_e32 v20, v37, v18
	v_max_u32_e32 v18, v39, v8
	v_med3_u32 v8, v16, v10, v8
	v_min_u32_e32 v10, v40, v26
	v_max_u32_e32 v26, v25, v1
	v_min_u32_e32 v1, v25, v1
	v_max_u32_e32 v25, v2, v1
	v_min_u32_e32 v1, v2, v1
	v_max_u32_e32 v2, v4, v1
	v_min_u32_e32 v1, v4, v1
	v_max_u32_e32 v4, v3, v1
	v_min_u32_e32 v1, v3, v1
	v_max_u32_e32 v3, v22, v1
	v_min_u32_e32 v1, v22, v1
	v_max_u32_e32 v22, v15, v1
	v_min_u32_e32 v1, v15, v1
	v_max_u32_e32 v15, v23, v1
	v_min_u32_e32 v1, v23, v1
	v_max_u32_e32 v23, v12, v1
	v_min_u32_e32 v1, v12, v1
	v_max_u32_e32 v12, v17, v1
	v_min_u32_e32 v1, v17, v1
	v_max_u32_e32 v17, v14, v1
	v_min_u32_e32 v1, v14, v1
	v_max_u32_e32 v14, v20, v1
	v_min_u32_e32 v1, v20, v1
	v_max_u32_e32 v20, v6, v1
	v_min_u32_e32 v1, v6, v1
	v_max_u32_e32 v6, v18, v1
	v_min_u32_e32 v1, v18, v1
	v_max_u32_e32 v16, v41, v10
	v_max_u32_e32 v18, v8, v1
	v_min_u32_e32 v1, v8, v1
	v_min_u32_e32 v10, v41, v10
	v_max_u32_e32 v8, v16, v1
	v_min_u32_e32 v1, v16, v1
	v_max3_u32 v10, v0, v10, v1
	v_and_b32_e32 v0, 0x7fffff00, v26
	v_bitop3_b32 v1, v26, s33, v26 bitop3:0xcf
	v_cmp_gt_i32_e32 vcc, 0, v26
	v_and_b32_e32 v16, 0x7fffff00, v25
	v_bitop3_b32 v27, v25, s33, v25 bitop3:0xcf
	v_cndmask_b32_e32 v0, v1, v0, vcc
	v_cmp_gt_i32_e32 vcc, 0, v25
	v_sub_f32_e32 v1, v0, v0
	v_bitop3_b32 v28, v2, s33, v2 bitop3:0xcf
	v_cndmask_b32_e32 v16, v27, v16, vcc
	v_and_b32_e32 v27, 0x7fffff00, v2
	v_cmp_gt_i32_e32 vcc, 0, v2
	v_mul_f32_e32 v1, 0x3fb8aa3b, v1
	v_sub_f32_e32 v16, v16, v0
	v_cndmask_b32_e32 v27, v28, v27, vcc
	v_and_b32_e32 v28, 0x7fffff00, v4
	v_bitop3_b32 v29, v4, s33, v4 bitop3:0xcf
	v_cmp_gt_i32_e32 vcc, 0, v4
	v_exp_f32_e32 v1, v1
	v_mul_f32_e32 v16, 0x3fb8aa3b, v16
	v_sub_f32_e32 v27, v27, v0
	v_cndmask_b32_e32 v28, v29, v28, vcc
	v_and_b32_e32 v30, 0x7fffff00, v3
	v_bitop3_b32 v31, v3, s33, v3 bitop3:0xcf
	v_cmp_gt_i32_e32 vcc, 0, v3
	v_exp_f32_e32 v16, v16
	v_mul_f32_e32 v27, 0x3fb8aa3b, v27
	v_sub_f32_e32 v28, v28, v0
	v_cndmask_b32_e32 v30, v31, v30, vcc
	v_and_b32_e32 v31, 0x7fffff00, v22
	v_bitop3_b32 v32, v22, s33, v22 bitop3:0xcf
	v_cmp_gt_i32_e32 vcc, 0, v22
	v_exp_f32_e32 v27, v27
	v_mul_f32_e32 v28, 0x3fb8aa3b, v28
	v_sub_f32_e32 v30, v30, v0
	v_cndmask_b32_e32 v31, v32, v31, vcc
	v_and_b32_e32 v32, 0x7fffff00, v15
	v_bitop3_b32 v33, v15, s33, v15 bitop3:0xcf
	v_cmp_gt_i32_e32 vcc, 0, v15
	v_exp_f32_e32 v28, v28
	v_mul_f32_e32 v30, 0x3fb8aa3b, v30
	v_sub_f32_e32 v31, v31, v0
	v_cndmask_b32_e32 v32, v33, v32, vcc
	v_and_b32_e32 v33, 0x7fffff00, v23
	v_bitop3_b32 v34, v23, s33, v23 bitop3:0xcf
	v_cmp_gt_i32_e32 vcc, 0, v23
	v_add_f32_e32 v29, 0, v1
	v_exp_f32_e32 v30, v30
	v_mul_f32_e32 v31, 0x3fb8aa3b, v31
	v_sub_f32_e32 v32, v32, v0
	v_cndmask_b32_e32 v33, v34, v33, vcc
	v_and_b32_e32 v34, 0x7fffff00, v12
	v_bitop3_b32 v35, v12, s33, v12 bitop3:0xcf
	v_cmp_gt_i32_e32 vcc, 0, v12
	v_add_f32_e32 v29, v29, v16
	v_exp_f32_e32 v31, v31
	v_mul_f32_e32 v32, 0x3fb8aa3b, v32
	v_sub_f32_e32 v33, v33, v0
	v_cndmask_b32_e32 v34, v35, v34, vcc
	v_and_b32_e32 v35, 0x7fffff00, v17
	v_bitop3_b32 v36, v17, s33, v17 bitop3:0xcf
	v_cmp_gt_i32_e32 vcc, 0, v17
	v_add_f32_e32 v29, v29, v27
	v_exp_f32_e32 v32, v32
	v_mul_f32_e32 v33, 0x3fb8aa3b, v33
	v_sub_f32_e32 v34, v34, v0
	v_cndmask_b32_e32 v35, v36, v35, vcc
	v_and_b32_e32 v36, 0x7fffff00, v14
	v_bitop3_b32 v37, v14, s33, v14 bitop3:0xcf
	v_cmp_gt_i32_e32 vcc, 0, v14
	v_add_f32_e32 v29, v29, v28
	v_exp_f32_e32 v33, v33
	v_mul_f32_e32 v34, 0x3fb8aa3b, v34
	v_sub_f32_e32 v35, v35, v0
	v_cndmask_b32_e32 v36, v37, v36, vcc
	v_and_b32_e32 v37, 0x7fffff00, v20
	v_bitop3_b32 v38, v20, s33, v20 bitop3:0xcf
	v_cmp_gt_i32_e32 vcc, 0, v20
	v_add_f32_e32 v29, v29, v30
; #define LDS_WAIT() asm volatile("s_waitcnt lgkmcnt(0)" ::: "memory")
; __device__ __forceinline__ float key2f(unsigned k) { const unsigned u = (k & 0x80000000u) ? (k & 0x7fffffffu) : ~k; return __uint_as_float(u); }
; __device__ __forceinline__ void peer_tile(const Args& A, LAS unsigned char* lds, int tile) {
;     ...
;             float fv[16], den = 0.f; const float f0 = key2f(Lf[0] & ~255u);
; #pragma unroll
;             for (int k = 0; k < 16; ++k) { fv[k] = __expf(key2f(Lf[k] & ~255u) - f0); den += fv[k]; }
;             const float rden = 1.f / den;
;             LDS_WAIT();
; #pragma unroll
;             for (int k = 0; k < 16; ++k) { const unsigned code = 255u - (Lf[k] & 255u); const unsigned e = idx[code >> 4] * 128u + idx[16 + (code & 15u)];
;                 u32x2 sv; sv.x = e; sv.y = __float_as_uint(fv[k] * rden); SEL[(tl * 8 + h) * 16 + k] = sv; }
	v_exp_f32_e32 v34, v34
	v_mul_f32_e32 v35, 0x3fb8aa3b, v35
	v_sub_f32_e32 v36, v36, v0
	v_cndmask_b32_e32 v37, v38, v37, vcc
	v_and_b32_e32 v38, 0x7fffff00, v6
	v_bitop3_b32 v39, v6, s33, v6 bitop3:0xcf
	v_cmp_gt_i32_e32 vcc, 0, v6
	v_add_f32_e32 v29, v29, v31
	v_exp_f32_e32 v35, v35
	v_mul_f32_e32 v36, 0x3fb8aa3b, v36
	v_sub_f32_e32 v37, v37, v0
	v_cndmask_b32_e32 v38, v39, v38, vcc
	v_and_b32_e32 v39, 0x7fffff00, v18
	v_bitop3_b32 v40, v18, s33, v18 bitop3:0xcf
	v_cmp_gt_i32_e32 vcc, 0, v18
	v_add_f32_e32 v29, v29, v32
	v_exp_f32_e32 v36, v36
	v_mul_f32_e32 v37, 0x3fb8aa3b, v37
	v_sub_f32_e32 v38, v38, v0
	v_cndmask_b32_e32 v39, v40, v39, vcc
	v_and_b32_e32 v40, 0x7fffff00, v8
	v_bitop3_b32 v41, v8, s33, v8 bitop3:0xcf
	v_cmp_gt_i32_e32 vcc, 0, v8
	v_add_f32_e32 v29, v29, v33
	v_exp_f32_e32 v37, v37
	v_mul_f32_e32 v38, 0x3fb8aa3b, v38
	v_sub_f32_e32 v39, v39, v0
	v_cndmask_b32_e32 v40, v41, v40, vcc
	v_and_b32_e32 v41, 0x7fffff00, v10
	v_bitop3_b32 v42, v10, s33, v10 bitop3:0xcf
	v_cmp_gt_i32_e32 vcc, 0, v10
	v_add_f32_e32 v29, v29, v34
	v_exp_f32_e32 v38, v38
	v_mul_f32_e32 v39, 0x3fb8aa3b, v39
	v_sub_f32_e32 v40, v40, v0
	v_cndmask_b32_e32 v41, v42, v41, vcc
	v_add_f32_e32 v29, v29, v35
	v_exp_f32_e32 v39, v39
	v_mul_f32_e32 v40, 0x3fb8aa3b, v40
	v_sub_f32_e32 v0, v41, v0
	v_add_f32_e32 v29, v29, v36
	v_exp_f32_e32 v40, v40
	v_mul_f32_e32 v0, 0x3fb8aa3b, v0
	v_add_f32_e32 v29, v29, v37
	v_exp_f32_e32 v41, v0
	v_add_f32_e32 v0, v29, v38
	v_add_f32_e32 v0, v0, v39
	v_add_f32_e32 v0, v0, v40
	v_add_f32_e32 v0, v0, v41
	v_div_scale_f32 v29, s[0:1], v0, v0, 1.0
	v_rcp_f32_e32 v42, v29
	v_not_b32_e32 v21, v26
	v_not_b32_e32 v24, v25
	v_fma_f32 v43, -v29, v42, 1.0
	v_fmac_f32_e32 v42, v43, v42
	v_div_scale_f32 v43, vcc, 1.0, v0, 1.0
	v_mul_f32_e32 v44, v43, v42
	v_fma_f32 v45, -v29, v44, v43
	v_fmac_f32_e32 v44, v45, v42
	v_fma_f32 v29, -v29, v44, v43
	v_div_fmas_f32 v29, v29, v42, v44
	v_div_fixup_f32 v29, v29, v0, 1.0
	v_and_b32_e32 v0, 48, v19
	v_lshrrev_b32_e32 v19, 2, v21
	v_and_b32_e32 v19, 60, v19
	v_bitop3_b32 v21, v26, 15, v26 bitop3:0xc
	v_add_u32_e32 v19, v5, v19
	v_lshl_add_u32 v21, v21, 2, v5
	ds_read_b32 v19, v19
	ds_read_b32 v21, v21 offset:64
	v_lshlrev_b32_e32 v0, 3, v0
	v_add3_u32 v11, v13, v11, v0
	v_mul_f32_e32 v1, v1, v29
	v_not_b32_e32 v13, v2
	s_waitcnt lgkmcnt(0)
	v_lshl_add_u32 v0, v19, 7, v21
	ds_write_b64 v11, v[0:1]
	v_lshrrev_b32_e32 v0, 2, v24
	v_and_b32_e32 v0, 60, v0
	v_bitop3_b32 v1, v25, 15, v25 bitop3:0xc
	v_add_u32_e32 v0, v5, v0
	v_lshl_add_u32 v1, v1, 2, v5
	ds_read_b32 v0, v0
	ds_read_b32 v1, v1 offset:64
	v_cmp_eq_u32_e32 vcc, 0, v9
	s_waitcnt lgkmcnt(0)
	v_lshl_add_u32 v0, v0, 7, v1
	v_mul_f32_e32 v1, v16, v29
	ds_write_b64 v11, v[0:1] offset:8
	v_lshrrev_b32_e32 v0, 2, v13
	v_and_b32_e32 v0, 60, v0
	v_bitop3_b32 v1, v2, 15, v2 bitop3:0xc
	v_add_u32_e32 v0, v5, v0
	v_lshl_add_u32 v1, v1, 2, v5
	ds_read_b32 v0, v0
	ds_read_b32 v1, v1 offset:64
	v_not_b32_e32 v2, v4
	s_waitcnt lgkmcnt(0)
	v_lshl_add_u32 v0, v0, 7, v1
	v_mul_f32_e32 v1, v27, v29
	ds_write_b64 v11, v[0:1] offset:16
	v_lshrrev_b32_e32 v0, 2, v2
	v_and_b32_e32 v0, 60, v0
	v_bitop3_b32 v1, v4, 15, v4 bitop3:0xc
	v_add_u32_e32 v0, v5, v0
	v_lshl_add_u32 v1, v1, 2, v5
	ds_read_b32 v0, v0
	ds_read_b32 v1, v1 offset:64
	v_not_b32_e32 v2, v3
	v_mul_lo_u32 v4, v7, s36
	s_waitcnt lgkmcnt(0)
	v_lshl_add_u32 v0, v0, 7, v1
	v_mul_f32_e32 v1, v28, v29
	ds_write_b64 v11, v[0:1] offset:24
	v_lshrrev_b32_e32 v0, 2, v2
	v_and_b32_e32 v0, 60, v0
	v_bitop3_b32 v1, v3, 15, v3 bitop3:0xc
	v_add_u32_e32 v0, v5, v0
	v_lshl_add_u32 v1, v1, 2, v5
	ds_read_b32 v0, v0
	ds_read_b32 v1, v1 offset:64
	v_not_b32_e32 v2, v22
	s_waitcnt lgkmcnt(0)
	v_lshl_add_u32 v0, v0, 7, v1
	v_mul_f32_e32 v1, v30, v29
	ds_write_b64 v11, v[0:1] offset:32
	v_lshrrev_b32_e32 v0, 2, v2
	v_and_b32_e32 v0, 60, v0
	v_bitop3_b32 v1, v22, 15, v22 bitop3:0xc
	v_add_u32_e32 v0, v5, v0
	v_lshl_add_u32 v1, v1, 2, v5
	ds_read_b32 v0, v0
	ds_read_b32 v1, v1 offset:64
	v_not_b32_e32 v2, v15
	s_waitcnt lgkmcnt(0)
	v_lshl_add_u32 v0, v0, 7, v1
	v_mul_f32_e32 v1, v31, v29
	ds_write_b64 v11, v[0:1] offset:40
	v_lshrrev_b32_e32 v0, 2, v2
	v_and_b32_e32 v0, 60, v0
	v_bitop3_b32 v1, v15, 15, v15 bitop3:0xc
	v_add_u32_e32 v0, v5, v0
	v_lshl_add_u32 v1, v1, 2, v5
	ds_read_b32 v0, v0
	ds_read_b32 v1, v1 offset:64
	v_not_b32_e32 v2, v23
	s_waitcnt lgkmcnt(0)
	v_lshl_add_u32 v0, v0, 7, v1
	v_mul_f32_e32 v1, v32, v29
	ds_write_b64 v11, v[0:1] offset:48
	v_lshrrev_b32_e32 v0, 2, v2
	v_and_b32_e32 v0, 60, v0
	v_bitop3_b32 v1, v23, 15, v23 bitop3:0xc
	v_add_u32_e32 v0, v5, v0
	v_lshl_add_u32 v1, v1, 2, v5
	ds_read_b32 v0, v0
	ds_read_b32 v1, v1 offset:64
	v_not_b32_e32 v2, v12
	s_waitcnt lgkmcnt(0)
	v_lshl_add_u32 v0, v0, 7, v1
	v_mul_f32_e32 v1, v33, v29
	ds_write_b64 v11, v[0:1] offset:56
	v_lshrrev_b32_e32 v0, 2, v2
	v_and_b32_e32 v0, 60, v0
	v_bitop3_b32 v1, v12, 15, v12 bitop3:0xc
	v_add_u32_e32 v0, v5, v0
	v_lshl_add_u32 v1, v1, 2, v5
	ds_read_b32 v0, v0
	ds_read_b32 v1, v1 offset:64
	v_not_b32_e32 v2, v17
	s_waitcnt lgkmcnt(0)
	v_lshl_add_u32 v0, v0, 7, v1
	v_mul_f32_e32 v1, v34, v29
	ds_write_b64 v11, v[0:1] offset:64
	v_lshrrev_b32_e32 v0, 2, v2
	v_and_b32_e32 v0, 60, v0
	v_bitop3_b32 v1, v17, 15, v17 bitop3:0xc
	v_add_u32_e32 v0, v5, v0
	v_lshl_add_u32 v1, v1, 2, v5
	ds_read_b32 v0, v0
	ds_read_b32 v1, v1 offset:64
	v_not_b32_e32 v2, v14
	s_waitcnt lgkmcnt(0)
	v_lshl_add_u32 v0, v0, 7, v1
	v_mul_f32_e32 v1, v35, v29
	ds_write_b64 v11, v[0:1] offset:72
	v_lshrrev_b32_e32 v0, 2, v2
	v_and_b32_e32 v0, 60, v0
	v_bitop3_b32 v1, v14, 15, v14 bitop3:0xc
	v_add_u32_e32 v0, v5, v0
	v_lshl_add_u32 v1, v1, 2, v5
	ds_read_b32 v0, v0
	ds_read_b32 v1, v1 offset:64
	v_not_b32_e32 v2, v20
	s_waitcnt lgkmcnt(0)
; __device__ __forceinline__ unsigned pk2(float lo, float hi) { const f32x2 v = {lo, hi}; const bf16x2_t b = __builtin_convertvector(v, bf16x2_t); return __builtin_bit_cast(unsigned, b); }
; __device__ __forceinline__ float bflo(unsigned u) { return __uint_as_float(u << 16); }
; __device__ __forceinline__ float bfhi(unsigned u) { return __uint_as_float(u & 0xffff0000u); }
; __device__ __forceinline__ void peer_tile(const Args& A, LAS unsigned char* lds, int tile) {
;     ...
;             for (int k = 0; k < 16; ++k) { const unsigned code = 255u - (Lf[k] & 255u); const unsigned e = idx[code >> 4] * 128u + idx[16 + (code & 15u)];
;                 u32x2 sv; sv.x = e; sv.y = __float_as_uint(fv[k] * rden); SEL[(tl * 8 + h) * 16 + k] = sv; }
;     ...
;     const bf16_t* A3 = (const bf16_t*)(A.ws + WS_A3); const float* RSq = (const float*)(A.ws + WS_RS);
;     for (int pass = 0; pass < 2; ++pass) {
;         const int tb = 8 * w + 4 * pass;
;         u32x4 xpa[4], xpb[4]; f32x2 oacc[4][8];
; #pragma unroll
;         for (int tk = 0; tk < 4; ++tk) { const size_t m = (size_t)tile * 64 + tb + tk;
;             { const u32x4 ra = *(const u32x4*)(A3 + m * 1024 + 16 * lane), rb = *(const u32x4*)(A3 + m * 1024 + 16 * lane + 8);
;               float xr_; { const f32x4 p0 = *(const f32x4*)(RSq + m * 16), p1 = *(const f32x4*)(RSq + m * 16 + 4), p2 = *(const f32x4*)(RSq + m * 16 + 8), p3 = *(const f32x4*)(RSq + m * 16 + 12);
;                 const f32x4 ps = (p0 + p1) + (p2 + p3); xr_ = rsqrtf(((ps[0] + ps[1]) + (ps[2] + ps[3])) * (1.f / 1024.f) + 1e-6f); }
;               const unsigned rr[8] = {ra.x, ra.y, ra.z, ra.w, rb.x, rb.y, rb.z, rb.w}; unsigned hh[8];
;               const float* sp = MOD + (int)(m >> 11) * 6144 + 3072 + 16 * lane;
; #pragma unroll
;               for (int q = 0; q < 8; ++q) { const f32x2 sh = *(const f32x2*)(sp + 2 * q); hh[q] = pk2(bflo(rr[q]) * xr_ + sh[0], bfhi(rr[q]) * xr_ + sh[1]); }
;               xpa[tk] = (u32x4){hh[0], hh[1], hh[2], hh[3]}; xpb[tk] = (u32x4){hh[4], hh[5], hh[6], hh[7]}; }
; #pragma unroll
;             for (int q = 0; q < 8; ++q) oacc[tk][q] = (f32x2){0.f, 0.f}; }
	v_lshl_add_u32 v0, v0, 7, v1
	v_mul_f32_e32 v1, v36, v29
	ds_write_b64 v11, v[0:1] offset:80
	v_lshrrev_b32_e32 v0, 2, v2
	v_and_b32_e32 v0, 60, v0
	v_bitop3_b32 v1, v20, 15, v20 bitop3:0xc
	v_add_u32_e32 v0, v5, v0
	v_lshl_add_u32 v1, v1, 2, v5
	ds_read_b32 v0, v0
	ds_read_b32 v1, v1 offset:64
	v_not_b32_e32 v2, v6
	s_waitcnt lgkmcnt(0)
	v_lshl_add_u32 v0, v0, 7, v1
	v_mul_f32_e32 v1, v37, v29
	ds_write_b64 v11, v[0:1] offset:88
	v_lshrrev_b32_e32 v0, 2, v2
	v_and_b32_e32 v0, 60, v0
	v_bitop3_b32 v1, v6, 15, v6 bitop3:0xc
	v_add_u32_e32 v0, v5, v0
	v_lshl_add_u32 v1, v1, 2, v5
	ds_read_b32 v0, v0
	ds_read_b32 v1, v1 offset:64
	v_not_b32_e32 v2, v18
	s_waitcnt lgkmcnt(0)
	v_lshl_add_u32 v0, v0, 7, v1
	v_mul_f32_e32 v1, v38, v29
	ds_write_b64 v11, v[0:1] offset:96
	v_lshrrev_b32_e32 v0, 2, v2
	v_and_b32_e32 v0, 60, v0
	v_bitop3_b32 v1, v18, 15, v18 bitop3:0xc
	v_add_u32_e32 v0, v5, v0
	v_lshl_add_u32 v1, v1, 2, v5
	ds_read_b32 v0, v0
	ds_read_b32 v1, v1 offset:64
	v_not_b32_e32 v2, v8
	s_waitcnt lgkmcnt(0)
	v_lshl_add_u32 v0, v0, 7, v1
	v_mul_f32_e32 v1, v39, v29
	ds_write_b64 v11, v[0:1] offset:104
	v_lshrrev_b32_e32 v0, 2, v2
	v_and_b32_e32 v0, 60, v0
	v_bitop3_b32 v1, v8, 15, v8 bitop3:0xc
	v_add_u32_e32 v0, v5, v0
	v_lshl_add_u32 v1, v1, 2, v5
	ds_read_b32 v0, v0
	ds_read_b32 v1, v1 offset:64
	v_not_b32_e32 v2, v10
	s_waitcnt lgkmcnt(0)
	v_lshl_add_u32 v0, v0, 7, v1
	v_mul_f32_e32 v1, v40, v29
	ds_write_b64 v11, v[0:1] offset:112
	v_lshrrev_b32_e32 v0, 2, v2
	v_and_b32_e32 v0, 60, v0
	v_bitop3_b32 v1, v10, 15, v10 bitop3:0xc
	v_add_u32_e32 v0, v5, v0
	v_lshl_add_u32 v1, v1, 2, v5
	ds_read_b32 v0, v0
	ds_read_b32 v1, v1 offset:64
	v_lshlrev_b32_e32 v5, 13, v7
	v_lshl_or_b32 v6, v9, 3, v5
	s_waitcnt lgkmcnt(0)
	v_lshl_add_u32 v0, v0, 7, v1
	v_mul_f32_e32 v1, v41, v29
	ds_write_b64 v11, v[0:1] offset:120
	s_waitcnt lgkmcnt(0)
	s_barrier
	s_mov_b64 exec, -1
	v_and_b32_e32 v240, 63, v214
	v_lshrrev_b32_e32 v242, 6, v214
	v_lshlrev_b32_e32 v240, 4, v240
	v_readfirstlane_b32 s16, v242
	v_lshlrev_b32_e32 v245, 1, v240
	v_lshlrev_b32_e32 v246, 2, v240
	v_lshrrev_b32_e32 v247, 4, v240
	v_and_b32_e32 v247, 48, v247
	v_mov_b32_e32 v244, 0
	v_mov_b32_e32 v243, 0x358637bd
	v_mov_b32_e32 v242, 0xbf3a00e3
	s_add_u32 s4, s50, 0x1000000
	s_addc_u32 s5, s51, 0
	s_add_u32 s6, s50, 0x2000000
	s_addc_u32 s7, s51, 0
	s_add_u32 s8, s50, 0x3000000
	s_addc_u32 s9, s51, 0
	s_add_u32 s52, s50, 0x3010000
	s_addc_u32 s53, s51, 0
	s_add_u32 s12, s50, 0xb000000
	s_addc_u32 s13, s51, 0
	s_add_u32 s14, s50, 0xd000000
	s_addc_u32 s15, s51, 0
	s_lshr_b32 s0, s2, 5
	s_mul_i32 s0, s0, 0x6000
	s_add_u32 s10, s50, s0
	s_addc_u32 s11, s51, 0
	s_add_u32 s80, s10, 0x4000
	s_addc_u32 s81, s11, 0
	s_add_u32 s82, s10, 0x6000
	s_addc_u32 s83, s11, 0
	s_mul_i32 s22, s16, 9728
	s_cmp_eq_u32 s16, 7
	s_cselect_b32 s22, 0x21000, s22
	s_mov_b32 s85, 0xfffffc00
	s_mov_b32 s72, 0x3e6d3388
	s_lshl_b32 s76, s16, 3
	s_lshl_b32 s0, s2, 6
	s_add_i32 s77, s0, s76
	global_load_dwordx4 v[192:195], v246, s[80:81] offset:0
	global_load_dwordx4 v[196:199], v246, s[80:81] offset:16
	global_load_dwordx4 v[200:203], v246, s[80:81] offset:32
	global_load_dwordx4 v[204:207], v246, s[80:81] offset:48
	s_add_i32 s0, s77, 0
	s_lshl_b32 s1, s0, 11
	s_add_u32 s78, s12, s1
	s_addc_u32 s79, s13, 0
	global_load_dwordx4 v[128:131], v245, s[78:79]
	global_load_dwordx4 v[132:135], v245, s[78:79] offset:16
	global_load_dwordx4 v[136:139], v245, s[78:79] offset:2048
	global_load_dwordx4 v[140:143], v245, s[78:79] offset:2064
	s_lshl_b32 s1, s0, 6
	s_add_u32 s78, s14, s1
	s_addc_u32 s79, s15, 0
	global_load_dwordx4 v[144:147], v244, s[78:79] offset:0
	global_load_dwordx4 v[148:151], v244, s[78:79] offset:16
	global_load_dwordx4 v[152:155], v244, s[78:79] offset:32
	global_load_dwordx4 v[156:159], v244, s[78:79] offset:48
	global_load_dwordx4 v[160:163], v244, s[78:79] offset:64
	global_load_dwordx4 v[164:167], v244, s[78:79] offset:80
	global_load_dwordx4 v[168:171], v244, s[78:79] offset:96
	global_load_dwordx4 v[172:175], v244, s[78:79] offset:112
	s_waitcnt vmcnt(0)
	v_pk_add_f32 v[144:145], v[144:145], v[148:149]
	v_pk_add_f32 v[146:147], v[146:147], v[150:151]
	v_pk_add_f32 v[152:153], v[152:153], v[156:157]
	v_pk_add_f32 v[154:155], v[154:155], v[158:159]
	v_pk_add_f32 v[144:145], v[144:145], v[152:153]
	v_pk_add_f32 v[146:147], v[146:147], v[154:155]
	v_add_f32_e32 v144, v144, v145
	v_add_f32_e32 v146, v146, v147
	v_add_f32_e32 v144, v144, v146
	v_fmamk_f32 v144, v144, 0x3a800000, v243
	v_rsq_f32_e32 v144, v144
	v_pk_add_f32 v[160:161], v[160:161], v[164:165]
	v_pk_add_f32 v[162:163], v[162:163], v[166:167]
	v_pk_add_f32 v[168:169], v[168:169], v[172:173]
	v_pk_add_f32 v[170:171], v[170:171], v[174:175]
	v_pk_add_f32 v[160:161], v[160:161], v[168:169]
	v_pk_add_f32 v[162:163], v[162:163], v[170:171]
	v_add_f32_e32 v160, v160, v161
	v_add_f32_e32 v162, v162, v163
	v_add_f32_e32 v160, v160, v162
	v_fmamk_f32 v160, v160, 0x3a800000, v243
	v_rsq_f32_e32 v160, v160
	v_lshlrev_b32_e32 v208, 16, v128
	v_and_b32_e32 v209, 0xffff0000, v128
	v_fma_f32 v208, v208, v144, v192
	v_fma_f32 v209, v209, v144, v193
	v_cvt_pk_bf16_f32 v210, v208, v209
	v_lshlrev_b32_e32 v0, 16, v210
	v_and_b32_e32 v1, 0xffff0000, v210
	v_lshlrev_b32_e32 v208, 16, v129
	v_and_b32_e32 v209, 0xffff0000, v129
	v_fma_f32 v208, v208, v144, v194
	v_fma_f32 v209, v209, v144, v195
	v_cvt_pk_bf16_f32 v210, v208, v209
	v_lshlrev_b32_e32 v2, 16, v210
	v_and_b32_e32 v3, 0xffff0000, v210
	v_lshlrev_b32_e32 v208, 16, v130
	v_and_b32_e32 v209, 0xffff0000, v130
	v_fma_f32 v208, v208, v144, v196
	v_fma_f32 v209, v209, v144, v197
	v_cvt_pk_bf16_f32 v210, v208, v209
; __device__ __forceinline__ unsigned pk2(float lo, float hi) { const f32x2 v = {lo, hi}; const bf16x2_t b = __builtin_convertvector(v, bf16x2_t); return __builtin_bit_cast(unsigned, b); }
; __device__ __forceinline__ float bflo(unsigned u) { return __uint_as_float(u << 16); }
; __device__ __forceinline__ float bfhi(unsigned u) { return __uint_as_float(u & 0xffff0000u); }
; __device__ __forceinline__ void peer_tile(const Args& A, LAS unsigned char* lds, int tile) {
;     ...
;         for (int tk = 0; tk < 4; ++tk) { const size_t m = (size_t)tile * 64 + tb + tk;
;             { const u32x4 ra = *(const u32x4*)(A3 + m * 1024 + 16 * lane), rb = *(const u32x4*)(A3 + m * 1024 + 16 * lane + 8);
;               float xr_; { const f32x4 p0 = *(const f32x4*)(RSq + m * 16), p1 = *(const f32x4*)(RSq + m * 16 + 4), p2 = *(const f32x4*)(RSq + m * 16 + 8), p3 = *(const f32x4*)(RSq + m * 16 + 12);
;                 const f32x4 ps = (p0 + p1) + (p2 + p3); xr_ = rsqrtf(((ps[0] + ps[1]) + (ps[2] + ps[3])) * (1.f / 1024.f) + 1e-6f); }
;               const unsigned rr[8] = {ra.x, ra.y, ra.z, ra.w, rb.x, rb.y, rb.z, rb.w}; unsigned hh[8];
;               const float* sp = MOD + (int)(m >> 11) * 6144 + 3072 + 16 * lane;
; #pragma unroll
;               for (int q = 0; q < 8; ++q) { const f32x2 sh = *(const f32x2*)(sp + 2 * q); hh[q] = pk2(bflo(rr[q]) * xr_ + sh[0], bfhi(rr[q]) * xr_ + sh[1]); }
;               xpa[tk] = (u32x4){hh[0], hh[1], hh[2], hh[3]}; xpb[tk] = (u32x4){hh[4], hh[5], hh[6], hh[7]}; }
; #pragma unroll
;             for (int q = 0; q < 8; ++q) oacc[tk][q] = (f32x2){0.f, 0.f}; }
;     ...
;                 { const unsigned xx[8] = {xpa[tk].x, xpa[tk].y, xpa[tk].z, xpa[tk].w, xpb[tk].x, xpb[tk].y, xpb[tk].z, xpb[tk].w};
; #pragma unroll
;                   for (int q = 0; q < 8; ++q) xf[q] = (f32x2){bflo(xx[q]), bfhi(xx[q])}; }
	v_lshlrev_b32_e32 v4, 16, v210
	v_and_b32_e32 v5, 0xffff0000, v210
	v_lshlrev_b32_e32 v208, 16, v131
	v_and_b32_e32 v209, 0xffff0000, v131
	v_fma_f32 v208, v208, v144, v198
	v_fma_f32 v209, v209, v144, v199
	v_cvt_pk_bf16_f32 v210, v208, v209
	v_lshlrev_b32_e32 v6, 16, v210
	v_and_b32_e32 v7, 0xffff0000, v210
	v_lshlrev_b32_e32 v208, 16, v132
	v_and_b32_e32 v209, 0xffff0000, v132
	v_fma_f32 v208, v208, v144, v200
	v_fma_f32 v209, v209, v144, v201
	v_cvt_pk_bf16_f32 v210, v208, v209
	v_lshlrev_b32_e32 v8, 16, v210
	v_and_b32_e32 v9, 0xffff0000, v210
	v_lshlrev_b32_e32 v208, 16, v133
	v_and_b32_e32 v209, 0xffff0000, v133
	v_fma_f32 v208, v208, v144, v202
	v_fma_f32 v209, v209, v144, v203
	v_cvt_pk_bf16_f32 v210, v208, v209
	v_lshlrev_b32_e32 v10, 16, v210
	v_and_b32_e32 v11, 0xffff0000, v210
	v_lshlrev_b32_e32 v208, 16, v134
	v_and_b32_e32 v209, 0xffff0000, v134
	v_fma_f32 v208, v208, v144, v204
	v_fma_f32 v209, v209, v144, v205
	v_cvt_pk_bf16_f32 v210, v208, v209
	v_lshlrev_b32_e32 v12, 16, v210
	v_and_b32_e32 v13, 0xffff0000, v210
	v_lshlrev_b32_e32 v208, 16, v135
	v_and_b32_e32 v209, 0xffff0000, v135
	v_fma_f32 v208, v208, v144, v206
	v_fma_f32 v209, v209, v144, v207
	v_cvt_pk_bf16_f32 v210, v208, v209
	v_lshlrev_b32_e32 v14, 16, v210
	v_and_b32_e32 v15, 0xffff0000, v210
	v_lshlrev_b32_e32 v208, 16, v136
	v_and_b32_e32 v209, 0xffff0000, v136
	v_fma_f32 v208, v208, v160, v192
	v_fma_f32 v209, v209, v160, v193
	v_cvt_pk_bf16_f32 v210, v208, v209
	v_lshlrev_b32_e32 v16, 16, v210
	v_and_b32_e32 v17, 0xffff0000, v210
	v_lshlrev_b32_e32 v208, 16, v137
	v_and_b32_e32 v209, 0xffff0000, v137
	v_fma_f32 v208, v208, v160, v194
	v_fma_f32 v209, v209, v160, v195
	v_cvt_pk_bf16_f32 v210, v208, v209
	v_lshlrev_b32_e32 v18, 16, v210
	v_and_b32_e32 v19, 0xffff0000, v210
	v_lshlrev_b32_e32 v208, 16, v138
	v_and_b32_e32 v209, 0xffff0000, v138
	v_fma_f32 v208, v208, v160, v196
	v_fma_f32 v209, v209, v160, v197
	v_cvt_pk_bf16_f32 v210, v208, v209
	v_lshlrev_b32_e32 v20, 16, v210
	v_and_b32_e32 v21, 0xffff0000, v210
	v_lshlrev_b32_e32 v208, 16, v139
	v_and_b32_e32 v209, 0xffff0000, v139
	v_fma_f32 v208, v208, v160, v198
	v_fma_f32 v209, v209, v160, v199
	v_cvt_pk_bf16_f32 v210, v208, v209
	v_lshlrev_b32_e32 v22, 16, v210
	v_and_b32_e32 v23, 0xffff0000, v210
	v_lshlrev_b32_e32 v208, 16, v140
	v_and_b32_e32 v209, 0xffff0000, v140
	v_fma_f32 v208, v208, v160, v200
	v_fma_f32 v209, v209, v160, v201
	v_cvt_pk_bf16_f32 v210, v208, v209
	v_lshlrev_b32_e32 v24, 16, v210
	v_and_b32_e32 v25, 0xffff0000, v210
	v_lshlrev_b32_e32 v208, 16, v141
	v_and_b32_e32 v209, 0xffff0000, v141
	v_fma_f32 v208, v208, v160, v202
	v_fma_f32 v209, v209, v160, v203
	v_cvt_pk_bf16_f32 v210, v208, v209
	v_lshlrev_b32_e32 v26, 16, v210
	v_and_b32_e32 v27, 0xffff0000, v210
	v_lshlrev_b32_e32 v208, 16, v142
	v_and_b32_e32 v209, 0xffff0000, v142
	v_fma_f32 v208, v208, v160, v204
	v_fma_f32 v209, v209, v160, v205
	v_cvt_pk_bf16_f32 v210, v208, v209
	v_lshlrev_b32_e32 v28, 16, v210
	v_and_b32_e32 v29, 0xffff0000, v210
	v_lshlrev_b32_e32 v208, 16, v143
	v_and_b32_e32 v209, 0xffff0000, v143
	v_fma_f32 v208, v208, v160, v206
	v_fma_f32 v209, v209, v160, v207
	v_cvt_pk_bf16_f32 v210, v208, v209
	v_lshlrev_b32_e32 v30, 16, v210
	v_and_b32_e32 v31, 0xffff0000, v210
	s_add_i32 s0, s77, 2
	s_lshl_b32 s1, s0, 11
	s_add_u32 s78, s12, s1
	s_addc_u32 s79, s13, 0
	global_load_dwordx4 v[128:131], v245, s[78:79]
	global_load_dwordx4 v[132:135], v245, s[78:79] offset:16
	global_load_dwordx4 v[136:139], v245, s[78:79] offset:2048
	global_load_dwordx4 v[140:143], v245, s[78:79] offset:2064
	s_lshl_b32 s1, s0, 6
	s_add_u32 s78, s14, s1
	s_addc_u32 s79, s15, 0
	global_load_dwordx4 v[144:147], v244, s[78:79] offset:0
	global_load_dwordx4 v[148:151], v244, s[78:79] offset:16
	global_load_dwordx4 v[152:155], v244, s[78:79] offset:32
	global_load_dwordx4 v[156:159], v244, s[78:79] offset:48
	global_load_dwordx4 v[160:163], v244, s[78:79] offset:64
	global_load_dwordx4 v[164:167], v244, s[78:79] offset:80
	global_load_dwordx4 v[168:171], v244, s[78:79] offset:96
	global_load_dwordx4 v[172:175], v244, s[78:79] offset:112
	s_waitcnt vmcnt(0)
	v_pk_add_f32 v[144:145], v[144:145], v[148:149]
	v_pk_add_f32 v[146:147], v[146:147], v[150:151]
	v_pk_add_f32 v[152:153], v[152:153], v[156:157]
	v_pk_add_f32 v[154:155], v[154:155], v[158:159]
	v_pk_add_f32 v[144:145], v[144:145], v[152:153]
	v_pk_add_f32 v[146:147], v[146:147], v[154:155]
	v_add_f32_e32 v144, v144, v145
	v_add_f32_e32 v146, v146, v147
	v_add_f32_e32 v144, v144, v146
	v_fmamk_f32 v144, v144, 0x3a800000, v243
	v_rsq_f32_e32 v144, v144
	v_pk_add_f32 v[160:161], v[160:161], v[164:165]
	v_pk_add_f32 v[162:163], v[162:163], v[166:167]
	v_pk_add_f32 v[168:169], v[168:169], v[172:173]
	v_pk_add_f32 v[170:171], v[170:171], v[174:175]
	v_pk_add_f32 v[160:161], v[160:161], v[168:169]
	v_pk_add_f32 v[162:163], v[162:163], v[170:171]
	v_add_f32_e32 v160, v160, v161
	v_add_f32_e32 v162, v162, v163
	v_add_f32_e32 v160, v160, v162
	v_fmamk_f32 v160, v160, 0x3a800000, v243
	v_rsq_f32_e32 v160, v160
	v_lshlrev_b32_e32 v208, 16, v128
	v_and_b32_e32 v209, 0xffff0000, v128
	v_fma_f32 v208, v208, v144, v192
	v_fma_f32 v209, v209, v144, v193
	v_cvt_pk_bf16_f32 v210, v208, v209
	v_lshlrev_b32_e32 v32, 16, v210
	v_and_b32_e32 v33, 0xffff0000, v210
	v_lshlrev_b32_e32 v208, 16, v129
	v_and_b32_e32 v209, 0xffff0000, v129
	v_fma_f32 v208, v208, v144, v194
	v_fma_f32 v209, v209, v144, v195
	v_cvt_pk_bf16_f32 v210, v208, v209
	v_lshlrev_b32_e32 v34, 16, v210
	v_and_b32_e32 v35, 0xffff0000, v210
	v_lshlrev_b32_e32 v208, 16, v130
	v_and_b32_e32 v209, 0xffff0000, v130
	v_fma_f32 v208, v208, v144, v196
; __device__ __forceinline__ unsigned pk2(float lo, float hi) { const f32x2 v = {lo, hi}; const bf16x2_t b = __builtin_convertvector(v, bf16x2_t); return __builtin_bit_cast(unsigned, b); }
; __device__ __forceinline__ float bflo(unsigned u) { return __uint_as_float(u << 16); }
; __device__ __forceinline__ float bfhi(unsigned u) { return __uint_as_float(u & 0xffff0000u); }
; __device__ __forceinline__ void peer_tile(const Args& A, LAS unsigned char* lds, int tile) {
;     ...
;         for (int tk = 0; tk < 4; ++tk) { const size_t m = (size_t)tile * 64 + tb + tk;
;             { const u32x4 ra = *(const u32x4*)(A3 + m * 1024 + 16 * lane), rb = *(const u32x4*)(A3 + m * 1024 + 16 * lane + 8);
;               float xr_; { const f32x4 p0 = *(const f32x4*)(RSq + m * 16), p1 = *(const f32x4*)(RSq + m * 16 + 4), p2 = *(const f32x4*)(RSq + m * 16 + 8), p3 = *(const f32x4*)(RSq + m * 16 + 12);
;                 const f32x4 ps = (p0 + p1) + (p2 + p3); xr_ = rsqrtf(((ps[0] + ps[1]) + (ps[2] + ps[3])) * (1.f / 1024.f) + 1e-6f); }
;               const unsigned rr[8] = {ra.x, ra.y, ra.z, ra.w, rb.x, rb.y, rb.z, rb.w}; unsigned hh[8];
;               const float* sp = MOD + (int)(m >> 11) * 6144 + 3072 + 16 * lane;
; #pragma unroll
;               for (int q = 0; q < 8; ++q) { const f32x2 sh = *(const f32x2*)(sp + 2 * q); hh[q] = pk2(bflo(rr[q]) * xr_ + sh[0], bfhi(rr[q]) * xr_ + sh[1]); }
;               xpa[tk] = (u32x4){hh[0], hh[1], hh[2], hh[3]}; xpb[tk] = (u32x4){hh[4], hh[5], hh[6], hh[7]}; }
; #pragma unroll
;             for (int q = 0; q < 8; ++q) oacc[tk][q] = (f32x2){0.f, 0.f}; }
;     ...
;                 { const unsigned xx[8] = {xpa[tk].x, xpa[tk].y, xpa[tk].z, xpa[tk].w, xpb[tk].x, xpb[tk].y, xpb[tk].z, xpb[tk].w};
; #pragma unroll
;                   for (int q = 0; q < 8; ++q) xf[q] = (f32x2){bflo(xx[q]), bfhi(xx[q])}; }
	v_fma_f32 v209, v209, v144, v197
	v_cvt_pk_bf16_f32 v210, v208, v209
	v_lshlrev_b32_e32 v36, 16, v210
	v_and_b32_e32 v37, 0xffff0000, v210
	v_lshlrev_b32_e32 v208, 16, v131
	v_and_b32_e32 v209, 0xffff0000, v131
	v_fma_f32 v208, v208, v144, v198
	v_fma_f32 v209, v209, v144, v199
	v_cvt_pk_bf16_f32 v210, v208, v209
	v_lshlrev_b32_e32 v38, 16, v210
	v_and_b32_e32 v39, 0xffff0000, v210
	v_lshlrev_b32_e32 v208, 16, v132
	v_and_b32_e32 v209, 0xffff0000, v132
	v_fma_f32 v208, v208, v144, v200
	v_fma_f32 v209, v209, v144, v201
	v_cvt_pk_bf16_f32 v210, v208, v209
	v_lshlrev_b32_e32 v40, 16, v210
	v_and_b32_e32 v41, 0xffff0000, v210
	v_lshlrev_b32_e32 v208, 16, v133
	v_and_b32_e32 v209, 0xffff0000, v133
	v_fma_f32 v208, v208, v144, v202
	v_fma_f32 v209, v209, v144, v203
	v_cvt_pk_bf16_f32 v210, v208, v209
	v_lshlrev_b32_e32 v42, 16, v210
	v_and_b32_e32 v43, 0xffff0000, v210
	v_lshlrev_b32_e32 v208, 16, v134
	v_and_b32_e32 v209, 0xffff0000, v134
	v_fma_f32 v208, v208, v144, v204
	v_fma_f32 v209, v209, v144, v205
	v_cvt_pk_bf16_f32 v210, v208, v209
	v_lshlrev_b32_e32 v44, 16, v210
	v_and_b32_e32 v45, 0xffff0000, v210
	v_lshlrev_b32_e32 v208, 16, v135
	v_and_b32_e32 v209, 0xffff0000, v135
	v_fma_f32 v208, v208, v144, v206
	v_fma_f32 v209, v209, v144, v207
	v_cvt_pk_bf16_f32 v210, v208, v209
	v_lshlrev_b32_e32 v46, 16, v210
	v_and_b32_e32 v47, 0xffff0000, v210
	v_lshlrev_b32_e32 v208, 16, v136
	v_and_b32_e32 v209, 0xffff0000, v136
	v_fma_f32 v208, v208, v160, v192
	v_fma_f32 v209, v209, v160, v193
	v_cvt_pk_bf16_f32 v210, v208, v209
	v_lshlrev_b32_e32 v48, 16, v210
	v_and_b32_e32 v49, 0xffff0000, v210
	v_lshlrev_b32_e32 v208, 16, v137
	v_and_b32_e32 v209, 0xffff0000, v137
	v_fma_f32 v208, v208, v160, v194
	v_fma_f32 v209, v209, v160, v195
	v_cvt_pk_bf16_f32 v210, v208, v209
	v_lshlrev_b32_e32 v50, 16, v210
	v_and_b32_e32 v51, 0xffff0000, v210
	v_lshlrev_b32_e32 v208, 16, v138
	v_and_b32_e32 v209, 0xffff0000, v138
	v_fma_f32 v208, v208, v160, v196
	v_fma_f32 v209, v209, v160, v197
	v_cvt_pk_bf16_f32 v210, v208, v209
	v_lshlrev_b32_e32 v52, 16, v210
	v_and_b32_e32 v53, 0xffff0000, v210
	v_lshlrev_b32_e32 v208, 16, v139
	v_and_b32_e32 v209, 0xffff0000, v139
	v_fma_f32 v208, v208, v160, v198
	v_fma_f32 v209, v209, v160, v199
	v_cvt_pk_bf16_f32 v210, v208, v209
	v_lshlrev_b32_e32 v54, 16, v210
	v_and_b32_e32 v55, 0xffff0000, v210
	v_lshlrev_b32_e32 v208, 16, v140
	v_and_b32_e32 v209, 0xffff0000, v140
	v_fma_f32 v208, v208, v160, v200
	v_fma_f32 v209, v209, v160, v201
	v_cvt_pk_bf16_f32 v210, v208, v209
	v_lshlrev_b32_e32 v56, 16, v210
	v_and_b32_e32 v57, 0xffff0000, v210
	v_lshlrev_b32_e32 v208, 16, v141
	v_and_b32_e32 v209, 0xffff0000, v141
	v_fma_f32 v208, v208, v160, v202
	v_fma_f32 v209, v209, v160, v203
	v_cvt_pk_bf16_f32 v210, v208, v209
	v_lshlrev_b32_e32 v58, 16, v210
	v_and_b32_e32 v59, 0xffff0000, v210
	v_lshlrev_b32_e32 v208, 16, v142
	v_and_b32_e32 v209, 0xffff0000, v142
	v_fma_f32 v208, v208, v160, v204
	v_fma_f32 v209, v209, v160, v205
	v_cvt_pk_bf16_f32 v210, v208, v209
	v_lshlrev_b32_e32 v60, 16, v210
	v_and_b32_e32 v61, 0xffff0000, v210
	v_lshlrev_b32_e32 v208, 16, v143
	v_and_b32_e32 v209, 0xffff0000, v143
	v_fma_f32 v208, v208, v160, v206
	v_fma_f32 v209, v209, v160, v207
	v_cvt_pk_bf16_f32 v210, v208, v209
	v_lshlrev_b32_e32 v62, 16, v210
	v_and_b32_e32 v63, 0xffff0000, v210
	s_add_i32 s0, s77, 4
	s_lshl_b32 s1, s0, 11
	s_add_u32 s78, s12, s1
	s_addc_u32 s79, s13, 0
	global_load_dwordx4 v[128:131], v245, s[78:79]
	global_load_dwordx4 v[132:135], v245, s[78:79] offset:16
	global_load_dwordx4 v[136:139], v245, s[78:79] offset:2048
	global_load_dwordx4 v[140:143], v245, s[78:79] offset:2064
	s_lshl_b32 s1, s0, 6
	s_add_u32 s78, s14, s1
	s_addc_u32 s79, s15, 0
	global_load_dwordx4 v[144:147], v244, s[78:79] offset:0
	global_load_dwordx4 v[148:151], v244, s[78:79] offset:16
	global_load_dwordx4 v[152:155], v244, s[78:79] offset:32
	global_load_dwordx4 v[156:159], v244, s[78:79] offset:48
	global_load_dwordx4 v[160:163], v244, s[78:79] offset:64
	global_load_dwordx4 v[164:167], v244, s[78:79] offset:80
	global_load_dwordx4 v[168:171], v244, s[78:79] offset:96
	global_load_dwordx4 v[172:175], v244, s[78:79] offset:112
	s_waitcnt vmcnt(0)
	v_pk_add_f32 v[144:145], v[144:145], v[148:149]
	v_pk_add_f32 v[146:147], v[146:147], v[150:151]
	v_pk_add_f32 v[152:153], v[152:153], v[156:157]
	v_pk_add_f32 v[154:155], v[154:155], v[158:159]
	v_pk_add_f32 v[144:145], v[144:145], v[152:153]
	v_pk_add_f32 v[146:147], v[146:147], v[154:155]
	v_add_f32_e32 v144, v144, v145
	v_add_f32_e32 v146, v146, v147
	v_add_f32_e32 v144, v144, v146
	v_fmamk_f32 v144, v144, 0x3a800000, v243
	v_rsq_f32_e32 v144, v144
	v_pk_add_f32 v[160:161], v[160:161], v[164:165]
	v_pk_add_f32 v[162:163], v[162:163], v[166:167]
	v_pk_add_f32 v[168:169], v[168:169], v[172:173]
	v_pk_add_f32 v[170:171], v[170:171], v[174:175]
	v_pk_add_f32 v[160:161], v[160:161], v[168:169]
	v_pk_add_f32 v[162:163], v[162:163], v[170:171]
	v_add_f32_e32 v160, v160, v161
	v_add_f32_e32 v162, v162, v163
	v_add_f32_e32 v160, v160, v162
	v_fmamk_f32 v160, v160, 0x3a800000, v243
	v_rsq_f32_e32 v160, v160
	v_lshlrev_b32_e32 v208, 16, v128
	v_and_b32_e32 v209, 0xffff0000, v128
	v_fma_f32 v208, v208, v144, v192
	v_fma_f32 v209, v209, v144, v193
	v_cvt_pk_bf16_f32 v210, v208, v209
	v_lshlrev_b32_e32 v64, 16, v210
	v_and_b32_e32 v65, 0xffff0000, v210
	v_lshlrev_b32_e32 v208, 16, v129
	v_and_b32_e32 v209, 0xffff0000, v129
	v_fma_f32 v208, v208, v144, v194
	v_fma_f32 v209, v209, v144, v195
	v_cvt_pk_bf16_f32 v210, v208, v209
	v_lshlrev_b32_e32 v66, 16, v210
	v_and_b32_e32 v67, 0xffff0000, v210
	v_lshlrev_b32_e32 v208, 16, v130
; __device__ __forceinline__ unsigned pk2(float lo, float hi) { const f32x2 v = {lo, hi}; const bf16x2_t b = __builtin_convertvector(v, bf16x2_t); return __builtin_bit_cast(unsigned, b); }
; __device__ __forceinline__ float bflo(unsigned u) { return __uint_as_float(u << 16); }
; __device__ __forceinline__ float bfhi(unsigned u) { return __uint_as_float(u & 0xffff0000u); }
; __device__ __forceinline__ void peer_tile(const Args& A, LAS unsigned char* lds, int tile) {
;     ...
;         for (int tk = 0; tk < 4; ++tk) { const size_t m = (size_t)tile * 64 + tb + tk;
;             { const u32x4 ra = *(const u32x4*)(A3 + m * 1024 + 16 * lane), rb = *(const u32x4*)(A3 + m * 1024 + 16 * lane + 8);
;               float xr_; { const f32x4 p0 = *(const f32x4*)(RSq + m * 16), p1 = *(const f32x4*)(RSq + m * 16 + 4), p2 = *(const f32x4*)(RSq + m * 16 + 8), p3 = *(const f32x4*)(RSq + m * 16 + 12);
;                 const f32x4 ps = (p0 + p1) + (p2 + p3); xr_ = rsqrtf(((ps[0] + ps[1]) + (ps[2] + ps[3])) * (1.f / 1024.f) + 1e-6f); }
;               const unsigned rr[8] = {ra.x, ra.y, ra.z, ra.w, rb.x, rb.y, rb.z, rb.w}; unsigned hh[8];
;               const float* sp = MOD + (int)(m >> 11) * 6144 + 3072 + 16 * lane;
; #pragma unroll
;               for (int q = 0; q < 8; ++q) { const f32x2 sh = *(const f32x2*)(sp + 2 * q); hh[q] = pk2(bflo(rr[q]) * xr_ + sh[0], bfhi(rr[q]) * xr_ + sh[1]); }
;               xpa[tk] = (u32x4){hh[0], hh[1], hh[2], hh[3]}; xpb[tk] = (u32x4){hh[4], hh[5], hh[6], hh[7]}; }
; #pragma unroll
;             for (int q = 0; q < 8; ++q) oacc[tk][q] = (f32x2){0.f, 0.f}; }
;     ...
;                 { const unsigned xx[8] = {xpa[tk].x, xpa[tk].y, xpa[tk].z, xpa[tk].w, xpb[tk].x, xpb[tk].y, xpb[tk].z, xpb[tk].w};
; #pragma unroll
;                   for (int q = 0; q < 8; ++q) xf[q] = (f32x2){bflo(xx[q]), bfhi(xx[q])}; }
	v_and_b32_e32 v209, 0xffff0000, v130
	v_fma_f32 v208, v208, v144, v196
	v_fma_f32 v209, v209, v144, v197
	v_cvt_pk_bf16_f32 v210, v208, v209
	v_lshlrev_b32_e32 v68, 16, v210
	v_and_b32_e32 v69, 0xffff0000, v210
	v_lshlrev_b32_e32 v208, 16, v131
	v_and_b32_e32 v209, 0xffff0000, v131
	v_fma_f32 v208, v208, v144, v198
	v_fma_f32 v209, v209, v144, v199
	v_cvt_pk_bf16_f32 v210, v208, v209
	v_lshlrev_b32_e32 v70, 16, v210
	v_and_b32_e32 v71, 0xffff0000, v210
	v_lshlrev_b32_e32 v208, 16, v132
	v_and_b32_e32 v209, 0xffff0000, v132
	v_fma_f32 v208, v208, v144, v200
	v_fma_f32 v209, v209, v144, v201
	v_cvt_pk_bf16_f32 v210, v208, v209
	v_lshlrev_b32_e32 v72, 16, v210
	v_and_b32_e32 v73, 0xffff0000, v210
	v_lshlrev_b32_e32 v208, 16, v133
	v_and_b32_e32 v209, 0xffff0000, v133
	v_fma_f32 v208, v208, v144, v202
	v_fma_f32 v209, v209, v144, v203
	v_cvt_pk_bf16_f32 v210, v208, v209
	v_lshlrev_b32_e32 v74, 16, v210
	v_and_b32_e32 v75, 0xffff0000, v210
	v_lshlrev_b32_e32 v208, 16, v134
	v_and_b32_e32 v209, 0xffff0000, v134
	v_fma_f32 v208, v208, v144, v204
	v_fma_f32 v209, v209, v144, v205
	v_cvt_pk_bf16_f32 v210, v208, v209
	v_lshlrev_b32_e32 v76, 16, v210
	v_and_b32_e32 v77, 0xffff0000, v210
	v_lshlrev_b32_e32 v208, 16, v135
	v_and_b32_e32 v209, 0xffff0000, v135
	v_fma_f32 v208, v208, v144, v206
	v_fma_f32 v209, v209, v144, v207
	v_cvt_pk_bf16_f32 v210, v208, v209
	v_lshlrev_b32_e32 v78, 16, v210
	v_and_b32_e32 v79, 0xffff0000, v210
	v_lshlrev_b32_e32 v208, 16, v136
	v_and_b32_e32 v209, 0xffff0000, v136
	v_fma_f32 v208, v208, v160, v192
	v_fma_f32 v209, v209, v160, v193
	v_cvt_pk_bf16_f32 v210, v208, v209
	v_lshlrev_b32_e32 v80, 16, v210
	v_and_b32_e32 v81, 0xffff0000, v210
	v_lshlrev_b32_e32 v208, 16, v137
	v_and_b32_e32 v209, 0xffff0000, v137
	v_fma_f32 v208, v208, v160, v194
	v_fma_f32 v209, v209, v160, v195
	v_cvt_pk_bf16_f32 v210, v208, v209
	v_lshlrev_b32_e32 v82, 16, v210
	v_and_b32_e32 v83, 0xffff0000, v210
	v_lshlrev_b32_e32 v208, 16, v138
	v_and_b32_e32 v209, 0xffff0000, v138
	v_fma_f32 v208, v208, v160, v196
	v_fma_f32 v209, v209, v160, v197
	v_cvt_pk_bf16_f32 v210, v208, v209
	v_lshlrev_b32_e32 v84, 16, v210
	v_and_b32_e32 v85, 0xffff0000, v210
	v_lshlrev_b32_e32 v208, 16, v139
	v_and_b32_e32 v209, 0xffff0000, v139
	v_fma_f32 v208, v208, v160, v198
	v_fma_f32 v209, v209, v160, v199
	v_cvt_pk_bf16_f32 v210, v208, v209
	v_lshlrev_b32_e32 v86, 16, v210
	v_and_b32_e32 v87, 0xffff0000, v210
	v_lshlrev_b32_e32 v208, 16, v140
	v_and_b32_e32 v209, 0xffff0000, v140
	v_fma_f32 v208, v208, v160, v200
	v_fma_f32 v209, v209, v160, v201
	v_cvt_pk_bf16_f32 v210, v208, v209
	v_lshlrev_b32_e32 v88, 16, v210
	v_and_b32_e32 v89, 0xffff0000, v210
	v_lshlrev_b32_e32 v208, 16, v141
	v_and_b32_e32 v209, 0xffff0000, v141
	v_fma_f32 v208, v208, v160, v202
	v_fma_f32 v209, v209, v160, v203
	v_cvt_pk_bf16_f32 v210, v208, v209
	v_lshlrev_b32_e32 v90, 16, v210
	v_and_b32_e32 v91, 0xffff0000, v210
	v_lshlrev_b32_e32 v208, 16, v142
	v_and_b32_e32 v209, 0xffff0000, v142
	v_fma_f32 v208, v208, v160, v204
	v_fma_f32 v209, v209, v160, v205
	v_cvt_pk_bf16_f32 v210, v208, v209
	v_lshlrev_b32_e32 v92, 16, v210
	v_and_b32_e32 v93, 0xffff0000, v210
	v_lshlrev_b32_e32 v208, 16, v143
	v_and_b32_e32 v209, 0xffff0000, v143
	v_fma_f32 v208, v208, v160, v206
	v_fma_f32 v209, v209, v160, v207
	v_cvt_pk_bf16_f32 v210, v208, v209
	v_lshlrev_b32_e32 v94, 16, v210
	v_and_b32_e32 v95, 0xffff0000, v210
	s_add_i32 s0, s77, 6
	s_lshl_b32 s1, s0, 11
	s_add_u32 s78, s12, s1
	s_addc_u32 s79, s13, 0
	global_load_dwordx4 v[128:131], v245, s[78:79]
	global_load_dwordx4 v[132:135], v245, s[78:79] offset:16
	global_load_dwordx4 v[136:139], v245, s[78:79] offset:2048
	global_load_dwordx4 v[140:143], v245, s[78:79] offset:2064
	s_lshl_b32 s1, s0, 6
	s_add_u32 s78, s14, s1
	s_addc_u32 s79, s15, 0
	global_load_dwordx4 v[144:147], v244, s[78:79] offset:0
	global_load_dwordx4 v[148:151], v244, s[78:79] offset:16
	global_load_dwordx4 v[152:155], v244, s[78:79] offset:32
	global_load_dwordx4 v[156:159], v244, s[78:79] offset:48
	global_load_dwordx4 v[160:163], v244, s[78:79] offset:64
	global_load_dwordx4 v[164:167], v244, s[78:79] offset:80
	global_load_dwordx4 v[168:171], v244, s[78:79] offset:96
	global_load_dwordx4 v[172:175], v244, s[78:79] offset:112
	s_waitcnt vmcnt(0)
; __device__ __forceinline__ unsigned pk2(float lo, float hi) { const f32x2 v = {lo, hi}; const bf16x2_t b = __builtin_convertvector(v, bf16x2_t); return __builtin_bit_cast(unsigned, b); }
; __device__ __forceinline__ float bflo(unsigned u) { return __uint_as_float(u << 16); }
; __device__ __forceinline__ void peer_tile(const Args& A, LAS unsigned char* lds, int tile) {
;     ...
;     for (int ti = 0; ti < 8; ++ti) {
;         const int tl = 8 * w + ti;
;         const u32x2 e0 = SEL[tl * 128 + lane], e1 = SEL[tl * 128 + 64 + lane];
;         const int p0 = (int)(e0.x >> 10), p1 = (int)(e1.x >> 10);
;         int off = 0;
;         for (int p = 0; p < 16; ++p) {
;             const unsigned long long m0 = __ballot(p0 == p), m1 = __ballot(p1 == p);
;             const int c0 = __popcll(m0), c1 = __popcll(m1);
;             const int r0 = __builtin_amdgcn_mbcnt_hi((unsigned)(m0 >> 32), __builtin_amdgcn_mbcnt_lo((unsigned)m0, 0u));
;             const int r1 = __builtin_amdgcn_mbcnt_hi((unsigned)(m1 >> 32), __builtin_amdgcn_mbcnt_lo((unsigned)m1, 0u));
;             if (p0 == p) SORT[tl * 128 + off + r0] = e0;
;             if (p1 == p) SORT[tl * 128 + off + c0 + r1] = e1;
;             if (lane == 0) OFFS[tl * 17 + p] = off;
;             off += c0 + c1;
;         }
;         if (lane == 0) OFFS[tl * 17 + 16] = off;
;     }
;     ...
;         for (int tk = 0; tk < 4; ++tk) { const size_t m = (size_t)tile * 64 + tb + tk;
;             { const u32x4 ra = *(const u32x4*)(A3 + m * 1024 + 16 * lane), rb = *(const u32x4*)(A3 + m * 1024 + 16 * lane + 8);
;               float xr_; { const f32x4 p0 = *(const f32x4*)(RSq + m * 16), p1 = *(const f32x4*)(RSq + m * 16 + 4), p2 = *(const f32x4*)(RSq + m * 16 + 8), p3 = *(const f32x4*)(RSq + m * 16 + 12);
;                 const f32x4 ps = (p0 + p1) + (p2 + p3); xr_ = rsqrtf(((ps[0] + ps[1]) + (ps[2] + ps[3])) * (1.f / 1024.f) + 1e-6f); }
;               const unsigned rr[8] = {ra.x, ra.y, ra.z, ra.w, rb.x, rb.y, rb.z, rb.w}; unsigned hh[8];
;               const float* sp = MOD + (int)(m >> 11) * 6144 + 3072 + 16 * lane;
; #pragma unroll
;               for (int q = 0; q < 8; ++q) { const f32x2 sh = *(const f32x2*)(sp + 2 * q); hh[q] = pk2(bflo(rr[q]) * xr_ + sh[0], bfhi(rr[q]) * xr_ + sh[1]); }
;               xpa[tk] = (u32x4){hh[0], hh[1], hh[2], hh[3]}; xpb[tk] = (u32x4){hh[4], hh[5], hh[6], hh[7]}; }
	v_pk_add_f32 v[144:145], v[144:145], v[148:149]
	v_pk_add_f32 v[146:147], v[146:147], v[150:151]
	v_pk_add_f32 v[152:153], v[152:153], v[156:157]
	v_pk_add_f32 v[154:155], v[154:155], v[158:159]
	v_pk_add_f32 v[144:145], v[144:145], v[152:153]
	v_pk_add_f32 v[146:147], v[146:147], v[154:155]
	v_add_f32_e32 v144, v144, v145
	v_add_f32_e32 v146, v146, v147
	v_add_f32_e32 v144, v144, v146
	v_fmamk_f32 v144, v144, 0x3a800000, v243
	v_rsq_f32_e32 v144, v144
	v_pk_add_f32 v[160:161], v[160:161], v[164:165]
	v_pk_add_f32 v[162:163], v[162:163], v[166:167]
	v_pk_add_f32 v[168:169], v[168:169], v[172:173]
	v_pk_add_f32 v[170:171], v[170:171], v[174:175]
	v_pk_add_f32 v[160:161], v[160:161], v[168:169]
	v_pk_add_f32 v[162:163], v[162:163], v[170:171]
	v_add_f32_e32 v160, v160, v161
	v_add_f32_e32 v162, v162, v163
	v_add_f32_e32 v160, v160, v162
	v_fmamk_f32 v160, v160, 0x3a800000, v243
	v_rsq_f32_e32 v160, v160
	v_lshlrev_b32_e32 v208, 16, v128
	v_and_b32_e32 v209, 0xffff0000, v128
	v_fma_f32 v208, v208, v144, v192
	v_fma_f32 v209, v209, v144, v193
	v_cvt_pk_bf16_f32 v210, v208, v209
	v_lshlrev_b32_e32 v96, 16, v210
	v_and_b32_e32 v97, 0xffff0000, v210
	v_lshlrev_b32_e32 v208, 16, v129
	v_and_b32_e32 v209, 0xffff0000, v129
	v_fma_f32 v208, v208, v144, v194
	v_fma_f32 v209, v209, v144, v195
	v_cvt_pk_bf16_f32 v210, v208, v209
	v_lshlrev_b32_e32 v98, 16, v210
	v_and_b32_e32 v99, 0xffff0000, v210
	v_lshlrev_b32_e32 v208, 16, v130
	v_and_b32_e32 v209, 0xffff0000, v130
	v_fma_f32 v208, v208, v144, v196
	v_fma_f32 v209, v209, v144, v197
	v_cvt_pk_bf16_f32 v210, v208, v209
	v_lshlrev_b32_e32 v100, 16, v210
	v_and_b32_e32 v101, 0xffff0000, v210
	v_lshlrev_b32_e32 v208, 16, v131
	v_and_b32_e32 v209, 0xffff0000, v131
	v_fma_f32 v208, v208, v144, v198
	v_fma_f32 v209, v209, v144, v199
	v_cvt_pk_bf16_f32 v210, v208, v209
	v_lshlrev_b32_e32 v102, 16, v210
	v_and_b32_e32 v103, 0xffff0000, v210
	v_lshlrev_b32_e32 v208, 16, v132
	v_and_b32_e32 v209, 0xffff0000, v132
	v_fma_f32 v208, v208, v144, v200
	v_fma_f32 v209, v209, v144, v201
	v_cvt_pk_bf16_f32 v210, v208, v209
	v_lshlrev_b32_e32 v104, 16, v210
	v_and_b32_e32 v105, 0xffff0000, v210
	v_lshlrev_b32_e32 v208, 16, v133
	v_and_b32_e32 v209, 0xffff0000, v133
	v_fma_f32 v208, v208, v144, v202
	v_fma_f32 v209, v209, v144, v203
	v_cvt_pk_bf16_f32 v210, v208, v209
	v_lshlrev_b32_e32 v106, 16, v210
	v_and_b32_e32 v107, 0xffff0000, v210
	v_lshlrev_b32_e32 v208, 16, v134
	v_and_b32_e32 v209, 0xffff0000, v134
	v_fma_f32 v208, v208, v144, v204
	v_fma_f32 v209, v209, v144, v205
	v_cvt_pk_bf16_f32 v210, v208, v209
	v_lshlrev_b32_e32 v108, 16, v210
	v_and_b32_e32 v109, 0xffff0000, v210
	v_lshlrev_b32_e32 v208, 16, v135
	v_and_b32_e32 v209, 0xffff0000, v135
	v_fma_f32 v208, v208, v144, v206
	v_fma_f32 v209, v209, v144, v207
	v_cvt_pk_bf16_f32 v210, v208, v209
	v_lshlrev_b32_e32 v110, 16, v210
	v_and_b32_e32 v111, 0xffff0000, v210
	v_lshlrev_b32_e32 v208, 16, v136
	v_and_b32_e32 v209, 0xffff0000, v136
	v_fma_f32 v208, v208, v160, v192
	v_fma_f32 v209, v209, v160, v193
	v_cvt_pk_bf16_f32 v210, v208, v209
	v_lshlrev_b32_e32 v112, 16, v210
	v_and_b32_e32 v113, 0xffff0000, v210
	v_lshlrev_b32_e32 v208, 16, v137
	v_and_b32_e32 v209, 0xffff0000, v137
	v_fma_f32 v208, v208, v160, v194
	v_fma_f32 v209, v209, v160, v195
	v_cvt_pk_bf16_f32 v210, v208, v209
	v_lshlrev_b32_e32 v114, 16, v210
	v_and_b32_e32 v115, 0xffff0000, v210
	v_lshlrev_b32_e32 v208, 16, v138
	v_and_b32_e32 v209, 0xffff0000, v138
	v_fma_f32 v208, v208, v160, v196
	v_fma_f32 v209, v209, v160, v197
	v_cvt_pk_bf16_f32 v210, v208, v209
	v_lshlrev_b32_e32 v116, 16, v210
	v_and_b32_e32 v117, 0xffff0000, v210
	v_lshlrev_b32_e32 v208, 16, v139
	v_and_b32_e32 v209, 0xffff0000, v139
	v_fma_f32 v208, v208, v160, v198
	v_fma_f32 v209, v209, v160, v199
	v_cvt_pk_bf16_f32 v210, v208, v209
	v_lshlrev_b32_e32 v118, 16, v210
	v_and_b32_e32 v119, 0xffff0000, v210
	v_lshlrev_b32_e32 v208, 16, v140
	v_and_b32_e32 v209, 0xffff0000, v140
	v_fma_f32 v208, v208, v160, v200
	v_fma_f32 v209, v209, v160, v201
	v_cvt_pk_bf16_f32 v210, v208, v209
	v_lshlrev_b32_e32 v120, 16, v210
	v_and_b32_e32 v121, 0xffff0000, v210
	v_lshlrev_b32_e32 v208, 16, v141
	v_and_b32_e32 v209, 0xffff0000, v141
	v_fma_f32 v208, v208, v160, v202
	v_fma_f32 v209, v209, v160, v203
	v_cvt_pk_bf16_f32 v210, v208, v209
	v_lshlrev_b32_e32 v122, 16, v210
	v_and_b32_e32 v123, 0xffff0000, v210
	v_lshlrev_b32_e32 v208, 16, v142
	v_and_b32_e32 v209, 0xffff0000, v142
	v_fma_f32 v208, v208, v160, v204
	v_fma_f32 v209, v209, v160, v205
	v_cvt_pk_bf16_f32 v210, v208, v209
	v_lshlrev_b32_e32 v124, 16, v210
	v_and_b32_e32 v125, 0xffff0000, v210
	v_lshlrev_b32_e32 v208, 16, v143
	v_and_b32_e32 v209, 0xffff0000, v143
	v_fma_f32 v208, v208, v160, v206
	v_fma_f32 v209, v209, v160, v207
	v_cvt_pk_bf16_f32 v210, v208, v209
	v_lshlrev_b32_e32 v126, 16, v210
	v_and_b32_e32 v127, 0xffff0000, v210
	v_mov_b32_e32 v216, 0
	v_mov_b32_e32 v217, 0
	v_mov_b32_e32 v218, 0
	v_mov_b32_e32 v219, 0
	v_add_u32_e32 v220, s22, v240
	ds_write_b128 v220, v[216:219] offset:0
	ds_write_b128 v220, v[216:219] offset:1024
	ds_write_b128 v220, v[216:219] offset:2048
	ds_write_b128 v220, v[216:219] offset:3072
	ds_write_b128 v220, v[216:219] offset:4096
	ds_write_b128 v220, v[216:219] offset:5120
	ds_write_b128 v220, v[216:219] offset:6144
	ds_write_b128 v220, v[216:219] offset:7168
	ds_write_b128 v220, v[216:219] offset:8192
	v_lshrrev_b32_e32 v222, 1, v240
	v_add_u32_e32 v220, s22, v222
	ds_write_b64 v220, v[216:217] offset:9216
	s_lshl_b32 s0, s76, 10
	s_add_i32 s0, s0, 0x11000
	v_add_u32_e32 v221, s0, v222
	ds_read_b64 v[128:129], v221 offset:0
	ds_read_b64 v[130:131], v221 offset:512
	ds_read_b64 v[132:133], v221 offset:1024
	ds_read_b64 v[134:135], v221 offset:1536
	ds_read_b64 v[136:137], v221 offset:2048
	ds_read_b64 v[138:139], v221 offset:2560
	ds_read_b64 v[140:141], v221 offset:3072
	ds_read_b64 v[142:143], v221 offset:3584
	ds_read_b64 v[144:145], v221 offset:4096
	ds_read_b64 v[146:147], v221 offset:4608
	ds_read_b64 v[148:149], v221 offset:5120
	ds_read_b64 v[150:151], v221 offset:5632
	ds_read_b64 v[152:153], v221 offset:6144
	ds_read_b64 v[154:155], v221 offset:6656
	ds_read_b64 v[156:157], v221 offset:7168
	ds_read_b64 v[158:159], v221 offset:7680
	s_waitcnt lgkmcnt(0)
; __device__ __forceinline__ void peer_tile(const Args& A, LAS unsigned char* lds, int tile) {
;     ...
;     for (int ti = 0; ti < 8; ++ti) {
;         const int tl = 8 * w + ti;
;         const u32x2 e0 = SEL[tl * 128 + lane], e1 = SEL[tl * 128 + 64 + lane];
;         const int p0 = (int)(e0.x >> 10), p1 = (int)(e1.x >> 10);
;         int off = 0;
;         for (int p = 0; p < 16; ++p) {
;             const unsigned long long m0 = __ballot(p0 == p), m1 = __ballot(p1 == p);
;             const int c0 = __popcll(m0), c1 = __popcll(m1);
;             const int r0 = __builtin_amdgcn_mbcnt_hi((unsigned)(m0 >> 32), __builtin_amdgcn_mbcnt_lo((unsigned)m0, 0u));
;             const int r1 = __builtin_amdgcn_mbcnt_hi((unsigned)(m1 >> 32), __builtin_amdgcn_mbcnt_lo((unsigned)m1, 0u));
;             if (p0 == p) SORT[tl * 128 + off + r0] = e0;
;             if (p1 == p) SORT[tl * 128 + off + c0 + r1] = e1;
;             if (lane == 0) OFFS[tl * 17 + p] = off;
;             off += c0 + c1;
;         }
;         if (lane == 0) OFFS[tl * 17 + 16] = off;
;     }
	v_lshrrev_b32_e32 v160, 12, v128
	v_lshl_or_b32 v128, v128, 10, 0
	v_lshrrev_b32_e32 v161, 12, v130
	v_lshl_or_b32 v130, v130, 10, 0
	v_lshrrev_b32_e32 v162, 12, v132
	v_lshl_or_b32 v132, v132, 10, 1
	v_lshrrev_b32_e32 v163, 12, v134
	v_lshl_or_b32 v134, v134, 10, 1
	v_lshrrev_b32_e32 v164, 12, v136
	v_lshl_or_b32 v136, v136, 10, 2
	v_lshrrev_b32_e32 v165, 12, v138
	v_lshl_or_b32 v138, v138, 10, 2
	v_lshrrev_b32_e32 v166, 12, v140
	v_lshl_or_b32 v140, v140, 10, 3
	v_lshrrev_b32_e32 v167, 12, v142
	v_lshl_or_b32 v142, v142, 10, 3
	v_lshrrev_b32_e32 v168, 12, v144
	v_lshl_or_b32 v144, v144, 10, 4
	v_lshrrev_b32_e32 v169, 12, v146
	v_lshl_or_b32 v146, v146, 10, 4
	v_lshrrev_b32_e32 v170, 12, v148
	v_lshl_or_b32 v148, v148, 10, 5
	v_lshrrev_b32_e32 v171, 12, v150
	v_lshl_or_b32 v150, v150, 10, 5
	v_lshrrev_b32_e32 v172, 12, v152
	v_lshl_or_b32 v152, v152, 10, 6
	v_lshrrev_b32_e32 v173, 12, v154
	v_lshl_or_b32 v154, v154, 10, 6
	v_lshrrev_b32_e32 v174, 12, v156
	v_lshl_or_b32 v156, v156, 10, 7
	v_lshrrev_b32_e32 v175, 12, v158
	v_lshl_or_b32 v158, v158, 10, 7
	s_mov_b32 s74, 0
	s_mov_b32 s75, 0
.Lbuild_c:
	v_cmp_eq_u32_e64 s[68:69], s74, v160
	v_cmp_eq_u32_e64 s[70:71], s74, v161
	s_nop 0
	s_lshl_b32 s3, s75, 5
	s_add_i32 s3, s3, s22
	s_bcnt1_i32_b64 s0, s[68:69]
	s_bcnt1_i32_b64 s1, s[70:71]
	v_mbcnt_lo_u32_b32 v222, s68, 0
	v_mbcnt_hi_u32_b32 v222, s69, v222
	v_mbcnt_lo_u32_b32 v223, s70, 0
	v_mbcnt_hi_u32_b32 v223, s71, v223
	v_add_u32_e32 v223, s0, v223
	v_lshl_add_u32 v222, v222, 3, s3
	v_lshl_add_u32 v223, v223, 3, s3
	s_mov_b64 exec, s[68:69]
	ds_write_b64 v222, v[128:129]
	s_mov_b64 exec, s[70:71]
	ds_write_b64 v223, v[130:131]
	s_mov_b64 exec, -1
	s_add_i32 s0, s0, s1
	s_add_i32 s0, s0, 3
	s_lshr_b32 s0, s0, 2
	s_add_i32 s75, s75, s0
	v_cmp_eq_u32_e64 s[68:69], s74, v162
	v_cmp_eq_u32_e64 s[70:71], s74, v163
	s_nop 0
	s_lshl_b32 s3, s75, 5
	s_add_i32 s3, s3, s22
	s_bcnt1_i32_b64 s0, s[68:69]
	s_bcnt1_i32_b64 s1, s[70:71]
	v_mbcnt_lo_u32_b32 v222, s68, 0
	v_mbcnt_hi_u32_b32 v222, s69, v222
	v_mbcnt_lo_u32_b32 v223, s70, 0
	v_mbcnt_hi_u32_b32 v223, s71, v223
	v_add_u32_e32 v223, s0, v223
	v_lshl_add_u32 v222, v222, 3, s3
	v_lshl_add_u32 v223, v223, 3, s3
	s_mov_b64 exec, s[68:69]
	ds_write_b64 v222, v[132:133]
	s_mov_b64 exec, s[70:71]
	ds_write_b64 v223, v[134:135]
	s_mov_b64 exec, -1
	s_add_i32 s0, s0, s1
	s_add_i32 s0, s0, 3
	s_lshr_b32 s0, s0, 2
	s_add_i32 s75, s75, s0
	v_cmp_eq_u32_e64 s[68:69], s74, v164
	v_cmp_eq_u32_e64 s[70:71], s74, v165
	s_nop 0
	s_lshl_b32 s3, s75, 5
	s_add_i32 s3, s3, s22
	s_bcnt1_i32_b64 s0, s[68:69]
	s_bcnt1_i32_b64 s1, s[70:71]
	v_mbcnt_lo_u32_b32 v222, s68, 0
	v_mbcnt_hi_u32_b32 v222, s69, v222
	v_mbcnt_lo_u32_b32 v223, s70, 0
	v_mbcnt_hi_u32_b32 v223, s71, v223
	v_add_u32_e32 v223, s0, v223
	v_lshl_add_u32 v222, v222, 3, s3
	v_lshl_add_u32 v223, v223, 3, s3
	s_mov_b64 exec, s[68:69]
	ds_write_b64 v222, v[136:137]
	s_mov_b64 exec, s[70:71]
	ds_write_b64 v223, v[138:139]
	s_mov_b64 exec, -1
	s_add_i32 s0, s0, s1
	s_add_i32 s0, s0, 3
	s_lshr_b32 s0, s0, 2
	s_add_i32 s75, s75, s0
	v_cmp_eq_u32_e64 s[68:69], s74, v166
	v_cmp_eq_u32_e64 s[70:71], s74, v167
	s_nop 0
	s_lshl_b32 s3, s75, 5
	s_add_i32 s3, s3, s22
	s_bcnt1_i32_b64 s0, s[68:69]
	s_bcnt1_i32_b64 s1, s[70:71]
	v_mbcnt_lo_u32_b32 v222, s68, 0
	v_mbcnt_hi_u32_b32 v222, s69, v222
	v_mbcnt_lo_u32_b32 v223, s70, 0
	v_mbcnt_hi_u32_b32 v223, s71, v223
	v_add_u32_e32 v223, s0, v223
	v_lshl_add_u32 v222, v222, 3, s3
	v_lshl_add_u32 v223, v223, 3, s3
	s_mov_b64 exec, s[68:69]
	ds_write_b64 v222, v[140:141]
	s_mov_b64 exec, s[70:71]
	ds_write_b64 v223, v[142:143]
	s_mov_b64 exec, -1
	s_add_i32 s0, s0, s1
	s_add_i32 s0, s0, 3
	s_lshr_b32 s0, s0, 2
	s_add_i32 s75, s75, s0
	v_cmp_eq_u32_e64 s[68:69], s74, v168
	v_cmp_eq_u32_e64 s[70:71], s74, v169
	s_nop 0
	s_lshl_b32 s3, s75, 5
	s_add_i32 s3, s3, s22
	s_bcnt1_i32_b64 s0, s[68:69]
	s_bcnt1_i32_b64 s1, s[70:71]
	v_mbcnt_lo_u32_b32 v222, s68, 0
	v_mbcnt_hi_u32_b32 v222, s69, v222
	v_mbcnt_lo_u32_b32 v223, s70, 0
	v_mbcnt_hi_u32_b32 v223, s71, v223
	v_add_u32_e32 v223, s0, v223
	v_lshl_add_u32 v222, v222, 3, s3
	v_lshl_add_u32 v223, v223, 3, s3
	s_mov_b64 exec, s[68:69]
	ds_write_b64 v222, v[144:145]
	s_mov_b64 exec, s[70:71]
	ds_write_b64 v223, v[146:147]
	s_mov_b64 exec, -1
	s_add_i32 s0, s0, s1
	s_add_i32 s0, s0, 3
	s_lshr_b32 s0, s0, 2
	s_add_i32 s75, s75, s0
	v_cmp_eq_u32_e64 s[68:69], s74, v170
	v_cmp_eq_u32_e64 s[70:71], s74, v171
	s_nop 0
	s_lshl_b32 s3, s75, 5
	s_add_i32 s3, s3, s22
	s_bcnt1_i32_b64 s0, s[68:69]
	s_bcnt1_i32_b64 s1, s[70:71]
	v_mbcnt_lo_u32_b32 v222, s68, 0
	v_mbcnt_hi_u32_b32 v222, s69, v222
	v_mbcnt_lo_u32_b32 v223, s70, 0
	v_mbcnt_hi_u32_b32 v223, s71, v223
	v_add_u32_e32 v223, s0, v223
	v_lshl_add_u32 v222, v222, 3, s3
	v_lshl_add_u32 v223, v223, 3, s3
	s_mov_b64 exec, s[68:69]
	ds_write_b64 v222, v[148:149]
	s_mov_b64 exec, s[70:71]
	ds_write_b64 v223, v[150:151]
	s_mov_b64 exec, -1
	s_add_i32 s0, s0, s1
	s_add_i32 s0, s0, 3
	s_lshr_b32 s0, s0, 2
	s_add_i32 s75, s75, s0
	v_cmp_eq_u32_e64 s[68:69], s74, v172
	v_cmp_eq_u32_e64 s[70:71], s74, v173
	s_nop 0
	s_lshl_b32 s3, s75, 5
	s_add_i32 s3, s3, s22
	s_bcnt1_i32_b64 s0, s[68:69]
	s_bcnt1_i32_b64 s1, s[70:71]
	v_mbcnt_lo_u32_b32 v222, s68, 0
	v_mbcnt_hi_u32_b32 v222, s69, v222
	v_mbcnt_lo_u32_b32 v223, s70, 0
	v_mbcnt_hi_u32_b32 v223, s71, v223
	v_add_u32_e32 v223, s0, v223
	v_lshl_add_u32 v222, v222, 3, s3
	v_lshl_add_u32 v223, v223, 3, s3
	s_mov_b64 exec, s[68:69]
	ds_write_b64 v222, v[152:153]
	s_mov_b64 exec, s[70:71]
	ds_write_b64 v223, v[154:155]
	s_mov_b64 exec, -1
	s_add_i32 s0, s0, s1
	s_add_i32 s0, s0, 3
	s_lshr_b32 s0, s0, 2
	s_add_i32 s75, s75, s0
	v_cmp_eq_u32_e64 s[68:69], s74, v174
	v_cmp_eq_u32_e64 s[70:71], s74, v175
	s_nop 0
	s_lshl_b32 s3, s75, 5
	s_add_i32 s3, s3, s22
	s_bcnt1_i32_b64 s0, s[68:69]
	s_bcnt1_i32_b64 s1, s[70:71]
	v_mbcnt_lo_u32_b32 v222, s68, 0
	v_mbcnt_hi_u32_b32 v222, s69, v222
	v_mbcnt_lo_u32_b32 v223, s70, 0
	v_mbcnt_hi_u32_b32 v223, s71, v223
	v_add_u32_e32 v223, s0, v223
	v_lshl_add_u32 v222, v222, 3, s3
	v_lshl_add_u32 v223, v223, 3, s3
	s_mov_b64 exec, s[68:69]
	ds_write_b64 v222, v[156:157]
	s_mov_b64 exec, s[70:71]
	ds_write_b64 v223, v[158:159]
	s_mov_b64 exec, -1
	s_add_i32 s0, s0, s1
	s_add_i32 s0, s0, 3
	s_lshr_b32 s0, s0, 2
	s_add_i32 s75, s75, s0
	s_add_i32 s74, s74, 1
	s_cmp_lt_u32 s74, 4
	s_cbranch_scc1 .Lbuild_c
; #define IT_ADVANCE() do { it_j += 4; while (it_j >= it_end) { if (it_done) break; ++it_tk; if (it_tk == 4) { it_tk = 0; ++it_p; if (it_p == 16) { it_done = true; it_p = 15; it_j = 0; it_end = 1; break; } } \
;             it_j = __builtin_amdgcn_readfirstlane(OFFS[(tb + it_tk) * 17 + it_p]); it_end = __builtin_amdgcn_readfirstlane(OFFS[(tb + it_tk) * 17 + it_p + 1]); } } while (0)
; __device__ __forceinline__ void peer_tile(const Args& A, LAS unsigned char* lds, int tile) {
;     ...
;         int it_p = 0, it_tk = -1, it_j = 0, it_end = 0; bool it_done = false;
;     ...
;         u32x4 uA[4], vA[4], uB[4], vB[4]; float cgA = 0.f, suA = 0.f, svA = 0.f, cgB = 0.f, suB = 0.f, svB = 0.f;
; #pragma unroll
;         for (int k = 0; k < 4; ++k) { uA[k] = (u32x4){0u, 0u, 0u, 0u}; vA[k] = uA[k]; uB[k] = uA[k]; vB[k] = uA[k]; }
;         IT_ADVANCE();
;         LOAD_SET(uA, vA, cgA, suA, svA);
;         for (int p = 0; p < 16; ++p) {
	s_mov_b32 s91, s75
	s_add_i32 s20, s91, 3
	s_and_b32 s20, s20, -4
	s_waitcnt vmcnt(0) lgkmcnt(0)
	v_lshrrev_b32_e32 v241, 1, v247
	v_add_u32_e32 v241, s22, v241
	v_lshrrev_b32_e32 v208, 6, v240
	v_and_b32_e32 v208, 3, v208
	v_lshrrev_b32_e32 v209, 1, v208
	v_lshlrev_b32_e32 v208, 1, v208
	v_and_b32_e32 v208, 2, v208
	v_or_b32_e32 v208, v208, v209
	v_lshlrev_b32_e32 v208, 3, v208
	v_lshlrev_b32_e32 v209, 1, v247
	v_add3_u32 v211, v208, v209, s22
	ds_read_b64 v[232:233], v241 offset:0
	s_waitcnt lgkmcnt(0)
	v_readlane_b32 s64, v232, 0
	v_readlane_b32 s65, v232, 16
	v_readlane_b32 s66, v232, 32
	v_readlane_b32 s67, v232, 48
	s_and_b32 s64, s64, s85
	s_and_b32 s65, s65, s85
	s_and_b32 s66, s66, s85
	s_and_b32 s67, s67, s85
	s_add_u32 s24, s4, s64
	s_addc_u32 s25, s5, 0
	s_add_u32 s26, s4, s65
	s_addc_u32 s27, s5, 0
	s_add_u32 s28, s4, s66
	s_addc_u32 s29, s5, 0
	s_add_u32 s30, s4, s67
	s_addc_u32 s31, s5, 0
	global_load_dwordx4 v[128:131], v240, s[24:25]
	global_load_dwordx4 v[132:135], v240, s[26:27]
	global_load_dwordx4 v[136:139], v240, s[28:29]
	global_load_dwordx4 v[140:143], v240, s[30:31]
	v_readfirstlane_b32 s94, v232
	ds_read_b64 v[232:233], v241 offset:32
	s_waitcnt lgkmcnt(0)
	v_readlane_b32 s64, v232, 0
	v_readlane_b32 s65, v232, 16
	v_readlane_b32 s66, v232, 32
	v_readlane_b32 s67, v232, 48
	s_and_b32 s64, s64, s85
	s_and_b32 s65, s65, s85
	s_and_b32 s66, s66, s85
	s_and_b32 s67, s67, s85
	s_add_u32 s24, s4, s64
	s_addc_u32 s25, s5, 0
	s_add_u32 s26, s4, s65
	s_addc_u32 s27, s5, 0
	s_add_u32 s28, s4, s66
	s_addc_u32 s29, s5, 0
	s_add_u32 s30, s4, s67
	s_addc_u32 s31, s5, 0
	global_load_dwordx4 v[144:147], v240, s[24:25]
	global_load_dwordx4 v[148:151], v240, s[26:27]
	global_load_dwordx4 v[152:155], v240, s[28:29]
	global_load_dwordx4 v[156:159], v240, s[30:31]
	v_readfirstlane_b32 s95, v232
	ds_read_b64 v[232:233], v241 offset:64
	s_waitcnt lgkmcnt(0)
	v_readlane_b32 s64, v232, 0
	v_readlane_b32 s65, v232, 16
	v_readlane_b32 s66, v232, 32
	v_readlane_b32 s67, v232, 48
	s_and_b32 s64, s64, s85
	s_and_b32 s65, s65, s85
	s_and_b32 s66, s66, s85
	s_and_b32 s67, s67, s85
	s_add_u32 s24, s4, s64
	s_addc_u32 s25, s5, 0
	s_add_u32 s26, s4, s65
	s_addc_u32 s27, s5, 0
	s_add_u32 s28, s4, s66
	s_addc_u32 s29, s5, 0
	s_add_u32 s30, s4, s67
	s_addc_u32 s31, s5, 0
	global_load_dwordx4 v[160:163], v240, s[24:25]
	global_load_dwordx4 v[164:167], v240, s[26:27]
	global_load_dwordx4 v[168:171], v240, s[28:29]
	global_load_dwordx4 v[172:175], v240, s[30:31]
	v_readfirstlane_b32 s96, v232
	ds_read_b64 v[232:233], v241 offset:96
	ds_read_b64 v[248:249], v211
	s_mov_b32 s21, 0
.LU_s0:
	s_cmp_ge_u32 s21, s20
	s_cbranch_scc1 .LU_done
	s_waitcnt lgkmcnt(0)
	v_lshrrev_b32_e32 v208, 8, v248
	v_readlane_b32 s64, v232, 0
	v_readlane_b32 s65, v232, 16
	v_readlane_b32 s66, v232, 32
	v_readlane_b32 s67, v232, 48
	s_and_b32 s64, s64, s85
	s_and_b32 s65, s65, s85
	s_and_b32 s66, s66, s85
	s_and_b32 s67, s67, s85
	s_add_u32 s24, s4, s64
	s_addc_u32 s25, s5, 0
	s_add_u32 s26, s4, s65
	s_addc_u32 s27, s5, 0
	s_add_u32 s28, s4, s66
	s_addc_u32 s29, s5, 0
	s_add_u32 s30, s4, s67
	s_addc_u32 s31, s5, 0
	global_load_dword v252, v208, s[8:9]
	global_load_dword v253, v208, s[52:53]
	global_load_dwordx4 v[176:179], v240, s[24:25]
	global_load_dwordx4 v[180:183], v240, s[26:27]
	global_load_dwordx4 v[184:187], v240, s[28:29]
	global_load_dwordx4 v[188:191], v240, s[30:31]
	v_readfirstlane_b32 s97, v232
	ds_read_b64 v[232:233], v241 offset:128
	s_and_b32 s23, s94, 7
	s_waitcnt vmcnt(14)
	s_cmp_ge_u32 s23, 4
	s_cbranch_scc1 .LU_s0_h
	s_cmp_ge_u32 s23, 2
	s_cbranch_scc1 .LU_s0_23
	s_cmp_eq_u32 s23, 0
	s_cbranch_scc1 .LU_s0_t0
	s_branch .LU_s0_t1

; #define IT_ADVANCE() do { it_j += 4; while (it_j >= it_end) { if (it_done) break; ++it_tk; if (it_tk == 4) { it_tk = 0; ++it_p; if (it_p == 16) { it_done = true; it_p = 15; it_j = 0; it_end = 1; break; } } \
;             it_j = __builtin_amdgcn_readfirstlane(OFFS[(tb + it_tk) * 17 + it_p]); it_end = __builtin_amdgcn_readfirstlane(OFFS[(tb + it_tk) * 17 + it_p + 1]); } } while (0)
; __device__ __forceinline__ void peer_tile(const Args& A, LAS unsigned char* lds, int tile) {
;     ...
;                 for (int j0 = beg; j0 < end; j0 += 8) {
;                     IT_ADVANCE();
;                     LOAD_SET(uB, vB, cgB, suB, svB);
.LU_s0_tail:
	v_add_f32_e32 v192, v216, v217
	v_add_f32_e32 v193, v218, v219
	v_add_f32_e32 v194, v220, v221
	v_add_f32_e32 v195, v222, v223
.LU_s1:
	s_waitcnt lgkmcnt(0)
	v_readlane_b32 s64, v232, 0
	v_readlane_b32 s65, v232, 16
	v_readlane_b32 s66, v232, 32
	v_readlane_b32 s67, v232, 48
	s_and_b32 s64, s64, s85
	s_and_b32 s65, s65, s85
	s_and_b32 s66, s66, s85
	s_and_b32 s67, s67, s85
	s_add_u32 s24, s4, s64
	s_addc_u32 s25, s5, 0
	s_add_u32 s26, s4, s65
	s_addc_u32 s27, s5, 0
	s_add_u32 s28, s4, s66
	s_addc_u32 s29, s5, 0
	s_add_u32 s30, s4, s67
	s_addc_u32 s31, s5, 0
	global_load_dwordx4 v[128:131], v240, s[24:25]
	global_load_dwordx4 v[132:135], v240, s[26:27]
	global_load_dwordx4 v[136:139], v240, s[28:29]
	global_load_dwordx4 v[140:143], v240, s[30:31]
	v_readfirstlane_b32 s94, v232
	ds_read_b64 v[232:233], v241 offset:160
	s_and_b32 s23, s95, 7
	s_waitcnt vmcnt(14)
	s_cmp_ge_u32 s23, 4
	s_cbranch_scc1 .LU_s1_h
	s_cmp_ge_u32 s23, 2
	s_cbranch_scc1 .LU_s1_23
	s_cmp_eq_u32 s23, 0
	s_cbranch_scc1 .LU_s1_t0
	s_branch .LU_s1_t1

; #define IT_ADVANCE() do { it_j += 4; while (it_j >= it_end) { if (it_done) break; ++it_tk; if (it_tk == 4) { it_tk = 0; ++it_p; if (it_p == 16) { it_done = true; it_p = 15; it_j = 0; it_end = 1; break; } } \
;             it_j = __builtin_amdgcn_readfirstlane(OFFS[(tb + it_tk) * 17 + it_p]); it_end = __builtin_amdgcn_readfirstlane(OFFS[(tb + it_tk) * 17 + it_p + 1]); } } while (0)
; __device__ __forceinline__ void peer_tile(const Args& A, LAS unsigned char* lds, int tile) {
;     ...
;                 for (int j0 = beg; j0 < end; j0 += 8) {
;                     IT_ADVANCE();
;                     LOAD_SET(uB, vB, cgB, suB, svB);
.LU_s1_tail:
	v_add_f32_e32 v196, v216, v217
	v_add_f32_e32 v197, v218, v219
	v_add_f32_e32 v198, v220, v221
	v_add_f32_e32 v199, v222, v223
.LU_s2:
	s_waitcnt lgkmcnt(0)
	v_readlane_b32 s64, v232, 0
	v_readlane_b32 s65, v232, 16
	v_readlane_b32 s66, v232, 32
	v_readlane_b32 s67, v232, 48
	s_and_b32 s64, s64, s85
	s_and_b32 s65, s65, s85
	s_and_b32 s66, s66, s85
	s_and_b32 s67, s67, s85
	s_add_u32 s24, s4, s64
	s_addc_u32 s25, s5, 0
	s_add_u32 s26, s4, s65
	s_addc_u32 s27, s5, 0
	s_add_u32 s28, s4, s66
	s_addc_u32 s29, s5, 0
	s_add_u32 s30, s4, s67
	s_addc_u32 s31, s5, 0
	global_load_dwordx4 v[144:147], v240, s[24:25]
	global_load_dwordx4 v[148:151], v240, s[26:27]
	global_load_dwordx4 v[152:155], v240, s[28:29]
	global_load_dwordx4 v[156:159], v240, s[30:31]
	v_readfirstlane_b32 s95, v232
	ds_read_b64 v[232:233], v241 offset:192
	s_and_b32 s23, s96, 7
	s_waitcnt vmcnt(14)
	s_cmp_ge_u32 s23, 4
	s_cbranch_scc1 .LU_s2_h
	s_cmp_ge_u32 s23, 2
	s_cbranch_scc1 .LU_s2_23
	s_cmp_eq_u32 s23, 0
	s_cbranch_scc1 .LU_s2_t0
	s_branch .LU_s2_t1

; #define IT_ADVANCE() do { it_j += 4; while (it_j >= it_end) { if (it_done) break; ++it_tk; if (it_tk == 4) { it_tk = 0; ++it_p; if (it_p == 16) { it_done = true; it_p = 15; it_j = 0; it_end = 1; break; } } \
;             it_j = __builtin_amdgcn_readfirstlane(OFFS[(tb + it_tk) * 17 + it_p]); it_end = __builtin_amdgcn_readfirstlane(OFFS[(tb + it_tk) * 17 + it_p + 1]); } } while (0)
; __device__ __forceinline__ void peer_tile(const Args& A, LAS unsigned char* lds, int tile) {
;     ...
;                 for (int j0 = beg; j0 < end; j0 += 8) {
;                     IT_ADVANCE();
;                     LOAD_SET(uB, vB, cgB, suB, svB);
.LU_s2_tail:
	v_add_f32_e32 v200, v216, v217
	v_add_f32_e32 v201, v218, v219
	v_add_f32_e32 v202, v220, v221
	v_add_f32_e32 v203, v222, v223
.LU_s3:
	s_waitcnt lgkmcnt(0)
	v_readlane_b32 s64, v232, 0
	v_readlane_b32 s65, v232, 16
	v_readlane_b32 s66, v232, 32
	v_readlane_b32 s67, v232, 48
	s_and_b32 s64, s64, s85
	s_and_b32 s65, s65, s85
	s_and_b32 s66, s66, s85
	s_and_b32 s67, s67, s85
	s_add_u32 s24, s4, s64
	s_addc_u32 s25, s5, 0
	s_add_u32 s26, s4, s65
	s_addc_u32 s27, s5, 0
	s_add_u32 s28, s4, s66
	s_addc_u32 s29, s5, 0
	s_add_u32 s30, s4, s67
	s_addc_u32 s31, s5, 0
	global_load_dwordx4 v[160:163], v240, s[24:25]
	global_load_dwordx4 v[164:167], v240, s[26:27]
	global_load_dwordx4 v[168:171], v240, s[28:29]
	global_load_dwordx4 v[172:175], v240, s[30:31]
	v_readfirstlane_b32 s96, v232
	ds_read_b64 v[232:233], v241 offset:224
	s_and_b32 s23, s97, 7
	s_waitcnt vmcnt(12)
	s_cmp_ge_u32 s23, 4
	s_cbranch_scc1 .LU_s3_h
	s_cmp_ge_u32 s23, 2
	s_cbranch_scc1 .LU_s3_23
	s_cmp_eq_u32 s23, 0
	s_cbranch_scc1 .LU_s3_t0
	s_branch .LU_s3_t1

.LU_s3_tail:
	v_add_f32_e32 v204, v216, v217
	v_add_f32_e32 v205, v218, v219
	v_add_f32_e32 v206, v220, v221
	v_add_f32_e32 v207, v222, v223
	s_nop 0
	v_permlane32_swap_b32_e32 v192, v200
	v_permlane32_swap_b32_e32 v193, v201
	v_permlane32_swap_b32_e32 v194, v202
	v_permlane32_swap_b32_e32 v195, v203
	v_permlane32_swap_b32_e32 v196, v204
	v_permlane32_swap_b32_e32 v197, v205
	v_permlane32_swap_b32_e32 v198, v206
	v_permlane32_swap_b32_e32 v199, v207
	v_add_f32_e32 v192, v192, v200
	v_add_f32_e32 v193, v193, v201
	v_add_f32_e32 v194, v194, v202
	v_add_f32_e32 v195, v195, v203
	v_add_f32_e32 v196, v196, v204
	v_add_f32_e32 v197, v197, v205
	v_add_f32_e32 v198, v198, v206
	v_add_f32_e32 v199, v199, v207
	v_permlane16_swap_b32_e32 v192, v196
	v_permlane16_swap_b32_e32 v193, v197
	v_permlane16_swap_b32_e32 v194, v198
	v_permlane16_swap_b32_e32 v195, v199
	v_add_f32_e32 v192, v192, v196
	v_add_f32_e32 v193, v193, v197
	v_add_f32_e32 v194, v194, v198
	v_add_f32_e32 v195, v195, v199
	v_add_f32_dpp v216, v192, v192 row_ror:8 row_mask:0xf bank_mask:0xf
	v_add_f32_dpp v218, v194, v194 row_ror:8 row_mask:0xf bank_mask:0xf
	v_add_f32_dpp v216, v193, v193 row_ror:8 row_mask:0xf bank_mask:0xc
	v_add_f32_dpp v218, v195, v195 row_ror:8 row_mask:0xf bank_mask:0xc
	s_nop 1
	v_add_f32_dpp v220, v216, v216 row_half_mirror row_mask:0xf bank_mask:0xf
	v_add_f32_dpp v220, v218, v218 row_half_mirror row_mask:0xf bank_mask:0xa
	s_nop 1
	v_add_f32_dpp v220, v220, v220 quad_perm:[1,0,3,2] row_mask:0xf bank_mask:0xf
	s_nop 1
	v_add_f32_dpp v220, v220, v220 quad_perm:[2,3,0,1] row_mask:0xf bank_mask:0xf
	v_mul_f32_e32 v216, v252, v220
	v_fma_f32 v218, |v216|, s72, 1.0
	v_mul_f32_e32 v222, v216, v216
	v_rcp_f32_e32 v218, v218
	v_mul_f32_e32 v222, 0xbf38aa3b, v222
	v_exp_f32_e32 v222, v222
	v_fmamk_f32 v224, v218, 0x3f07dc22, v242
	v_fmaak_f32 v224, v218, v224, 0x3f35f0e3
	v_fmaak_f32 v224, v218, v224, 0xbe11a98e
	v_fmaak_f32 v224, v218, v224, 0x3e027906
	v_mul_f32_e32 v224, v218, v224
	v_mul_f32_e32 v224, v222, v224
	v_mul_f32_e32 v226, v216, v224
	v_fma_f32 v224, -v216, v224, v216
	v_cmp_gt_f32_e32 vcc, 0, v216
	s_nop 1
	v_cndmask_b32_e32 v224, v224, v226, vcc
	v_mul_f32_e32 v224, v249, v224
	v_mul_f32_e32 v224, v253, v224
	ds_write_b32 v211, v224 offset:4
	v_add_u32_e32 v211, 128, v211
	v_add_u32_e32 v241, 128, v241
	ds_read_b64 v[248:249], v211
	s_add_i32 s21, s21, 4
	s_branch .LU_s0
; #define IT_ADVANCE() do { it_j += 4; while (it_j >= it_end) { if (it_done) break; ++it_tk; if (it_tk == 4) { it_tk = 0; ++it_p; if (it_p == 16) { it_done = true; it_p = 15; it_j = 0; it_end = 1; break; } } \
;             it_j = __builtin_amdgcn_readfirstlane(OFFS[(tb + it_tk) * 17 + it_p]); it_end = __builtin_amdgcn_readfirstlane(OFFS[(tb + it_tk) * 17 + it_p + 1]); } } while (0)
; __device__ __forceinline__ void peer_tile(const Args& A, LAS unsigned char* lds, int tile) {
;     ...
; #pragma unroll
;             for (int q = 0; q < 8; ++q) oacc[tk][q] = (f32x2){0.f, 0.f}; }
;         int it_p = 0, it_tk = -1, it_j = 0, it_end = 0; bool it_done = false;
;     ...
;         u32x4 uA[4], vA[4], uB[4], vB[4]; float cgA = 0.f, suA = 0.f, svA = 0.f, cgB = 0.f, suB = 0.f, svB = 0.f;
; #pragma unroll
;         for (int k = 0; k < 4; ++k) { uA[k] = (u32x4){0u, 0u, 0u, 0u}; vA[k] = uA[k]; uB[k] = uA[k]; vB[k] = uA[k]; }
;         IT_ADVANCE();
;         LOAD_SET(uA, vA, cgA, suA, svA);
.LU_done:
	s_waitcnt vmcnt(0) lgkmcnt(0)
	v_mov_b64_e32 v[0:1], 0
	v_mov_b64_e32 v[2:3], 0
	v_mov_b64_e32 v[4:5], 0
	v_mov_b64_e32 v[6:7], 0
	v_mov_b64_e32 v[8:9], 0
	v_mov_b64_e32 v[10:11], 0
	v_mov_b64_e32 v[12:13], 0
	v_mov_b64_e32 v[14:15], 0
	v_mov_b64_e32 v[16:17], 0
	v_mov_b64_e32 v[18:19], 0
	v_mov_b64_e32 v[20:21], 0
	v_mov_b64_e32 v[22:23], 0
	v_mov_b64_e32 v[24:25], 0
	v_mov_b64_e32 v[26:27], 0
	v_mov_b64_e32 v[28:29], 0
	v_mov_b64_e32 v[30:31], 0
	v_mov_b64_e32 v[32:33], 0
	v_mov_b64_e32 v[34:35], 0
	v_mov_b64_e32 v[36:37], 0
	v_mov_b64_e32 v[38:39], 0
	v_mov_b64_e32 v[40:41], 0
	v_mov_b64_e32 v[42:43], 0
	v_mov_b64_e32 v[44:45], 0
	v_mov_b64_e32 v[46:47], 0
	v_mov_b64_e32 v[48:49], 0
	v_mov_b64_e32 v[50:51], 0
	v_mov_b64_e32 v[52:53], 0
	v_mov_b64_e32 v[54:55], 0
	v_mov_b64_e32 v[56:57], 0
	v_mov_b64_e32 v[58:59], 0
	v_mov_b64_e32 v[60:61], 0
	v_mov_b64_e32 v[62:63], 0
	v_mov_b64_e32 v[64:65], 0
	v_mov_b64_e32 v[66:67], 0
	v_mov_b64_e32 v[68:69], 0
	v_mov_b64_e32 v[70:71], 0
	v_mov_b64_e32 v[72:73], 0
	v_mov_b64_e32 v[74:75], 0
	v_mov_b64_e32 v[76:77], 0
	v_mov_b64_e32 v[78:79], 0
	v_mov_b64_e32 v[80:81], 0
	v_mov_b64_e32 v[82:83], 0
	v_mov_b64_e32 v[84:85], 0
	v_mov_b64_e32 v[86:87], 0
	v_mov_b64_e32 v[88:89], 0
	v_mov_b64_e32 v[90:91], 0
	v_mov_b64_e32 v[92:93], 0
	v_mov_b64_e32 v[94:95], 0
	v_mov_b64_e32 v[96:97], 0
	v_mov_b64_e32 v[98:99], 0
	v_mov_b64_e32 v[100:101], 0
	v_mov_b64_e32 v[102:103], 0
	v_mov_b64_e32 v[104:105], 0
	v_mov_b64_e32 v[106:107], 0
	v_mov_b64_e32 v[108:109], 0
	v_mov_b64_e32 v[110:111], 0
	v_mov_b64_e32 v[112:113], 0
	v_mov_b64_e32 v[114:115], 0
	v_mov_b64_e32 v[116:117], 0
	v_mov_b64_e32 v[118:119], 0
	v_mov_b64_e32 v[120:121], 0
	v_mov_b64_e32 v[122:123], 0
	v_mov_b64_e32 v[124:125], 0
	v_mov_b64_e32 v[126:127], 0
	s_mov_b32 s20, s91
	s_waitcnt vmcnt(0) lgkmcnt(0)
	v_lshrrev_b32_e32 v241, 1, v247
	v_add_u32_e32 v241, s22, v241
	ds_read_b64 v[232:233], v241 offset:0
	s_waitcnt lgkmcnt(0)
	v_readlane_b32 s64, v232, 0
	v_readlane_b32 s65, v232, 16
	v_readlane_b32 s66, v232, 32
	v_readlane_b32 s67, v232, 48
	s_and_b32 s64, s64, s85
	s_and_b32 s65, s65, s85
	s_and_b32 s66, s66, s85
	s_and_b32 s67, s67, s85
	s_add_u32 s24, s6, s64
	s_addc_u32 s25, s7, 0
	s_add_u32 s26, s6, s65
	s_addc_u32 s27, s7, 0
	s_add_u32 s28, s6, s66
	s_addc_u32 s29, s7, 0
	s_add_u32 s30, s6, s67
	s_addc_u32 s31, s7, 0
	global_load_dwordx4 v[128:131], v240, s[24:25]
	global_load_dwordx4 v[132:135], v240, s[26:27]
	global_load_dwordx4 v[136:139], v240, s[28:29]
	global_load_dwordx4 v[140:143], v240, s[30:31]
	ds_read_b64 v[232:233], v241 offset:32
	s_waitcnt lgkmcnt(0)
	v_readlane_b32 s64, v232, 0
	v_readlane_b32 s65, v232, 16
	v_readlane_b32 s66, v232, 32
	v_readlane_b32 s67, v232, 48
	s_and_b32 s64, s64, s85
	s_and_b32 s65, s65, s85
	s_and_b32 s66, s66, s85
	s_and_b32 s67, s67, s85
	s_add_u32 s24, s6, s64
	s_addc_u32 s25, s7, 0
	s_add_u32 s26, s6, s65
	s_addc_u32 s27, s7, 0
	s_add_u32 s28, s6, s66
	s_addc_u32 s29, s7, 0
	s_add_u32 s30, s6, s67
	s_addc_u32 s31, s7, 0
	global_load_dwordx4 v[144:147], v240, s[24:25]
	global_load_dwordx4 v[148:151], v240, s[26:27]
	global_load_dwordx4 v[152:155], v240, s[28:29]
	global_load_dwordx4 v[156:159], v240, s[30:31]
	ds_read_b64 v[232:233], v241 offset:64
	s_waitcnt lgkmcnt(0)
	v_readlane_b32 s64, v232, 0
	v_readlane_b32 s65, v232, 16
	v_readlane_b32 s66, v232, 32
	v_readlane_b32 s67, v232, 48
	s_and_b32 s64, s64, s85
	s_and_b32 s65, s65, s85
	s_and_b32 s66, s66, s85
	s_and_b32 s67, s67, s85
	s_add_u32 s24, s6, s64
	s_addc_u32 s25, s7, 0
	s_add_u32 s26, s6, s65
	s_addc_u32 s27, s7, 0
	s_add_u32 s28, s6, s66
	s_addc_u32 s29, s7, 0
	s_add_u32 s30, s6, s67
	s_addc_u32 s31, s7, 0
	global_load_dwordx4 v[160:163], v240, s[24:25]
	global_load_dwordx4 v[164:167], v240, s[26:27]
	global_load_dwordx4 v[168:171], v240, s[28:29]
	global_load_dwordx4 v[172:175], v240, s[30:31]
	ds_read_b64 v[236:237], v241 offset:0
	ds_read_b64 v[232:233], v241 offset:96
	s_mov_b32 s21, 0
.LV_s0:
	s_cmp_ge_u32 s21, s20
	s_cbranch_scc1 .LV_done
	s_waitcnt lgkmcnt(0)
	v_readlane_b32 s64, v232, 0
	v_readlane_b32 s65, v232, 16
	v_readlane_b32 s66, v232, 32
	v_readlane_b32 s67, v232, 48
	s_and_b32 s64, s64, s85
	s_and_b32 s65, s65, s85
	s_and_b32 s66, s66, s85
	s_and_b32 s67, s67, s85
	s_add_u32 s24, s6, s64
	s_addc_u32 s25, s7, 0
	s_add_u32 s26, s6, s65
	s_addc_u32 s27, s7, 0
	s_add_u32 s28, s6, s66
	s_addc_u32 s29, s7, 0
	s_add_u32 s30, s6, s67
	s_addc_u32 s31, s7, 0
	global_load_dwordx4 v[176:179], v240, s[24:25]
	global_load_dwordx4 v[180:183], v240, s[26:27]
	global_load_dwordx4 v[184:187], v240, s[28:29]
	global_load_dwordx4 v[188:191], v240, s[30:31]
	v_readfirstlane_b32 s23, v236
	v_readlane_b32 s56, v237, 0
	v_readlane_b32 s58, v237, 16
	v_readlane_b32 s60, v237, 32
	v_readlane_b32 s62, v237, 48
	s_and_b32 s23, s23, 7
	s_waitcnt vmcnt(12)
	s_cmp_ge_u32 s23, 4
	s_cbranch_scc1 .LV_s0_h
	s_cmp_ge_u32 s23, 2
	s_cbranch_scc1 .LV_s0_23
	s_cmp_eq_u32 s23, 0
	s_cbranch_scc1 .LV_s0_t0
	s_branch .LV_s0_t1

; #define IT_ADVANCE() do { it_j += 4; while (it_j >= it_end) { if (it_done) break; ++it_tk; if (it_tk == 4) { it_tk = 0; ++it_p; if (it_p == 16) { it_done = true; it_p = 15; it_j = 0; it_end = 1; break; } } \
;             it_j = __builtin_amdgcn_readfirstlane(OFFS[(tb + it_tk) * 17 + it_p]); it_end = __builtin_amdgcn_readfirstlane(OFFS[(tb + it_tk) * 17 + it_p + 1]); } } while (0)
; __device__ __forceinline__ void peer_tile(const Args& A, LAS unsigned char* lds, int tile) {
;     ...
;                 for (int j0 = beg; j0 < end; j0 += 8) {
;                     IT_ADVANCE();
;                     LOAD_SET(uB, vB, cgB, suB, svB);
;                     COMPUTE_SET(uA, vA, cgA, suA, svA);
;                     if (j0 + 4 < end) {
;                         IT_ADVANCE();
;                         LOAD_SET(uA, vA, cgA, suA, svA);
.LV_s0_tail:
	ds_read_b64 v[236:237], v241 offset:32
	ds_read_b64 v[232:233], v241 offset:128
	s_add_i32 s21, s21, 1
.LV_s1:
	s_cmp_ge_u32 s21, s20
	s_cbranch_scc1 .LV_done
	s_waitcnt lgkmcnt(0)
	v_readlane_b32 s64, v232, 0
	v_readlane_b32 s65, v232, 16
	v_readlane_b32 s66, v232, 32
	v_readlane_b32 s67, v232, 48
	s_and_b32 s64, s64, s85
	s_and_b32 s65, s65, s85
	s_and_b32 s66, s66, s85
	s_and_b32 s67, s67, s85
	s_add_u32 s24, s6, s64
	s_addc_u32 s25, s7, 0
	s_add_u32 s26, s6, s65
	s_addc_u32 s27, s7, 0
	s_add_u32 s28, s6, s66
	s_addc_u32 s29, s7, 0
	s_add_u32 s30, s6, s67
	s_addc_u32 s31, s7, 0
	global_load_dwordx4 v[128:131], v240, s[24:25]
	global_load_dwordx4 v[132:135], v240, s[26:27]
	global_load_dwordx4 v[136:139], v240, s[28:29]
	global_load_dwordx4 v[140:143], v240, s[30:31]
	v_readfirstlane_b32 s23, v236
	v_readlane_b32 s56, v237, 0
	v_readlane_b32 s58, v237, 16
	v_readlane_b32 s60, v237, 32
	v_readlane_b32 s62, v237, 48
	s_and_b32 s23, s23, 7
	s_waitcnt vmcnt(12)
	s_cmp_ge_u32 s23, 4
	s_cbranch_scc1 .LV_s1_h
	s_cmp_ge_u32 s23, 2
	s_cbranch_scc1 .LV_s1_23
	s_cmp_eq_u32 s23, 0
	s_cbranch_scc1 .LV_s1_t0
	s_branch .LV_s1_t1

; #define IT_ADVANCE() do { it_j += 4; while (it_j >= it_end) { if (it_done) break; ++it_tk; if (it_tk == 4) { it_tk = 0; ++it_p; if (it_p == 16) { it_done = true; it_p = 15; it_j = 0; it_end = 1; break; } } \
;             it_j = __builtin_amdgcn_readfirstlane(OFFS[(tb + it_tk) * 17 + it_p]); it_end = __builtin_amdgcn_readfirstlane(OFFS[(tb + it_tk) * 17 + it_p + 1]); } } while (0)
; __device__ __forceinline__ void peer_tile(const Args& A, LAS unsigned char* lds, int tile) {
;     ...
;                 for (int j0 = beg; j0 < end; j0 += 8) {
;                     IT_ADVANCE();
;                     LOAD_SET(uB, vB, cgB, suB, svB);
;                     COMPUTE_SET(uA, vA, cgA, suA, svA);
;                     if (j0 + 4 < end) {
;                         IT_ADVANCE();
;                         LOAD_SET(uA, vA, cgA, suA, svA);
.LV_s1_tail:
	ds_read_b64 v[236:237], v241 offset:64
	ds_read_b64 v[232:233], v241 offset:160
	s_add_i32 s21, s21, 1
.LV_s2:
	s_cmp_ge_u32 s21, s20
	s_cbranch_scc1 .LV_done
	s_waitcnt lgkmcnt(0)
	v_readlane_b32 s64, v232, 0
	v_readlane_b32 s65, v232, 16
	v_readlane_b32 s66, v232, 32
	v_readlane_b32 s67, v232, 48
	s_and_b32 s64, s64, s85
	s_and_b32 s65, s65, s85
	s_and_b32 s66, s66, s85
	s_and_b32 s67, s67, s85
	s_add_u32 s24, s6, s64
	s_addc_u32 s25, s7, 0
	s_add_u32 s26, s6, s65
	s_addc_u32 s27, s7, 0
	s_add_u32 s28, s6, s66
	s_addc_u32 s29, s7, 0
	s_add_u32 s30, s6, s67
	s_addc_u32 s31, s7, 0
	global_load_dwordx4 v[144:147], v240, s[24:25]
	global_load_dwordx4 v[148:151], v240, s[26:27]
	global_load_dwordx4 v[152:155], v240, s[28:29]
	global_load_dwordx4 v[156:159], v240, s[30:31]
	v_readfirstlane_b32 s23, v236
	v_readlane_b32 s56, v237, 0
	v_readlane_b32 s58, v237, 16
	v_readlane_b32 s60, v237, 32
	v_readlane_b32 s62, v237, 48
	s_and_b32 s23, s23, 7
	s_waitcnt vmcnt(12)
	s_cmp_ge_u32 s23, 4
	s_cbranch_scc1 .LV_s2_h
	s_cmp_ge_u32 s23, 2
	s_cbranch_scc1 .LV_s2_23
	s_cmp_eq_u32 s23, 0
	s_cbranch_scc1 .LV_s2_t0
	s_branch .LV_s2_t1

; #define IT_ADVANCE() do { it_j += 4; while (it_j >= it_end) { if (it_done) break; ++it_tk; if (it_tk == 4) { it_tk = 0; ++it_p; if (it_p == 16) { it_done = true; it_p = 15; it_j = 0; it_end = 1; break; } } \
;             it_j = __builtin_amdgcn_readfirstlane(OFFS[(tb + it_tk) * 17 + it_p]); it_end = __builtin_amdgcn_readfirstlane(OFFS[(tb + it_tk) * 17 + it_p + 1]); } } while (0)
; __device__ __forceinline__ void peer_tile(const Args& A, LAS unsigned char* lds, int tile) {
;     ...
;                 for (int j0 = beg; j0 < end; j0 += 8) {
;                     IT_ADVANCE();
;                     LOAD_SET(uB, vB, cgB, suB, svB);
;                     COMPUTE_SET(uA, vA, cgA, suA, svA);
;                     if (j0 + 4 < end) {
;                         IT_ADVANCE();
;                         LOAD_SET(uA, vA, cgA, suA, svA);
.LV_s2_tail:
	ds_read_b64 v[236:237], v241 offset:96
	ds_read_b64 v[232:233], v241 offset:192
	s_add_i32 s21, s21, 1
.LV_s3:
	s_cmp_ge_u32 s21, s20
	s_cbranch_scc1 .LV_done
	s_waitcnt lgkmcnt(0)
	v_readlane_b32 s64, v232, 0
	v_readlane_b32 s65, v232, 16
	v_readlane_b32 s66, v232, 32
	v_readlane_b32 s67, v232, 48
	s_and_b32 s64, s64, s85
	s_and_b32 s65, s65, s85
	s_and_b32 s66, s66, s85
	s_and_b32 s67, s67, s85
	s_add_u32 s24, s6, s64
	s_addc_u32 s25, s7, 0
	s_add_u32 s26, s6, s65
	s_addc_u32 s27, s7, 0
	s_add_u32 s28, s6, s66
	s_addc_u32 s29, s7, 0
	s_add_u32 s30, s6, s67
	s_addc_u32 s31, s7, 0
	global_load_dwordx4 v[160:163], v240, s[24:25]
	global_load_dwordx4 v[164:167], v240, s[26:27]
	global_load_dwordx4 v[168:171], v240, s[28:29]
	global_load_dwordx4 v[172:175], v240, s[30:31]
	v_readfirstlane_b32 s23, v236
	v_readlane_b32 s56, v237, 0
	v_readlane_b32 s58, v237, 16
	v_readlane_b32 s60, v237, 32
	v_readlane_b32 s62, v237, 48
	s_and_b32 s23, s23, 7
	s_waitcnt vmcnt(12)
	s_cmp_ge_u32 s23, 4
	s_cbranch_scc1 .LV_s3_h
	s_cmp_ge_u32 s23, 2
	s_cbranch_scc1 .LV_s3_23
	s_cmp_eq_u32 s23, 0
	s_cbranch_scc1 .LV_s3_t0
	s_branch .LV_s3_t1

; #define IT_ADVANCE() do { it_j += 4; while (it_j >= it_end) { if (it_done) break; ++it_tk; if (it_tk == 4) { it_tk = 0; ++it_p; if (it_p == 16) { it_done = true; it_p = 15; it_j = 0; it_end = 1; break; } } \
;             it_j = __builtin_amdgcn_readfirstlane(OFFS[(tb + it_tk) * 17 + it_p]); it_end = __builtin_amdgcn_readfirstlane(OFFS[(tb + it_tk) * 17 + it_p + 1]); } } while (0)
; __device__ __forceinline__ void peer_tile(const Args& A, LAS unsigned char* lds, int tile) {
;     ...
;                 for (int j0 = beg; j0 < end; j0 += 8) {
;                     IT_ADVANCE();
;                     LOAD_SET(uB, vB, cgB, suB, svB);
;                     COMPUTE_SET(uA, vA, cgA, suA, svA);
;                     if (j0 + 4 < end) {
;                         IT_ADVANCE();
;                         LOAD_SET(uA, vA, cgA, suA, svA);
;                         COMPUTE_SET(uB, vB, cgB, suB, svB);
;     ...
;         for (int tk = 0; tk < 4; ++tk) {
;             const size_t m = (size_t)tile * 64 + tb + tk; const int b = (int)(m >> 11);
;             float* orow = A.out + m * 1024 + 16 * lane;
;             const float* g2 = MOD + b * 6144 + 5120 + 16 * lane;
;             f32x4 xv[4]; float ss = 0.f;
; #pragma unroll
;             for (int j = 0; j < 4; ++j) { const f32x4 x1 = *(const f32x4*)(orow + 4 * j), gg = *(const f32x4*)(g2 + 4 * j);
;                 const f32x4 pe = (f32x4){oacc[tk][2 * j][0], oacc[tk][2 * j][1], oacc[tk][2 * j + 1][0], oacc[tk][2 * j + 1][1]};
;                 xv[j] = x1 + gg * pe; ss += (xv[j][0] * xv[j][0] + xv[j][1] * xv[j][1]) + (xv[j][2] * xv[j][2] + xv[j][3] * xv[j][3]); }
.LV_s3_tail:
	ds_read_b64 v[236:237], v241 offset:128
	ds_read_b64 v[232:233], v241 offset:224
	s_add_i32 s21, s21, 1
	v_add_u32_e32 v241, 128, v241
	s_branch .LV_s0
.LV_done:
	s_waitcnt vmcnt(0) lgkmcnt(0)
	global_load_dwordx4 v[192:195], v246, s[82:83]
	global_load_dwordx4 v[196:199], v246, s[82:83] offset:16
	global_load_dwordx4 v[200:203], v246, s[82:83] offset:32
	global_load_dwordx4 v[204:207], v246, s[82:83] offset:48
	global_load_dwordx4 v[216:219], v246, s[46:47]
	global_load_dwordx4 v[220:223], v246, s[46:47] offset:16
	global_load_dwordx4 v[224:227], v246, s[46:47] offset:32
	global_load_dwordx4 v[228:231], v246, s[46:47] offset:48
	s_add_i32 s0, s77, 0
	s_lshl_b32 s0, s0, 12
	s_add_u32 s24, s48, s0
	s_addc_u32 s25, s49, 0
	s_add_i32 s0, s77, 1
	s_lshl_b32 s0, s0, 12
	s_add_u32 s26, s48, s0
	s_addc_u32 s27, s49, 0
	s_add_i32 s0, s77, 2
	s_lshl_b32 s0, s0, 12
	s_add_u32 s28, s48, s0
	s_addc_u32 s29, s49, 0
	s_add_i32 s0, s77, 3
	s_lshl_b32 s0, s0, 12
	s_add_u32 s30, s48, s0
	s_addc_u32 s31, s49, 0
	global_load_dwordx4 v[128:131], v246, s[24:25]
	global_load_dwordx4 v[132:135], v246, s[24:25] offset:16
	global_load_dwordx4 v[136:139], v246, s[24:25] offset:32
	global_load_dwordx4 v[140:143], v246, s[24:25] offset:48
	global_load_dwordx4 v[144:147], v246, s[26:27]
	global_load_dwordx4 v[148:151], v246, s[26:27] offset:16
	global_load_dwordx4 v[152:155], v246, s[26:27] offset:32
	global_load_dwordx4 v[156:159], v246, s[26:27] offset:48
	global_load_dwordx4 v[160:163], v246, s[28:29]
	global_load_dwordx4 v[164:167], v246, s[28:29] offset:16
	global_load_dwordx4 v[168:171], v246, s[28:29] offset:32
	global_load_dwordx4 v[172:175], v246, s[28:29] offset:48
	global_load_dwordx4 v[176:179], v246, s[30:31]
	global_load_dwordx4 v[180:183], v246, s[30:31] offset:16
	global_load_dwordx4 v[184:187], v246, s[30:31] offset:32
	global_load_dwordx4 v[188:191], v246, s[30:31] offset:48
	s_waitcnt vmcnt(0)
	v_pk_fma_f32 v[128:129], v[0:1], v[192:193], v[128:129]
	v_pk_fma_f32 v[130:131], v[2:3], v[194:195], v[130:131]
	v_pk_fma_f32 v[132:133], v[4:5], v[196:197], v[132:133]
	v_pk_fma_f32 v[134:135], v[6:7], v[198:199], v[134:135]
	v_pk_fma_f32 v[136:137], v[8:9], v[200:201], v[136:137]
	v_pk_fma_f32 v[138:139], v[10:11], v[202:203], v[138:139]
	v_pk_fma_f32 v[140:141], v[12:13], v[204:205], v[140:141]
	v_pk_fma_f32 v[142:143], v[14:15], v[206:207], v[142:143]
	v_pk_mul_f32 v[248:249], v[128:129], v[128:129]
	v_pk_fma_f32 v[248:249], v[130:131], v[130:131], v[248:249]
	v_pk_fma_f32 v[248:249], v[132:133], v[132:133], v[248:249]
	v_pk_fma_f32 v[248:249], v[134:135], v[134:135], v[248:249]
	v_pk_fma_f32 v[248:249], v[136:137], v[136:137], v[248:249]
	v_pk_fma_f32 v[248:249], v[138:139], v[138:139], v[248:249]
	v_pk_fma_f32 v[248:249], v[140:141], v[140:141], v[248:249]
	v_pk_fma_f32 v[248:249], v[142:143], v[142:143], v[248:249]
	v_pk_fma_f32 v[144:145], v[16:17], v[192:193], v[144:145]
	v_pk_fma_f32 v[146:147], v[18:19], v[194:195], v[146:147]
	v_pk_fma_f32 v[148:149], v[20:21], v[196:197], v[148:149]
	v_pk_fma_f32 v[150:151], v[22:23], v[198:199], v[150:151]
	v_pk_fma_f32 v[152:153], v[24:25], v[200:201], v[152:153]
	v_pk_fma_f32 v[154:155], v[26:27], v[202:203], v[154:155]
	v_pk_fma_f32 v[156:157], v[28:29], v[204:205], v[156:157]
	v_pk_fma_f32 v[158:159], v[30:31], v[206:207], v[158:159]
	v_pk_mul_f32 v[250:251], v[144:145], v[144:145]
	v_pk_fma_f32 v[250:251], v[146:147], v[146:147], v[250:251]
	v_pk_fma_f32 v[250:251], v[148:149], v[148:149], v[250:251]
	v_pk_fma_f32 v[250:251], v[150:151], v[150:151], v[250:251]
	v_pk_fma_f32 v[250:251], v[152:153], v[152:153], v[250:251]
	v_pk_fma_f32 v[250:251], v[154:155], v[154:155], v[250:251]
	v_pk_fma_f32 v[250:251], v[156:157], v[156:157], v[250:251]
	v_pk_fma_f32 v[250:251], v[158:159], v[158:159], v[250:251]
	v_pk_fma_f32 v[160:161], v[32:33], v[192:193], v[160:161]
	v_pk_fma_f32 v[162:163], v[34:35], v[194:195], v[162:163]
	v_pk_fma_f32 v[164:165], v[36:37], v[196:197], v[164:165]
	v_pk_fma_f32 v[166:167], v[38:39], v[198:199], v[166:167]
	v_pk_fma_f32 v[168:169], v[40:41], v[200:201], v[168:169]
	v_pk_fma_f32 v[170:171], v[42:43], v[202:203], v[170:171]
	v_pk_fma_f32 v[172:173], v[44:45], v[204:205], v[172:173]
	v_pk_fma_f32 v[174:175], v[46:47], v[206:207], v[174:175]
	v_pk_mul_f32 v[252:253], v[160:161], v[160:161]
	v_pk_fma_f32 v[252:253], v[162:163], v[162:163], v[252:253]
	v_pk_fma_f32 v[252:253], v[164:165], v[164:165], v[252:253]
	v_pk_fma_f32 v[252:253], v[166:167], v[166:167], v[252:253]
	v_pk_fma_f32 v[252:253], v[168:169], v[168:169], v[252:253]
	v_pk_fma_f32 v[252:253], v[170:171], v[170:171], v[252:253]
	v_pk_fma_f32 v[252:253], v[172:173], v[172:173], v[252:253]
	v_pk_fma_f32 v[252:253], v[174:175], v[174:175], v[252:253]
	v_pk_fma_f32 v[176:177], v[48:49], v[192:193], v[176:177]
	v_pk_fma_f32 v[178:179], v[50:51], v[194:195], v[178:179]
	v_pk_fma_f32 v[180:181], v[52:53], v[196:197], v[180:181]
	v_pk_fma_f32 v[182:183], v[54:55], v[198:199], v[182:183]
	v_pk_fma_f32 v[184:185], v[56:57], v[200:201], v[184:185]
	v_pk_fma_f32 v[186:187], v[58:59], v[202:203], v[186:187]
	v_pk_fma_f32 v[188:189], v[60:61], v[204:205], v[188:189]
	v_pk_fma_f32 v[190:191], v[62:63], v[206:207], v[190:191]
	v_pk_mul_f32 v[254:255], v[176:177], v[176:177]
	v_pk_fma_f32 v[254:255], v[178:179], v[178:179], v[254:255]
	v_pk_fma_f32 v[254:255], v[180:181], v[180:181], v[254:255]
	v_pk_fma_f32 v[254:255], v[182:183], v[182:183], v[254:255]
	v_pk_fma_f32 v[254:255], v[184:185], v[184:185], v[254:255]
	v_pk_fma_f32 v[254:255], v[186:187], v[186:187], v[254:255]
	v_pk_fma_f32 v[254:255], v[188:189], v[188:189], v[254:255]
; __device__ __forceinline__ float wave_sum(float v) {
;     { const auto r = __builtin_amdgcn_permlane32_swap(__float_as_uint(v), __float_as_uint(v), false, false); v = __uint_as_float(r[0]) + __uint_as_float(r[1]); }
;     { const auto r = __builtin_amdgcn_permlane16_swap(__float_as_uint(v), __float_as_uint(v), false, false); v = __uint_as_float(r[0]) + __uint_as_float(r[1]); }
;     v += __int_as_float(__builtin_amdgcn_mov_dpp(__float_as_int(v), 0xB1, 0xF, 0xF, true));
;     v += __int_as_float(__builtin_amdgcn_mov_dpp(__float_as_int(v), 0x4E, 0xF, 0xF, true));
;     v += __int_as_float(__builtin_amdgcn_mov_dpp(__float_as_int(v), 0x141, 0xF, 0xF, true));
;     v += __int_as_float(__builtin_amdgcn_mov_dpp(__float_as_int(v), 0x140, 0xF, 0xF, true));
;     return v;
; __device__ __forceinline__ void peer_tile(const Args& A, LAS unsigned char* lds, int tile) {
;     ...
;             for (int j = 0; j < 4; ++j) { const f32x4 x1 = *(const f32x4*)(orow + 4 * j), gg = *(const f32x4*)(g2 + 4 * j);
;                 const f32x4 pe = (f32x4){oacc[tk][2 * j][0], oacc[tk][2 * j][1], oacc[tk][2 * j + 1][0], oacc[tk][2 * j + 1][1]};
;                 xv[j] = x1 + gg * pe; ss += (xv[j][0] * xv[j][0] + xv[j][1] * xv[j][1]) + (xv[j][2] * xv[j][2] + xv[j][3] * xv[j][3]); }
;             const float rstd = rsqrtf(wave_sum(ss) * (1.f / 1024.f) + 1e-6f);
; #pragma unroll
;             for (int j = 0; j < 4; ++j) { const f32x4 fg = *(const f32x4*)(A.final_g + 16 * lane + 4 * j); *(f32x4*)(orow + 4 * j) = xv[j] * rstd * fg; }
	v_pk_fma_f32 v[254:255], v[190:191], v[190:191], v[254:255]
	v_add_f32_e32 v248, v248, v249
	v_add_f32_e32 v250, v250, v251
	v_add_f32_e32 v252, v252, v253
	v_add_f32_e32 v254, v254, v255
	v_mov_b32_e32 v249, v248
	v_mov_b32_e32 v251, v250
	v_mov_b32_e32 v253, v252
	v_mov_b32_e32 v255, v254
	v_permlane32_swap_b32_e32 v248, v249
	v_permlane32_swap_b32_e32 v250, v251
	v_permlane32_swap_b32_e32 v252, v253
	v_permlane32_swap_b32_e32 v254, v255
	v_add_f32_e32 v248, v248, v249
	v_add_f32_e32 v250, v250, v251
	v_add_f32_e32 v252, v252, v253
	v_add_f32_e32 v254, v254, v255
	v_mov_b32_e32 v249, v248
	v_mov_b32_e32 v251, v250
	v_mov_b32_e32 v253, v252
	v_mov_b32_e32 v255, v254
	v_permlane16_swap_b32_e32 v248, v249
	v_permlane16_swap_b32_e32 v250, v251
	v_permlane16_swap_b32_e32 v252, v253
	v_permlane16_swap_b32_e32 v254, v255
	v_add_f32_e32 v248, v248, v249
	v_add_f32_e32 v250, v250, v251
	v_add_f32_e32 v252, v252, v253
	v_add_f32_e32 v254, v254, v255
	v_add_f32_dpp v248, v248, v248 quad_perm:[1,0,3,2] row_mask:0xf bank_mask:0xf bound_ctrl:1
	v_add_f32_dpp v250, v250, v250 quad_perm:[1,0,3,2] row_mask:0xf bank_mask:0xf bound_ctrl:1
	v_add_f32_dpp v252, v252, v252 quad_perm:[1,0,3,2] row_mask:0xf bank_mask:0xf bound_ctrl:1
	v_add_f32_dpp v254, v254, v254 quad_perm:[1,0,3,2] row_mask:0xf bank_mask:0xf bound_ctrl:1
	v_add_f32_dpp v248, v248, v248 quad_perm:[2,3,0,1] row_mask:0xf bank_mask:0xf bound_ctrl:1
	v_add_f32_dpp v250, v250, v250 quad_perm:[2,3,0,1] row_mask:0xf bank_mask:0xf bound_ctrl:1
	v_add_f32_dpp v252, v252, v252 quad_perm:[2,3,0,1] row_mask:0xf bank_mask:0xf bound_ctrl:1
	v_add_f32_dpp v254, v254, v254 quad_perm:[2,3,0,1] row_mask:0xf bank_mask:0xf bound_ctrl:1
	v_add_f32_dpp v248, v248, v248 row_half_mirror row_mask:0xf bank_mask:0xf bound_ctrl:1
	v_add_f32_dpp v250, v250, v250 row_half_mirror row_mask:0xf bank_mask:0xf bound_ctrl:1
	v_add_f32_dpp v252, v252, v252 row_half_mirror row_mask:0xf bank_mask:0xf bound_ctrl:1
	v_add_f32_dpp v254, v254, v254 row_half_mirror row_mask:0xf bank_mask:0xf bound_ctrl:1
	v_add_f32_dpp v248, v248, v248 row_mirror row_mask:0xf bank_mask:0xf bound_ctrl:1
	v_add_f32_dpp v250, v250, v250 row_mirror row_mask:0xf bank_mask:0xf bound_ctrl:1
	v_add_f32_dpp v252, v252, v252 row_mirror row_mask:0xf bank_mask:0xf bound_ctrl:1
	v_add_f32_dpp v254, v254, v254 row_mirror row_mask:0xf bank_mask:0xf bound_ctrl:1
	v_fmamk_f32 v248, v248, 0x3a800000, v243
	v_fmamk_f32 v250, v250, 0x3a800000, v243
	v_fmamk_f32 v252, v252, 0x3a800000, v243
	v_fmamk_f32 v254, v254, 0x3a800000, v243
	v_rsq_f32_e32 v248, v248
	v_rsq_f32_e32 v250, v250
	v_rsq_f32_e32 v252, v252
	v_rsq_f32_e32 v254, v254
	s_nop 0
	v_pk_mul_f32 v[128:129], v[128:129], v[248:249] op_sel_hi:[1,0]
	v_pk_mul_f32 v[130:131], v[130:131], v[248:249] op_sel_hi:[1,0]
	v_pk_mul_f32 v[132:133], v[132:133], v[248:249] op_sel_hi:[1,0]
	v_pk_mul_f32 v[134:135], v[134:135], v[248:249] op_sel_hi:[1,0]
	v_pk_mul_f32 v[136:137], v[136:137], v[248:249] op_sel_hi:[1,0]
	v_pk_mul_f32 v[138:139], v[138:139], v[248:249] op_sel_hi:[1,0]
	v_pk_mul_f32 v[140:141], v[140:141], v[248:249] op_sel_hi:[1,0]
	v_pk_mul_f32 v[142:143], v[142:143], v[248:249] op_sel_hi:[1,0]
	v_pk_mul_f32 v[128:129], v[216:217], v[128:129]
	v_pk_mul_f32 v[130:131], v[218:219], v[130:131]
	v_pk_mul_f32 v[132:133], v[220:221], v[132:133]
	v_pk_mul_f32 v[134:135], v[222:223], v[134:135]
	v_pk_mul_f32 v[136:137], v[224:225], v[136:137]
	v_pk_mul_f32 v[138:139], v[226:227], v[138:139]
	v_pk_mul_f32 v[140:141], v[228:229], v[140:141]
	v_pk_mul_f32 v[142:143], v[230:231], v[142:143]
	global_store_dwordx4 v246, v[128:131], s[24:25]
	global_store_dwordx4 v246, v[132:135], s[24:25] offset:16
	global_store_dwordx4 v246, v[136:139], s[24:25] offset:32
	global_store_dwordx4 v246, v[140:143], s[24:25] offset:48
	v_pk_mul_f32 v[144:145], v[144:145], v[250:251] op_sel_hi:[1,0]
	v_pk_mul_f32 v[146:147], v[146:147], v[250:251] op_sel_hi:[1,0]
	v_pk_mul_f32 v[148:149], v[148:149], v[250:251] op_sel_hi:[1,0]
	v_pk_mul_f32 v[150:151], v[150:151], v[250:251] op_sel_hi:[1,0]
	v_pk_mul_f32 v[152:153], v[152:153], v[250:251] op_sel_hi:[1,0]
	v_pk_mul_f32 v[154:155], v[154:155], v[250:251] op_sel_hi:[1,0]
	v_pk_mul_f32 v[156:157], v[156:157], v[250:251] op_sel_hi:[1,0]
	v_pk_mul_f32 v[158:159], v[158:159], v[250:251] op_sel_hi:[1,0]
	v_pk_mul_f32 v[144:145], v[216:217], v[144:145]
	v_pk_mul_f32 v[146:147], v[218:219], v[146:147]
	v_pk_mul_f32 v[148:149], v[220:221], v[148:149]
	v_pk_mul_f32 v[150:151], v[222:223], v[150:151]
	v_pk_mul_f32 v[152:153], v[224:225], v[152:153]
	v_pk_mul_f32 v[154:155], v[226:227], v[154:155]
	v_pk_mul_f32 v[156:157], v[228:229], v[156:157]
	v_pk_mul_f32 v[158:159], v[230:231], v[158:159]
	global_store_dwordx4 v246, v[144:147], s[26:27]
	global_store_dwordx4 v246, v[148:151], s[26:27] offset:16
	global_store_dwordx4 v246, v[152:155], s[26:27] offset:32
	global_store_dwordx4 v246, v[156:159], s[26:27] offset:48
	v_pk_mul_f32 v[160:161], v[160:161], v[252:253] op_sel_hi:[1,0]
	v_pk_mul_f32 v[162:163], v[162:163], v[252:253] op_sel_hi:[1,0]
	v_pk_mul_f32 v[164:165], v[164:165], v[252:253] op_sel_hi:[1,0]
	v_pk_mul_f32 v[166:167], v[166:167], v[252:253] op_sel_hi:[1,0]
	v_pk_mul_f32 v[168:169], v[168:169], v[252:253] op_sel_hi:[1,0]
	v_pk_mul_f32 v[170:171], v[170:171], v[252:253] op_sel_hi:[1,0]
	v_pk_mul_f32 v[172:173], v[172:173], v[252:253] op_sel_hi:[1,0]
	v_pk_mul_f32 v[174:175], v[174:175], v[252:253] op_sel_hi:[1,0]
	v_pk_mul_f32 v[160:161], v[216:217], v[160:161]
	v_pk_mul_f32 v[162:163], v[218:219], v[162:163]
	v_pk_mul_f32 v[164:165], v[220:221], v[164:165]
	v_pk_mul_f32 v[166:167], v[222:223], v[166:167]
; __device__ __forceinline__ void peer_tile(const Args& A, LAS unsigned char* lds, int tile) {
;     ...
;             for (int j = 0; j < 4; ++j) { const f32x4 x1 = *(const f32x4*)(orow + 4 * j), gg = *(const f32x4*)(g2 + 4 * j);
;                 const f32x4 pe = (f32x4){oacc[tk][2 * j][0], oacc[tk][2 * j][1], oacc[tk][2 * j + 1][0], oacc[tk][2 * j + 1][1]};
;                 xv[j] = x1 + gg * pe; ss += (xv[j][0] * xv[j][0] + xv[j][1] * xv[j][1]) + (xv[j][2] * xv[j][2] + xv[j][3] * xv[j][3]); }
;             const float rstd = rsqrtf(wave_sum(ss) * (1.f / 1024.f) + 1e-6f);
; #pragma unroll
;             for (int j = 0; j < 4; ++j) { const f32x4 fg = *(const f32x4*)(A.final_g + 16 * lane + 4 * j); *(f32x4*)(orow + 4 * j) = xv[j] * rstd * fg; }
	v_pk_mul_f32 v[168:169], v[224:225], v[168:169]
	v_pk_mul_f32 v[170:171], v[226:227], v[170:171]
	v_pk_mul_f32 v[172:173], v[228:229], v[172:173]
	v_pk_mul_f32 v[174:175], v[230:231], v[174:175]
	global_store_dwordx4 v246, v[160:163], s[28:29]
	global_store_dwordx4 v246, v[164:167], s[28:29] offset:16
	global_store_dwordx4 v246, v[168:171], s[28:29] offset:32
	global_store_dwordx4 v246, v[172:175], s[28:29] offset:48
	v_pk_mul_f32 v[176:177], v[176:177], v[254:255] op_sel_hi:[1,0]
	v_pk_mul_f32 v[178:179], v[178:179], v[254:255] op_sel_hi:[1,0]
	v_pk_mul_f32 v[180:181], v[180:181], v[254:255] op_sel_hi:[1,0]
	v_pk_mul_f32 v[182:183], v[182:183], v[254:255] op_sel_hi:[1,0]
	v_pk_mul_f32 v[184:185], v[184:185], v[254:255] op_sel_hi:[1,0]
	v_pk_mul_f32 v[186:187], v[186:187], v[254:255] op_sel_hi:[1,0]
	v_pk_mul_f32 v[188:189], v[188:189], v[254:255] op_sel_hi:[1,0]
	v_pk_mul_f32 v[190:191], v[190:191], v[254:255] op_sel_hi:[1,0]
	v_pk_mul_f32 v[176:177], v[216:217], v[176:177]
	v_pk_mul_f32 v[178:179], v[218:219], v[178:179]
	v_pk_mul_f32 v[180:181], v[220:221], v[180:181]
	v_pk_mul_f32 v[182:183], v[222:223], v[182:183]
	v_pk_mul_f32 v[184:185], v[224:225], v[184:185]
	v_pk_mul_f32 v[186:187], v[226:227], v[186:187]
	v_pk_mul_f32 v[188:189], v[228:229], v[188:189]
	v_pk_mul_f32 v[190:191], v[230:231], v[190:191]
	global_store_dwordx4 v246, v[176:179], s[30:31]
	global_store_dwordx4 v246, v[180:183], s[30:31] offset:16
	global_store_dwordx4 v246, v[184:187], s[30:31] offset:32
	global_store_dwordx4 v246, v[188:191], s[30:31] offset:48
	s_nop 1
	s_add_i32 s0, s77, 4
	s_lshl_b32 s0, s0, 12
	s_add_u32 s24, s48, s0
	s_addc_u32 s25, s49, 0
	s_add_i32 s0, s77, 5
	s_lshl_b32 s0, s0, 12
	s_add_u32 s26, s48, s0
	s_addc_u32 s27, s49, 0
	s_add_i32 s0, s77, 6
	s_lshl_b32 s0, s0, 12
	s_add_u32 s28, s48, s0
	s_addc_u32 s29, s49, 0
	s_add_i32 s0, s77, 7
	s_lshl_b32 s0, s0, 12
	s_add_u32 s30, s48, s0
	s_addc_u32 s31, s49, 0
	global_load_dwordx4 v[128:131], v246, s[24:25]
	global_load_dwordx4 v[132:135], v246, s[24:25] offset:16
	global_load_dwordx4 v[136:139], v246, s[24:25] offset:32
	global_load_dwordx4 v[140:143], v246, s[24:25] offset:48
	global_load_dwordx4 v[144:147], v246, s[26:27]
	global_load_dwordx4 v[148:151], v246, s[26:27] offset:16
	global_load_dwordx4 v[152:155], v246, s[26:27] offset:32
	global_load_dwordx4 v[156:159], v246, s[26:27] offset:48
	global_load_dwordx4 v[160:163], v246, s[28:29]
	global_load_dwordx4 v[164:167], v246, s[28:29] offset:16
	global_load_dwordx4 v[168:171], v246, s[28:29] offset:32
	global_load_dwordx4 v[172:175], v246, s[28:29] offset:48
	global_load_dwordx4 v[176:179], v246, s[30:31]
	global_load_dwordx4 v[180:183], v246, s[30:31] offset:16
	global_load_dwordx4 v[184:187], v246, s[30:31] offset:32
	global_load_dwordx4 v[188:191], v246, s[30:31] offset:48
	s_waitcnt vmcnt(0)
	v_pk_fma_f32 v[128:129], v[64:65], v[192:193], v[128:129]
	v_pk_fma_f32 v[130:131], v[66:67], v[194:195], v[130:131]
	v_pk_fma_f32 v[132:133], v[68:69], v[196:197], v[132:133]
	v_pk_fma_f32 v[134:135], v[70:71], v[198:199], v[134:135]
	v_pk_fma_f32 v[136:137], v[72:73], v[200:201], v[136:137]
	v_pk_fma_f32 v[138:139], v[74:75], v[202:203], v[138:139]
	v_pk_fma_f32 v[140:141], v[76:77], v[204:205], v[140:141]
	v_pk_fma_f32 v[142:143], v[78:79], v[206:207], v[142:143]
	v_pk_mul_f32 v[248:249], v[128:129], v[128:129]
	v_pk_fma_f32 v[248:249], v[130:131], v[130:131], v[248:249]
	v_pk_fma_f32 v[248:249], v[132:133], v[132:133], v[248:249]
	v_pk_fma_f32 v[248:249], v[134:135], v[134:135], v[248:249]
	v_pk_fma_f32 v[248:249], v[136:137], v[136:137], v[248:249]
	v_pk_fma_f32 v[248:249], v[138:139], v[138:139], v[248:249]
	v_pk_fma_f32 v[248:249], v[140:141], v[140:141], v[248:249]
	v_pk_fma_f32 v[248:249], v[142:143], v[142:143], v[248:249]
	v_pk_fma_f32 v[144:145], v[80:81], v[192:193], v[144:145]
	v_pk_fma_f32 v[146:147], v[82:83], v[194:195], v[146:147]
	v_pk_fma_f32 v[148:149], v[84:85], v[196:197], v[148:149]
	v_pk_fma_f32 v[150:151], v[86:87], v[198:199], v[150:151]
	v_pk_fma_f32 v[152:153], v[88:89], v[200:201], v[152:153]
	v_pk_fma_f32 v[154:155], v[90:91], v[202:203], v[154:155]
	v_pk_fma_f32 v[156:157], v[92:93], v[204:205], v[156:157]
	v_pk_fma_f32 v[158:159], v[94:95], v[206:207], v[158:159]
	v_pk_mul_f32 v[250:251], v[144:145], v[144:145]
	v_pk_fma_f32 v[250:251], v[146:147], v[146:147], v[250:251]
	v_pk_fma_f32 v[250:251], v[148:149], v[148:149], v[250:251]
	v_pk_fma_f32 v[250:251], v[150:151], v[150:151], v[250:251]
	v_pk_fma_f32 v[250:251], v[152:153], v[152:153], v[250:251]
	v_pk_fma_f32 v[250:251], v[154:155], v[154:155], v[250:251]
	v_pk_fma_f32 v[250:251], v[156:157], v[156:157], v[250:251]
	v_pk_fma_f32 v[250:251], v[158:159], v[158:159], v[250:251]
	v_pk_fma_f32 v[160:161], v[96:97], v[192:193], v[160:161]
	v_pk_fma_f32 v[162:163], v[98:99], v[194:195], v[162:163]
	v_pk_fma_f32 v[164:165], v[100:101], v[196:197], v[164:165]
	v_pk_fma_f32 v[166:167], v[102:103], v[198:199], v[166:167]
	v_pk_fma_f32 v[168:169], v[104:105], v[200:201], v[168:169]
	v_pk_fma_f32 v[170:171], v[106:107], v[202:203], v[170:171]
	v_pk_fma_f32 v[172:173], v[108:109], v[204:205], v[172:173]
	v_pk_fma_f32 v[174:175], v[110:111], v[206:207], v[174:175]
	v_pk_mul_f32 v[252:253], v[160:161], v[160:161]
	v_pk_fma_f32 v[252:253], v[162:163], v[162:163], v[252:253]
	v_pk_fma_f32 v[252:253], v[164:165], v[164:165], v[252:253]
	v_pk_fma_f32 v[252:253], v[166:167], v[166:167], v[252:253]
	v_pk_fma_f32 v[252:253], v[168:169], v[168:169], v[252:253]
	v_pk_fma_f32 v[252:253], v[170:171], v[170:171], v[252:253]
	v_pk_fma_f32 v[252:253], v[172:173], v[172:173], v[252:253]
; __device__ __forceinline__ float wave_sum(float v) {
;     { const auto r = __builtin_amdgcn_permlane32_swap(__float_as_uint(v), __float_as_uint(v), false, false); v = __uint_as_float(r[0]) + __uint_as_float(r[1]); }
;     { const auto r = __builtin_amdgcn_permlane16_swap(__float_as_uint(v), __float_as_uint(v), false, false); v = __uint_as_float(r[0]) + __uint_as_float(r[1]); }
;     v += __int_as_float(__builtin_amdgcn_mov_dpp(__float_as_int(v), 0xB1, 0xF, 0xF, true));
;     v += __int_as_float(__builtin_amdgcn_mov_dpp(__float_as_int(v), 0x4E, 0xF, 0xF, true));
;     v += __int_as_float(__builtin_amdgcn_mov_dpp(__float_as_int(v), 0x141, 0xF, 0xF, true));
;     v += __int_as_float(__builtin_amdgcn_mov_dpp(__float_as_int(v), 0x140, 0xF, 0xF, true));
;     return v;
; __device__ __forceinline__ void peer_tile(const Args& A, LAS unsigned char* lds, int tile) {
;     ...
;             for (int j = 0; j < 4; ++j) { const f32x4 x1 = *(const f32x4*)(orow + 4 * j), gg = *(const f32x4*)(g2 + 4 * j);
;                 const f32x4 pe = (f32x4){oacc[tk][2 * j][0], oacc[tk][2 * j][1], oacc[tk][2 * j + 1][0], oacc[tk][2 * j + 1][1]};
;                 xv[j] = x1 + gg * pe; ss += (xv[j][0] * xv[j][0] + xv[j][1] * xv[j][1]) + (xv[j][2] * xv[j][2] + xv[j][3] * xv[j][3]); }
;             const float rstd = rsqrtf(wave_sum(ss) * (1.f / 1024.f) + 1e-6f);
; #pragma unroll
;             for (int j = 0; j < 4; ++j) { const f32x4 fg = *(const f32x4*)(A.final_g + 16 * lane + 4 * j); *(f32x4*)(orow + 4 * j) = xv[j] * rstd * fg; }
	v_pk_fma_f32 v[252:253], v[174:175], v[174:175], v[252:253]
	v_pk_fma_f32 v[176:177], v[112:113], v[192:193], v[176:177]
	v_pk_fma_f32 v[178:179], v[114:115], v[194:195], v[178:179]
	v_pk_fma_f32 v[180:181], v[116:117], v[196:197], v[180:181]
	v_pk_fma_f32 v[182:183], v[118:119], v[198:199], v[182:183]
	v_pk_fma_f32 v[184:185], v[120:121], v[200:201], v[184:185]
	v_pk_fma_f32 v[186:187], v[122:123], v[202:203], v[186:187]
	v_pk_fma_f32 v[188:189], v[124:125], v[204:205], v[188:189]
	v_pk_fma_f32 v[190:191], v[126:127], v[206:207], v[190:191]
	v_pk_mul_f32 v[254:255], v[176:177], v[176:177]
	v_pk_fma_f32 v[254:255], v[178:179], v[178:179], v[254:255]
	v_pk_fma_f32 v[254:255], v[180:181], v[180:181], v[254:255]
	v_pk_fma_f32 v[254:255], v[182:183], v[182:183], v[254:255]
	v_pk_fma_f32 v[254:255], v[184:185], v[184:185], v[254:255]
	v_pk_fma_f32 v[254:255], v[186:187], v[186:187], v[254:255]
	v_pk_fma_f32 v[254:255], v[188:189], v[188:189], v[254:255]
	v_pk_fma_f32 v[254:255], v[190:191], v[190:191], v[254:255]
	v_add_f32_e32 v248, v248, v249
	v_add_f32_e32 v250, v250, v251
	v_add_f32_e32 v252, v252, v253
	v_add_f32_e32 v254, v254, v255
	v_mov_b32_e32 v249, v248
	v_mov_b32_e32 v251, v250
	v_mov_b32_e32 v253, v252
	v_mov_b32_e32 v255, v254
	v_permlane32_swap_b32_e32 v248, v249
	v_permlane32_swap_b32_e32 v250, v251
	v_permlane32_swap_b32_e32 v252, v253
	v_permlane32_swap_b32_e32 v254, v255
	v_add_f32_e32 v248, v248, v249
	v_add_f32_e32 v250, v250, v251
	v_add_f32_e32 v252, v252, v253
	v_add_f32_e32 v254, v254, v255
	v_mov_b32_e32 v249, v248
	v_mov_b32_e32 v251, v250
	v_mov_b32_e32 v253, v252
	v_mov_b32_e32 v255, v254
	v_permlane16_swap_b32_e32 v248, v249
	v_permlane16_swap_b32_e32 v250, v251
	v_permlane16_swap_b32_e32 v252, v253
	v_permlane16_swap_b32_e32 v254, v255
	v_add_f32_e32 v248, v248, v249
	v_add_f32_e32 v250, v250, v251
	v_add_f32_e32 v252, v252, v253
	v_add_f32_e32 v254, v254, v255
	v_add_f32_dpp v248, v248, v248 quad_perm:[1,0,3,2] row_mask:0xf bank_mask:0xf bound_ctrl:1
	v_add_f32_dpp v250, v250, v250 quad_perm:[1,0,3,2] row_mask:0xf bank_mask:0xf bound_ctrl:1
	v_add_f32_dpp v252, v252, v252 quad_perm:[1,0,3,2] row_mask:0xf bank_mask:0xf bound_ctrl:1
	v_add_f32_dpp v254, v254, v254 quad_perm:[1,0,3,2] row_mask:0xf bank_mask:0xf bound_ctrl:1
	v_add_f32_dpp v248, v248, v248 quad_perm:[2,3,0,1] row_mask:0xf bank_mask:0xf bound_ctrl:1
	v_add_f32_dpp v250, v250, v250 quad_perm:[2,3,0,1] row_mask:0xf bank_mask:0xf bound_ctrl:1
	v_add_f32_dpp v252, v252, v252 quad_perm:[2,3,0,1] row_mask:0xf bank_mask:0xf bound_ctrl:1
	v_add_f32_dpp v254, v254, v254 quad_perm:[2,3,0,1] row_mask:0xf bank_mask:0xf bound_ctrl:1
	v_add_f32_dpp v248, v248, v248 row_half_mirror row_mask:0xf bank_mask:0xf bound_ctrl:1
	v_add_f32_dpp v250, v250, v250 row_half_mirror row_mask:0xf bank_mask:0xf bound_ctrl:1
	v_add_f32_dpp v252, v252, v252 row_half_mirror row_mask:0xf bank_mask:0xf bound_ctrl:1
	v_add_f32_dpp v254, v254, v254 row_half_mirror row_mask:0xf bank_mask:0xf bound_ctrl:1
	v_add_f32_dpp v248, v248, v248 row_mirror row_mask:0xf bank_mask:0xf bound_ctrl:1
	v_add_f32_dpp v250, v250, v250 row_mirror row_mask:0xf bank_mask:0xf bound_ctrl:1
	v_add_f32_dpp v252, v252, v252 row_mirror row_mask:0xf bank_mask:0xf bound_ctrl:1
	v_add_f32_dpp v254, v254, v254 row_mirror row_mask:0xf bank_mask:0xf bound_ctrl:1
	v_fmamk_f32 v248, v248, 0x3a800000, v243
	v_fmamk_f32 v250, v250, 0x3a800000, v243
	v_fmamk_f32 v252, v252, 0x3a800000, v243
	v_fmamk_f32 v254, v254, 0x3a800000, v243
	v_rsq_f32_e32 v248, v248
	v_rsq_f32_e32 v250, v250
	v_rsq_f32_e32 v252, v252
	v_rsq_f32_e32 v254, v254
	s_nop 0
	v_pk_mul_f32 v[128:129], v[128:129], v[248:249] op_sel_hi:[1,0]
	v_pk_mul_f32 v[130:131], v[130:131], v[248:249] op_sel_hi:[1,0]
	v_pk_mul_f32 v[132:133], v[132:133], v[248:249] op_sel_hi:[1,0]
	v_pk_mul_f32 v[134:135], v[134:135], v[248:249] op_sel_hi:[1,0]
	v_pk_mul_f32 v[136:137], v[136:137], v[248:249] op_sel_hi:[1,0]
	v_pk_mul_f32 v[138:139], v[138:139], v[248:249] op_sel_hi:[1,0]
	v_pk_mul_f32 v[140:141], v[140:141], v[248:249] op_sel_hi:[1,0]
	v_pk_mul_f32 v[142:143], v[142:143], v[248:249] op_sel_hi:[1,0]
	v_pk_mul_f32 v[128:129], v[216:217], v[128:129]
; __device__ __forceinline__ void peer_tile(const Args& A, LAS unsigned char* lds, int tile) {
;     ...
;             const float rstd = rsqrtf(wave_sum(ss) * (1.f / 1024.f) + 1e-6f);
; #pragma unroll
;             for (int j = 0; j < 4; ++j) { const f32x4 fg = *(const f32x4*)(A.final_g + 16 * lane + 4 * j); *(f32x4*)(orow + 4 * j) = xv[j] * rstd * fg; }
	v_pk_mul_f32 v[130:131], v[218:219], v[130:131]
	v_pk_mul_f32 v[132:133], v[220:221], v[132:133]
	v_pk_mul_f32 v[134:135], v[222:223], v[134:135]
	v_pk_mul_f32 v[136:137], v[224:225], v[136:137]
	v_pk_mul_f32 v[138:139], v[226:227], v[138:139]
	v_pk_mul_f32 v[140:141], v[228:229], v[140:141]
	v_pk_mul_f32 v[142:143], v[230:231], v[142:143]
	global_store_dwordx4 v246, v[128:131], s[24:25]
	global_store_dwordx4 v246, v[132:135], s[24:25] offset:16
	global_store_dwordx4 v246, v[136:139], s[24:25] offset:32
	global_store_dwordx4 v246, v[140:143], s[24:25] offset:48
	v_pk_mul_f32 v[144:145], v[144:145], v[250:251] op_sel_hi:[1,0]
	v_pk_mul_f32 v[146:147], v[146:147], v[250:251] op_sel_hi:[1,0]
	v_pk_mul_f32 v[148:149], v[148:149], v[250:251] op_sel_hi:[1,0]
	v_pk_mul_f32 v[150:151], v[150:151], v[250:251] op_sel_hi:[1,0]
	v_pk_mul_f32 v[152:153], v[152:153], v[250:251] op_sel_hi:[1,0]
	v_pk_mul_f32 v[154:155], v[154:155], v[250:251] op_sel_hi:[1,0]
	v_pk_mul_f32 v[156:157], v[156:157], v[250:251] op_sel_hi:[1,0]
	v_pk_mul_f32 v[158:159], v[158:159], v[250:251] op_sel_hi:[1,0]
	v_pk_mul_f32 v[144:145], v[216:217], v[144:145]
	v_pk_mul_f32 v[146:147], v[218:219], v[146:147]
	v_pk_mul_f32 v[148:149], v[220:221], v[148:149]
	v_pk_mul_f32 v[150:151], v[222:223], v[150:151]
	v_pk_mul_f32 v[152:153], v[224:225], v[152:153]
	v_pk_mul_f32 v[154:155], v[226:227], v[154:155]
	v_pk_mul_f32 v[156:157], v[228:229], v[156:157]
	v_pk_mul_f32 v[158:159], v[230:231], v[158:159]
	global_store_dwordx4 v246, v[144:147], s[26:27]
	global_store_dwordx4 v246, v[148:151], s[26:27] offset:16
	global_store_dwordx4 v246, v[152:155], s[26:27] offset:32
	global_store_dwordx4 v246, v[156:159], s[26:27] offset:48
	v_pk_mul_f32 v[160:161], v[160:161], v[252:253] op_sel_hi:[1,0]
	v_pk_mul_f32 v[162:163], v[162:163], v[252:253] op_sel_hi:[1,0]
	v_pk_mul_f32 v[164:165], v[164:165], v[252:253] op_sel_hi:[1,0]
	v_pk_mul_f32 v[166:167], v[166:167], v[252:253] op_sel_hi:[1,0]
	v_pk_mul_f32 v[168:169], v[168:169], v[252:253] op_sel_hi:[1,0]
	v_pk_mul_f32 v[170:171], v[170:171], v[252:253] op_sel_hi:[1,0]
	v_pk_mul_f32 v[172:173], v[172:173], v[252:253] op_sel_hi:[1,0]
	v_pk_mul_f32 v[174:175], v[174:175], v[252:253] op_sel_hi:[1,0]
	v_pk_mul_f32 v[160:161], v[216:217], v[160:161]
	v_pk_mul_f32 v[162:163], v[218:219], v[162:163]
	v_pk_mul_f32 v[164:165], v[220:221], v[164:165]
	v_pk_mul_f32 v[166:167], v[222:223], v[166:167]
	v_pk_mul_f32 v[168:169], v[224:225], v[168:169]
	v_pk_mul_f32 v[170:171], v[226:227], v[170:171]
	v_pk_mul_f32 v[172:173], v[228:229], v[172:173]
	v_pk_mul_f32 v[174:175], v[230:231], v[174:175]
	global_store_dwordx4 v246, v[160:163], s[28:29]
	global_store_dwordx4 v246, v[164:167], s[28:29] offset:16
	global_store_dwordx4 v246, v[168:171], s[28:29] offset:32
	global_store_dwordx4 v246, v[172:175], s[28:29] offset:48
	v_pk_mul_f32 v[176:177], v[176:177], v[254:255] op_sel_hi:[1,0]
	v_pk_mul_f32 v[178:179], v[178:179], v[254:255] op_sel_hi:[1,0]
	v_pk_mul_f32 v[180:181], v[180:181], v[254:255] op_sel_hi:[1,0]
	v_pk_mul_f32 v[182:183], v[182:183], v[254:255] op_sel_hi:[1,0]
	v_pk_mul_f32 v[184:185], v[184:185], v[254:255] op_sel_hi:[1,0]
	v_pk_mul_f32 v[186:187], v[186:187], v[254:255] op_sel_hi:[1,0]
	v_pk_mul_f32 v[188:189], v[188:189], v[254:255] op_sel_hi:[1,0]
	v_pk_mul_f32 v[190:191], v[190:191], v[254:255] op_sel_hi:[1,0]
	v_pk_mul_f32 v[176:177], v[216:217], v[176:177]
	v_pk_mul_f32 v[178:179], v[218:219], v[178:179]
	v_pk_mul_f32 v[180:181], v[220:221], v[180:181]
	v_pk_mul_f32 v[182:183], v[222:223], v[182:183]
	v_pk_mul_f32 v[184:185], v[224:225], v[184:185]
	v_pk_mul_f32 v[186:187], v[226:227], v[186:187]
	v_pk_mul_f32 v[188:189], v[228:229], v[188:189]
	v_pk_mul_f32 v[190:191], v[230:231], v[190:191]
	global_store_dwordx4 v246, v[176:179], s[30:31]
	global_store_dwordx4 v246, v[180:183], s[30:31] offset:16
	global_store_dwordx4 v246, v[184:187], s[30:31] offset:32
	global_store_dwordx4 v246, v[188:191], s[30:31] offset:48
	s_nop 1
	v_mov_b32_e32 v113, 0
	v_mbcnt_lo_u32_b32 v215, -1, 0
	v_mbcnt_hi_u32_b32 v215, -1, v215
	v_and_b32_e32 v216, 64, v215
	v_add_u32_e32 v216, 64, v216
	v_xor_b32_e32 v217, 16, v215
	v_xor_b32_e32 v218, 32, v215
	s_branch .LBB0_698

